# same as previous plus twiddle-power chain in FFT passes reordered so dependent packed ops are not back-to-back
# speedup vs baseline: 1.0387x; 1.0021x over previous
; #define LAS __attribute__((address_space(3)))
; __device__ __forceinline__ cf twc(cf ws, int k16) { if (k16 == 0) return ws; if (k16 == 4) return cf{ws.y, -ws.x}; return cmul(ws, cf{c16(k16), -s16(k16)}); }
; template <int LR> __device__ __forceinline__ void dif_reg(cf (&x)[1 << LR], cf w) {
;     constexpr int R = 1 << LR; cf ws = w;
; #pragma unroll
;     for (int s = 0; s < LR; ++s) { const int half = R >> (s + 1);
; #pragma unroll
;         for (int m0 = 0; m0 < R; m0 += 2 * half)
; #pragma unroll
;             for (int mm = 0; mm < half; ++mm) { const int ia = m0 + mm, ib = ia + half; const cf a = x[ia], b = x[ib];
;                 x[ia] = cf{a.x + b.x, a.y + b.y}; const cf d{a.x - b.x, a.y - b.y};
;                 x[ib] = cmul(d, twc(ws, (mm << s) * (16 / R))); }
;         ws = cmul(ws, ws); }
; }
; template <int LR> __device__ __forceinline__ void dit_reg(cf (&x)[1 << LR], cf w) {
;     constexpr int R = 1 << LR; cf wsv[LR]; wsv[0] = w;
; #pragma unroll
;     for (int s = 1; s < LR; ++s) wsv[s] = cmul(wsv[s - 1], wsv[s - 1]);
; #pragma unroll
;     for (int s = LR - 1; s >= 0; --s) { const int half = R >> (s + 1);
; #pragma unroll
;         for (int m0 = 0; m0 < R; m0 += 2 * half)
; #pragma unroll
;             for (int mm = 0; mm < half; ++mm) { const int ia = m0 + mm, ib = ia + half; const cf a = x[ia];
;                 const cf b = cmulc(x[ib], twc(wsv[s], (mm << s) * (16 / R)));
;                 x[ia] = cf{a.x + b.x, a.y + b.y}; x[ib] = cf{a.x - b.x, a.y - b.y}; } }
; }
; __device__ __forceinline__ void lds_barrier() { asm volatile("s_waitcnt lgkmcnt(0)\n\ts_barrier" ::: "memory"); }
; template <int LR, bool INV> __device__ __forceinline__ void fft_pass(ldsf2 buf, int base, int stride, int twi) {
;     constexpr int R = 1 << LR; cf x[R];
;     const v2f wv = ((ldsf2)((LAS unsigned char*)buf + 139264))[twi];
; #pragma unroll
;     for (int m = 0; m < R; ++m) { const v2f v = buf[base + m * stride]; x[m] = cf{v.x, v.y}; }
;     const cf w{wv.x, wv.y};
;     if (INV) dit_reg<LR>(x, w); else dif_reg<LR>(x, w);
; #pragma unroll
;     for (int m = 0; m < R; ++m) buf[base + m * stride] = mkv2(x[m].x, x[m].y);
; }
.LBB0_334:
	v_cndmask_b32_e64 v3, 0, 1, s[10:11]
	v_add_u32_e32 v4, s0, v2
	v_cmp_ne_u32_e32 vcc, 1, v3
	v_ashrrev_i32_e32 v3, 4, v4
	v_lshl_add_u32 v4, v4, 3, 0
	v_add_u32_e32 v5, 0x22000, v4
	v_lshl_add_u32 v3, v3, 3, v4
	ds_read_b64 v[28:29], v5
	ds_read2st64_b64 v[4:7], v3 offset1:17
	ds_read2st64_b64 v[8:11], v3 offset0:68 offset1:85
	ds_read2st64_b64 v[12:15], v3 offset0:34 offset1:51
	ds_read2st64_b64 v[24:27], v3 offset0:102 offset1:119
	s_waitcnt lgkmcnt(4)
	v_pk_add_f32 v[30:31], v[28:29], v[28:29] op_sel:[0,1] op_sel_hi:[1,0] neg_lo:[0,0] neg_hi:[0,1]
	v_pk_mul_f32 v[36:37], v[28:29], v[28:29] op_sel:[1,1] op_sel_hi:[1,0]
	v_pk_mul_f32 v[32:33], v[30:31], s[16:17] op_sel:[0,0] op_sel_hi:[1,0]
	v_pk_fma_f32 v[36:37], v[28:29], v[28:29], v[36:37] op_sel:[0,0,0] op_sel_hi:[0,1,1] neg_lo:[0,0,1] neg_hi:[0,0,0]
	v_pk_mul_f32 v[34:35], v[30:31], s[16:17] op_sel:[1,0] op_sel_hi:[0,0] neg_lo:[0,0] neg_hi:[1,0]
	s_nop 0
	v_pk_mul_f32 v[38:39], v[36:37], v[36:37] op_sel:[1,1] op_sel_hi:[1,0]
	s_nop 0
	v_pk_fma_f32 v[38:39], v[36:37], v[36:37], v[38:39] op_sel:[0,0,0] op_sel_hi:[0,1,1] neg_lo:[0,0,1] neg_hi:[0,0,0]
	s_waitcnt lgkmcnt(0)
	v_pk_add_f32 v[40:41], v[4:5], v[8:9] neg_lo:[0,1] neg_hi:[0,1]
	v_pk_add_f32 v[42:43], v[6:7], v[10:11] neg_lo:[0,1] neg_hi:[0,1]
	v_pk_add_f32 v[44:45], v[12:13], v[24:25] neg_lo:[0,1] neg_hi:[0,1]
	v_pk_add_f32 v[46:47], v[14:15], v[26:27] neg_lo:[0,1] neg_hi:[0,1]
	v_pk_add_f32 v[4:5], v[4:5], v[8:9]
	v_pk_add_f32 v[6:7], v[6:7], v[10:11]
	v_pk_add_f32 v[12:13], v[12:13], v[24:25]
	v_pk_add_f32 v[14:15], v[14:15], v[26:27]
	v_pk_mul_f32 v[8:9], v[40:41], v[28:29] op_sel:[1,1] op_sel_hi:[1,0]
	v_pk_mul_f32 v[10:11], v[42:43], v[32:33] op_sel:[1,1] op_sel_hi:[1,0]
	v_pk_mul_f32 v[24:25], v[44:45], v[28:29] op_sel:[1,0] op_sel_hi:[1,1]
	v_pk_mul_f32 v[26:27], v[46:47], v[34:35] op_sel:[1,1] op_sel_hi:[1,0]
	v_pk_fma_f32 v[8:9], v[40:41], v[28:29], v[8:9] op_sel:[0,0,0] op_sel_hi:[0,1,1] neg_lo:[0,0,1] neg_hi:[0,0,0]
	v_pk_fma_f32 v[10:11], v[42:43], v[32:33], v[10:11] op_sel:[0,0,0] op_sel_hi:[0,1,1] neg_lo:[0,0,1] neg_hi:[0,0,0]
	v_pk_fma_f32 v[24:25], v[44:45], v[28:29], v[24:25] op_sel:[0,1,0] op_sel_hi:[0,0,1] neg_lo:[0,0,0] neg_hi:[0,1,0]
	v_pk_fma_f32 v[26:27], v[46:47], v[34:35], v[26:27] op_sel:[0,0,0] op_sel_hi:[0,1,1] neg_lo:[0,0,1] neg_hi:[0,0,0]
	v_pk_add_f32 v[40:41], v[4:5], v[12:13] neg_lo:[0,1] neg_hi:[0,1]
	v_pk_add_f32 v[42:43], v[6:7], v[14:15] neg_lo:[0,1] neg_hi:[0,1]
	v_pk_add_f32 v[44:45], v[8:9], v[24:25] neg_lo:[0,1] neg_hi:[0,1]
	v_pk_add_f32 v[46:47], v[10:11], v[26:27] neg_lo:[0,1] neg_hi:[0,1]
	v_pk_add_f32 v[4:5], v[4:5], v[12:13]
	v_pk_add_f32 v[6:7], v[6:7], v[14:15]
	v_pk_add_f32 v[8:9], v[8:9], v[24:25]
	v_pk_add_f32 v[10:11], v[10:11], v[26:27]
	v_pk_mul_f32 v[12:13], v[40:41], v[36:37] op_sel:[1,1] op_sel_hi:[1,0]
	v_pk_mul_f32 v[14:15], v[42:43], v[36:37] op_sel:[1,0] op_sel_hi:[1,1]
	v_pk_mul_f32 v[24:25], v[44:45], v[36:37] op_sel:[1,1] op_sel_hi:[1,0]
	v_pk_mul_f32 v[26:27], v[46:47], v[36:37] op_sel:[1,0] op_sel_hi:[1,1]
	v_pk_fma_f32 v[12:13], v[40:41], v[36:37], v[12:13] op_sel:[0,0,0] op_sel_hi:[0,1,1] neg_lo:[0,0,1] neg_hi:[0,0,0]
	v_pk_fma_f32 v[14:15], v[42:43], v[36:37], v[14:15] op_sel:[0,1,0] op_sel_hi:[0,0,1] neg_lo:[0,0,0] neg_hi:[0,1,0]
	v_pk_fma_f32 v[24:25], v[44:45], v[36:37], v[24:25] op_sel:[0,0,0] op_sel_hi:[0,1,1] neg_lo:[0,0,1] neg_hi:[0,0,0]
	v_pk_fma_f32 v[26:27], v[46:47], v[36:37], v[26:27] op_sel:[0,1,0] op_sel_hi:[0,0,1] neg_lo:[0,0,0] neg_hi:[0,1,0]
	v_pk_add_f32 v[40:41], v[4:5], v[6:7] neg_lo:[0,1] neg_hi:[0,1]
	v_pk_add_f32 v[42:43], v[12:13], v[14:15] neg_lo:[0,1] neg_hi:[0,1]
	v_pk_add_f32 v[44:45], v[8:9], v[10:11] neg_lo:[0,1] neg_hi:[0,1]
	v_pk_add_f32 v[46:47], v[24:25], v[26:27] neg_lo:[0,1] neg_hi:[0,1]
	v_pk_add_f32 v[4:5], v[4:5], v[6:7]
	v_pk_add_f32 v[12:13], v[12:13], v[14:15]
	v_pk_add_f32 v[8:9], v[8:9], v[10:11]
	v_pk_add_f32 v[24:25], v[24:25], v[26:27]
	v_pk_mul_f32 v[6:7], v[40:41], v[38:39] op_sel:[1,1] op_sel_hi:[1,0]
	v_pk_mul_f32 v[14:15], v[42:43], v[38:39] op_sel:[1,1] op_sel_hi:[1,0]
	v_pk_mul_f32 v[10:11], v[44:45], v[38:39] op_sel:[1,1] op_sel_hi:[1,0]
	v_pk_mul_f32 v[26:27], v[46:47], v[38:39] op_sel:[1,1] op_sel_hi:[1,0]
	v_pk_fma_f32 v[6:7], v[40:41], v[38:39], v[6:7] op_sel:[0,0,0] op_sel_hi:[0,1,1] neg_lo:[0,0,1] neg_hi:[0,0,0]
	v_pk_fma_f32 v[14:15], v[42:43], v[38:39], v[14:15] op_sel:[0,0,0] op_sel_hi:[0,1,1] neg_lo:[0,0,1] neg_hi:[0,0,0]
	v_pk_fma_f32 v[10:11], v[44:45], v[38:39], v[10:11] op_sel:[0,0,0] op_sel_hi:[0,1,1] neg_lo:[0,0,1] neg_hi:[0,0,0]
	v_pk_fma_f32 v[26:27], v[46:47], v[38:39], v[26:27] op_sel:[0,0,0] op_sel_hi:[0,1,1] neg_lo:[0,0,1] neg_hi:[0,0,0]
	ds_write2st64_b64 v3, v[4:5], v[6:7] offset1:17
	ds_write2st64_b64 v3, v[12:13], v[14:15] offset0:34 offset1:51
	ds_write2st64_b64 v3, v[8:9], v[10:11] offset0:68 offset1:85
	ds_write2st64_b64 v3, v[24:25], v[26:27] offset0:102 offset1:119
	s_movk_i32 s0, 0x200
	s_mov_b64 s[10:11], 0
	s_cbranch_vccz .LBB0_334
	s_waitcnt lgkmcnt(0)
	s_barrier
	v_lshlrev_b32_e32 v4, 4, v2
	v_and_b32_e32 v3, 63, v2
	v_and_b32_e32 v4, 0xfffffc00, v4
	s_mov_b32 s0, 0
	s_mov_b64 s[10:11], -1
; #define LAS __attribute__((address_space(3)))
; __device__ __forceinline__ cf twc(cf ws, int k16) { if (k16 == 0) return ws; if (k16 == 4) return cf{ws.y, -ws.x}; return cmul(ws, cf{c16(k16), -s16(k16)}); }
; template <int LR> __device__ __forceinline__ void dif_reg(cf (&x)[1 << LR], cf w) {
;     constexpr int R = 1 << LR; cf ws = w;
; #pragma unroll
;     for (int s = 0; s < LR; ++s) { const int half = R >> (s + 1);
; #pragma unroll
;         for (int m0 = 0; m0 < R; m0 += 2 * half)
; #pragma unroll
;             for (int mm = 0; mm < half; ++mm) { const int ia = m0 + mm, ib = ia + half; const cf a = x[ia], b = x[ib];
;                 x[ia] = cf{a.x + b.x, a.y + b.y}; const cf d{a.x - b.x, a.y - b.y};
;                 x[ib] = cmul(d, twc(ws, (mm << s) * (16 / R))); }
;         ws = cmul(ws, ws); }
; }
; template <int LR> __device__ __forceinline__ void dit_reg(cf (&x)[1 << LR], cf w) {
;     constexpr int R = 1 << LR; cf wsv[LR]; wsv[0] = w;
; #pragma unroll
;     for (int s = 1; s < LR; ++s) wsv[s] = cmul(wsv[s - 1], wsv[s - 1]);
; #pragma unroll
;     for (int s = LR - 1; s >= 0; --s) { const int half = R >> (s + 1);
; #pragma unroll
;         for (int m0 = 0; m0 < R; m0 += 2 * half)
; #pragma unroll
;             for (int mm = 0; mm < half; ++mm) { const int ia = m0 + mm, ib = ia + half; const cf a = x[ia];
;                 const cf b = cmulc(x[ib], twc(wsv[s], (mm << s) * (16 / R)));
;                 x[ia] = cf{a.x + b.x, a.y + b.y}; x[ib] = cf{a.x - b.x, a.y - b.y}; } }
; }
; __device__ __forceinline__ void lds_barrier() { asm volatile("s_waitcnt lgkmcnt(0)\n\ts_barrier" ::: "memory"); }
; template <int LR, bool INV> __device__ __forceinline__ void fft_pass(ldsf2 buf, int base, int stride, int twi) {
;     constexpr int R = 1 << LR; cf x[R];
;     const v2f wv = ((ldsf2)((LAS unsigned char*)buf + 139264))[twi];
; #pragma unroll
;     for (int m = 0; m < R; ++m) { const v2f v = buf[base + m * stride]; x[m] = cf{v.x, v.y}; }
;     const cf w{wv.x, wv.y};
;     if (INV) dit_reg<LR>(x, w); else dif_reg<LR>(x, w);
; #pragma unroll
;     for (int m = 0; m < R; ++m) buf[base + m * stride] = mkv2(x[m].x, x[m].y);
; }
.LBB0_336:
	v_cndmask_b32_e64 v5, 0, 1, s[10:11]
	v_or_b32_e32 v6, s0, v3
	v_cmp_ne_u32_e32 vcc, 1, v5
	v_or_b32_e32 v5, v6, v4
	v_lshl_add_u32 v6, v6, 6, 0
	v_ashrrev_i32_e32 v7, 4, v5
	v_add_u32_e32 v6, 0x22000, v6
	v_lshlrev_b32_e32 v5, 3, v5
	ds_read_b64 v[14:15], v6
	v_lshlrev_b32_e32 v6, 3, v7
	v_add3_u32 v5, 0, v5, v6
	v_add_u32_e32 v53, 0x800, v5
	ds_read2_b64 v[6:9], v5 offset1:136
	v_add_u32_e32 v58, 0x1000, v5
	v_add_u32_e32 v59, 0x1800, v5
	ds_read2_b64 v[10:13], v53 offset0:16 offset1:152
	ds_read2_b64 v[24:27], v58 offset0:32 offset1:168
	ds_read2_b64 v[28:31], v59 offset0:48 offset1:184
	s_waitcnt lgkmcnt(4)
	v_pk_add_f32 v[32:33], v[14:15], v[14:15] op_sel:[0,1] op_sel_hi:[1,0] neg_lo:[0,0] neg_hi:[0,1]
	v_pk_mul_f32 v[38:39], v[14:15], v[14:15] op_sel:[1,1] op_sel_hi:[1,0]
	v_pk_mul_f32 v[34:35], v[32:33], s[16:17] op_sel:[0,0] op_sel_hi:[1,0]
	v_pk_fma_f32 v[38:39], v[14:15], v[14:15], v[38:39] op_sel:[0,0,0] op_sel_hi:[0,1,1] neg_lo:[0,0,1] neg_hi:[0,0,0]
	v_pk_mul_f32 v[36:37], v[32:33], s[16:17] op_sel:[1,0] op_sel_hi:[0,0] neg_lo:[0,0] neg_hi:[1,0]
	s_nop 0
	v_pk_mul_f32 v[40:41], v[38:39], v[38:39] op_sel:[1,1] op_sel_hi:[1,0]
	s_nop 0
	v_pk_fma_f32 v[40:41], v[38:39], v[38:39], v[40:41] op_sel:[0,0,0] op_sel_hi:[0,1,1] neg_lo:[0,0,1] neg_hi:[0,0,0]
	s_waitcnt lgkmcnt(0)
	v_pk_add_f32 v[42:43], v[6:7], v[24:25] neg_lo:[0,1] neg_hi:[0,1]
	v_pk_add_f32 v[44:45], v[8:9], v[26:27] neg_lo:[0,1] neg_hi:[0,1]
	v_pk_add_f32 v[46:47], v[10:11], v[28:29] neg_lo:[0,1] neg_hi:[0,1]
	v_pk_add_f32 v[48:49], v[12:13], v[30:31] neg_lo:[0,1] neg_hi:[0,1]
	v_pk_add_f32 v[6:7], v[6:7], v[24:25]
	v_pk_add_f32 v[8:9], v[8:9], v[26:27]
	v_pk_add_f32 v[10:11], v[10:11], v[28:29]
	v_pk_add_f32 v[12:13], v[12:13], v[30:31]
	v_pk_mul_f32 v[24:25], v[42:43], v[14:15] op_sel:[1,1] op_sel_hi:[1,0]
	v_pk_mul_f32 v[26:27], v[44:45], v[34:35] op_sel:[1,1] op_sel_hi:[1,0]
	v_pk_mul_f32 v[28:29], v[46:47], v[14:15] op_sel:[1,0] op_sel_hi:[1,1]
	v_pk_mul_f32 v[30:31], v[48:49], v[36:37] op_sel:[1,1] op_sel_hi:[1,0]
	v_pk_fma_f32 v[24:25], v[42:43], v[14:15], v[24:25] op_sel:[0,0,0] op_sel_hi:[0,1,1] neg_lo:[0,0,1] neg_hi:[0,0,0]
	v_pk_fma_f32 v[26:27], v[44:45], v[34:35], v[26:27] op_sel:[0,0,0] op_sel_hi:[0,1,1] neg_lo:[0,0,1] neg_hi:[0,0,0]
	v_pk_fma_f32 v[28:29], v[46:47], v[14:15], v[28:29] op_sel:[0,1,0] op_sel_hi:[0,0,1] neg_lo:[0,0,0] neg_hi:[0,1,0]
	v_pk_fma_f32 v[30:31], v[48:49], v[36:37], v[30:31] op_sel:[0,0,0] op_sel_hi:[0,1,1] neg_lo:[0,0,1] neg_hi:[0,0,0]
	v_pk_add_f32 v[42:43], v[6:7], v[10:11] neg_lo:[0,1] neg_hi:[0,1]
	v_pk_add_f32 v[44:45], v[8:9], v[12:13] neg_lo:[0,1] neg_hi:[0,1]
	v_pk_add_f32 v[46:47], v[24:25], v[28:29] neg_lo:[0,1] neg_hi:[0,1]
	v_pk_add_f32 v[48:49], v[26:27], v[30:31] neg_lo:[0,1] neg_hi:[0,1]
	v_pk_add_f32 v[6:7], v[6:7], v[10:11]
	v_pk_add_f32 v[8:9], v[8:9], v[12:13]
	v_pk_add_f32 v[24:25], v[24:25], v[28:29]
	v_pk_add_f32 v[26:27], v[26:27], v[30:31]
	v_pk_mul_f32 v[10:11], v[42:43], v[38:39] op_sel:[1,1] op_sel_hi:[1,0]
	v_pk_mul_f32 v[12:13], v[44:45], v[38:39] op_sel:[1,0] op_sel_hi:[1,1]
	v_pk_mul_f32 v[28:29], v[46:47], v[38:39] op_sel:[1,1] op_sel_hi:[1,0]
	v_pk_mul_f32 v[30:31], v[48:49], v[38:39] op_sel:[1,0] op_sel_hi:[1,1]
	v_pk_fma_f32 v[10:11], v[42:43], v[38:39], v[10:11] op_sel:[0,0,0] op_sel_hi:[0,1,1] neg_lo:[0,0,1] neg_hi:[0,0,0]
	v_pk_fma_f32 v[12:13], v[44:45], v[38:39], v[12:13] op_sel:[0,1,0] op_sel_hi:[0,0,1] neg_lo:[0,0,0] neg_hi:[0,1,0]
	v_pk_fma_f32 v[28:29], v[46:47], v[38:39], v[28:29] op_sel:[0,0,0] op_sel_hi:[0,1,1] neg_lo:[0,0,1] neg_hi:[0,0,0]
	v_pk_fma_f32 v[30:31], v[48:49], v[38:39], v[30:31] op_sel:[0,1,0] op_sel_hi:[0,0,1] neg_lo:[0,0,0] neg_hi:[0,1,0]
	v_pk_add_f32 v[42:43], v[6:7], v[8:9] neg_lo:[0,1] neg_hi:[0,1]
	v_pk_add_f32 v[44:45], v[10:11], v[12:13] neg_lo:[0,1] neg_hi:[0,1]
	v_pk_add_f32 v[46:47], v[24:25], v[26:27] neg_lo:[0,1] neg_hi:[0,1]
	v_pk_add_f32 v[48:49], v[28:29], v[30:31] neg_lo:[0,1] neg_hi:[0,1]
	v_pk_add_f32 v[6:7], v[6:7], v[8:9]
	v_pk_add_f32 v[10:11], v[10:11], v[12:13]
	v_pk_add_f32 v[24:25], v[24:25], v[26:27]
	v_pk_add_f32 v[28:29], v[28:29], v[30:31]
	v_pk_mul_f32 v[8:9], v[42:43], v[40:41] op_sel:[1,1] op_sel_hi:[1,0]
	v_pk_mul_f32 v[12:13], v[44:45], v[40:41] op_sel:[1,1] op_sel_hi:[1,0]
	v_pk_mul_f32 v[26:27], v[46:47], v[40:41] op_sel:[1,1] op_sel_hi:[1,0]
	v_pk_mul_f32 v[30:31], v[48:49], v[40:41] op_sel:[1,1] op_sel_hi:[1,0]
	v_pk_fma_f32 v[8:9], v[42:43], v[40:41], v[8:9] op_sel:[0,0,0] op_sel_hi:[0,1,1] neg_lo:[0,0,1] neg_hi:[0,0,0]
	v_pk_fma_f32 v[12:13], v[44:45], v[40:41], v[12:13] op_sel:[0,0,0] op_sel_hi:[0,1,1] neg_lo:[0,0,1] neg_hi:[0,0,0]
	v_pk_fma_f32 v[26:27], v[46:47], v[40:41], v[26:27] op_sel:[0,0,0] op_sel_hi:[0,1,1] neg_lo:[0,0,1] neg_hi:[0,0,0]
	v_pk_fma_f32 v[30:31], v[48:49], v[40:41], v[30:31] op_sel:[0,0,0] op_sel_hi:[0,1,1] neg_lo:[0,0,1] neg_hi:[0,0,0]
	ds_write2_b64 v5, v[6:7], v[8:9] offset1:136
	ds_write2_b64 v53, v[10:11], v[12:13] offset0:16 offset1:152
	ds_write2_b64 v58, v[24:25], v[26:27] offset0:32 offset1:168
	ds_write2_b64 v59, v[28:29], v[30:31] offset0:48 offset1:184
	s_mov_b32 s0, 64
	s_mov_b64 s[10:11], 0
	s_cbranch_vccz .LBB0_336
	v_and_b32_e32 v2, 15, v2
	s_waitcnt lgkmcnt(0)
	v_lshlrev_b32_e32 v3, 3, v3
	v_lshlrev_b32_e32 v5, 9, v2
	v_and_or_b32 v3, v3, s90, v4
	v_add_u32_e32 v4, 0, v5
	v_lshl_add_u32 v2, v2, 3, 0
	s_mov_b32 s0, 0
	s_mov_b64 s[10:11], -1
	v_add_u32_e32 v4, 0x22000, v4
; #define LAS __attribute__((address_space(3)))
; __device__ __forceinline__ cf twc(cf ws, int k16) { if (k16 == 0) return ws; if (k16 == 4) return cf{ws.y, -ws.x}; return cmul(ws, cf{c16(k16), -s16(k16)}); }
; template <int LR> __device__ __forceinline__ void dif_reg(cf (&x)[1 << LR], cf w) {
;     constexpr int R = 1 << LR; cf ws = w;
; #pragma unroll
;     for (int s = 0; s < LR; ++s) { const int half = R >> (s + 1);
; #pragma unroll
;         for (int m0 = 0; m0 < R; m0 += 2 * half)
; #pragma unroll
;             for (int mm = 0; mm < half; ++mm) { const int ia = m0 + mm, ib = ia + half; const cf a = x[ia], b = x[ib];
;                 x[ia] = cf{a.x + b.x, a.y + b.y}; const cf d{a.x - b.x, a.y - b.y};
;                 x[ib] = cmul(d, twc(ws, (mm << s) * (16 / R))); }
;         ws = cmul(ws, ws); }
; }
; template <int LR> __device__ __forceinline__ void dit_reg(cf (&x)[1 << LR], cf w) {
;     constexpr int R = 1 << LR; cf wsv[LR]; wsv[0] = w;
; #pragma unroll
;     for (int s = 1; s < LR; ++s) wsv[s] = cmul(wsv[s - 1], wsv[s - 1]);
; #pragma unroll
;     for (int s = LR - 1; s >= 0; --s) { const int half = R >> (s + 1);
; #pragma unroll
;         for (int m0 = 0; m0 < R; m0 += 2 * half)
; #pragma unroll
;             for (int mm = 0; mm < half; ++mm) { const int ia = m0 + mm, ib = ia + half; const cf a = x[ia];
;                 const cf b = cmulc(x[ib], twc(wsv[s], (mm << s) * (16 / R)));
;                 x[ia] = cf{a.x + b.x, a.y + b.y}; x[ib] = cf{a.x - b.x, a.y - b.y}; } }
; }
; __device__ __forceinline__ void lds_barrier() { asm volatile("s_waitcnt lgkmcnt(0)\n\ts_barrier" ::: "memory"); }
; template <int LR, bool INV> __device__ __forceinline__ void fft_pass(ldsf2 buf, int base, int stride, int twi) {
;     constexpr int R = 1 << LR; cf x[R];
;     const v2f wv = ((ldsf2)((LAS unsigned char*)buf + 139264))[twi];
; #pragma unroll
;     for (int m = 0; m < R; ++m) { const v2f v = buf[base + m * stride]; x[m] = cf{v.x, v.y}; }
;     const cf w{wv.x, wv.y};
;     if (INV) dit_reg<LR>(x, w); else dif_reg<LR>(x, w);
; #pragma unroll
;     for (int m = 0; m < R; ++m) buf[base + m * stride] = mkv2(x[m].x, x[m].y);
; }
.LBB0_338:
	v_or_b32_e32 v5, s0, v3
	ds_read_b64 v[14:15], v4
	v_lshlrev_b32_e32 v6, 3, v5
	v_ashrrev_i32_e32 v5, 1, v5
	v_add3_u32 v5, v2, v6, v5
	ds_read2_b64 v[6:9], v5 offset1:17
	ds_read2_b64 v[10:13], v5 offset0:34 offset1:51
	ds_read2_b64 v[24:27], v5 offset0:68 offset1:85
	ds_read2_b64 v[28:31], v5 offset0:102 offset1:119
	s_waitcnt lgkmcnt(4)
	v_pk_add_f32 v[32:33], v[14:15], v[14:15] op_sel:[0,1] op_sel_hi:[1,0] neg_lo:[0,0] neg_hi:[0,1]
	v_pk_mul_f32 v[38:39], v[14:15], v[14:15] op_sel:[1,1] op_sel_hi:[1,0]
	v_pk_mul_f32 v[34:35], v[32:33], s[16:17] op_sel:[0,0] op_sel_hi:[1,0]
	v_pk_fma_f32 v[38:39], v[14:15], v[14:15], v[38:39] op_sel:[0,0,0] op_sel_hi:[0,1,1] neg_lo:[0,0,1] neg_hi:[0,0,0]
	v_pk_mul_f32 v[36:37], v[32:33], s[16:17] op_sel:[1,0] op_sel_hi:[0,0] neg_lo:[0,0] neg_hi:[1,0]
	s_nop 0
	v_pk_mul_f32 v[40:41], v[38:39], v[38:39] op_sel:[1,1] op_sel_hi:[1,0]
	s_nop 0
	v_pk_fma_f32 v[40:41], v[38:39], v[38:39], v[40:41] op_sel:[0,0,0] op_sel_hi:[0,1,1] neg_lo:[0,0,1] neg_hi:[0,0,0]
	s_waitcnt lgkmcnt(0)
	v_pk_add_f32 v[42:43], v[6:7], v[24:25] neg_lo:[0,1] neg_hi:[0,1]
	v_pk_add_f32 v[44:45], v[8:9], v[26:27] neg_lo:[0,1] neg_hi:[0,1]
	v_pk_add_f32 v[46:47], v[10:11], v[28:29] neg_lo:[0,1] neg_hi:[0,1]
	v_pk_add_f32 v[48:49], v[12:13], v[30:31] neg_lo:[0,1] neg_hi:[0,1]
	v_pk_add_f32 v[6:7], v[6:7], v[24:25]
	v_pk_add_f32 v[8:9], v[8:9], v[26:27]
	v_pk_add_f32 v[10:11], v[10:11], v[28:29]
	v_pk_add_f32 v[12:13], v[12:13], v[30:31]
	v_pk_mul_f32 v[24:25], v[42:43], v[14:15] op_sel:[1,1] op_sel_hi:[1,0]
	v_pk_mul_f32 v[26:27], v[44:45], v[34:35] op_sel:[1,1] op_sel_hi:[1,0]
	v_pk_mul_f32 v[28:29], v[46:47], v[14:15] op_sel:[1,0] op_sel_hi:[1,1]
	v_pk_mul_f32 v[30:31], v[48:49], v[36:37] op_sel:[1,1] op_sel_hi:[1,0]
	v_pk_fma_f32 v[24:25], v[42:43], v[14:15], v[24:25] op_sel:[0,0,0] op_sel_hi:[0,1,1] neg_lo:[0,0,1] neg_hi:[0,0,0]
	v_pk_fma_f32 v[26:27], v[44:45], v[34:35], v[26:27] op_sel:[0,0,0] op_sel_hi:[0,1,1] neg_lo:[0,0,1] neg_hi:[0,0,0]
	v_pk_fma_f32 v[28:29], v[46:47], v[14:15], v[28:29] op_sel:[0,1,0] op_sel_hi:[0,0,1] neg_lo:[0,0,0] neg_hi:[0,1,0]
	v_pk_fma_f32 v[30:31], v[48:49], v[36:37], v[30:31] op_sel:[0,0,0] op_sel_hi:[0,1,1] neg_lo:[0,0,1] neg_hi:[0,0,0]
	v_pk_add_f32 v[42:43], v[6:7], v[10:11] neg_lo:[0,1] neg_hi:[0,1]
	v_pk_add_f32 v[44:45], v[8:9], v[12:13] neg_lo:[0,1] neg_hi:[0,1]
	v_pk_add_f32 v[46:47], v[24:25], v[28:29] neg_lo:[0,1] neg_hi:[0,1]
	v_pk_add_f32 v[48:49], v[26:27], v[30:31] neg_lo:[0,1] neg_hi:[0,1]
	v_pk_add_f32 v[6:7], v[6:7], v[10:11]
	v_pk_add_f32 v[8:9], v[8:9], v[12:13]
	v_pk_add_f32 v[24:25], v[24:25], v[28:29]
	v_pk_add_f32 v[26:27], v[26:27], v[30:31]
	v_pk_mul_f32 v[10:11], v[42:43], v[38:39] op_sel:[1,1] op_sel_hi:[1,0]
	v_pk_mul_f32 v[12:13], v[44:45], v[38:39] op_sel:[1,0] op_sel_hi:[1,1]
	v_pk_mul_f32 v[28:29], v[46:47], v[38:39] op_sel:[1,1] op_sel_hi:[1,0]
	v_pk_mul_f32 v[30:31], v[48:49], v[38:39] op_sel:[1,0] op_sel_hi:[1,1]
	v_pk_fma_f32 v[10:11], v[42:43], v[38:39], v[10:11] op_sel:[0,0,0] op_sel_hi:[0,1,1] neg_lo:[0,0,1] neg_hi:[0,0,0]
	v_pk_fma_f32 v[12:13], v[44:45], v[38:39], v[12:13] op_sel:[0,1,0] op_sel_hi:[0,0,1] neg_lo:[0,0,0] neg_hi:[0,1,0]
	v_pk_fma_f32 v[28:29], v[46:47], v[38:39], v[28:29] op_sel:[0,0,0] op_sel_hi:[0,1,1] neg_lo:[0,0,1] neg_hi:[0,0,0]
	v_pk_fma_f32 v[30:31], v[48:49], v[38:39], v[30:31] op_sel:[0,1,0] op_sel_hi:[0,0,1] neg_lo:[0,0,0] neg_hi:[0,1,0]
	v_pk_add_f32 v[42:43], v[6:7], v[8:9] neg_lo:[0,1] neg_hi:[0,1]
	v_pk_add_f32 v[44:45], v[10:11], v[12:13] neg_lo:[0,1] neg_hi:[0,1]
	v_pk_add_f32 v[46:47], v[24:25], v[26:27] neg_lo:[0,1] neg_hi:[0,1]
	v_pk_add_f32 v[48:49], v[28:29], v[30:31] neg_lo:[0,1] neg_hi:[0,1]
	v_pk_add_f32 v[6:7], v[6:7], v[8:9]
	v_pk_add_f32 v[10:11], v[10:11], v[12:13]
	v_pk_add_f32 v[24:25], v[24:25], v[26:27]
	v_pk_add_f32 v[28:29], v[28:29], v[30:31]
	v_pk_mul_f32 v[8:9], v[42:43], v[40:41] op_sel:[1,1] op_sel_hi:[1,0]
	v_pk_mul_f32 v[12:13], v[44:45], v[40:41] op_sel:[1,1] op_sel_hi:[1,0]
	v_pk_mul_f32 v[26:27], v[46:47], v[40:41] op_sel:[1,1] op_sel_hi:[1,0]
	v_pk_mul_f32 v[30:31], v[48:49], v[40:41] op_sel:[1,1] op_sel_hi:[1,0]
	v_pk_fma_f32 v[8:9], v[42:43], v[40:41], v[8:9] op_sel:[0,0,0] op_sel_hi:[0,1,1] neg_lo:[0,0,1] neg_hi:[0,0,0]
	v_pk_fma_f32 v[12:13], v[44:45], v[40:41], v[12:13] op_sel:[0,0,0] op_sel_hi:[0,1,1] neg_lo:[0,0,1] neg_hi:[0,0,0]
	v_pk_fma_f32 v[26:27], v[46:47], v[40:41], v[26:27] op_sel:[0,0,0] op_sel_hi:[0,1,1] neg_lo:[0,0,1] neg_hi:[0,0,0]
	v_pk_fma_f32 v[30:31], v[48:49], v[40:41], v[30:31] op_sel:[0,0,0] op_sel_hi:[0,1,1] neg_lo:[0,0,1] neg_hi:[0,0,0]
	ds_write2_b64 v5, v[6:7], v[8:9] offset1:17
	ds_write2_b64 v5, v[10:11], v[12:13] offset0:34 offset1:51
	ds_write2_b64 v5, v[24:25], v[26:27] offset0:68 offset1:85
	ds_write2_b64 v5, v[28:29], v[30:31] offset0:102 offset1:119
	s_movk_i32 s0, 0x200
	s_and_b64 vcc, exec, s[10:11]
	s_mov_b64 s[10:11], 0
	s_cbranch_vccnz .LBB0_338
; __device__ __forceinline__ cf twc(cf ws, int k16) { if (k16 == 0) return ws; if (k16 == 4) return cf{ws.y, -ws.x}; return cmul(ws, cf{c16(k16), -s16(k16)}); }
; template <int LR> __device__ __forceinline__ void dif_reg(cf (&x)[1 << LR], cf w) {
;     constexpr int R = 1 << LR; cf ws = w;
; #pragma unroll
;     for (int s = 0; s < LR; ++s) { const int half = R >> (s + 1);
; #pragma unroll
;         for (int m0 = 0; m0 < R; m0 += 2 * half)
; #pragma unroll
;             for (int mm = 0; mm < half; ++mm) { const int ia = m0 + mm, ib = ia + half; const cf a = x[ia], b = x[ib];
;                 x[ia] = cf{a.x + b.x, a.y + b.y}; const cf d{a.x - b.x, a.y - b.y};
;                 x[ib] = cmul(d, twc(ws, (mm << s) * (16 / R))); }
;         ws = cmul(ws, ws); }
; }
; __device__ __forceinline__ void make_spec(ldsf2 buf, LAS unsigned* spec, const float* __restrict__ kfrow) {
;     ...
;     cf x[16];
; #pragma unroll
;     for (int m = 0; m < 16; ++m) { const v2f v = buf[tid * 17 + m]; x[m] = cf{v.x, v.y}; }
;     dif_reg<4>(x, cf{1.0f, 0.0f});
; #pragma unroll
;     for (int m = 0; m < 16; ++m) { h2_t hv; hv.x = (_Float16)x[m].x; hv.y = (_Float16)x[m].y; spec[tid * 17 + m] = __builtin_bit_cast(unsigned, hv); }
	s_waitcnt lgkmcnt(0)
	ds_read2_b64 v[2:5], v1 offset1:1
	ds_read2_b64 v[6:9], v1 offset0:2 offset1:3
	ds_read2_b64 v[10:13], v1 offset0:4 offset1:5
	ds_read2_b64 v[24:27], v1 offset0:6 offset1:7
	ds_read2_b64 v[28:31], v1 offset0:8 offset1:9
	ds_read2_b64 v[32:35], v1 offset0:10 offset1:11
	ds_read2_b64 v[36:39], v1 offset0:12 offset1:13
	ds_read2_b64 v[40:43], v1 offset0:14 offset1:15
	s_movk_i32 s0, 0x44
	v_mul_lo_u32 v0, v0, s0
	v_add_u32_e32 v0, 0, v0
	v_add_u32_e32 v70, 0x11000, v0
	s_waitcnt lgkmcnt(3)
	v_pk_add_f32 v[0:1], v[2:3], v[28:29]
	v_pk_add_f32 v[14:15], v[4:5], v[30:31]
	s_waitcnt lgkmcnt(2)
	v_pk_add_f32 v[44:45], v[6:7], v[32:33]
	v_pk_add_f32 v[46:47], v[8:9], v[34:35]
	s_waitcnt lgkmcnt(1)
	v_pk_add_f32 v[48:49], v[10:11], v[36:37]
	v_pk_add_f32 v[50:51], v[12:13], v[38:39]
	s_waitcnt lgkmcnt(0)
	v_pk_add_f32 v[52:53], v[24:25], v[40:41]
	v_pk_add_f32 v[54:55], v[26:27], v[42:43]
	v_pk_add_f32 v[56:57], v[0:1], v[48:49]
	v_pk_add_f32 v[58:59], v[14:15], v[50:51]
	v_pk_add_f32 v[60:61], v[44:45], v[52:53]
	v_pk_add_f32 v[62:63], v[46:47], v[54:55]
	v_pk_add_f32 v[64:65], v[56:57], v[60:61]
	v_pk_add_f32 v[66:67], v[58:59], v[62:63]
	v_pk_add_f32 v[56:57], v[56:57], v[60:61] neg_lo:[0,1] neg_hi:[0,1]
	v_pk_add_f32 v[68:69], v[64:65], v[66:67]
	v_pk_add_f32 v[64:65], v[64:65], v[66:67] neg_lo:[0,1] neg_hi:[0,1]
	v_cvt_pk_f16_f32 v71, v68, v69
	v_pk_mul_f32 v[66:67], v[64:65], 0 op_sel_hi:[1,0]
	v_pk_mul_f32 v[60:61], v[56:57], 0 op_sel_hi:[1,0]
	v_pk_add_f32 v[68:69], v[64:65], v[66:67] op_sel:[0,1] op_sel_hi:[1,0] neg_lo:[0,1] neg_hi:[0,1]
	v_pk_add_f32 v[64:65], v[64:65], v[66:67] op_sel:[0,1] op_sel_hi:[1,0]
	v_pk_add_f32 v[0:1], v[0:1], v[48:49] neg_lo:[0,1] neg_hi:[0,1]
	v_cvt_pk_f16_f32 v64, v68, v65
	ds_write2_b32 v70, v71, v64 offset1:1
	v_pk_add_f32 v[64:65], v[56:57], v[60:61] op_sel:[0,1] op_sel_hi:[1,0] neg_lo:[0,1] neg_hi:[0,1]
	v_pk_add_f32 v[56:57], v[56:57], v[60:61] op_sel:[0,1] op_sel_hi:[1,0]
	v_pk_mul_f32 v[48:49], v[0:1], 0 op_sel_hi:[1,0]
	v_mov_b32_e32 v65, v57
	v_pk_add_f32 v[56:57], v[58:59], v[62:63] neg_lo:[0,1] neg_hi:[0,1]
	s_mov_b32 s0, s87
	v_pk_fma_f32 v[58:59], v[56:57], 0, v[56:57] op_sel:[0,0,1] op_sel_hi:[1,0,0]
	v_pk_fma_f32 v[56:57], v[56:57], 0, v[56:57] op_sel:[0,0,1] op_sel_hi:[1,0,0] neg_lo:[0,0,1] neg_hi:[0,0,1]
	s_mov_b32 s1, s16
	v_mov_b32_e32 v59, v57
	v_pk_add_f32 v[56:57], v[64:65], v[58:59]
	s_mov_b32 s17, s87
	v_cvt_pk_f16_f32 v62, v56, v57
	v_pk_add_f32 v[56:57], v[64:65], v[58:59] neg_lo:[0,1] neg_hi:[0,1]
	s_mov_b32 s10, s5
	v_pk_mul_f32 v[58:59], v[56:57], 0 op_sel_hi:[1,0]
	s_mov_b32 s14, s13
	v_pk_add_f32 v[60:61], v[56:57], v[58:59] op_sel:[0,1] op_sel_hi:[1,0] neg_lo:[0,1] neg_hi:[0,1]
	v_pk_add_f32 v[56:57], v[56:57], v[58:59] op_sel:[0,1] op_sel_hi:[1,0]
	v_mov_b32_e32 v58, v51
	v_cvt_pk_f16_f32 v56, v60, v57
	ds_write2_b32 v70, v62, v56 offset0:2 offset1:3
	v_pk_add_f32 v[56:57], v[0:1], v[48:49] op_sel:[0,1] op_sel_hi:[1,0] neg_lo:[0,1] neg_hi:[0,1]
	v_pk_add_f32 v[0:1], v[0:1], v[48:49] op_sel:[0,1] op_sel_hi:[1,0]
	v_mov_b32_e32 v48, v54
	v_mov_b32_e32 v57, v1
	v_pk_add_f32 v[0:1], v[44:45], v[52:53] neg_lo:[0,1] neg_hi:[0,1]
	v_mov_b32_e32 v49, v51
	v_pk_fma_f32 v[44:45], v[0:1], 0, v[0:1] op_sel:[0,0,1] op_sel_hi:[1,0,0]
	v_pk_fma_f32 v[0:1], v[0:1], 0, v[0:1] op_sel:[0,0,1] op_sel_hi:[1,0,0] neg_lo:[0,0,1] neg_hi:[0,0,1]
	v_mov_b32_e32 v52, v50
	v_mov_b32_e32 v45, v1
	v_mov_b32_e32 v0, v46
	v_mov_b32_e32 v1, v15
	v_pk_add_f32 v[0:1], v[0:1], v[48:49] neg_lo:[0,1] neg_hi:[0,1]
	v_mov_b32_e32 v48, v14
	v_mov_b32_e32 v49, v46
	v_mov_b32_e32 v53, v54
	v_pk_add_f32 v[48:49], v[48:49], v[52:53] neg_lo:[0,1] neg_hi:[0,1]
	v_mov_b32_e32 v52, v15
	v_mov_b32_e32 v53, v47
	v_mov_b32_e32 v59, v55
	v_pk_mov_b32 v[14:15], v[46:47], v[14:15] op_sel:[1,0]
	v_pk_mov_b32 v[46:47], v[54:55], v[50:51] op_sel:[1,0]
	v_pk_add_f32 v[52:53], v[52:53], v[58:59] neg_lo:[0,1] neg_hi:[0,1]
	v_pk_add_f32 v[14:15], v[14:15], v[46:47] neg_lo:[0,1] neg_hi:[0,1]
	v_pk_mul_f32 v[46:47], v[52:53], s[16:17]
	v_pk_mul_f32 v[14:15], v[14:15], s[0:1]
	s_mov_b32 s15, s4
	v_pk_fma_f32 v[0:1], v[0:1], s[0:1], v[14:15] neg_lo:[0,0,1] neg_hi:[0,0,1]
	v_pk_fma_f32 v[14:15], v[48:49], s[16:17], v[46:47]
	v_pk_add_f32 v[46:47], v[56:57], v[44:45]
	v_pk_add_f32 v[48:49], v[14:15], v[0:1]
	v_pk_add_f32 v[44:45], v[56:57], v[44:45] neg_lo:[0,1] neg_hi:[0,1]
	v_pk_add_f32 v[50:51], v[46:47], v[48:49]
	v_pk_add_f32 v[46:47], v[46:47], v[48:49] neg_lo:[0,1] neg_hi:[0,1]
	v_cvt_pk_f16_f32 v52, v50, v51
	v_pk_mul_f32 v[48:49], v[46:47], 0 op_sel_hi:[1,0]
	s_mov_b32 s35, s5
	v_pk_add_f32 v[50:51], v[46:47], v[48:49] op_sel:[0,1] op_sel_hi:[1,0] neg_lo:[0,1] neg_hi:[0,1]
	v_pk_add_f32 v[46:47], v[46:47], v[48:49] op_sel:[0,1] op_sel_hi:[1,0]
	s_add_i32 s30, s46, 0x400
	v_cvt_pk_f16_f32 v46, v50, v47
	ds_write2_b32 v70, v52, v46 offset0:4 offset1:5
	v_pk_mul_f32 v[46:47], v[44:45], 0 op_sel_hi:[1,0]
	s_ashr_i32 s31, s30, 31
	v_pk_add_f32 v[48:49], v[44:45], v[46:47] op_sel:[0,1] op_sel_hi:[1,0] neg_lo:[0,1] neg_hi:[0,1]
	v_pk_add_f32 v[44:45], v[44:45], v[46:47] op_sel:[0,1] op_sel_hi:[1,0]
	s_nop 0
	v_mov_b32_e32 v49, v45
	v_mov_b32_e32 v44, v14
	v_mov_b32_e32 v45, v1
	v_mov_b32_e32 v1, v15
	v_pk_add_f32 v[0:1], v[44:45], v[0:1] neg_lo:[0,1] neg_hi:[0,1]
	s_nop 0
	v_pk_fma_f32 v[14:15], v[0:1], 0, v[0:1] op_sel:[0,0,1] op_sel_hi:[1,0,0]
	v_pk_fma_f32 v[0:1], v[0:1], 0, v[0:1] op_sel:[0,0,1] op_sel_hi:[1,0,0] neg_lo:[0,0,1] neg_hi:[0,0,1]
	s_nop 0
	v_mov_b32_e32 v15, v1
	v_pk_add_f32 v[0:1], v[48:49], v[14:15]
	s_nop 0
	v_cvt_pk_f16_f32 v46, v0, v1
	v_pk_add_f32 v[0:1], v[48:49], v[14:15] neg_lo:[0,1] neg_hi:[0,1]
; __device__ __forceinline__ cf twc(cf ws, int k16) { if (k16 == 0) return ws; if (k16 == 4) return cf{ws.y, -ws.x}; return cmul(ws, cf{c16(k16), -s16(k16)}); }
; template <int LR> __device__ __forceinline__ void dif_reg(cf (&x)[1 << LR], cf w) {
;     constexpr int R = 1 << LR; cf ws = w;
; #pragma unroll
;     for (int s = 0; s < LR; ++s) { const int half = R >> (s + 1);
; #pragma unroll
;         for (int m0 = 0; m0 < R; m0 += 2 * half)
; #pragma unroll
;             for (int mm = 0; mm < half; ++mm) { const int ia = m0 + mm, ib = ia + half; const cf a = x[ia], b = x[ib];
;                 x[ia] = cf{a.x + b.x, a.y + b.y}; const cf d{a.x - b.x, a.y - b.y};
;                 x[ib] = cmul(d, twc(ws, (mm << s) * (16 / R))); }
;         ws = cmul(ws, ws); }
; }
; __device__ __forceinline__ void make_spec(ldsf2 buf, LAS unsigned* spec, const float* __restrict__ kfrow) {
;     ...
;     cf x[16];
; #pragma unroll
;     for (int m = 0; m < 16; ++m) { const v2f v = buf[tid * 17 + m]; x[m] = cf{v.x, v.y}; }
;     dif_reg<4>(x, cf{1.0f, 0.0f});
; #pragma unroll
;     for (int m = 0; m < 16; ++m) { h2_t hv; hv.x = (_Float16)x[m].x; hv.y = (_Float16)x[m].y; spec[tid * 17 + m] = __builtin_bit_cast(unsigned, hv); }
	s_nop 0
	v_pk_mul_f32 v[14:15], v[0:1], 0 op_sel_hi:[1,0]
	s_nop 0
	v_pk_add_f32 v[44:45], v[0:1], v[14:15] op_sel:[0,1] op_sel_hi:[1,0] neg_lo:[0,1] neg_hi:[0,1]
	v_pk_add_f32 v[0:1], v[0:1], v[14:15] op_sel:[0,1] op_sel_hi:[1,0]
	s_nop 0
	v_cvt_pk_f16_f32 v0, v44, v1
	ds_write2_b32 v70, v46, v0 offset0:6 offset1:7
	v_pk_add_f32 v[0:1], v[2:3], v[28:29] neg_lo:[0,1] neg_hi:[0,1]
	s_nop 0
	v_pk_mul_f32 v[2:3], v[0:1], 0 op_sel_hi:[1,0]
	s_nop 0
	v_pk_add_f32 v[14:15], v[0:1], v[2:3] op_sel:[0,1] op_sel_hi:[1,0] neg_lo:[0,1] neg_hi:[0,1]
	v_pk_add_f32 v[0:1], v[0:1], v[2:3] op_sel:[0,1] op_sel_hi:[1,0]
	v_pk_add_f32 v[2:3], v[4:5], v[30:31] neg_lo:[0,1] neg_hi:[0,1]
	v_pk_mov_b32 v[0:1], v[0:1], v[14:15] op_sel:[1,0]
	v_pk_mul_f32 v[4:5], v[2:3], s[4:5] op_sel_hi:[1,0]
	s_nop 0
	v_pk_fma_f32 v[14:15], v[2:3], s[10:11], v[4:5] op_sel:[0,0,1] op_sel_hi:[1,0,0]
	v_pk_fma_f32 v[2:3], v[2:3], s[10:11], v[4:5] op_sel:[0,0,1] op_sel_hi:[1,0,0] neg_lo:[1,0,0] neg_hi:[1,0,0]
	v_pk_add_f32 v[4:5], v[8:9], v[34:35] neg_lo:[0,1] neg_hi:[0,1]
	v_mov_b32_e32 v34, v40
	v_pk_mul_f32 v[8:9], v[4:5], s[10:11] op_sel_hi:[1,0]
	v_mov_b32_e32 v35, v32
	v_pk_fma_f32 v[28:29], v[4:5], s[4:5], v[8:9] op_sel:[0,0,1] op_sel_hi:[1,0,0]
	v_pk_fma_f32 v[4:5], v[4:5], s[4:5], v[8:9] op_sel:[0,0,1] op_sel_hi:[1,0,0] neg_lo:[1,0,0] neg_hi:[1,0,0]
	v_pk_add_f32 v[8:9], v[10:11], v[36:37] neg_lo:[0,1] neg_hi:[0,1]
	v_mov_b32_e32 v36, v41
	v_pk_mul_f32 v[10:11], v[8:9], 0 op_sel_hi:[1,0]
	v_mov_b32_e32 v37, v33
	v_pk_add_f32 v[30:31], v[10:11], v[8:9] op_sel:[1,0] op_sel_hi:[0,1]
	v_pk_add_f32 v[8:9], v[10:11], v[8:9] op_sel:[1,0] op_sel_hi:[0,1] neg_lo:[0,1] neg_hi:[0,1]
	v_pk_add_f32 v[10:11], v[12:13], v[38:39] neg_lo:[0,1] neg_hi:[0,1]
	v_mov_b32_e32 v9, v31
	v_pk_mul_f32 v[12:13], v[10:11], s[10:11] op_sel_hi:[1,0]
	v_pk_mov_b32 v[30:31], v[32:33], v[40:41] op_sel:[1,0]
	v_pk_fma_f32 v[10:11], v[10:11], s[14:15], v[12:13] op_sel:[0,0,1] op_sel_hi:[1,1,0] neg_lo:[0,0,1] neg_hi:[0,0,1]
	v_pk_mov_b32 v[12:13], v[6:7], v[24:25] op_sel:[1,0]
	v_mov_b32_e32 v33, v41
	v_pk_add_f32 v[12:13], v[12:13], v[30:31] neg_lo:[0,1] neg_hi:[0,1]
	v_mov_b32_e32 v30, v24
	v_mov_b32_e32 v31, v6
	v_pk_add_f32 v[30:31], v[30:31], v[34:35] neg_lo:[0,1] neg_hi:[0,1]
	v_mov_b32_e32 v34, v25
	v_mov_b32_e32 v35, v7
	v_mov_b32_e32 v7, v25
	v_pk_add_f32 v[34:35], v[34:35], v[36:37] neg_lo:[0,1] neg_hi:[0,1]
	v_pk_add_f32 v[6:7], v[6:7], v[32:33] neg_lo:[0,1] neg_hi:[0,1]
	v_pk_mul_f32 v[24:25], v[34:35], s[0:1]
	v_pk_mul_f32 v[6:7], v[6:7], s[16:17]
	v_mov_b32_e32 v3, v15
	v_pk_fma_f32 v[6:7], v[12:13], s[16:17], v[6:7] neg_lo:[0,0,1] neg_hi:[0,0,1]
	v_pk_fma_f32 v[12:13], v[30:31], s[0:1], v[24:25]
	v_pk_add_f32 v[24:25], v[26:27], v[42:43] neg_lo:[0,1] neg_hi:[0,1]
	v_mov_b32_e32 v28, v4
	v_pk_mul_f32 v[26:27], v[24:25], s[4:5] op_sel_hi:[1,0]
	v_pk_add_f32 v[30:31], v[2:3], v[10:11]
	v_pk_fma_f32 v[24:25], v[24:25], s[34:35], v[26:27] op_sel:[0,0,1] op_sel_hi:[1,1,0] neg_lo:[0,0,1] neg_hi:[0,0,1]
	v_pk_add_f32 v[26:27], v[0:1], v[8:9]
	v_pk_add_f32 v[32:33], v[12:13], v[6:7]
	v_pk_add_f32 v[34:35], v[28:29], v[24:25]
	v_pk_add_f32 v[36:37], v[26:27], v[32:33]
	v_pk_add_f32 v[38:39], v[30:31], v[34:35]
	v_pk_add_f32 v[26:27], v[26:27], v[32:33] neg_lo:[0,1] neg_hi:[0,1]
	v_pk_add_f32 v[40:41], v[36:37], v[38:39]
	v_pk_add_f32 v[36:37], v[36:37], v[38:39] neg_lo:[0,1] neg_hi:[0,1]
	v_pk_mov_b32 v[40:41], v[40:41], v[40:41] op_sel:[1,0]
	v_pk_mul_f32 v[38:39], v[36:37], 0 op_sel_hi:[1,0]
	v_cvt_pk_f16_f32 v3, v40, v41
	v_pk_add_f32 v[40:41], v[36:37], v[38:39] op_sel:[0,1] op_sel_hi:[1,0] neg_lo:[0,1] neg_hi:[0,1]
	v_pk_add_f32 v[36:37], v[36:37], v[38:39] op_sel:[0,1] op_sel_hi:[1,0]
	v_pk_mul_f32 v[32:33], v[26:27], 0 op_sel_hi:[1,0]
	v_pk_mov_b32 v[36:37], v[40:41], v[36:37] op_sel:[1,0]
	v_pk_add_f32 v[30:31], v[30:31], v[34:35] neg_lo:[0,1] neg_hi:[0,1]
	v_cvt_pk_f16_f32 v28, v36, v37
	v_pk_add_f32 v[36:37], v[26:27], v[32:33] op_sel:[0,1] op_sel_hi:[1,0] neg_lo:[0,1] neg_hi:[0,1]
	v_pk_add_f32 v[26:27], v[26:27], v[32:33] op_sel:[0,1] op_sel_hi:[1,0]
	v_pk_mul_f32 v[32:33], v[30:31], 0 op_sel_hi:[1,0]
	v_pk_mov_b32 v[26:27], v[36:37], v[26:27] op_sel:[1,0]
	v_pk_add_f32 v[34:35], v[32:33], v[30:31] op_sel:[1,0] op_sel_hi:[0,1]
	v_pk_add_f32 v[30:31], v[32:33], v[30:31] op_sel:[1,0] op_sel_hi:[0,1] neg_lo:[0,1] neg_hi:[0,1]
	v_mov_b32_e32 v35, v31
	v_pk_add_f32 v[30:31], v[26:27], v[34:35]
	v_pk_add_f32 v[26:27], v[26:27], v[34:35] neg_lo:[0,1] neg_hi:[0,1]
	ds_write2_b32 v70, v3, v28 offset0:8 offset1:9
	v_cvt_pk_f16_f32 v3, v30, v31
	v_pk_mul_f32 v[30:31], v[26:27], 0 op_sel_hi:[1,0]
	v_pk_add_f32 v[0:1], v[0:1], v[8:9] neg_lo:[0,1] neg_hi:[0,1]
; #define LAS __attribute__((address_space(3)))
; __device__ __forceinline__ int otid() { int t = threadIdx.x; asm volatile("" : "+v"(t)); return t; }
; __device__ __forceinline__ void lds_barrier() { asm volatile("s_waitcnt lgkmcnt(0)\n\ts_barrier" ::: "memory"); }
; __device__ __forceinline__ void make_spec(ldsf2 buf, LAS unsigned* spec, const float* __restrict__ kfrow) {
;     const int tid = otid();
; #pragma unroll
;     for (int q = 0; q < 4; ++q) { const float4 v = *(const float4*)(kfrow + tid * 16 + q * 4);
;         buf[tid * 17 + q * 4 + 0] = mkv2(v.x, 0.f); buf[tid * 17 + q * 4 + 1] = mkv2(v.y, 0.f); buf[tid * 17 + q * 4 + 2] = mkv2(v.z, 0.f); buf[tid * 17 + q * 4 + 3] = mkv2(v.w, 0.f); }
;     __syncthreads();
;     ...
;     cf x[16];
; #pragma unroll
;     for (int m = 0; m < 16; ++m) { const v2f v = buf[tid * 17 + m]; x[m] = cf{v.x, v.y}; }
;     dif_reg<4>(x, cf{1.0f, 0.0f});
; #pragma unroll
;     for (int m = 0; m < 16; ++m) { h2_t hv; hv.x = (_Float16)x[m].x; hv.y = (_Float16)x[m].y; spec[tid * 17 + m] = __builtin_bit_cast(unsigned, hv); }
;     lds_barrier();
	v_pk_add_f32 v[32:33], v[26:27], v[30:31] op_sel:[0,1] op_sel_hi:[1,0] neg_lo:[0,1] neg_hi:[0,1]
	v_pk_add_f32 v[26:27], v[26:27], v[30:31] op_sel:[0,1] op_sel_hi:[1,0]
	v_pk_mul_f32 v[8:9], v[0:1], 0 op_sel_hi:[1,0]
	v_cvt_pk_f16_f32 v26, v32, v27
	ds_write2_b32 v70, v3, v26 offset0:10 offset1:11
	v_pk_add_f32 v[26:27], v[0:1], v[8:9] op_sel:[0,1] op_sel_hi:[1,0] neg_lo:[0,1] neg_hi:[0,1]
	v_pk_add_f32 v[0:1], v[0:1], v[8:9] op_sel:[0,1] op_sel_hi:[1,0]
	v_pk_mov_b32 v[8:9], v[12:13], v[6:7] op_sel:[1,0]
	v_pk_mov_b32 v[6:7], v[6:7], v[12:13] op_sel:[1,0]
	v_mov_b32_e32 v3, v29
	v_pk_add_f32 v[6:7], v[8:9], v[6:7] neg_lo:[0,1] neg_hi:[0,1]
	v_pk_mov_b32 v[4:5], v[14:15], v[4:5] op_sel:[1,0]
	v_pk_fma_f32 v[8:9], v[6:7], 0, v[6:7] op_sel:[0,0,1] op_sel_hi:[1,0,0]
	v_pk_fma_f32 v[6:7], v[6:7], 0, v[6:7] op_sel:[0,0,1] op_sel_hi:[1,0,0] neg_lo:[0,0,1] neg_hi:[0,0,1]
	v_pk_mov_b32 v[0:1], v[26:27], v[0:1] op_sel:[1,0]
	v_mov_b32_e32 v9, v7
	v_mov_b32_e32 v6, v10
	v_mov_b32_e32 v7, v25
	v_pk_add_f32 v[2:3], v[2:3], v[6:7] neg_lo:[0,1] neg_hi:[0,1]
	v_pk_mov_b32 v[6:7], v[10:11], v[24:25] op_sel:[1,0]
	v_pk_mul_f32 v[2:3], v[2:3], s[16:17]
	v_pk_add_f32 v[4:5], v[4:5], v[6:7] neg_lo:[0,1] neg_hi:[0,1]
	s_lshl_b64 s[0:1], s[30:31], 15
	v_pk_fma_f32 v[6:7], v[4:5], s[16:17], v[2:3] neg_lo:[1,0,0] neg_hi:[1,0,0]
	v_pk_fma_f32 v[2:3], v[4:5], s[16:17], v[2:3]
	v_pk_mov_b32 v[10:11], v[6:7], v[6:7] op_sel:[1,0]
	v_pk_add_f32 v[4:5], v[0:1], v[8:9]
	v_pk_add_f32 v[6:7], v[2:3], v[6:7] op_sel:[0,1] op_sel_hi:[1,0]
	v_pk_add_f32 v[0:1], v[0:1], v[8:9] neg_lo:[0,1] neg_hi:[0,1]
	v_pk_add_f32 v[12:13], v[4:5], v[6:7]
	v_pk_add_f32 v[4:5], v[4:5], v[6:7] neg_lo:[0,1] neg_hi:[0,1]
	v_cvt_pk_f16_f32 v14, v12, v13
	v_pk_mul_f32 v[6:7], v[4:5], 0 op_sel_hi:[1,0]
	v_readlane_b32 s10, v252, 40
	v_pk_add_f32 v[12:13], v[4:5], v[6:7] op_sel:[0,1] op_sel_hi:[1,0] neg_lo:[0,1] neg_hi:[0,1]
	v_pk_add_f32 v[4:5], v[4:5], v[6:7] op_sel:[0,1] op_sel_hi:[1,0]
	v_readlane_b32 s11, v252, 41
	v_cvt_pk_f16_f32 v4, v12, v5
	ds_write2_b32 v70, v14, v4 offset0:12 offset1:13
	v_pk_mul_f32 v[4:5], v[0:1], 0 op_sel_hi:[1,0]
	s_add_u32 s0, s10, s0
	v_pk_add_f32 v[6:7], v[0:1], v[4:5] op_sel:[0,1] op_sel_hi:[1,0] neg_lo:[0,1] neg_hi:[0,1]
	v_pk_add_f32 v[0:1], v[0:1], v[4:5] op_sel:[0,1] op_sel_hi:[1,0]
	s_addc_u32 s1, s11, s1
	v_mov_b32_e32 v7, v1
	v_mov_b32_e32 v0, v2
	v_mov_b32_e32 v1, v11
	v_mov_b32_e32 v11, v3
	v_pk_add_f32 v[0:1], v[0:1], v[10:11] neg_lo:[0,1] neg_hi:[0,1]
	s_mov_b64 s[10:11], -1
	v_pk_fma_f32 v[2:3], v[0:1], 0, v[0:1] op_sel:[0,0,1] op_sel_hi:[1,0,0]
	v_pk_fma_f32 v[0:1], v[0:1], 0, v[0:1] op_sel:[0,0,1] op_sel_hi:[1,0,0] neg_lo:[0,0,1] neg_hi:[0,0,1]
	s_nop 0
	v_mov_b32_e32 v3, v1
	v_pk_add_f32 v[0:1], v[6:7], v[2:3]
	s_nop 0
	v_cvt_pk_f16_f32 v8, v0, v1
	v_pk_add_f32 v[0:1], v[6:7], v[2:3] neg_lo:[0,1] neg_hi:[0,1]
	s_nop 0
	v_pk_mul_f32 v[2:3], v[0:1], 0 op_sel_hi:[1,0]
	s_nop 0
	v_pk_add_f32 v[4:5], v[0:1], v[2:3] op_sel:[0,1] op_sel_hi:[1,0] neg_lo:[0,1] neg_hi:[0,1]
	v_pk_add_f32 v[0:1], v[0:1], v[2:3] op_sel:[0,1] op_sel_hi:[1,0]
	s_nop 0
	v_cvt_pk_f16_f32 v0, v4, v1
	ds_write2_b32 v70, v8, v0 offset0:14 offset1:15
	v_mov_b32_e32 v0, v195
	s_waitcnt lgkmcnt(0)
	s_barrier
	s_nop 0
	v_lshlrev_b32_e32 v2, 4, v0
	v_ashrrev_i32_e32 v3, 31, v2
	v_lshl_add_u64 v[14:15], v[2:3], 2, s[0:1]
	global_load_dwordx4 v[2:5], v[14:15], off
	global_load_dwordx4 v[6:9], v[14:15], off offset:16
	global_load_dwordx4 v[10:13], v[14:15], off offset:32
	global_load_dwordx4 v[24:27], v[14:15], off offset:48
	s_movk_i32 s0, 0x88
	v_mul_lo_u32 v1, v0, s0
	v_add_u32_e32 v1, 0, v1
	s_mov_b32 s0, 0
	s_waitcnt vmcnt(3)
	v_mov_b32_e32 v192, v2
	v_mov_b32_e32 v2, v3
	v_mov_b32_e32 v3, v193
	ds_write2_b64 v1, v[192:193], v[2:3] offset1:1
	v_mov_b32_e32 v192, v4
	v_mov_b32_e32 v2, v5
	ds_write2_b64 v1, v[192:193], v[2:3] offset0:2 offset1:3
	s_waitcnt vmcnt(2)
	v_mov_b32_e32 v192, v6
	v_mov_b32_e32 v2, v7
	ds_write2_b64 v1, v[192:193], v[2:3] offset0:4 offset1:5
	v_mov_b32_e32 v192, v8
	v_mov_b32_e32 v2, v9
	ds_write2_b64 v1, v[192:193], v[2:3] offset0:6 offset1:7
	s_waitcnt vmcnt(1)
	v_mov_b32_e32 v192, v10
	v_mov_b32_e32 v2, v11
	ds_write2_b64 v1, v[192:193], v[2:3] offset0:8 offset1:9
	v_mov_b32_e32 v192, v12
	v_mov_b32_e32 v2, v13
	ds_write2_b64 v1, v[192:193], v[2:3] offset0:10 offset1:11
	s_waitcnt vmcnt(0)
	v_mov_b32_e32 v192, v24
	v_mov_b32_e32 v2, v25
	ds_write2_b64 v1, v[192:193], v[2:3] offset0:12 offset1:13
	v_mov_b32_e32 v192, v26
	v_mov_b32_e32 v2, v27
	ds_write2_b64 v1, v[192:193], v[2:3] offset0:14 offset1:15
	v_mov_b32_e32 v2, v195
	s_waitcnt lgkmcnt(0)
	s_barrier

; #define LAS __attribute__((address_space(3)))
; __device__ __forceinline__ cf twc(cf ws, int k16) { if (k16 == 0) return ws; if (k16 == 4) return cf{ws.y, -ws.x}; return cmul(ws, cf{c16(k16), -s16(k16)}); }
; template <int LR> __device__ __forceinline__ void dif_reg(cf (&x)[1 << LR], cf w) {
;     constexpr int R = 1 << LR; cf ws = w;
; #pragma unroll
;     for (int s = 0; s < LR; ++s) { const int half = R >> (s + 1);
; #pragma unroll
;         for (int m0 = 0; m0 < R; m0 += 2 * half)
; #pragma unroll
;             for (int mm = 0; mm < half; ++mm) { const int ia = m0 + mm, ib = ia + half; const cf a = x[ia], b = x[ib];
;                 x[ia] = cf{a.x + b.x, a.y + b.y}; const cf d{a.x - b.x, a.y - b.y};
;                 x[ib] = cmul(d, twc(ws, (mm << s) * (16 / R))); }
;         ws = cmul(ws, ws); }
; }
; template <int LR> __device__ __forceinline__ void dit_reg(cf (&x)[1 << LR], cf w) {
;     constexpr int R = 1 << LR; cf wsv[LR]; wsv[0] = w;
; #pragma unroll
;     for (int s = 1; s < LR; ++s) wsv[s] = cmul(wsv[s - 1], wsv[s - 1]);
; #pragma unroll
;     for (int s = LR - 1; s >= 0; --s) { const int half = R >> (s + 1);
; #pragma unroll
;         for (int m0 = 0; m0 < R; m0 += 2 * half)
; #pragma unroll
;             for (int mm = 0; mm < half; ++mm) { const int ia = m0 + mm, ib = ia + half; const cf a = x[ia];
;                 const cf b = cmulc(x[ib], twc(wsv[s], (mm << s) * (16 / R)));
;                 x[ia] = cf{a.x + b.x, a.y + b.y}; x[ib] = cf{a.x - b.x, a.y - b.y}; } }
; }
; __device__ __forceinline__ void lds_barrier() { asm volatile("s_waitcnt lgkmcnt(0)\n\ts_barrier" ::: "memory"); }
; template <int LR, bool INV> __device__ __forceinline__ void fft_pass(ldsf2 buf, int base, int stride, int twi) {
;     constexpr int R = 1 << LR; cf x[R];
;     const v2f wv = ((ldsf2)((LAS unsigned char*)buf + 139264))[twi];
; #pragma unroll
;     for (int m = 0; m < R; ++m) { const v2f v = buf[base + m * stride]; x[m] = cf{v.x, v.y}; }
;     const cf w{wv.x, wv.y};
;     if (INV) dit_reg<LR>(x, w); else dif_reg<LR>(x, w);
; #pragma unroll
;     for (int m = 0; m < R; ++m) buf[base + m * stride] = mkv2(x[m].x, x[m].y);
; }
.LBB0_344:
	v_or_b32_e32 v5, s0, v3
	ds_read_b64 v[14:15], v4
	v_lshlrev_b32_e32 v6, 3, v5
	v_ashrrev_i32_e32 v5, 1, v5
	v_add3_u32 v5, v2, v6, v5
	ds_read2_b64 v[6:9], v5 offset1:17
	ds_read2_b64 v[10:13], v5 offset0:34 offset1:51
	ds_read2_b64 v[24:27], v5 offset0:68 offset1:85
	ds_read2_b64 v[28:31], v5 offset0:102 offset1:119
	s_waitcnt lgkmcnt(4)
	v_pk_add_f32 v[32:33], v[14:15], v[14:15] op_sel:[0,1] op_sel_hi:[1,0] neg_lo:[0,0] neg_hi:[0,1]
	v_pk_mul_f32 v[38:39], v[14:15], v[14:15] op_sel:[1,1] op_sel_hi:[1,0]
	v_pk_mul_f32 v[34:35], v[32:33], s[16:17] op_sel:[0,0] op_sel_hi:[1,0]
	v_pk_fma_f32 v[38:39], v[14:15], v[14:15], v[38:39] op_sel:[0,0,0] op_sel_hi:[0,1,1] neg_lo:[0,0,1] neg_hi:[0,0,0]
	v_pk_mul_f32 v[36:37], v[32:33], s[16:17] op_sel:[1,0] op_sel_hi:[0,0] neg_lo:[0,0] neg_hi:[1,0]
	s_nop 0
	v_pk_mul_f32 v[40:41], v[38:39], v[38:39] op_sel:[1,1] op_sel_hi:[1,0]
	s_nop 0
	v_pk_fma_f32 v[40:41], v[38:39], v[38:39], v[40:41] op_sel:[0,0,0] op_sel_hi:[0,1,1] neg_lo:[0,0,1] neg_hi:[0,0,0]
	s_waitcnt lgkmcnt(0)
	v_pk_add_f32 v[42:43], v[6:7], v[24:25] neg_lo:[0,1] neg_hi:[0,1]
	v_pk_add_f32 v[44:45], v[8:9], v[26:27] neg_lo:[0,1] neg_hi:[0,1]
	v_pk_add_f32 v[46:47], v[10:11], v[28:29] neg_lo:[0,1] neg_hi:[0,1]
	v_pk_add_f32 v[48:49], v[12:13], v[30:31] neg_lo:[0,1] neg_hi:[0,1]
	v_pk_add_f32 v[6:7], v[6:7], v[24:25]
	v_pk_add_f32 v[8:9], v[8:9], v[26:27]
	v_pk_add_f32 v[10:11], v[10:11], v[28:29]
	v_pk_add_f32 v[12:13], v[12:13], v[30:31]
	v_pk_mul_f32 v[24:25], v[42:43], v[14:15] op_sel:[1,1] op_sel_hi:[1,0]
	v_pk_mul_f32 v[26:27], v[44:45], v[34:35] op_sel:[1,1] op_sel_hi:[1,0]
	v_pk_mul_f32 v[28:29], v[46:47], v[14:15] op_sel:[1,0] op_sel_hi:[1,1]
	v_pk_mul_f32 v[30:31], v[48:49], v[36:37] op_sel:[1,1] op_sel_hi:[1,0]
	v_pk_fma_f32 v[24:25], v[42:43], v[14:15], v[24:25] op_sel:[0,0,0] op_sel_hi:[0,1,1] neg_lo:[0,0,1] neg_hi:[0,0,0]
	v_pk_fma_f32 v[26:27], v[44:45], v[34:35], v[26:27] op_sel:[0,0,0] op_sel_hi:[0,1,1] neg_lo:[0,0,1] neg_hi:[0,0,0]
	v_pk_fma_f32 v[28:29], v[46:47], v[14:15], v[28:29] op_sel:[0,1,0] op_sel_hi:[0,0,1] neg_lo:[0,0,0] neg_hi:[0,1,0]
	v_pk_fma_f32 v[30:31], v[48:49], v[36:37], v[30:31] op_sel:[0,0,0] op_sel_hi:[0,1,1] neg_lo:[0,0,1] neg_hi:[0,0,0]
	v_pk_add_f32 v[42:43], v[6:7], v[10:11] neg_lo:[0,1] neg_hi:[0,1]
	v_pk_add_f32 v[44:45], v[8:9], v[12:13] neg_lo:[0,1] neg_hi:[0,1]
	v_pk_add_f32 v[46:47], v[24:25], v[28:29] neg_lo:[0,1] neg_hi:[0,1]
	v_pk_add_f32 v[48:49], v[26:27], v[30:31] neg_lo:[0,1] neg_hi:[0,1]
	v_pk_add_f32 v[6:7], v[6:7], v[10:11]
	v_pk_add_f32 v[8:9], v[8:9], v[12:13]
	v_pk_add_f32 v[24:25], v[24:25], v[28:29]
	v_pk_add_f32 v[26:27], v[26:27], v[30:31]
	v_pk_mul_f32 v[10:11], v[42:43], v[38:39] op_sel:[1,1] op_sel_hi:[1,0]
	v_pk_mul_f32 v[12:13], v[44:45], v[38:39] op_sel:[1,0] op_sel_hi:[1,1]
	v_pk_mul_f32 v[28:29], v[46:47], v[38:39] op_sel:[1,1] op_sel_hi:[1,0]
	v_pk_mul_f32 v[30:31], v[48:49], v[38:39] op_sel:[1,0] op_sel_hi:[1,1]
	v_pk_fma_f32 v[10:11], v[42:43], v[38:39], v[10:11] op_sel:[0,0,0] op_sel_hi:[0,1,1] neg_lo:[0,0,1] neg_hi:[0,0,0]
	v_pk_fma_f32 v[12:13], v[44:45], v[38:39], v[12:13] op_sel:[0,1,0] op_sel_hi:[0,0,1] neg_lo:[0,0,0] neg_hi:[0,1,0]
	v_pk_fma_f32 v[28:29], v[46:47], v[38:39], v[28:29] op_sel:[0,0,0] op_sel_hi:[0,1,1] neg_lo:[0,0,1] neg_hi:[0,0,0]
	v_pk_fma_f32 v[30:31], v[48:49], v[38:39], v[30:31] op_sel:[0,1,0] op_sel_hi:[0,0,1] neg_lo:[0,0,0] neg_hi:[0,1,0]
	v_pk_add_f32 v[42:43], v[6:7], v[8:9] neg_lo:[0,1] neg_hi:[0,1]
	v_pk_add_f32 v[44:45], v[10:11], v[12:13] neg_lo:[0,1] neg_hi:[0,1]
	v_pk_add_f32 v[46:47], v[24:25], v[26:27] neg_lo:[0,1] neg_hi:[0,1]
	v_pk_add_f32 v[48:49], v[28:29], v[30:31] neg_lo:[0,1] neg_hi:[0,1]
	v_pk_add_f32 v[6:7], v[6:7], v[8:9]
	v_pk_add_f32 v[10:11], v[10:11], v[12:13]
	v_pk_add_f32 v[24:25], v[24:25], v[26:27]
	v_pk_add_f32 v[28:29], v[28:29], v[30:31]
	v_pk_mul_f32 v[8:9], v[42:43], v[40:41] op_sel:[1,1] op_sel_hi:[1,0]
	v_pk_mul_f32 v[12:13], v[44:45], v[40:41] op_sel:[1,1] op_sel_hi:[1,0]
	v_pk_mul_f32 v[26:27], v[46:47], v[40:41] op_sel:[1,1] op_sel_hi:[1,0]
	v_pk_mul_f32 v[30:31], v[48:49], v[40:41] op_sel:[1,1] op_sel_hi:[1,0]
	v_pk_fma_f32 v[8:9], v[42:43], v[40:41], v[8:9] op_sel:[0,0,0] op_sel_hi:[0,1,1] neg_lo:[0,0,1] neg_hi:[0,0,0]
	v_pk_fma_f32 v[12:13], v[44:45], v[40:41], v[12:13] op_sel:[0,0,0] op_sel_hi:[0,1,1] neg_lo:[0,0,1] neg_hi:[0,0,0]
	v_pk_fma_f32 v[26:27], v[46:47], v[40:41], v[26:27] op_sel:[0,0,0] op_sel_hi:[0,1,1] neg_lo:[0,0,1] neg_hi:[0,0,0]
	v_pk_fma_f32 v[30:31], v[48:49], v[40:41], v[30:31] op_sel:[0,0,0] op_sel_hi:[0,1,1] neg_lo:[0,0,1] neg_hi:[0,0,0]
	ds_write2_b64 v5, v[6:7], v[8:9] offset1:17
	ds_write2_b64 v5, v[10:11], v[12:13] offset0:34 offset1:51
	ds_write2_b64 v5, v[24:25], v[26:27] offset0:68 offset1:85
	ds_write2_b64 v5, v[28:29], v[30:31] offset0:102 offset1:119
	s_movk_i32 s0, 0x200
	s_and_b64 vcc, exec, s[10:11]
	s_mov_b64 s[10:11], 0
	s_cbranch_vccnz .LBB0_344
; __device__ __forceinline__ cf twc(cf ws, int k16) { if (k16 == 0) return ws; if (k16 == 4) return cf{ws.y, -ws.x}; return cmul(ws, cf{c16(k16), -s16(k16)}); }
; template <int LR> __device__ __forceinline__ void dif_reg(cf (&x)[1 << LR], cf w) {
;     constexpr int R = 1 << LR; cf ws = w;
; #pragma unroll
;     for (int s = 0; s < LR; ++s) { const int half = R >> (s + 1);
; #pragma unroll
;         for (int m0 = 0; m0 < R; m0 += 2 * half)
; #pragma unroll
;             for (int mm = 0; mm < half; ++mm) { const int ia = m0 + mm, ib = ia + half; const cf a = x[ia], b = x[ib];
;                 x[ia] = cf{a.x + b.x, a.y + b.y}; const cf d{a.x - b.x, a.y - b.y};
;                 x[ib] = cmul(d, twc(ws, (mm << s) * (16 / R))); }
;         ws = cmul(ws, ws); }
; }
; __device__ __forceinline__ void make_spec(ldsf2 buf, LAS unsigned* spec, const float* __restrict__ kfrow) {
;     ...
;     cf x[16];
; #pragma unroll
;     for (int m = 0; m < 16; ++m) { const v2f v = buf[tid * 17 + m]; x[m] = cf{v.x, v.y}; }
;     dif_reg<4>(x, cf{1.0f, 0.0f});
; #pragma unroll
;     for (int m = 0; m < 16; ++m) { h2_t hv; hv.x = (_Float16)x[m].x; hv.y = (_Float16)x[m].y; spec[tid * 17 + m] = __builtin_bit_cast(unsigned, hv); }
	s_waitcnt lgkmcnt(0)
	ds_read2_b64 v[2:5], v1 offset1:1
	ds_read2_b64 v[6:9], v1 offset0:2 offset1:3
	ds_read2_b64 v[10:13], v1 offset0:4 offset1:5
	ds_read2_b64 v[24:27], v1 offset0:6 offset1:7
	ds_read2_b64 v[28:31], v1 offset0:8 offset1:9
	ds_read2_b64 v[32:35], v1 offset0:10 offset1:11
	ds_read2_b64 v[36:39], v1 offset0:12 offset1:13
	ds_read2_b64 v[40:43], v1 offset0:14 offset1:15
	s_movk_i32 s0, 0x44
	v_mul_lo_u32 v0, v0, s0
	v_add_u32_e32 v0, 0, v0
	v_add_u32_e32 v70, 0x19800, v0
	s_waitcnt lgkmcnt(3)
	v_pk_add_f32 v[0:1], v[2:3], v[28:29]
	v_pk_add_f32 v[14:15], v[4:5], v[30:31]
	s_waitcnt lgkmcnt(2)
	v_pk_add_f32 v[44:45], v[6:7], v[32:33]
	v_pk_add_f32 v[46:47], v[8:9], v[34:35]
	s_waitcnt lgkmcnt(1)
	v_pk_add_f32 v[48:49], v[10:11], v[36:37]
	v_pk_add_f32 v[50:51], v[12:13], v[38:39]
	s_waitcnt lgkmcnt(0)
	v_pk_add_f32 v[52:53], v[24:25], v[40:41]
	v_pk_add_f32 v[54:55], v[26:27], v[42:43]
	v_pk_add_f32 v[56:57], v[0:1], v[48:49]
	v_pk_add_f32 v[58:59], v[14:15], v[50:51]
	v_pk_add_f32 v[60:61], v[44:45], v[52:53]
	v_pk_add_f32 v[62:63], v[46:47], v[54:55]
	v_pk_add_f32 v[64:65], v[56:57], v[60:61]
	v_pk_add_f32 v[66:67], v[58:59], v[62:63]
	v_pk_add_f32 v[56:57], v[56:57], v[60:61] neg_lo:[0,1] neg_hi:[0,1]
	v_pk_add_f32 v[68:69], v[64:65], v[66:67]
	v_pk_add_f32 v[64:65], v[64:65], v[66:67] neg_lo:[0,1] neg_hi:[0,1]
	v_cvt_pk_f16_f32 v71, v68, v69
	v_pk_mul_f32 v[66:67], v[64:65], 0 op_sel_hi:[1,0]
	v_pk_mul_f32 v[60:61], v[56:57], 0 op_sel_hi:[1,0]
	v_pk_add_f32 v[68:69], v[64:65], v[66:67] op_sel:[0,1] op_sel_hi:[1,0] neg_lo:[0,1] neg_hi:[0,1]
	v_pk_add_f32 v[64:65], v[64:65], v[66:67] op_sel:[0,1] op_sel_hi:[1,0]
	v_pk_add_f32 v[0:1], v[0:1], v[48:49] neg_lo:[0,1] neg_hi:[0,1]
	v_cvt_pk_f16_f32 v64, v68, v65
	ds_write2_b32 v70, v71, v64 offset1:1
	v_pk_add_f32 v[64:65], v[56:57], v[60:61] op_sel:[0,1] op_sel_hi:[1,0] neg_lo:[0,1] neg_hi:[0,1]
	v_pk_add_f32 v[56:57], v[56:57], v[60:61] op_sel:[0,1] op_sel_hi:[1,0]
	v_pk_mul_f32 v[48:49], v[0:1], 0 op_sel_hi:[1,0]
	v_mov_b32_e32 v65, v57
	v_pk_add_f32 v[56:57], v[58:59], v[62:63] neg_lo:[0,1] neg_hi:[0,1]
	s_mov_b32 s0, s87
	v_pk_fma_f32 v[58:59], v[56:57], 0, v[56:57] op_sel:[0,0,1] op_sel_hi:[1,0,0]
	v_pk_fma_f32 v[56:57], v[56:57], 0, v[56:57] op_sel:[0,0,1] op_sel_hi:[1,0,0] neg_lo:[0,0,1] neg_hi:[0,0,1]
	s_mov_b32 s1, s16
	v_mov_b32_e32 v59, v57
	v_pk_add_f32 v[56:57], v[64:65], v[58:59]
	s_mov_b32 s17, s87
	v_cvt_pk_f16_f32 v62, v56, v57
	v_pk_add_f32 v[56:57], v[64:65], v[58:59] neg_lo:[0,1] neg_hi:[0,1]
	s_mov_b32 s10, s5
	v_pk_mul_f32 v[58:59], v[56:57], 0 op_sel_hi:[1,0]
	s_mov_b32 s14, s13
	v_pk_add_f32 v[60:61], v[56:57], v[58:59] op_sel:[0,1] op_sel_hi:[1,0] neg_lo:[0,1] neg_hi:[0,1]
	v_pk_add_f32 v[56:57], v[56:57], v[58:59] op_sel:[0,1] op_sel_hi:[1,0]
	v_mov_b32_e32 v58, v51
	v_cvt_pk_f16_f32 v56, v60, v57
	ds_write2_b32 v70, v62, v56 offset0:2 offset1:3
	v_pk_add_f32 v[56:57], v[0:1], v[48:49] op_sel:[0,1] op_sel_hi:[1,0] neg_lo:[0,1] neg_hi:[0,1]
	v_pk_add_f32 v[0:1], v[0:1], v[48:49] op_sel:[0,1] op_sel_hi:[1,0]
	v_mov_b32_e32 v48, v54
	v_mov_b32_e32 v57, v1
	v_pk_add_f32 v[0:1], v[44:45], v[52:53] neg_lo:[0,1] neg_hi:[0,1]
	v_mov_b32_e32 v49, v51
	v_pk_fma_f32 v[44:45], v[0:1], 0, v[0:1] op_sel:[0,0,1] op_sel_hi:[1,0,0]
	v_pk_fma_f32 v[0:1], v[0:1], 0, v[0:1] op_sel:[0,0,1] op_sel_hi:[1,0,0] neg_lo:[0,0,1] neg_hi:[0,0,1]
	v_mov_b32_e32 v52, v50
	v_mov_b32_e32 v45, v1
	v_mov_b32_e32 v0, v46
	v_mov_b32_e32 v1, v15
	v_pk_add_f32 v[0:1], v[0:1], v[48:49] neg_lo:[0,1] neg_hi:[0,1]
	v_mov_b32_e32 v48, v14
	v_mov_b32_e32 v49, v46
	v_mov_b32_e32 v53, v54
	v_pk_add_f32 v[48:49], v[48:49], v[52:53] neg_lo:[0,1] neg_hi:[0,1]
	v_mov_b32_e32 v52, v15
	v_mov_b32_e32 v53, v47
	v_mov_b32_e32 v59, v55
	v_pk_mov_b32 v[14:15], v[46:47], v[14:15] op_sel:[1,0]
	v_pk_mov_b32 v[46:47], v[54:55], v[50:51] op_sel:[1,0]
	v_pk_add_f32 v[52:53], v[52:53], v[58:59] neg_lo:[0,1] neg_hi:[0,1]
	v_pk_add_f32 v[14:15], v[14:15], v[46:47] neg_lo:[0,1] neg_hi:[0,1]
	v_pk_mul_f32 v[46:47], v[52:53], s[16:17]
	v_pk_mul_f32 v[14:15], v[14:15], s[0:1]
	s_mov_b32 s15, s4
	v_pk_fma_f32 v[0:1], v[0:1], s[0:1], v[14:15] neg_lo:[0,0,1] neg_hi:[0,0,1]
	v_pk_fma_f32 v[14:15], v[48:49], s[16:17], v[46:47]
	v_pk_add_f32 v[46:47], v[56:57], v[44:45]
	v_pk_add_f32 v[48:49], v[14:15], v[0:1]
	v_pk_add_f32 v[44:45], v[56:57], v[44:45] neg_lo:[0,1] neg_hi:[0,1]
	v_pk_add_f32 v[50:51], v[46:47], v[48:49]
	v_pk_add_f32 v[46:47], v[46:47], v[48:49] neg_lo:[0,1] neg_hi:[0,1]
	v_cvt_pk_f16_f32 v52, v50, v51
	v_pk_mul_f32 v[48:49], v[46:47], 0 op_sel_hi:[1,0]
	s_mov_b32 s35, s5
	v_pk_add_f32 v[50:51], v[46:47], v[48:49] op_sel:[0,1] op_sel_hi:[1,0] neg_lo:[0,1] neg_hi:[0,1]
	v_pk_add_f32 v[46:47], v[46:47], v[48:49] op_sel:[0,1] op_sel_hi:[1,0]
	s_mov_b32 s48, 0
	v_cvt_pk_f16_f32 v46, v50, v47
	ds_write2_b32 v70, v52, v46 offset0:4 offset1:5
	v_pk_mul_f32 v[46:47], v[44:45], 0 op_sel_hi:[1,0]
	s_mov_b32 s49, s48
	v_pk_add_f32 v[48:49], v[44:45], v[46:47] op_sel:[0,1] op_sel_hi:[1,0] neg_lo:[0,1] neg_hi:[0,1]
	v_pk_add_f32 v[44:45], v[44:45], v[46:47] op_sel:[0,1] op_sel_hi:[1,0]
	s_mov_b32 s50, s48
	v_mov_b32_e32 v49, v45
	v_mov_b32_e32 v44, v14
	v_mov_b32_e32 v45, v1
	v_mov_b32_e32 v1, v15
	v_pk_add_f32 v[0:1], v[44:45], v[0:1] neg_lo:[0,1] neg_hi:[0,1]
	s_mov_b32 s51, s48
	v_pk_fma_f32 v[14:15], v[0:1], 0, v[0:1] op_sel:[0,0,1] op_sel_hi:[1,0,0]
	v_pk_fma_f32 v[0:1], v[0:1], 0, v[0:1] op_sel:[0,0,1] op_sel_hi:[1,0,0] neg_lo:[0,0,1] neg_hi:[0,0,1]
	s_mov_b32 s53, s48
	v_mov_b32_e32 v15, v1
	v_pk_add_f32 v[0:1], v[48:49], v[14:15]
	s_nop 0
	v_cvt_pk_f16_f32 v46, v0, v1
	v_pk_add_f32 v[0:1], v[48:49], v[14:15] neg_lo:[0,1] neg_hi:[0,1]
; __device__ __forceinline__ cf twc(cf ws, int k16) { if (k16 == 0) return ws; if (k16 == 4) return cf{ws.y, -ws.x}; return cmul(ws, cf{c16(k16), -s16(k16)}); }
; template <int LR> __device__ __forceinline__ void dif_reg(cf (&x)[1 << LR], cf w) {
;     constexpr int R = 1 << LR; cf ws = w;
; #pragma unroll
;     for (int s = 0; s < LR; ++s) { const int half = R >> (s + 1);
; #pragma unroll
;         for (int m0 = 0; m0 < R; m0 += 2 * half)
; #pragma unroll
;             for (int mm = 0; mm < half; ++mm) { const int ia = m0 + mm, ib = ia + half; const cf a = x[ia], b = x[ib];
;                 x[ia] = cf{a.x + b.x, a.y + b.y}; const cf d{a.x - b.x, a.y - b.y};
;                 x[ib] = cmul(d, twc(ws, (mm << s) * (16 / R))); }
;         ws = cmul(ws, ws); }
; }
; __device__ __forceinline__ void make_spec(ldsf2 buf, LAS unsigned* spec, const float* __restrict__ kfrow) {
;     ...
;     cf x[16];
; #pragma unroll
;     for (int m = 0; m < 16; ++m) { const v2f v = buf[tid * 17 + m]; x[m] = cf{v.x, v.y}; }
;     dif_reg<4>(x, cf{1.0f, 0.0f});
; #pragma unroll
;     for (int m = 0; m < 16; ++m) { h2_t hv; hv.x = (_Float16)x[m].x; hv.y = (_Float16)x[m].y; spec[tid * 17 + m] = __builtin_bit_cast(unsigned, hv); }
	s_nop 0
	v_pk_mul_f32 v[14:15], v[0:1], 0 op_sel_hi:[1,0]
	s_nop 0
	v_pk_add_f32 v[44:45], v[0:1], v[14:15] op_sel:[0,1] op_sel_hi:[1,0] neg_lo:[0,1] neg_hi:[0,1]
	v_pk_add_f32 v[0:1], v[0:1], v[14:15] op_sel:[0,1] op_sel_hi:[1,0]
	s_nop 0
	v_cvt_pk_f16_f32 v0, v44, v1
	ds_write2_b32 v70, v46, v0 offset0:6 offset1:7
	v_pk_add_f32 v[0:1], v[2:3], v[28:29] neg_lo:[0,1] neg_hi:[0,1]
	s_nop 0
	v_pk_mul_f32 v[2:3], v[0:1], 0 op_sel_hi:[1,0]
	s_nop 0
	v_pk_add_f32 v[14:15], v[0:1], v[2:3] op_sel:[0,1] op_sel_hi:[1,0] neg_lo:[0,1] neg_hi:[0,1]
	v_pk_add_f32 v[0:1], v[0:1], v[2:3] op_sel:[0,1] op_sel_hi:[1,0]
	v_pk_add_f32 v[2:3], v[4:5], v[30:31] neg_lo:[0,1] neg_hi:[0,1]
	v_pk_mov_b32 v[0:1], v[0:1], v[14:15] op_sel:[1,0]
	v_pk_mul_f32 v[4:5], v[2:3], s[4:5] op_sel_hi:[1,0]
	s_nop 0
	v_pk_fma_f32 v[14:15], v[2:3], s[10:11], v[4:5] op_sel:[0,0,1] op_sel_hi:[1,0,0]
	v_pk_fma_f32 v[2:3], v[2:3], s[10:11], v[4:5] op_sel:[0,0,1] op_sel_hi:[1,0,0] neg_lo:[1,0,0] neg_hi:[1,0,0]
	v_pk_add_f32 v[4:5], v[8:9], v[34:35] neg_lo:[0,1] neg_hi:[0,1]
	v_mov_b32_e32 v34, v40
	v_pk_mul_f32 v[8:9], v[4:5], s[10:11] op_sel_hi:[1,0]
	v_mov_b32_e32 v35, v32
	v_pk_fma_f32 v[28:29], v[4:5], s[4:5], v[8:9] op_sel:[0,0,1] op_sel_hi:[1,0,0]
	v_pk_fma_f32 v[4:5], v[4:5], s[4:5], v[8:9] op_sel:[0,0,1] op_sel_hi:[1,0,0] neg_lo:[1,0,0] neg_hi:[1,0,0]
	v_pk_add_f32 v[8:9], v[10:11], v[36:37] neg_lo:[0,1] neg_hi:[0,1]
	v_mov_b32_e32 v36, v41
	v_pk_mul_f32 v[10:11], v[8:9], 0 op_sel_hi:[1,0]
	v_mov_b32_e32 v37, v33
	v_pk_add_f32 v[30:31], v[10:11], v[8:9] op_sel:[1,0] op_sel_hi:[0,1]
	v_pk_add_f32 v[8:9], v[10:11], v[8:9] op_sel:[1,0] op_sel_hi:[0,1] neg_lo:[0,1] neg_hi:[0,1]
	v_pk_add_f32 v[10:11], v[12:13], v[38:39] neg_lo:[0,1] neg_hi:[0,1]
	v_mov_b32_e32 v9, v31
	v_pk_mul_f32 v[12:13], v[10:11], s[10:11] op_sel_hi:[1,0]
	v_pk_mov_b32 v[30:31], v[32:33], v[40:41] op_sel:[1,0]
	v_pk_fma_f32 v[10:11], v[10:11], s[14:15], v[12:13] op_sel:[0,0,1] op_sel_hi:[1,1,0] neg_lo:[0,0,1] neg_hi:[0,0,1]
	v_pk_mov_b32 v[12:13], v[6:7], v[24:25] op_sel:[1,0]
	v_mov_b32_e32 v33, v41
	v_pk_add_f32 v[12:13], v[12:13], v[30:31] neg_lo:[0,1] neg_hi:[0,1]
	v_mov_b32_e32 v30, v24
	v_mov_b32_e32 v31, v6
	v_pk_add_f32 v[30:31], v[30:31], v[34:35] neg_lo:[0,1] neg_hi:[0,1]
	v_mov_b32_e32 v34, v25
	v_mov_b32_e32 v35, v7
	v_mov_b32_e32 v7, v25
	v_pk_add_f32 v[34:35], v[34:35], v[36:37] neg_lo:[0,1] neg_hi:[0,1]
	v_pk_add_f32 v[6:7], v[6:7], v[32:33] neg_lo:[0,1] neg_hi:[0,1]
	v_pk_mul_f32 v[24:25], v[34:35], s[0:1]
	v_pk_mul_f32 v[6:7], v[6:7], s[16:17]
	v_mov_b32_e32 v3, v15
	v_pk_fma_f32 v[6:7], v[12:13], s[16:17], v[6:7] neg_lo:[0,0,1] neg_hi:[0,0,1]
	v_pk_fma_f32 v[12:13], v[30:31], s[0:1], v[24:25]
	v_pk_add_f32 v[24:25], v[26:27], v[42:43] neg_lo:[0,1] neg_hi:[0,1]
	v_mov_b32_e32 v28, v4
	v_pk_mul_f32 v[26:27], v[24:25], s[4:5] op_sel_hi:[1,0]
	v_pk_add_f32 v[30:31], v[2:3], v[10:11]
	v_pk_fma_f32 v[24:25], v[24:25], s[34:35], v[26:27] op_sel:[0,0,1] op_sel_hi:[1,1,0] neg_lo:[0,0,1] neg_hi:[0,0,1]
	v_pk_add_f32 v[26:27], v[0:1], v[8:9]
	v_pk_add_f32 v[32:33], v[12:13], v[6:7]
	v_pk_add_f32 v[34:35], v[28:29], v[24:25]
	v_pk_add_f32 v[36:37], v[26:27], v[32:33]
	v_pk_add_f32 v[38:39], v[30:31], v[34:35]
	v_pk_add_f32 v[26:27], v[26:27], v[32:33] neg_lo:[0,1] neg_hi:[0,1]
	v_pk_add_f32 v[40:41], v[36:37], v[38:39]
	v_pk_add_f32 v[36:37], v[36:37], v[38:39] neg_lo:[0,1] neg_hi:[0,1]
	v_pk_mov_b32 v[40:41], v[40:41], v[40:41] op_sel:[1,0]
	v_pk_mul_f32 v[38:39], v[36:37], 0 op_sel_hi:[1,0]
	v_cvt_pk_f16_f32 v3, v40, v41
	v_pk_add_f32 v[40:41], v[36:37], v[38:39] op_sel:[0,1] op_sel_hi:[1,0] neg_lo:[0,1] neg_hi:[0,1]
	v_pk_add_f32 v[36:37], v[36:37], v[38:39] op_sel:[0,1] op_sel_hi:[1,0]
	v_pk_mul_f32 v[32:33], v[26:27], 0 op_sel_hi:[1,0]
	v_pk_mov_b32 v[36:37], v[40:41], v[36:37] op_sel:[1,0]
	v_pk_add_f32 v[30:31], v[30:31], v[34:35] neg_lo:[0,1] neg_hi:[0,1]
	v_cvt_pk_f16_f32 v28, v36, v37
	v_pk_add_f32 v[36:37], v[26:27], v[32:33] op_sel:[0,1] op_sel_hi:[1,0] neg_lo:[0,1] neg_hi:[0,1]
	v_pk_add_f32 v[26:27], v[26:27], v[32:33] op_sel:[0,1] op_sel_hi:[1,0]
	v_pk_mul_f32 v[32:33], v[30:31], 0 op_sel_hi:[1,0]
	v_pk_mov_b32 v[26:27], v[36:37], v[26:27] op_sel:[1,0]
	v_pk_add_f32 v[34:35], v[32:33], v[30:31] op_sel:[1,0] op_sel_hi:[0,1]
	v_pk_add_f32 v[30:31], v[32:33], v[30:31] op_sel:[1,0] op_sel_hi:[0,1] neg_lo:[0,1] neg_hi:[0,1]
	v_mov_b32_e32 v35, v31
	v_pk_add_f32 v[30:31], v[26:27], v[34:35]
	v_pk_add_f32 v[26:27], v[26:27], v[34:35] neg_lo:[0,1] neg_hi:[0,1]
	ds_write2_b32 v70, v3, v28 offset0:8 offset1:9
	v_cvt_pk_f16_f32 v3, v30, v31
	v_pk_mul_f32 v[30:31], v[26:27], 0 op_sel_hi:[1,0]
	v_pk_add_f32 v[0:1], v[0:1], v[8:9] neg_lo:[0,1] neg_hi:[0,1]
	v_pk_add_f32 v[32:33], v[26:27], v[30:31] op_sel:[0,1] op_sel_hi:[1,0] neg_lo:[0,1] neg_hi:[0,1]
	v_pk_add_f32 v[26:27], v[26:27], v[30:31] op_sel:[0,1] op_sel_hi:[1,0]
; __device__ __forceinline__ void lds_barrier() { asm volatile("s_waitcnt lgkmcnt(0)\n\ts_barrier" ::: "memory"); }
; __device__ __forceinline__ void make_spec(ldsf2 buf, LAS unsigned* spec, const float* __restrict__ kfrow) {
;     ...
;     cf x[16];
; #pragma unroll
;     for (int m = 0; m < 16; ++m) { const v2f v = buf[tid * 17 + m]; x[m] = cf{v.x, v.y}; }
;     dif_reg<4>(x, cf{1.0f, 0.0f});
; #pragma unroll
;     for (int m = 0; m < 16; ++m) { h2_t hv; hv.x = (_Float16)x[m].x; hv.y = (_Float16)x[m].y; spec[tid * 17 + m] = __builtin_bit_cast(unsigned, hv); }
;     lds_barrier();
; __device__ void ph_hyena_fft(const Params& P, int j, const bf16_t* __restrict__ projAT, const float* __restrict__ kf, bf16_t* __restrict__ yaT, unsigned char* lds_raw) {
;     ...
;         const float wv0 = cw[c], wv1 = cw[3072 + c], wv2 = cw[6144 + c], bv = cb[c];
;         const float wa0 = cw[1024 + c], wa1 = cw[3072 + 1024 + c], wa2 = cw[6144 + 1024 + c], ba = cb[1024 + c];
;         const float wb0 = cw[2048 + c], wb1 = cw[3072 + 2048 + c], wb2 = cw[6144 + 2048 + c], bb = cb[2048 + c];
;         const float sk0 = skip[c], sk1 = skip[1024 + c];
;         const bf16_t* vrow = projAT + (size_t)c * T_TOK; const bf16_t* x1row = projAT + (size_t)(1024 + c) * T_TOK;
;         const bf16_t* x2row = projAT + (size_t)(2048 + c) * T_TOK; const bf16_t* grow = projAT + (size_t)(3072 + c) * T_TOK;
	v_pk_mul_f32 v[8:9], v[0:1], 0 op_sel_hi:[1,0]
	v_cvt_pk_f16_f32 v26, v32, v27
	ds_write2_b32 v70, v3, v26 offset0:10 offset1:11
	v_pk_add_f32 v[26:27], v[0:1], v[8:9] op_sel:[0,1] op_sel_hi:[1,0] neg_lo:[0,1] neg_hi:[0,1]
	v_pk_add_f32 v[0:1], v[0:1], v[8:9] op_sel:[0,1] op_sel_hi:[1,0]
	v_pk_mov_b32 v[8:9], v[12:13], v[6:7] op_sel:[1,0]
	v_pk_mov_b32 v[6:7], v[6:7], v[12:13] op_sel:[1,0]
	v_mov_b32_e32 v3, v29
	v_pk_add_f32 v[6:7], v[8:9], v[6:7] neg_lo:[0,1] neg_hi:[0,1]
	v_pk_mov_b32 v[4:5], v[14:15], v[4:5] op_sel:[1,0]
	v_pk_fma_f32 v[8:9], v[6:7], 0, v[6:7] op_sel:[0,0,1] op_sel_hi:[1,0,0]
	v_pk_fma_f32 v[6:7], v[6:7], 0, v[6:7] op_sel:[0,0,1] op_sel_hi:[1,0,0] neg_lo:[0,0,1] neg_hi:[0,0,1]
	v_pk_mov_b32 v[0:1], v[26:27], v[0:1] op_sel:[1,0]
	v_mov_b32_e32 v9, v7
	v_mov_b32_e32 v6, v10
	v_mov_b32_e32 v7, v25
	v_pk_add_f32 v[2:3], v[2:3], v[6:7] neg_lo:[0,1] neg_hi:[0,1]
	v_pk_mov_b32 v[6:7], v[10:11], v[24:25] op_sel:[1,0]
	v_pk_mul_f32 v[2:3], v[2:3], s[16:17]
	v_pk_add_f32 v[4:5], v[4:5], v[6:7] neg_lo:[0,1] neg_hi:[0,1]
	s_lshl_b64 s[0:1], s[46:47], 2
	v_pk_fma_f32 v[6:7], v[4:5], s[16:17], v[2:3] neg_lo:[1,0,0] neg_hi:[1,0,0]
	v_pk_fma_f32 v[2:3], v[4:5], s[16:17], v[2:3]
	v_pk_mov_b32 v[10:11], v[6:7], v[6:7] op_sel:[1,0]
	v_pk_add_f32 v[4:5], v[0:1], v[8:9]
	v_pk_add_f32 v[6:7], v[2:3], v[6:7] op_sel:[0,1] op_sel_hi:[1,0]
	v_pk_add_f32 v[0:1], v[0:1], v[8:9] neg_lo:[0,1] neg_hi:[0,1]
	v_pk_add_f32 v[12:13], v[4:5], v[6:7]
	v_pk_add_f32 v[4:5], v[4:5], v[6:7] neg_lo:[0,1] neg_hi:[0,1]
	v_cvt_pk_f16_f32 v14, v12, v13
	v_pk_mul_f32 v[6:7], v[4:5], 0 op_sel_hi:[1,0]
	s_add_u32 s14, s38, s0
	v_pk_add_f32 v[12:13], v[4:5], v[6:7] op_sel:[0,1] op_sel_hi:[1,0] neg_lo:[0,1] neg_hi:[0,1]
	v_pk_add_f32 v[4:5], v[4:5], v[6:7] op_sel:[0,1] op_sel_hi:[1,0]
	s_addc_u32 s15, s39, s1
	v_cvt_pk_f16_f32 v4, v12, v5
	ds_write2_b32 v70, v14, v4 offset0:12 offset1:13
	v_pk_mul_f32 v[4:5], v[0:1], 0 op_sel_hi:[1,0]
	s_lshl_b64 s[10:11], s[46:47], 16
	v_pk_add_f32 v[6:7], v[0:1], v[4:5] op_sel:[0,1] op_sel_hi:[1,0] neg_lo:[0,1] neg_hi:[0,1]
	v_pk_add_f32 v[0:1], v[0:1], v[4:5] op_sel:[0,1] op_sel_hi:[1,0]
	s_add_u32 s26, s54, s0
	v_mov_b32_e32 v7, v1
	v_mov_b32_e32 v0, v2
	v_mov_b32_e32 v1, v11
	v_mov_b32_e32 v11, v3
	v_pk_add_f32 v[0:1], v[0:1], v[10:11] neg_lo:[0,1] neg_hi:[0,1]
	s_addc_u32 s27, s55, s1
	v_pk_fma_f32 v[2:3], v[0:1], 0, v[0:1] op_sel:[0,0,1] op_sel_hi:[1,0,0]
	v_pk_fma_f32 v[0:1], v[0:1], 0, v[0:1] op_sel:[0,0,1] op_sel_hi:[1,0,0] neg_lo:[0,0,1] neg_hi:[0,0,1]
	s_add_u32 s0, s56, s0
	v_mov_b32_e32 v3, v1
	v_pk_add_f32 v[0:1], v[6:7], v[2:3]
	s_addc_u32 s1, s57, s1
	v_cvt_pk_f16_f32 v8, v0, v1
	v_pk_add_f32 v[0:1], v[6:7], v[2:3] neg_lo:[0,1] neg_hi:[0,1]
	s_nop 0
	v_pk_mul_f32 v[2:3], v[0:1], 0 op_sel_hi:[1,0]
	s_nop 0
	v_pk_add_f32 v[4:5], v[0:1], v[2:3] op_sel:[0,1] op_sel_hi:[1,0] neg_lo:[0,1] neg_hi:[0,1]
	v_pk_add_f32 v[0:1], v[0:1], v[2:3] op_sel:[0,1] op_sel_hi:[1,0]
	s_nop 0
	v_cvt_pk_f16_f32 v0, v4, v1
	ds_write2_b32 v70, v8, v0 offset0:14 offset1:15
	s_waitcnt lgkmcnt(0)
	s_barrier
	v_mov_b32_e32 v0, 0x3000
	global_load_dword v25, v193, s[14:15]
	global_load_dword v24, v0, s[14:15]
	v_mov_b32_e32 v0, 0x6000
	global_load_dword v26, v0, s[14:15]
	v_mov_b32_e32 v0, 0x7000
	global_load_dword v28, v193, s[26:27]
	global_load_dword v30, v231, s[14:15]
	global_load_dword v32, v230, s[14:15]
	global_load_dword v34, v0, s[14:15]
	global_load_dword v36, v231, s[26:27]
	global_load_dword v39, v238, s[14:15]
	v_mov_b32_e32 v0, 0x5000
	global_load_dword v38, v0, s[14:15]
	v_mov_b32_e32 v0, 0x8000
	global_load_dword v40, v0, s[14:15]
	global_load_dword v42, v238, s[26:27]
	global_load_dword v44, v193, s[0:1]
	global_load_dword v46, v231, s[0:1]
	s_lshl_b64 s[0:1], s[6:7], 1
	v_readlane_b32 s14, v252, 36
	v_readlane_b32 s15, v252, 37
	s_add_u32 s47, s14, s0
	s_addc_u32 s58, s15, s1
	s_lshl_b64 s[6:7], s[30:31], 16
	s_add_u32 s59, s14, s6
	s_addc_u32 s60, s15, s7
	s_add_u32 s6, s14, s10
	s_addc_u32 s7, s15, s11
	s_add_u32 s61, s6, 0x8000000
	s_addc_u32 s52, s7, 0
	v_lshl_add_u64 v[0:1], v[18:19], 0, s[10:11]
	s_mov_b64 s[6:7], 0xc000000
	v_lshl_add_u64 v[48:49], v[0:1], 0, s[6:7]
	v_lshl_add_u64 v[50:51], v[20:21], 0, s[0:1]
	s_waitcnt vmcnt(13)
	v_mov_b32_e32 v58, v25
	v_mov_b32_e32 v59, v25
	s_waitcnt vmcnt(12)
	v_mov_b32_e32 v60, v24
	s_waitcnt vmcnt(10)
	v_mov_b32_e32 v29, v28
	v_mov_b32_e32 v27, v26
	s_waitcnt vmcnt(6)
	v_mov_b32_e32 v37, v36
	s_waitcnt vmcnt(5)
	v_mov_b32_e32 v52, v39
	v_mov_b32_e32 v53, v39
	s_waitcnt vmcnt(4)
	v_mov_b32_e32 v54, v38
	s_waitcnt vmcnt(3)
	v_mov_b32_e32 v41, v40
	s_waitcnt vmcnt(2)
	v_mov_b32_e32 v43, v42
	s_waitcnt vmcnt(0)
	v_mov_b32_e32 v47, v46
	v_mov_b32_e32 v55, v38
	v_mov_b32_e32 v45, v44
	v_mov_b32_e32 v35, v34
	v_mov_b32_e32 v31, v30
	v_mov_b32_e32 v33, v32
	v_mov_b32_e32 v56, v32
	v_mov_b32_e32 v57, v30
	v_mov_b32_e32 v61, v24

; #define LAS __attribute__((address_space(3)))
; __device__ __forceinline__ cf twc(cf ws, int k16) { if (k16 == 0) return ws; if (k16 == 4) return cf{ws.y, -ws.x}; return cmul(ws, cf{c16(k16), -s16(k16)}); }
; template <int LR> __device__ __forceinline__ void dif_reg(cf (&x)[1 << LR], cf w) {
;     constexpr int R = 1 << LR; cf ws = w;
; #pragma unroll
;     for (int s = 0; s < LR; ++s) { const int half = R >> (s + 1);
; #pragma unroll
;         for (int m0 = 0; m0 < R; m0 += 2 * half)
; #pragma unroll
;             for (int mm = 0; mm < half; ++mm) { const int ia = m0 + mm, ib = ia + half; const cf a = x[ia], b = x[ib];
;                 x[ia] = cf{a.x + b.x, a.y + b.y}; const cf d{a.x - b.x, a.y - b.y};
;                 x[ib] = cmul(d, twc(ws, (mm << s) * (16 / R))); }
;         ws = cmul(ws, ws); }
; }
; template <int LR> __device__ __forceinline__ void dit_reg(cf (&x)[1 << LR], cf w) {
;     constexpr int R = 1 << LR; cf wsv[LR]; wsv[0] = w;
; #pragma unroll
;     for (int s = 1; s < LR; ++s) wsv[s] = cmul(wsv[s - 1], wsv[s - 1]);
; #pragma unroll
;     for (int s = LR - 1; s >= 0; --s) { const int half = R >> (s + 1);
; #pragma unroll
;         for (int m0 = 0; m0 < R; m0 += 2 * half)
; #pragma unroll
;             for (int mm = 0; mm < half; ++mm) { const int ia = m0 + mm, ib = ia + half; const cf a = x[ia];
;                 const cf b = cmulc(x[ib], twc(wsv[s], (mm << s) * (16 / R)));
;                 x[ia] = cf{a.x + b.x, a.y + b.y}; x[ib] = cf{a.x - b.x, a.y - b.y}; } }
; }
; __device__ __forceinline__ void lds_barrier() { asm volatile("s_waitcnt lgkmcnt(0)\n\ts_barrier" ::: "memory"); }
; template <int LR, bool INV> __device__ __forceinline__ void fft_pass(ldsf2 buf, int base, int stride, int twi) {
;     constexpr int R = 1 << LR; cf x[R];
;     const v2f wv = ((ldsf2)((LAS unsigned char*)buf + 139264))[twi];
; #pragma unroll
;     for (int m = 0; m < R; ++m) { const v2f v = buf[base + m * stride]; x[m] = cf{v.x, v.y}; }
;     const cf w{wv.x, wv.y};
;     if (INV) dit_reg<LR>(x, w); else dif_reg<LR>(x, w);
; #pragma unroll
;     for (int m = 0; m < R; ++m) buf[base + m * stride] = mkv2(x[m].x, x[m].y);
; }
.LBB0_347:
	v_add_u32_e32 v72, s0, v68
	v_ashrrev_i32_e32 v69, 4, v72
	v_lshl_add_u32 v72, v72, 3, 0
	v_add_u32_e32 v73, 0x22000, v72
	v_lshl_add_u32 v69, v69, 3, v72
	ds_read_b64 v[88:89], v73
	ds_read2st64_b64 v[72:75], v69 offset1:17
	ds_read2st64_b64 v[76:79], v69 offset0:68 offset1:85
	ds_read2st64_b64 v[80:83], v69 offset0:34 offset1:51
	ds_read2st64_b64 v[84:87], v69 offset0:102 offset1:119
	s_movk_i32 s0, 0x200
	v_add_u32_e32 v112, s0, v68
	v_ashrrev_i32_e32 v114, 4, v112
	v_lshl_add_u32 v112, v112, 3, 0
	v_add_u32_e32 v116, 0x22000, v112
	v_lshl_add_u32 v114, v114, 3, v112
	ds_read_b64 v[118:119], v116
	ds_read2st64_b64 v[120:123], v114 offset1:17
	ds_read2st64_b64 v[124:127], v114 offset0:68 offset1:85
	ds_read2st64_b64 v[128:131], v114 offset0:34 offset1:51
	ds_read2st64_b64 v[132:135], v114 offset0:102 offset1:119
	s_waitcnt lgkmcnt(5)
	v_pk_add_f32 v[90:91], v[88:89], v[88:89] op_sel:[0,1] op_sel_hi:[1,0] neg_lo:[0,0] neg_hi:[0,1]
	v_pk_mul_f32 v[96:97], v[88:89], v[88:89] op_sel:[1,1] op_sel_hi:[1,0]
	v_pk_mul_f32 v[92:93], v[90:91], s[16:17] op_sel:[0,0] op_sel_hi:[1,0]
	v_pk_fma_f32 v[96:97], v[88:89], v[88:89], v[96:97] op_sel:[0,0,0] op_sel_hi:[0,1,1] neg_lo:[0,0,1] neg_hi:[0,0,0]
	v_pk_mul_f32 v[94:95], v[90:91], s[16:17] op_sel:[1,0] op_sel_hi:[0,0] neg_lo:[0,0] neg_hi:[1,0]
	s_nop 0
	v_pk_mul_f32 v[98:99], v[96:97], v[96:97] op_sel:[1,1] op_sel_hi:[1,0]
	s_nop 0
	v_pk_fma_f32 v[98:99], v[96:97], v[96:97], v[98:99] op_sel:[0,0,0] op_sel_hi:[0,1,1] neg_lo:[0,0,1] neg_hi:[0,0,0]
	v_pk_add_f32 v[100:101], v[72:73], v[76:77] neg_lo:[0,1] neg_hi:[0,1]
	v_pk_add_f32 v[102:103], v[74:75], v[78:79] neg_lo:[0,1] neg_hi:[0,1]
	v_pk_add_f32 v[104:105], v[80:81], v[84:85] neg_lo:[0,1] neg_hi:[0,1]
	v_pk_add_f32 v[106:107], v[82:83], v[86:87] neg_lo:[0,1] neg_hi:[0,1]
	v_pk_add_f32 v[72:73], v[72:73], v[76:77]
	v_pk_add_f32 v[74:75], v[74:75], v[78:79]
	v_pk_add_f32 v[80:81], v[80:81], v[84:85]
	v_pk_add_f32 v[82:83], v[82:83], v[86:87]
	v_pk_mul_f32 v[76:77], v[100:101], v[88:89] op_sel:[1,1] op_sel_hi:[1,0]
	v_pk_mul_f32 v[78:79], v[102:103], v[92:93] op_sel:[1,1] op_sel_hi:[1,0]
	v_pk_mul_f32 v[84:85], v[104:105], v[88:89] op_sel:[1,0] op_sel_hi:[1,1]
	v_pk_mul_f32 v[86:87], v[106:107], v[94:95] op_sel:[1,1] op_sel_hi:[1,0]
	v_pk_fma_f32 v[76:77], v[100:101], v[88:89], v[76:77] op_sel:[0,0,0] op_sel_hi:[0,1,1] neg_lo:[0,0,1] neg_hi:[0,0,0]
	v_pk_fma_f32 v[78:79], v[102:103], v[92:93], v[78:79] op_sel:[0,0,0] op_sel_hi:[0,1,1] neg_lo:[0,0,1] neg_hi:[0,0,0]
	v_pk_fma_f32 v[84:85], v[104:105], v[88:89], v[84:85] op_sel:[0,1,0] op_sel_hi:[0,0,1] neg_lo:[0,0,0] neg_hi:[0,1,0]
	v_pk_fma_f32 v[86:87], v[106:107], v[94:95], v[86:87] op_sel:[0,0,0] op_sel_hi:[0,1,1] neg_lo:[0,0,1] neg_hi:[0,0,0]
	v_pk_add_f32 v[100:101], v[72:73], v[80:81] neg_lo:[0,1] neg_hi:[0,1]
	v_pk_add_f32 v[102:103], v[74:75], v[82:83] neg_lo:[0,1] neg_hi:[0,1]
	v_pk_add_f32 v[104:105], v[76:77], v[84:85] neg_lo:[0,1] neg_hi:[0,1]
	v_pk_add_f32 v[106:107], v[78:79], v[86:87] neg_lo:[0,1] neg_hi:[0,1]
	v_pk_add_f32 v[72:73], v[72:73], v[80:81]
	v_pk_add_f32 v[74:75], v[74:75], v[82:83]
	v_pk_add_f32 v[76:77], v[76:77], v[84:85]
	v_pk_add_f32 v[78:79], v[78:79], v[86:87]
	v_pk_mul_f32 v[80:81], v[100:101], v[96:97] op_sel:[1,1] op_sel_hi:[1,0]
	v_pk_mul_f32 v[82:83], v[102:103], v[96:97] op_sel:[1,0] op_sel_hi:[1,1]
	v_pk_mul_f32 v[84:85], v[104:105], v[96:97] op_sel:[1,1] op_sel_hi:[1,0]
	v_pk_mul_f32 v[86:87], v[106:107], v[96:97] op_sel:[1,0] op_sel_hi:[1,1]
	v_pk_fma_f32 v[80:81], v[100:101], v[96:97], v[80:81] op_sel:[0,0,0] op_sel_hi:[0,1,1] neg_lo:[0,0,1] neg_hi:[0,0,0]
	v_pk_fma_f32 v[82:83], v[102:103], v[96:97], v[82:83] op_sel:[0,1,0] op_sel_hi:[0,0,1] neg_lo:[0,0,0] neg_hi:[0,1,0]
	v_pk_fma_f32 v[84:85], v[104:105], v[96:97], v[84:85] op_sel:[0,0,0] op_sel_hi:[0,1,1] neg_lo:[0,0,1] neg_hi:[0,0,0]
	v_pk_fma_f32 v[86:87], v[106:107], v[96:97], v[86:87] op_sel:[0,1,0] op_sel_hi:[0,0,1] neg_lo:[0,0,0] neg_hi:[0,1,0]
	v_pk_add_f32 v[100:101], v[72:73], v[74:75] neg_lo:[0,1] neg_hi:[0,1]
	v_pk_add_f32 v[102:103], v[80:81], v[82:83] neg_lo:[0,1] neg_hi:[0,1]
	v_pk_add_f32 v[104:105], v[76:77], v[78:79] neg_lo:[0,1] neg_hi:[0,1]
	v_pk_add_f32 v[106:107], v[84:85], v[86:87] neg_lo:[0,1] neg_hi:[0,1]
	v_pk_add_f32 v[72:73], v[72:73], v[74:75]
	v_pk_add_f32 v[80:81], v[80:81], v[82:83]
	v_pk_add_f32 v[76:77], v[76:77], v[78:79]
	v_pk_add_f32 v[84:85], v[84:85], v[86:87]
	v_pk_mul_f32 v[74:75], v[100:101], v[98:99] op_sel:[1,1] op_sel_hi:[1,0]
	v_pk_mul_f32 v[82:83], v[102:103], v[98:99] op_sel:[1,1] op_sel_hi:[1,0]
	v_pk_mul_f32 v[78:79], v[104:105], v[98:99] op_sel:[1,1] op_sel_hi:[1,0]
	v_pk_mul_f32 v[86:87], v[106:107], v[98:99] op_sel:[1,1] op_sel_hi:[1,0]
	v_pk_fma_f32 v[74:75], v[100:101], v[98:99], v[74:75] op_sel:[0,0,0] op_sel_hi:[0,1,1] neg_lo:[0,0,1] neg_hi:[0,0,0]
	v_pk_fma_f32 v[82:83], v[102:103], v[98:99], v[82:83] op_sel:[0,0,0] op_sel_hi:[0,1,1] neg_lo:[0,0,1] neg_hi:[0,0,0]
	v_pk_fma_f32 v[78:79], v[104:105], v[98:99], v[78:79] op_sel:[0,0,0] op_sel_hi:[0,1,1] neg_lo:[0,0,1] neg_hi:[0,0,0]
	v_pk_fma_f32 v[86:87], v[106:107], v[98:99], v[86:87] op_sel:[0,0,0] op_sel_hi:[0,1,1] neg_lo:[0,0,1] neg_hi:[0,0,0]
	ds_write2st64_b64 v69, v[72:73], v[74:75] offset1:17
	ds_write2st64_b64 v69, v[80:81], v[82:83] offset0:34 offset1:51
	ds_write2st64_b64 v69, v[76:77], v[78:79] offset0:68 offset1:85
	ds_write2st64_b64 v69, v[84:85], v[86:87] offset0:102 offset1:119
	s_waitcnt lgkmcnt(4)
; #define LAS __attribute__((address_space(3)))
; __device__ __forceinline__ cf twc(cf ws, int k16) { if (k16 == 0) return ws; if (k16 == 4) return cf{ws.y, -ws.x}; return cmul(ws, cf{c16(k16), -s16(k16)}); }
; template <int LR> __device__ __forceinline__ void dif_reg(cf (&x)[1 << LR], cf w) {
;     constexpr int R = 1 << LR; cf ws = w;
; #pragma unroll
;     for (int s = 0; s < LR; ++s) { const int half = R >> (s + 1);
; #pragma unroll
;         for (int m0 = 0; m0 < R; m0 += 2 * half)
; #pragma unroll
;             for (int mm = 0; mm < half; ++mm) { const int ia = m0 + mm, ib = ia + half; const cf a = x[ia], b = x[ib];
;                 x[ia] = cf{a.x + b.x, a.y + b.y}; const cf d{a.x - b.x, a.y - b.y};
;                 x[ib] = cmul(d, twc(ws, (mm << s) * (16 / R))); }
;         ws = cmul(ws, ws); }
; }
; template <int LR> __device__ __forceinline__ void dit_reg(cf (&x)[1 << LR], cf w) {
;     constexpr int R = 1 << LR; cf wsv[LR]; wsv[0] = w;
; #pragma unroll
;     for (int s = 1; s < LR; ++s) wsv[s] = cmul(wsv[s - 1], wsv[s - 1]);
; #pragma unroll
;     for (int s = LR - 1; s >= 0; --s) { const int half = R >> (s + 1);
; #pragma unroll
;         for (int m0 = 0; m0 < R; m0 += 2 * half)
; #pragma unroll
;             for (int mm = 0; mm < half; ++mm) { const int ia = m0 + mm, ib = ia + half; const cf a = x[ia];
;                 const cf b = cmulc(x[ib], twc(wsv[s], (mm << s) * (16 / R)));
;                 x[ia] = cf{a.x + b.x, a.y + b.y}; x[ib] = cf{a.x - b.x, a.y - b.y}; } }
; }
; __device__ __forceinline__ void lds_barrier() { asm volatile("s_waitcnt lgkmcnt(0)\n\ts_barrier" ::: "memory"); }
; template <int LR, bool INV> __device__ __forceinline__ void fft_pass(ldsf2 buf, int base, int stride, int twi) {
;     constexpr int R = 1 << LR; cf x[R];
;     const v2f wv = ((ldsf2)((LAS unsigned char*)buf + 139264))[twi];
; #pragma unroll
;     for (int m = 0; m < R; ++m) { const v2f v = buf[base + m * stride]; x[m] = cf{v.x, v.y}; }
;     const cf w{wv.x, wv.y};
;     if (INV) dit_reg<LR>(x, w); else dif_reg<LR>(x, w);
; #pragma unroll
;     for (int m = 0; m < R; ++m) buf[base + m * stride] = mkv2(x[m].x, x[m].y);
; }
	v_pk_add_f32 v[148:149], v[118:119], v[118:119] op_sel:[0,1] op_sel_hi:[1,0] neg_lo:[0,0] neg_hi:[0,1]
	v_pk_mul_f32 v[154:155], v[118:119], v[118:119] op_sel:[1,1] op_sel_hi:[1,0]
	v_pk_mul_f32 v[150:151], v[148:149], s[16:17] op_sel:[0,0] op_sel_hi:[1,0]
	v_pk_fma_f32 v[154:155], v[118:119], v[118:119], v[154:155] op_sel:[0,0,0] op_sel_hi:[0,1,1] neg_lo:[0,0,1] neg_hi:[0,0,0]
	v_pk_mul_f32 v[152:153], v[148:149], s[16:17] op_sel:[1,0] op_sel_hi:[0,0] neg_lo:[0,0] neg_hi:[1,0]
	s_nop 0
	v_pk_mul_f32 v[156:157], v[154:155], v[154:155] op_sel:[1,1] op_sel_hi:[1,0]
	s_nop 0
	v_pk_fma_f32 v[156:157], v[154:155], v[154:155], v[156:157] op_sel:[0,0,0] op_sel_hi:[0,1,1] neg_lo:[0,0,1] neg_hi:[0,0,0]
	v_pk_add_f32 v[158:159], v[120:121], v[124:125] neg_lo:[0,1] neg_hi:[0,1]
	v_pk_add_f32 v[160:161], v[122:123], v[126:127] neg_lo:[0,1] neg_hi:[0,1]
	v_pk_add_f32 v[162:163], v[128:129], v[132:133] neg_lo:[0,1] neg_hi:[0,1]
	v_pk_add_f32 v[164:165], v[130:131], v[134:135] neg_lo:[0,1] neg_hi:[0,1]
	v_pk_add_f32 v[120:121], v[120:121], v[124:125]
	v_pk_add_f32 v[122:123], v[122:123], v[126:127]
	v_pk_add_f32 v[128:129], v[128:129], v[132:133]
	v_pk_add_f32 v[130:131], v[130:131], v[134:135]
	v_pk_mul_f32 v[124:125], v[158:159], v[118:119] op_sel:[1,1] op_sel_hi:[1,0]
	v_pk_mul_f32 v[126:127], v[160:161], v[150:151] op_sel:[1,1] op_sel_hi:[1,0]
	v_pk_mul_f32 v[132:133], v[162:163], v[118:119] op_sel:[1,0] op_sel_hi:[1,1]
	v_pk_mul_f32 v[134:135], v[164:165], v[152:153] op_sel:[1,1] op_sel_hi:[1,0]
	v_pk_fma_f32 v[124:125], v[158:159], v[118:119], v[124:125] op_sel:[0,0,0] op_sel_hi:[0,1,1] neg_lo:[0,0,1] neg_hi:[0,0,0]
	v_pk_fma_f32 v[126:127], v[160:161], v[150:151], v[126:127] op_sel:[0,0,0] op_sel_hi:[0,1,1] neg_lo:[0,0,1] neg_hi:[0,0,0]
	v_pk_fma_f32 v[132:133], v[162:163], v[118:119], v[132:133] op_sel:[0,1,0] op_sel_hi:[0,0,1] neg_lo:[0,0,0] neg_hi:[0,1,0]
	v_pk_fma_f32 v[134:135], v[164:165], v[152:153], v[134:135] op_sel:[0,0,0] op_sel_hi:[0,1,1] neg_lo:[0,0,1] neg_hi:[0,0,0]
	v_pk_add_f32 v[158:159], v[120:121], v[128:129] neg_lo:[0,1] neg_hi:[0,1]
	v_pk_add_f32 v[160:161], v[122:123], v[130:131] neg_lo:[0,1] neg_hi:[0,1]
	v_pk_add_f32 v[162:163], v[124:125], v[132:133] neg_lo:[0,1] neg_hi:[0,1]
	v_pk_add_f32 v[164:165], v[126:127], v[134:135] neg_lo:[0,1] neg_hi:[0,1]
	v_pk_add_f32 v[120:121], v[120:121], v[128:129]
	v_pk_add_f32 v[122:123], v[122:123], v[130:131]
	v_pk_add_f32 v[124:125], v[124:125], v[132:133]
	v_pk_add_f32 v[126:127], v[126:127], v[134:135]
	v_pk_mul_f32 v[128:129], v[158:159], v[154:155] op_sel:[1,1] op_sel_hi:[1,0]
	v_pk_mul_f32 v[130:131], v[160:161], v[154:155] op_sel:[1,0] op_sel_hi:[1,1]
	v_pk_mul_f32 v[132:133], v[162:163], v[154:155] op_sel:[1,1] op_sel_hi:[1,0]
	v_pk_mul_f32 v[134:135], v[164:165], v[154:155] op_sel:[1,0] op_sel_hi:[1,1]
	v_pk_fma_f32 v[128:129], v[158:159], v[154:155], v[128:129] op_sel:[0,0,0] op_sel_hi:[0,1,1] neg_lo:[0,0,1] neg_hi:[0,0,0]
	v_pk_fma_f32 v[130:131], v[160:161], v[154:155], v[130:131] op_sel:[0,1,0] op_sel_hi:[0,0,1] neg_lo:[0,0,0] neg_hi:[0,1,0]
	v_pk_fma_f32 v[132:133], v[162:163], v[154:155], v[132:133] op_sel:[0,0,0] op_sel_hi:[0,1,1] neg_lo:[0,0,1] neg_hi:[0,0,0]
	v_pk_fma_f32 v[134:135], v[164:165], v[154:155], v[134:135] op_sel:[0,1,0] op_sel_hi:[0,0,1] neg_lo:[0,0,0] neg_hi:[0,1,0]
	v_pk_add_f32 v[158:159], v[120:121], v[122:123] neg_lo:[0,1] neg_hi:[0,1]
	v_pk_add_f32 v[160:161], v[128:129], v[130:131] neg_lo:[0,1] neg_hi:[0,1]
	v_pk_add_f32 v[162:163], v[124:125], v[126:127] neg_lo:[0,1] neg_hi:[0,1]
	v_pk_add_f32 v[164:165], v[132:133], v[134:135] neg_lo:[0,1] neg_hi:[0,1]
	v_pk_add_f32 v[120:121], v[120:121], v[122:123]
	v_pk_add_f32 v[128:129], v[128:129], v[130:131]
	v_pk_add_f32 v[124:125], v[124:125], v[126:127]
	v_pk_add_f32 v[132:133], v[132:133], v[134:135]
	v_pk_mul_f32 v[122:123], v[158:159], v[156:157] op_sel:[1,1] op_sel_hi:[1,0]
	v_pk_mul_f32 v[130:131], v[160:161], v[156:157] op_sel:[1,1] op_sel_hi:[1,0]
	v_pk_mul_f32 v[126:127], v[162:163], v[156:157] op_sel:[1,1] op_sel_hi:[1,0]
	v_pk_mul_f32 v[134:135], v[164:165], v[156:157] op_sel:[1,1] op_sel_hi:[1,0]
	v_pk_fma_f32 v[122:123], v[158:159], v[156:157], v[122:123] op_sel:[0,0,0] op_sel_hi:[0,1,1] neg_lo:[0,0,1] neg_hi:[0,0,0]
	v_pk_fma_f32 v[130:131], v[160:161], v[156:157], v[130:131] op_sel:[0,0,0] op_sel_hi:[0,1,1] neg_lo:[0,0,1] neg_hi:[0,0,0]
	v_pk_fma_f32 v[126:127], v[162:163], v[156:157], v[126:127] op_sel:[0,0,0] op_sel_hi:[0,1,1] neg_lo:[0,0,1] neg_hi:[0,0,0]
	v_pk_fma_f32 v[134:135], v[164:165], v[156:157], v[134:135] op_sel:[0,0,0] op_sel_hi:[0,1,1] neg_lo:[0,0,1] neg_hi:[0,0,0]
	ds_write2st64_b64 v114, v[120:121], v[122:123] offset1:17
	ds_write2st64_b64 v114, v[128:129], v[130:131] offset0:34 offset1:51
	ds_write2st64_b64 v114, v[124:125], v[126:127] offset0:68 offset1:85
	ds_write2st64_b64 v114, v[132:133], v[134:135] offset0:102 offset1:119
	s_mov_b64 s[6:7], 0
	s_waitcnt lgkmcnt(0)
	s_barrier
	v_lshlrev_b32_e32 v72, 4, v68
	v_and_b32_e32 v69, 63, v68
	v_and_b32_e32 v72, 0xfffffc00, v72
	s_mov_b32 s0, 0
	s_mov_b64 s[6:7], -1
; #define LAS __attribute__((address_space(3)))
; __device__ __forceinline__ cf twc(cf ws, int k16) { if (k16 == 0) return ws; if (k16 == 4) return cf{ws.y, -ws.x}; return cmul(ws, cf{c16(k16), -s16(k16)}); }
; template <int LR> __device__ __forceinline__ void dif_reg(cf (&x)[1 << LR], cf w) {
;     constexpr int R = 1 << LR; cf ws = w;
; #pragma unroll
;     for (int s = 0; s < LR; ++s) { const int half = R >> (s + 1);
; #pragma unroll
;         for (int m0 = 0; m0 < R; m0 += 2 * half)
; #pragma unroll
;             for (int mm = 0; mm < half; ++mm) { const int ia = m0 + mm, ib = ia + half; const cf a = x[ia], b = x[ib];
;                 x[ia] = cf{a.x + b.x, a.y + b.y}; const cf d{a.x - b.x, a.y - b.y};
;                 x[ib] = cmul(d, twc(ws, (mm << s) * (16 / R))); }
;         ws = cmul(ws, ws); }
; }
; template <int LR> __device__ __forceinline__ void dit_reg(cf (&x)[1 << LR], cf w) {
;     constexpr int R = 1 << LR; cf wsv[LR]; wsv[0] = w;
; #pragma unroll
;     for (int s = 1; s < LR; ++s) wsv[s] = cmul(wsv[s - 1], wsv[s - 1]);
; #pragma unroll
;     for (int s = LR - 1; s >= 0; --s) { const int half = R >> (s + 1);
; #pragma unroll
;         for (int m0 = 0; m0 < R; m0 += 2 * half)
; #pragma unroll
;             for (int mm = 0; mm < half; ++mm) { const int ia = m0 + mm, ib = ia + half; const cf a = x[ia];
;                 const cf b = cmulc(x[ib], twc(wsv[s], (mm << s) * (16 / R)));
;                 x[ia] = cf{a.x + b.x, a.y + b.y}; x[ib] = cf{a.x - b.x, a.y - b.y}; } }
; }
; __device__ __forceinline__ void lds_barrier() { asm volatile("s_waitcnt lgkmcnt(0)\n\ts_barrier" ::: "memory"); }
; template <int LR, bool INV> __device__ __forceinline__ void fft_pass(ldsf2 buf, int base, int stride, int twi) {
;     constexpr int R = 1 << LR; cf x[R];
;     const v2f wv = ((ldsf2)((LAS unsigned char*)buf + 139264))[twi];
; #pragma unroll
;     for (int m = 0; m < R; ++m) { const v2f v = buf[base + m * stride]; x[m] = cf{v.x, v.y}; }
;     const cf w{wv.x, wv.y};
;     if (INV) dit_reg<LR>(x, w); else dif_reg<LR>(x, w);
; #pragma unroll
;     for (int m = 0; m < R; ++m) buf[base + m * stride] = mkv2(x[m].x, x[m].y);
; }
.LBB0_349:
	v_or_b32_e32 v74, s0, v69
	v_or_b32_e32 v73, v74, v72
	v_lshl_add_u32 v74, v74, 6, 0
	v_ashrrev_i32_e32 v75, 4, v73
	v_add_u32_e32 v74, 0x22000, v74
	v_lshlrev_b32_e32 v73, 3, v73
	ds_read_b64 v[90:91], v74
	v_lshlrev_b32_e32 v74, 3, v75
	v_add3_u32 v73, 0, v73, v74
	v_add_u32_e32 v113, 0x800, v73
	ds_read2_b64 v[74:77], v73 offset1:136
	v_add_u32_e32 v118, 0x1000, v73
	v_add_u32_e32 v119, 0x1800, v73
	ds_read2_b64 v[78:81], v113 offset0:16 offset1:152
	ds_read2_b64 v[82:85], v118 offset0:32 offset1:168
	ds_read2_b64 v[86:89], v119 offset0:48 offset1:184
	s_mov_b32 s0, 64
	v_or_b32_e32 v120, s0, v69
	v_or_b32_e32 v122, v120, v72
	v_lshl_add_u32 v120, v120, 6, 0
	v_ashrrev_i32_e32 v124, 4, v122
	v_add_u32_e32 v120, 0x22000, v120
	v_lshlrev_b32_e32 v122, 3, v122
	ds_read_b64 v[126:127], v120
	v_lshlrev_b32_e32 v120, 3, v124
	v_add3_u32 v122, 0, v122, v120
	v_add_u32_e32 v128, 0x800, v122
	ds_read2_b64 v[130:133], v122 offset1:136
	v_add_u32_e32 v134, 0x1000, v122
	v_add_u32_e32 v148, 0x1800, v122
	ds_read2_b64 v[150:153], v128 offset0:16 offset1:152
	ds_read2_b64 v[154:157], v134 offset0:32 offset1:168
	ds_read2_b64 v[158:161], v148 offset0:48 offset1:184
	s_waitcnt lgkmcnt(5)
	v_pk_add_f32 v[92:93], v[90:91], v[90:91] op_sel:[0,1] op_sel_hi:[1,0] neg_lo:[0,0] neg_hi:[0,1]
	v_pk_mul_f32 v[98:99], v[90:91], v[90:91] op_sel:[1,1] op_sel_hi:[1,0]
	v_pk_mul_f32 v[94:95], v[92:93], s[16:17] op_sel:[0,0] op_sel_hi:[1,0]
	v_pk_fma_f32 v[98:99], v[90:91], v[90:91], v[98:99] op_sel:[0,0,0] op_sel_hi:[0,1,1] neg_lo:[0,0,1] neg_hi:[0,0,0]
	v_pk_mul_f32 v[96:97], v[92:93], s[16:17] op_sel:[1,0] op_sel_hi:[0,0] neg_lo:[0,0] neg_hi:[1,0]
	s_nop 0
	v_pk_mul_f32 v[100:101], v[98:99], v[98:99] op_sel:[1,1] op_sel_hi:[1,0]
	s_nop 0
	v_pk_fma_f32 v[100:101], v[98:99], v[98:99], v[100:101] op_sel:[0,0,0] op_sel_hi:[0,1,1] neg_lo:[0,0,1] neg_hi:[0,0,0]
	v_pk_add_f32 v[102:103], v[74:75], v[82:83] neg_lo:[0,1] neg_hi:[0,1]
	v_pk_add_f32 v[104:105], v[76:77], v[84:85] neg_lo:[0,1] neg_hi:[0,1]
	v_pk_add_f32 v[106:107], v[78:79], v[86:87] neg_lo:[0,1] neg_hi:[0,1]
	v_pk_add_f32 v[108:109], v[80:81], v[88:89] neg_lo:[0,1] neg_hi:[0,1]
	v_pk_add_f32 v[74:75], v[74:75], v[82:83]
	v_pk_add_f32 v[76:77], v[76:77], v[84:85]
	v_pk_add_f32 v[78:79], v[78:79], v[86:87]
	v_pk_add_f32 v[80:81], v[80:81], v[88:89]
	v_pk_mul_f32 v[82:83], v[102:103], v[90:91] op_sel:[1,1] op_sel_hi:[1,0]
	v_pk_mul_f32 v[84:85], v[104:105], v[94:95] op_sel:[1,1] op_sel_hi:[1,0]
	v_pk_mul_f32 v[86:87], v[106:107], v[90:91] op_sel:[1,0] op_sel_hi:[1,1]
	v_pk_mul_f32 v[88:89], v[108:109], v[96:97] op_sel:[1,1] op_sel_hi:[1,0]
	v_pk_fma_f32 v[82:83], v[102:103], v[90:91], v[82:83] op_sel:[0,0,0] op_sel_hi:[0,1,1] neg_lo:[0,0,1] neg_hi:[0,0,0]
	v_pk_fma_f32 v[84:85], v[104:105], v[94:95], v[84:85] op_sel:[0,0,0] op_sel_hi:[0,1,1] neg_lo:[0,0,1] neg_hi:[0,0,0]
	v_pk_fma_f32 v[86:87], v[106:107], v[90:91], v[86:87] op_sel:[0,1,0] op_sel_hi:[0,0,1] neg_lo:[0,0,0] neg_hi:[0,1,0]
	v_pk_fma_f32 v[88:89], v[108:109], v[96:97], v[88:89] op_sel:[0,0,0] op_sel_hi:[0,1,1] neg_lo:[0,0,1] neg_hi:[0,0,0]
	v_pk_add_f32 v[102:103], v[74:75], v[78:79] neg_lo:[0,1] neg_hi:[0,1]
	v_pk_add_f32 v[104:105], v[76:77], v[80:81] neg_lo:[0,1] neg_hi:[0,1]
	v_pk_add_f32 v[106:107], v[82:83], v[86:87] neg_lo:[0,1] neg_hi:[0,1]
	v_pk_add_f32 v[108:109], v[84:85], v[88:89] neg_lo:[0,1] neg_hi:[0,1]
	v_pk_add_f32 v[74:75], v[74:75], v[78:79]
	v_pk_add_f32 v[76:77], v[76:77], v[80:81]
	v_pk_add_f32 v[82:83], v[82:83], v[86:87]
	v_pk_add_f32 v[84:85], v[84:85], v[88:89]
	v_pk_mul_f32 v[78:79], v[102:103], v[98:99] op_sel:[1,1] op_sel_hi:[1,0]
	v_pk_mul_f32 v[80:81], v[104:105], v[98:99] op_sel:[1,0] op_sel_hi:[1,1]
	v_pk_mul_f32 v[86:87], v[106:107], v[98:99] op_sel:[1,1] op_sel_hi:[1,0]
	v_pk_mul_f32 v[88:89], v[108:109], v[98:99] op_sel:[1,0] op_sel_hi:[1,1]
	v_pk_fma_f32 v[78:79], v[102:103], v[98:99], v[78:79] op_sel:[0,0,0] op_sel_hi:[0,1,1] neg_lo:[0,0,1] neg_hi:[0,0,0]
	v_pk_fma_f32 v[80:81], v[104:105], v[98:99], v[80:81] op_sel:[0,1,0] op_sel_hi:[0,0,1] neg_lo:[0,0,0] neg_hi:[0,1,0]
	v_pk_fma_f32 v[86:87], v[106:107], v[98:99], v[86:87] op_sel:[0,0,0] op_sel_hi:[0,1,1] neg_lo:[0,0,1] neg_hi:[0,0,0]
	v_pk_fma_f32 v[88:89], v[108:109], v[98:99], v[88:89] op_sel:[0,1,0] op_sel_hi:[0,0,1] neg_lo:[0,0,0] neg_hi:[0,1,0]
	v_pk_add_f32 v[102:103], v[74:75], v[76:77] neg_lo:[0,1] neg_hi:[0,1]
	v_pk_add_f32 v[104:105], v[78:79], v[80:81] neg_lo:[0,1] neg_hi:[0,1]
	v_pk_add_f32 v[106:107], v[82:83], v[84:85] neg_lo:[0,1] neg_hi:[0,1]
	v_pk_add_f32 v[108:109], v[86:87], v[88:89] neg_lo:[0,1] neg_hi:[0,1]
	v_pk_add_f32 v[74:75], v[74:75], v[76:77]
	v_pk_add_f32 v[78:79], v[78:79], v[80:81]
	v_pk_add_f32 v[82:83], v[82:83], v[84:85]
	v_pk_add_f32 v[86:87], v[86:87], v[88:89]
	v_pk_mul_f32 v[76:77], v[102:103], v[100:101] op_sel:[1,1] op_sel_hi:[1,0]
	v_pk_mul_f32 v[80:81], v[104:105], v[100:101] op_sel:[1,1] op_sel_hi:[1,0]
	v_pk_mul_f32 v[84:85], v[106:107], v[100:101] op_sel:[1,1] op_sel_hi:[1,0]
	v_pk_mul_f32 v[88:89], v[108:109], v[100:101] op_sel:[1,1] op_sel_hi:[1,0]
	v_pk_fma_f32 v[76:77], v[102:103], v[100:101], v[76:77] op_sel:[0,0,0] op_sel_hi:[0,1,1] neg_lo:[0,0,1] neg_hi:[0,0,0]
	v_pk_fma_f32 v[80:81], v[104:105], v[100:101], v[80:81] op_sel:[0,0,0] op_sel_hi:[0,1,1] neg_lo:[0,0,1] neg_hi:[0,0,0]
	v_pk_fma_f32 v[84:85], v[106:107], v[100:101], v[84:85] op_sel:[0,0,0] op_sel_hi:[0,1,1] neg_lo:[0,0,1] neg_hi:[0,0,0]
	v_pk_fma_f32 v[88:89], v[108:109], v[100:101], v[88:89] op_sel:[0,0,0] op_sel_hi:[0,1,1] neg_lo:[0,0,1] neg_hi:[0,0,0]
	ds_write2_b64 v73, v[74:75], v[76:77] offset1:136
	ds_write2_b64 v113, v[78:79], v[80:81] offset0:16 offset1:152
	ds_write2_b64 v118, v[82:83], v[84:85] offset0:32 offset1:168
	ds_write2_b64 v119, v[86:87], v[88:89] offset0:48 offset1:184
	s_waitcnt lgkmcnt(4)
; #define LAS __attribute__((address_space(3)))
; __device__ __forceinline__ cf twc(cf ws, int k16) { if (k16 == 0) return ws; if (k16 == 4) return cf{ws.y, -ws.x}; return cmul(ws, cf{c16(k16), -s16(k16)}); }
; template <int LR> __device__ __forceinline__ void dif_reg(cf (&x)[1 << LR], cf w) {
;     constexpr int R = 1 << LR; cf ws = w;
; #pragma unroll
;     for (int s = 0; s < LR; ++s) { const int half = R >> (s + 1);
; #pragma unroll
;         for (int m0 = 0; m0 < R; m0 += 2 * half)
; #pragma unroll
;             for (int mm = 0; mm < half; ++mm) { const int ia = m0 + mm, ib = ia + half; const cf a = x[ia], b = x[ib];
;                 x[ia] = cf{a.x + b.x, a.y + b.y}; const cf d{a.x - b.x, a.y - b.y};
;                 x[ib] = cmul(d, twc(ws, (mm << s) * (16 / R))); }
;         ws = cmul(ws, ws); }
; }
; template <int LR> __device__ __forceinline__ void dit_reg(cf (&x)[1 << LR], cf w) {
;     constexpr int R = 1 << LR; cf wsv[LR]; wsv[0] = w;
; #pragma unroll
;     for (int s = 1; s < LR; ++s) wsv[s] = cmul(wsv[s - 1], wsv[s - 1]);
; #pragma unroll
;     for (int s = LR - 1; s >= 0; --s) { const int half = R >> (s + 1);
; #pragma unroll
;         for (int m0 = 0; m0 < R; m0 += 2 * half)
; #pragma unroll
;             for (int mm = 0; mm < half; ++mm) { const int ia = m0 + mm, ib = ia + half; const cf a = x[ia];
;                 const cf b = cmulc(x[ib], twc(wsv[s], (mm << s) * (16 / R)));
;                 x[ia] = cf{a.x + b.x, a.y + b.y}; x[ib] = cf{a.x - b.x, a.y - b.y}; } }
; }
; __device__ __forceinline__ void lds_barrier() { asm volatile("s_waitcnt lgkmcnt(0)\n\ts_barrier" ::: "memory"); }
; template <int LR, bool INV> __device__ __forceinline__ void fft_pass(ldsf2 buf, int base, int stride, int twi) {
;     constexpr int R = 1 << LR; cf x[R];
;     const v2f wv = ((ldsf2)((LAS unsigned char*)buf + 139264))[twi];
; #pragma unroll
;     for (int m = 0; m < R; ++m) { const v2f v = buf[base + m * stride]; x[m] = cf{v.x, v.y}; }
;     const cf w{wv.x, wv.y};
;     if (INV) dit_reg<LR>(x, w); else dif_reg<LR>(x, w);
; #pragma unroll
;     for (int m = 0; m < R; ++m) buf[base + m * stride] = mkv2(x[m].x, x[m].y);
; }
	v_pk_add_f32 v[162:163], v[126:127], v[126:127] op_sel:[0,1] op_sel_hi:[1,0] neg_lo:[0,0] neg_hi:[0,1]
	v_pk_mul_f32 v[168:169], v[126:127], v[126:127] op_sel:[1,1] op_sel_hi:[1,0]
	v_pk_mul_f32 v[164:165], v[162:163], s[16:17] op_sel:[0,0] op_sel_hi:[1,0]
	v_pk_fma_f32 v[168:169], v[126:127], v[126:127], v[168:169] op_sel:[0,0,0] op_sel_hi:[0,1,1] neg_lo:[0,0,1] neg_hi:[0,0,0]
	v_pk_mul_f32 v[166:167], v[162:163], s[16:17] op_sel:[1,0] op_sel_hi:[0,0] neg_lo:[0,0] neg_hi:[1,0]
	s_nop 0
	v_pk_mul_f32 v[170:171], v[168:169], v[168:169] op_sel:[1,1] op_sel_hi:[1,0]
	s_nop 0
	v_pk_fma_f32 v[170:171], v[168:169], v[168:169], v[170:171] op_sel:[0,0,0] op_sel_hi:[0,1,1] neg_lo:[0,0,1] neg_hi:[0,0,0]
	v_pk_add_f32 v[172:173], v[130:131], v[154:155] neg_lo:[0,1] neg_hi:[0,1]
	v_pk_add_f32 v[174:175], v[132:133], v[156:157] neg_lo:[0,1] neg_hi:[0,1]
	v_pk_add_f32 v[188:189], v[150:151], v[158:159] neg_lo:[0,1] neg_hi:[0,1]
	v_pk_add_f32 v[190:191], v[152:153], v[160:161] neg_lo:[0,1] neg_hi:[0,1]
	v_pk_add_f32 v[130:131], v[130:131], v[154:155]
	v_pk_add_f32 v[132:133], v[132:133], v[156:157]
	v_pk_add_f32 v[150:151], v[150:151], v[158:159]
	v_pk_add_f32 v[152:153], v[152:153], v[160:161]
	v_pk_mul_f32 v[154:155], v[172:173], v[126:127] op_sel:[1,1] op_sel_hi:[1,0]
	v_pk_mul_f32 v[156:157], v[174:175], v[164:165] op_sel:[1,1] op_sel_hi:[1,0]
	v_pk_mul_f32 v[158:159], v[188:189], v[126:127] op_sel:[1,0] op_sel_hi:[1,1]
	v_pk_mul_f32 v[160:161], v[190:191], v[166:167] op_sel:[1,1] op_sel_hi:[1,0]
	v_pk_fma_f32 v[154:155], v[172:173], v[126:127], v[154:155] op_sel:[0,0,0] op_sel_hi:[0,1,1] neg_lo:[0,0,1] neg_hi:[0,0,0]
	v_pk_fma_f32 v[156:157], v[174:175], v[164:165], v[156:157] op_sel:[0,0,0] op_sel_hi:[0,1,1] neg_lo:[0,0,1] neg_hi:[0,0,0]
	v_pk_fma_f32 v[158:159], v[188:189], v[126:127], v[158:159] op_sel:[0,1,0] op_sel_hi:[0,0,1] neg_lo:[0,0,0] neg_hi:[0,1,0]
	v_pk_fma_f32 v[160:161], v[190:191], v[166:167], v[160:161] op_sel:[0,0,0] op_sel_hi:[0,1,1] neg_lo:[0,0,1] neg_hi:[0,0,0]
	v_pk_add_f32 v[172:173], v[130:131], v[150:151] neg_lo:[0,1] neg_hi:[0,1]
	v_pk_add_f32 v[174:175], v[132:133], v[152:153] neg_lo:[0,1] neg_hi:[0,1]
	v_pk_add_f32 v[188:189], v[154:155], v[158:159] neg_lo:[0,1] neg_hi:[0,1]
	v_pk_add_f32 v[190:191], v[156:157], v[160:161] neg_lo:[0,1] neg_hi:[0,1]
	v_pk_add_f32 v[130:131], v[130:131], v[150:151]
	v_pk_add_f32 v[132:133], v[132:133], v[152:153]
	v_pk_add_f32 v[154:155], v[154:155], v[158:159]
	v_pk_add_f32 v[156:157], v[156:157], v[160:161]
	v_pk_mul_f32 v[150:151], v[172:173], v[168:169] op_sel:[1,1] op_sel_hi:[1,0]
	v_pk_mul_f32 v[152:153], v[174:175], v[168:169] op_sel:[1,0] op_sel_hi:[1,1]
	v_pk_mul_f32 v[158:159], v[188:189], v[168:169] op_sel:[1,1] op_sel_hi:[1,0]
	v_pk_mul_f32 v[160:161], v[190:191], v[168:169] op_sel:[1,0] op_sel_hi:[1,1]
	v_pk_fma_f32 v[150:151], v[172:173], v[168:169], v[150:151] op_sel:[0,0,0] op_sel_hi:[0,1,1] neg_lo:[0,0,1] neg_hi:[0,0,0]
	v_pk_fma_f32 v[152:153], v[174:175], v[168:169], v[152:153] op_sel:[0,1,0] op_sel_hi:[0,0,1] neg_lo:[0,0,0] neg_hi:[0,1,0]
	v_pk_fma_f32 v[158:159], v[188:189], v[168:169], v[158:159] op_sel:[0,0,0] op_sel_hi:[0,1,1] neg_lo:[0,0,1] neg_hi:[0,0,0]
	v_pk_fma_f32 v[160:161], v[190:191], v[168:169], v[160:161] op_sel:[0,1,0] op_sel_hi:[0,0,1] neg_lo:[0,0,0] neg_hi:[0,1,0]
	v_pk_add_f32 v[172:173], v[130:131], v[132:133] neg_lo:[0,1] neg_hi:[0,1]
	v_pk_add_f32 v[174:175], v[150:151], v[152:153] neg_lo:[0,1] neg_hi:[0,1]
	v_pk_add_f32 v[188:189], v[154:155], v[156:157] neg_lo:[0,1] neg_hi:[0,1]
	v_pk_add_f32 v[190:191], v[158:159], v[160:161] neg_lo:[0,1] neg_hi:[0,1]
	v_pk_add_f32 v[130:131], v[130:131], v[132:133]
	v_pk_add_f32 v[150:151], v[150:151], v[152:153]
	v_pk_add_f32 v[154:155], v[154:155], v[156:157]
	v_pk_add_f32 v[158:159], v[158:159], v[160:161]
	v_pk_mul_f32 v[132:133], v[172:173], v[170:171] op_sel:[1,1] op_sel_hi:[1,0]
	v_pk_mul_f32 v[152:153], v[174:175], v[170:171] op_sel:[1,1] op_sel_hi:[1,0]
	v_pk_mul_f32 v[156:157], v[188:189], v[170:171] op_sel:[1,1] op_sel_hi:[1,0]
	v_pk_mul_f32 v[160:161], v[190:191], v[170:171] op_sel:[1,1] op_sel_hi:[1,0]
	v_pk_fma_f32 v[132:133], v[172:173], v[170:171], v[132:133] op_sel:[0,0,0] op_sel_hi:[0,1,1] neg_lo:[0,0,1] neg_hi:[0,0,0]
	v_pk_fma_f32 v[152:153], v[174:175], v[170:171], v[152:153] op_sel:[0,0,0] op_sel_hi:[0,1,1] neg_lo:[0,0,1] neg_hi:[0,0,0]
	v_pk_fma_f32 v[156:157], v[188:189], v[170:171], v[156:157] op_sel:[0,0,0] op_sel_hi:[0,1,1] neg_lo:[0,0,1] neg_hi:[0,0,0]
	v_pk_fma_f32 v[160:161], v[190:191], v[170:171], v[160:161] op_sel:[0,0,0] op_sel_hi:[0,1,1] neg_lo:[0,0,1] neg_hi:[0,0,0]
	ds_write2_b64 v122, v[130:131], v[132:133] offset1:136
	ds_write2_b64 v128, v[150:151], v[152:153] offset0:16 offset1:152
	ds_write2_b64 v134, v[154:155], v[156:157] offset0:32 offset1:168
	ds_write2_b64 v148, v[158:159], v[160:161] offset0:48 offset1:184
	s_mov_b64 s[6:7], 0
	v_and_b32_e32 v68, 15, v68
	s_waitcnt lgkmcnt(0)
	v_lshlrev_b32_e32 v69, 3, v69
	v_lshlrev_b32_e32 v73, 9, v68
	v_and_or_b32 v69, v69, s90, v72
	v_add_u32_e32 v72, 0, v73
	v_lshl_add_u32 v68, v68, 3, 0
	s_mov_b32 s0, 0
	s_mov_b64 s[6:7], -1
	v_add_u32_e32 v72, 0x22000, v72
; #define LAS __attribute__((address_space(3)))
; __device__ __forceinline__ cf twc(cf ws, int k16) { if (k16 == 0) return ws; if (k16 == 4) return cf{ws.y, -ws.x}; return cmul(ws, cf{c16(k16), -s16(k16)}); }
; template <int LR> __device__ __forceinline__ void dif_reg(cf (&x)[1 << LR], cf w) {
;     constexpr int R = 1 << LR; cf ws = w;
; #pragma unroll
;     for (int s = 0; s < LR; ++s) { const int half = R >> (s + 1);
; #pragma unroll
;         for (int m0 = 0; m0 < R; m0 += 2 * half)
; #pragma unroll
;             for (int mm = 0; mm < half; ++mm) { const int ia = m0 + mm, ib = ia + half; const cf a = x[ia], b = x[ib];
;                 x[ia] = cf{a.x + b.x, a.y + b.y}; const cf d{a.x - b.x, a.y - b.y};
;                 x[ib] = cmul(d, twc(ws, (mm << s) * (16 / R))); }
;         ws = cmul(ws, ws); }
; }
; template <int LR> __device__ __forceinline__ void dit_reg(cf (&x)[1 << LR], cf w) {
;     constexpr int R = 1 << LR; cf wsv[LR]; wsv[0] = w;
; #pragma unroll
;     for (int s = 1; s < LR; ++s) wsv[s] = cmul(wsv[s - 1], wsv[s - 1]);
; #pragma unroll
;     for (int s = LR - 1; s >= 0; --s) { const int half = R >> (s + 1);
; #pragma unroll
;         for (int m0 = 0; m0 < R; m0 += 2 * half)
; #pragma unroll
;             for (int mm = 0; mm < half; ++mm) { const int ia = m0 + mm, ib = ia + half; const cf a = x[ia];
;                 const cf b = cmulc(x[ib], twc(wsv[s], (mm << s) * (16 / R)));
;                 x[ia] = cf{a.x + b.x, a.y + b.y}; x[ib] = cf{a.x - b.x, a.y - b.y}; } }
; }
; __device__ __forceinline__ void lds_barrier() { asm volatile("s_waitcnt lgkmcnt(0)\n\ts_barrier" ::: "memory"); }
; template <int LR, bool INV> __device__ __forceinline__ void fft_pass(ldsf2 buf, int base, int stride, int twi) {
;     constexpr int R = 1 << LR; cf x[R];
;     const v2f wv = ((ldsf2)((LAS unsigned char*)buf + 139264))[twi];
; #pragma unroll
;     for (int m = 0; m < R; ++m) { const v2f v = buf[base + m * stride]; x[m] = cf{v.x, v.y}; }
;     const cf w{wv.x, wv.y};
;     if (INV) dit_reg<LR>(x, w); else dif_reg<LR>(x, w);
; #pragma unroll
;     for (int m = 0; m < R; ++m) buf[base + m * stride] = mkv2(x[m].x, x[m].y);
; }
.LBB0_351:
	v_or_b32_e32 v73, s0, v69
	ds_read_b64 v[90:91], v72
	v_lshlrev_b32_e32 v74, 3, v73
	v_ashrrev_i32_e32 v73, 1, v73
	v_add3_u32 v73, v68, v74, v73
	ds_read2_b64 v[74:77], v73 offset1:17
	ds_read2_b64 v[78:81], v73 offset0:34 offset1:51
	ds_read2_b64 v[82:85], v73 offset0:68 offset1:85
	ds_read2_b64 v[86:89], v73 offset0:102 offset1:119
	s_movk_i32 s0, 0x200
	v_or_b32_e32 v118, s0, v69
	ds_read_b64 v[120:121], v72
	v_lshlrev_b32_e32 v122, 3, v118
	v_ashrrev_i32_e32 v118, 1, v118
	v_add3_u32 v118, v68, v122, v118
	ds_read2_b64 v[124:127], v118 offset1:17
	ds_read2_b64 v[128:131], v118 offset0:34 offset1:51
	ds_read2_b64 v[132:135], v118 offset0:68 offset1:85
	ds_read2_b64 v[148:151], v118 offset0:102 offset1:119
	s_waitcnt lgkmcnt(5)
	v_pk_add_f32 v[92:93], v[90:91], v[90:91] op_sel:[0,1] op_sel_hi:[1,0] neg_lo:[0,0] neg_hi:[0,1]
	v_pk_mul_f32 v[98:99], v[90:91], v[90:91] op_sel:[1,1] op_sel_hi:[1,0]
	v_pk_mul_f32 v[94:95], v[92:93], s[16:17] op_sel:[0,0] op_sel_hi:[1,0]
	v_pk_fma_f32 v[98:99], v[90:91], v[90:91], v[98:99] op_sel:[0,0,0] op_sel_hi:[0,1,1] neg_lo:[0,0,1] neg_hi:[0,0,0]
	v_pk_mul_f32 v[96:97], v[92:93], s[16:17] op_sel:[1,0] op_sel_hi:[0,0] neg_lo:[0,0] neg_hi:[1,0]
	s_nop 0
	v_pk_mul_f32 v[100:101], v[98:99], v[98:99] op_sel:[1,1] op_sel_hi:[1,0]
	s_nop 0
	v_pk_fma_f32 v[100:101], v[98:99], v[98:99], v[100:101] op_sel:[0,0,0] op_sel_hi:[0,1,1] neg_lo:[0,0,1] neg_hi:[0,0,0]
	v_pk_add_f32 v[102:103], v[74:75], v[82:83] neg_lo:[0,1] neg_hi:[0,1]
	v_pk_add_f32 v[104:105], v[76:77], v[84:85] neg_lo:[0,1] neg_hi:[0,1]
	v_pk_add_f32 v[106:107], v[78:79], v[86:87] neg_lo:[0,1] neg_hi:[0,1]
	v_pk_add_f32 v[108:109], v[80:81], v[88:89] neg_lo:[0,1] neg_hi:[0,1]
	v_pk_add_f32 v[74:75], v[74:75], v[82:83]
	v_pk_add_f32 v[76:77], v[76:77], v[84:85]
	v_pk_add_f32 v[78:79], v[78:79], v[86:87]
	v_pk_add_f32 v[80:81], v[80:81], v[88:89]
	v_pk_mul_f32 v[82:83], v[102:103], v[90:91] op_sel:[1,1] op_sel_hi:[1,0]
	v_pk_mul_f32 v[84:85], v[104:105], v[94:95] op_sel:[1,1] op_sel_hi:[1,0]
	v_pk_mul_f32 v[86:87], v[106:107], v[90:91] op_sel:[1,0] op_sel_hi:[1,1]
	v_pk_mul_f32 v[88:89], v[108:109], v[96:97] op_sel:[1,1] op_sel_hi:[1,0]
	v_pk_fma_f32 v[82:83], v[102:103], v[90:91], v[82:83] op_sel:[0,0,0] op_sel_hi:[0,1,1] neg_lo:[0,0,1] neg_hi:[0,0,0]
	v_pk_fma_f32 v[84:85], v[104:105], v[94:95], v[84:85] op_sel:[0,0,0] op_sel_hi:[0,1,1] neg_lo:[0,0,1] neg_hi:[0,0,0]
	v_pk_fma_f32 v[86:87], v[106:107], v[90:91], v[86:87] op_sel:[0,1,0] op_sel_hi:[0,0,1] neg_lo:[0,0,0] neg_hi:[0,1,0]
	v_pk_fma_f32 v[88:89], v[108:109], v[96:97], v[88:89] op_sel:[0,0,0] op_sel_hi:[0,1,1] neg_lo:[0,0,1] neg_hi:[0,0,0]
	v_pk_add_f32 v[102:103], v[74:75], v[78:79] neg_lo:[0,1] neg_hi:[0,1]
	v_pk_add_f32 v[104:105], v[76:77], v[80:81] neg_lo:[0,1] neg_hi:[0,1]
	v_pk_add_f32 v[106:107], v[82:83], v[86:87] neg_lo:[0,1] neg_hi:[0,1]
	v_pk_add_f32 v[108:109], v[84:85], v[88:89] neg_lo:[0,1] neg_hi:[0,1]
	v_pk_add_f32 v[74:75], v[74:75], v[78:79]
	v_pk_add_f32 v[76:77], v[76:77], v[80:81]
	v_pk_add_f32 v[82:83], v[82:83], v[86:87]
	v_pk_add_f32 v[84:85], v[84:85], v[88:89]
	v_pk_mul_f32 v[78:79], v[102:103], v[98:99] op_sel:[1,1] op_sel_hi:[1,0]
	v_pk_mul_f32 v[80:81], v[104:105], v[98:99] op_sel:[1,0] op_sel_hi:[1,1]
	v_pk_mul_f32 v[86:87], v[106:107], v[98:99] op_sel:[1,1] op_sel_hi:[1,0]
	v_pk_mul_f32 v[88:89], v[108:109], v[98:99] op_sel:[1,0] op_sel_hi:[1,1]
	v_pk_fma_f32 v[78:79], v[102:103], v[98:99], v[78:79] op_sel:[0,0,0] op_sel_hi:[0,1,1] neg_lo:[0,0,1] neg_hi:[0,0,0]
	v_pk_fma_f32 v[80:81], v[104:105], v[98:99], v[80:81] op_sel:[0,1,0] op_sel_hi:[0,0,1] neg_lo:[0,0,0] neg_hi:[0,1,0]
	v_pk_fma_f32 v[86:87], v[106:107], v[98:99], v[86:87] op_sel:[0,0,0] op_sel_hi:[0,1,1] neg_lo:[0,0,1] neg_hi:[0,0,0]
	v_pk_fma_f32 v[88:89], v[108:109], v[98:99], v[88:89] op_sel:[0,1,0] op_sel_hi:[0,0,1] neg_lo:[0,0,0] neg_hi:[0,1,0]
	v_pk_add_f32 v[102:103], v[74:75], v[76:77] neg_lo:[0,1] neg_hi:[0,1]
	v_pk_add_f32 v[104:105], v[78:79], v[80:81] neg_lo:[0,1] neg_hi:[0,1]
	v_pk_add_f32 v[106:107], v[82:83], v[84:85] neg_lo:[0,1] neg_hi:[0,1]
	v_pk_add_f32 v[108:109], v[86:87], v[88:89] neg_lo:[0,1] neg_hi:[0,1]
	v_pk_add_f32 v[74:75], v[74:75], v[76:77]
	v_pk_add_f32 v[78:79], v[78:79], v[80:81]
	v_pk_add_f32 v[82:83], v[82:83], v[84:85]
	v_pk_add_f32 v[86:87], v[86:87], v[88:89]
	v_pk_mul_f32 v[76:77], v[102:103], v[100:101] op_sel:[1,1] op_sel_hi:[1,0]
	v_pk_mul_f32 v[80:81], v[104:105], v[100:101] op_sel:[1,1] op_sel_hi:[1,0]
	v_pk_mul_f32 v[84:85], v[106:107], v[100:101] op_sel:[1,1] op_sel_hi:[1,0]
	v_pk_mul_f32 v[88:89], v[108:109], v[100:101] op_sel:[1,1] op_sel_hi:[1,0]
	v_pk_fma_f32 v[76:77], v[102:103], v[100:101], v[76:77] op_sel:[0,0,0] op_sel_hi:[0,1,1] neg_lo:[0,0,1] neg_hi:[0,0,0]
	v_pk_fma_f32 v[80:81], v[104:105], v[100:101], v[80:81] op_sel:[0,0,0] op_sel_hi:[0,1,1] neg_lo:[0,0,1] neg_hi:[0,0,0]
	v_pk_fma_f32 v[84:85], v[106:107], v[100:101], v[84:85] op_sel:[0,0,0] op_sel_hi:[0,1,1] neg_lo:[0,0,1] neg_hi:[0,0,0]
	v_pk_fma_f32 v[88:89], v[108:109], v[100:101], v[88:89] op_sel:[0,0,0] op_sel_hi:[0,1,1] neg_lo:[0,0,1] neg_hi:[0,0,0]
	ds_write2_b64 v73, v[74:75], v[76:77] offset1:17
	ds_write2_b64 v73, v[78:79], v[80:81] offset0:34 offset1:51
	ds_write2_b64 v73, v[82:83], v[84:85] offset0:68 offset1:85
	ds_write2_b64 v73, v[86:87], v[88:89] offset0:102 offset1:119
	s_waitcnt lgkmcnt(4)
; __device__ __forceinline__ int otid() { int t = threadIdx.x; asm volatile("" : "+v"(t)); return t; }
; __device__ __forceinline__ cf twc(cf ws, int k16) { if (k16 == 0) return ws; if (k16 == 4) return cf{ws.y, -ws.x}; return cmul(ws, cf{c16(k16), -s16(k16)}); }
; template <int LR> __device__ __forceinline__ void dif_reg(cf (&x)[1 << LR], cf w) {
;     constexpr int R = 1 << LR; cf ws = w;
; #pragma unroll
;     for (int s = 0; s < LR; ++s) { const int half = R >> (s + 1);
; #pragma unroll
;         for (int m0 = 0; m0 < R; m0 += 2 * half)
; #pragma unroll
;             for (int mm = 0; mm < half; ++mm) { const int ia = m0 + mm, ib = ia + half; const cf a = x[ia], b = x[ib];
;                 x[ia] = cf{a.x + b.x, a.y + b.y}; const cf d{a.x - b.x, a.y - b.y};
;                 x[ib] = cmul(d, twc(ws, (mm << s) * (16 / R))); }
;         ws = cmul(ws, ws); }
; }
; __device__ __forceinline__ void fft_conv(ldsf2 buf, const LAS unsigned* spec) {
;     ...
;     { const int tid = otid(); cf x[16];
; #pragma unroll
;       for (int m = 0; m < 16; ++m) { const v2f v = buf[tid * 17 + m]; x[m] = cf{v.x, v.y}; }
;       dif_reg<4>(x, cf{1.0f, 0.0f});
; #pragma unroll
;       for (int m = 0; m < 16; ++m) { const h2_t hv = __builtin_bit_cast(h2_t, spec[tid * 17 + m]); x[m] = cmul(x[m], cf{(float)hv.x, (float)hv.y}); }
	v_pk_add_f32 v[152:153], v[120:121], v[120:121] op_sel:[0,1] op_sel_hi:[1,0] neg_lo:[0,0] neg_hi:[0,1]
	v_pk_mul_f32 v[158:159], v[120:121], v[120:121] op_sel:[1,1] op_sel_hi:[1,0]
	v_pk_mul_f32 v[154:155], v[152:153], s[16:17] op_sel:[0,0] op_sel_hi:[1,0]
	v_pk_fma_f32 v[158:159], v[120:121], v[120:121], v[158:159] op_sel:[0,0,0] op_sel_hi:[0,1,1] neg_lo:[0,0,1] neg_hi:[0,0,0]
	v_pk_mul_f32 v[156:157], v[152:153], s[16:17] op_sel:[1,0] op_sel_hi:[0,0] neg_lo:[0,0] neg_hi:[1,0]
	s_nop 0
	v_pk_mul_f32 v[160:161], v[158:159], v[158:159] op_sel:[1,1] op_sel_hi:[1,0]
	s_nop 0
	v_pk_fma_f32 v[160:161], v[158:159], v[158:159], v[160:161] op_sel:[0,0,0] op_sel_hi:[0,1,1] neg_lo:[0,0,1] neg_hi:[0,0,0]
	v_pk_add_f32 v[162:163], v[124:125], v[132:133] neg_lo:[0,1] neg_hi:[0,1]
	v_pk_add_f32 v[164:165], v[126:127], v[134:135] neg_lo:[0,1] neg_hi:[0,1]
	v_pk_add_f32 v[166:167], v[128:129], v[148:149] neg_lo:[0,1] neg_hi:[0,1]
	v_pk_add_f32 v[168:169], v[130:131], v[150:151] neg_lo:[0,1] neg_hi:[0,1]
	v_pk_add_f32 v[124:125], v[124:125], v[132:133]
	v_pk_add_f32 v[126:127], v[126:127], v[134:135]
	v_pk_add_f32 v[128:129], v[128:129], v[148:149]
	v_pk_add_f32 v[130:131], v[130:131], v[150:151]
	v_pk_mul_f32 v[132:133], v[162:163], v[120:121] op_sel:[1,1] op_sel_hi:[1,0]
	v_pk_mul_f32 v[134:135], v[164:165], v[154:155] op_sel:[1,1] op_sel_hi:[1,0]
	v_pk_mul_f32 v[148:149], v[166:167], v[120:121] op_sel:[1,0] op_sel_hi:[1,1]
	v_pk_mul_f32 v[150:151], v[168:169], v[156:157] op_sel:[1,1] op_sel_hi:[1,0]
	v_pk_fma_f32 v[132:133], v[162:163], v[120:121], v[132:133] op_sel:[0,0,0] op_sel_hi:[0,1,1] neg_lo:[0,0,1] neg_hi:[0,0,0]
	v_pk_fma_f32 v[134:135], v[164:165], v[154:155], v[134:135] op_sel:[0,0,0] op_sel_hi:[0,1,1] neg_lo:[0,0,1] neg_hi:[0,0,0]
	v_pk_fma_f32 v[148:149], v[166:167], v[120:121], v[148:149] op_sel:[0,1,0] op_sel_hi:[0,0,1] neg_lo:[0,0,0] neg_hi:[0,1,0]
	v_pk_fma_f32 v[150:151], v[168:169], v[156:157], v[150:151] op_sel:[0,0,0] op_sel_hi:[0,1,1] neg_lo:[0,0,1] neg_hi:[0,0,0]
	v_pk_add_f32 v[162:163], v[124:125], v[128:129] neg_lo:[0,1] neg_hi:[0,1]
	v_pk_add_f32 v[164:165], v[126:127], v[130:131] neg_lo:[0,1] neg_hi:[0,1]
	v_pk_add_f32 v[166:167], v[132:133], v[148:149] neg_lo:[0,1] neg_hi:[0,1]
	v_pk_add_f32 v[168:169], v[134:135], v[150:151] neg_lo:[0,1] neg_hi:[0,1]
	v_pk_add_f32 v[124:125], v[124:125], v[128:129]
	v_pk_add_f32 v[126:127], v[126:127], v[130:131]
	v_pk_add_f32 v[132:133], v[132:133], v[148:149]
	v_pk_add_f32 v[134:135], v[134:135], v[150:151]
	v_pk_mul_f32 v[128:129], v[162:163], v[158:159] op_sel:[1,1] op_sel_hi:[1,0]
	v_pk_mul_f32 v[130:131], v[164:165], v[158:159] op_sel:[1,0] op_sel_hi:[1,1]
	v_pk_mul_f32 v[148:149], v[166:167], v[158:159] op_sel:[1,1] op_sel_hi:[1,0]
	v_pk_mul_f32 v[150:151], v[168:169], v[158:159] op_sel:[1,0] op_sel_hi:[1,1]
	v_pk_fma_f32 v[128:129], v[162:163], v[158:159], v[128:129] op_sel:[0,0,0] op_sel_hi:[0,1,1] neg_lo:[0,0,1] neg_hi:[0,0,0]
	v_pk_fma_f32 v[130:131], v[164:165], v[158:159], v[130:131] op_sel:[0,1,0] op_sel_hi:[0,0,1] neg_lo:[0,0,0] neg_hi:[0,1,0]
	v_pk_fma_f32 v[148:149], v[166:167], v[158:159], v[148:149] op_sel:[0,0,0] op_sel_hi:[0,1,1] neg_lo:[0,0,1] neg_hi:[0,0,0]
	v_pk_fma_f32 v[150:151], v[168:169], v[158:159], v[150:151] op_sel:[0,1,0] op_sel_hi:[0,0,1] neg_lo:[0,0,0] neg_hi:[0,1,0]
	v_pk_add_f32 v[162:163], v[124:125], v[126:127] neg_lo:[0,1] neg_hi:[0,1]
	v_pk_add_f32 v[164:165], v[128:129], v[130:131] neg_lo:[0,1] neg_hi:[0,1]
	v_pk_add_f32 v[166:167], v[132:133], v[134:135] neg_lo:[0,1] neg_hi:[0,1]
	v_pk_add_f32 v[168:169], v[148:149], v[150:151] neg_lo:[0,1] neg_hi:[0,1]
	v_pk_add_f32 v[124:125], v[124:125], v[126:127]
	v_pk_add_f32 v[128:129], v[128:129], v[130:131]
	v_pk_add_f32 v[132:133], v[132:133], v[134:135]
	v_pk_add_f32 v[148:149], v[148:149], v[150:151]
	v_pk_mul_f32 v[126:127], v[162:163], v[160:161] op_sel:[1,1] op_sel_hi:[1,0]
	v_pk_mul_f32 v[130:131], v[164:165], v[160:161] op_sel:[1,1] op_sel_hi:[1,0]
	v_pk_mul_f32 v[134:135], v[166:167], v[160:161] op_sel:[1,1] op_sel_hi:[1,0]
	v_pk_mul_f32 v[150:151], v[168:169], v[160:161] op_sel:[1,1] op_sel_hi:[1,0]
	v_pk_fma_f32 v[126:127], v[162:163], v[160:161], v[126:127] op_sel:[0,0,0] op_sel_hi:[0,1,1] neg_lo:[0,0,1] neg_hi:[0,0,0]
	v_pk_fma_f32 v[130:131], v[164:165], v[160:161], v[130:131] op_sel:[0,0,0] op_sel_hi:[0,1,1] neg_lo:[0,0,1] neg_hi:[0,0,0]
	v_pk_fma_f32 v[134:135], v[166:167], v[160:161], v[134:135] op_sel:[0,0,0] op_sel_hi:[0,1,1] neg_lo:[0,0,1] neg_hi:[0,0,0]
	v_pk_fma_f32 v[150:151], v[168:169], v[160:161], v[150:151] op_sel:[0,0,0] op_sel_hi:[0,1,1] neg_lo:[0,0,1] neg_hi:[0,0,0]
	ds_write2_b64 v118, v[124:125], v[126:127] offset1:17
	ds_write2_b64 v118, v[128:129], v[130:131] offset0:34 offset1:51
	ds_write2_b64 v118, v[132:133], v[134:135] offset0:68 offset1:85
	ds_write2_b64 v118, v[148:149], v[150:151] offset0:102 offset1:119
	s_mov_b64 s[6:7], 0
	v_mov_b32_e32 v158, v195
	s_movk_i32 s0, 0x88
	s_waitcnt lgkmcnt(0)
	s_mov_b32 s86, s63
	v_mul_lo_u32 v68, v158, s0
	v_add_u32_e32 v147, 0, v68
	ds_read2_b64 v[72:75], v147 offset1:1
	ds_read2_b64 v[76:79], v147 offset0:2 offset1:3
	ds_read2_b64 v[90:93], v147 offset0:4 offset1:5
	ds_read2_b64 v[94:97], v147 offset0:6 offset1:7
	ds_read2_b64 v[98:101], v147 offset0:8 offset1:9
	ds_read2_b64 v[102:105], v147 offset0:10 offset1:11
	ds_read2_b64 v[118:121], v147 offset0:12 offset1:13
	ds_read2_b64 v[126:129], v147 offset0:14 offset1:15
	s_mov_b32 s6, s63
	s_mov_b32 s7, s16
	s_mov_b32 s17, s5
	s_mov_b32 s0, s16
	s_mov_b32 s1, s4
	s_mov_b32 s0, s63
	s_mov_b32 s1, s5
	s_mov_b32 s0, s87
	s_mov_b32 s1, s4
	s_mov_b32 s1, s5
	s_mov_b32 s35, s4
	s_mov_b32 s12, s63
	s_movk_i32 s0, 0x44
	v_mul_lo_u32 v106, v158, s0
	v_add_u32_e32 v106, 0, v106
	v_add_u32_e32 v106, 0x11000, v106
	ds_read2_b32 v[156:157], v106 offset1:1
	ds_read2_b32 v[158:159], v106 offset0:2 offset1:3
	ds_read2_b32 v[160:161], v106 offset0:4 offset1:5
	ds_read2_b32 v[162:163], v106 offset0:6 offset1:7
	ds_read2_b32 v[164:165], v106 offset0:8 offset1:9
	ds_read2_b32 v[134:135], v106 offset0:10 offset1:11
	ds_read2_b32 v[130:131], v106 offset0:12 offset1:13
	ds_read2_b32 v[168:169], v106 offset0:14 offset1:15
	s_mov_b32 s0, s5
	s_mov_b64 s[6:7], -1
	s_mov_b32 s35, s13
	s_mov_b32 s0, s13
	s_waitcnt lgkmcnt(8)
; __device__ __forceinline__ cf twc(cf ws, int k16) { if (k16 == 0) return ws; if (k16 == 4) return cf{ws.y, -ws.x}; return cmul(ws, cf{c16(k16), -s16(k16)}); }
; template <int LR> __device__ __forceinline__ void dif_reg(cf (&x)[1 << LR], cf w) {
;     constexpr int R = 1 << LR; cf ws = w;
; #pragma unroll
;     for (int s = 0; s < LR; ++s) { const int half = R >> (s + 1);
; #pragma unroll
;         for (int m0 = 0; m0 < R; m0 += 2 * half)
; #pragma unroll
;             for (int mm = 0; mm < half; ++mm) { const int ia = m0 + mm, ib = ia + half; const cf a = x[ia], b = x[ib];
;                 x[ia] = cf{a.x + b.x, a.y + b.y}; const cf d{a.x - b.x, a.y - b.y};
;                 x[ib] = cmul(d, twc(ws, (mm << s) * (16 / R))); }
;         ws = cmul(ws, ws); }
; }
	v_pk_add_f32 v[80:81], v[72:73], v[98:99]
	v_pk_add_f32 v[82:83], v[74:75], v[100:101]
	v_pk_add_f32 v[84:85], v[76:77], v[102:103]
	v_pk_add_f32 v[86:87], v[78:79], v[104:105]
	v_pk_add_f32 v[72:73], v[72:73], v[98:99] neg_lo:[0,1] neg_hi:[0,1]
	v_pk_add_f32 v[74:75], v[74:75], v[100:101] neg_lo:[0,1] neg_hi:[0,1]
	v_pk_add_f32 v[76:77], v[76:77], v[102:103] neg_lo:[0,1] neg_hi:[0,1]
	v_pk_add_f32 v[78:79], v[78:79], v[104:105] neg_lo:[0,1] neg_hi:[0,1]
	v_pk_mul_f32 v[100:101], v[74:75], s[4:5] op_sel:[1,1] op_sel_hi:[1,0] neg_lo:[0,1] neg_hi:[0,0]
	v_pk_mul_f32 v[102:103], v[76:77], s[16:17] op_sel:[1,0] op_sel_hi:[1,0] neg_lo:[0,1] neg_hi:[0,0]
	v_pk_mul_f32 v[104:105], v[78:79], s[4:5] op_sel:[1,0] op_sel_hi:[1,1] neg_lo:[0,1] neg_hi:[0,0]
	v_pk_fma_f32 v[100:101], v[74:75], s[4:5], v[100:101] op_sel:[0,0,0] op_sel_hi:[0,1,1] neg_lo:[0,0,1] neg_hi:[0,1,0]
	v_pk_fma_f32 v[102:103], v[76:77], s[16:17], v[102:103] op_sel:[0,0,0] op_sel_hi:[0,0,1] neg_lo:[0,0,1] neg_hi:[0,1,0]
	v_pk_fma_f32 v[104:105], v[78:79], s[4:5], v[104:105] op_sel:[0,1,0] op_sel_hi:[0,0,1] neg_lo:[0,0,1] neg_hi:[0,1,0]
	v_pk_add_f32 v[88:89], v[90:91], v[118:119]
	v_pk_add_f32 v[108:109], v[92:93], v[120:121]
	v_pk_add_f32 v[110:111], v[94:95], v[126:127]
	v_pk_add_f32 v[112:113], v[96:97], v[128:129]
	v_pk_add_f32 v[90:91], v[90:91], v[118:119] op_sel:[1,1] op_sel_hi:[0,0] neg_lo:[0,1] neg_hi:[1,0]
	v_pk_add_f32 v[92:93], v[92:93], v[120:121] neg_lo:[0,1] neg_hi:[0,1]
	v_pk_add_f32 v[94:95], v[94:95], v[126:127] neg_lo:[0,1] neg_hi:[0,1]
	v_pk_add_f32 v[96:97], v[96:97], v[128:129] neg_lo:[0,1] neg_hi:[0,1]
	v_pk_mul_f32 v[120:121], v[92:93], s[4:5] op_sel:[1,0] op_sel_hi:[1,1] neg_lo:[0,1] neg_hi:[0,1]
	v_pk_mul_f32 v[126:127], v[94:95], s[16:17] op_sel:[1,0] op_sel_hi:[1,0] neg_lo:[0,1] neg_hi:[0,1]
	v_pk_mul_f32 v[128:129], v[96:97], s[4:5] op_sel:[1,1] op_sel_hi:[1,0] neg_lo:[0,1] neg_hi:[0,1]
	v_pk_fma_f32 v[120:121], v[92:93], s[4:5], v[120:121] op_sel:[0,1,0] op_sel_hi:[0,0,1] neg_lo:[0,1,1] neg_hi:[0,1,0]
	v_pk_fma_f32 v[126:127], v[94:95], s[16:17], v[126:127] op_sel:[0,0,0] op_sel_hi:[0,0,1] neg_lo:[0,1,1] neg_hi:[0,1,0]
	v_pk_fma_f32 v[128:129], v[96:97], s[4:5], v[128:129] op_sel:[0,0,0] op_sel_hi:[0,1,1] neg_lo:[0,1,1] neg_hi:[0,1,0]
	v_pk_add_f32 v[114:115], v[80:81], v[88:89]
	v_pk_add_f32 v[116:117], v[82:83], v[108:109]
	v_pk_add_f32 v[122:123], v[84:85], v[110:111]
	v_pk_add_f32 v[124:125], v[86:87], v[112:113]
	v_pk_add_f32 v[80:81], v[80:81], v[88:89] neg_lo:[0,1] neg_hi:[0,1]
	v_pk_add_f32 v[82:83], v[82:83], v[108:109] neg_lo:[0,1] neg_hi:[0,1]
	v_pk_add_f32 v[84:85], v[84:85], v[110:111] op_sel:[1,1] op_sel_hi:[0,0] neg_lo:[0,1] neg_hi:[1,0]
	v_pk_add_f32 v[86:87], v[86:87], v[112:113] neg_lo:[0,1] neg_hi:[0,1]
	v_pk_mul_f32 v[108:109], v[82:83], s[16:17] op_sel:[1,0] op_sel_hi:[1,0] neg_lo:[0,1] neg_hi:[0,0]
	v_pk_mul_f32 v[112:113], v[86:87], s[16:17] op_sel:[1,0] op_sel_hi:[1,0] neg_lo:[0,1] neg_hi:[0,1]
	v_pk_fma_f32 v[108:109], v[82:83], s[16:17], v[108:109] op_sel:[0,0,0] op_sel_hi:[0,0,1] neg_lo:[0,0,1] neg_hi:[0,1,0]
	v_pk_fma_f32 v[112:113], v[86:87], s[16:17], v[112:113] op_sel:[0,0,0] op_sel_hi:[0,0,1] neg_lo:[0,1,1] neg_hi:[0,1,0]
	v_pk_add_f32 v[132:133], v[72:73], v[90:91]
	v_pk_add_f32 v[148:149], v[100:101], v[120:121]
	v_pk_add_f32 v[150:151], v[102:103], v[126:127]
	v_pk_add_f32 v[152:153], v[104:105], v[128:129]
	v_pk_add_f32 v[72:73], v[72:73], v[90:91] neg_lo:[0,1] neg_hi:[0,1]
	v_pk_add_f32 v[100:101], v[100:101], v[120:121] neg_lo:[0,1] neg_hi:[0,1]
	v_pk_add_f32 v[102:103], v[102:103], v[126:127] op_sel:[1,1] op_sel_hi:[0,0] neg_lo:[0,1] neg_hi:[1,0]
	v_pk_add_f32 v[104:105], v[104:105], v[128:129] neg_lo:[0,1] neg_hi:[0,1]
	v_pk_mul_f32 v[120:121], v[100:101], s[16:17] op_sel:[1,0] op_sel_hi:[1,0] neg_lo:[0,1] neg_hi:[0,0]
	v_pk_mul_f32 v[128:129], v[104:105], s[16:17] op_sel:[1,0] op_sel_hi:[1,0] neg_lo:[0,1] neg_hi:[0,1]
	v_pk_fma_f32 v[120:121], v[100:101], s[16:17], v[120:121] op_sel:[0,0,0] op_sel_hi:[0,0,1] neg_lo:[0,0,1] neg_hi:[0,1,0]
	v_pk_fma_f32 v[128:129], v[104:105], s[16:17], v[128:129] op_sel:[0,0,0] op_sel_hi:[0,0,1] neg_lo:[0,1,1] neg_hi:[0,1,0]
	v_pk_add_f32 v[154:155], v[114:115], v[122:123]
	v_pk_add_f32 v[166:167], v[116:117], v[124:125]
	v_pk_add_f32 v[98:99], v[80:81], v[84:85]
	v_pk_add_f32 v[74:75], v[108:109], v[112:113]
	v_pk_add_f32 v[114:115], v[114:115], v[122:123] neg_lo:[0,1] neg_hi:[0,1]
	v_pk_add_f32 v[116:117], v[116:117], v[124:125] op_sel:[1,1] op_sel_hi:[0,0] neg_lo:[0,1] neg_hi:[1,0]
	v_pk_add_f32 v[80:81], v[80:81], v[84:85] neg_lo:[0,1] neg_hi:[0,1]
	v_pk_add_f32 v[108:109], v[108:109], v[112:113] op_sel:[1,1] op_sel_hi:[0,0] neg_lo:[0,1] neg_hi:[1,0]
	v_pk_add_f32 v[76:77], v[132:133], v[150:151]
	v_pk_add_f32 v[78:79], v[148:149], v[152:153]
	v_pk_add_f32 v[118:119], v[72:73], v[102:103]
	v_pk_add_f32 v[92:93], v[120:121], v[128:129]
	v_pk_add_f32 v[132:133], v[132:133], v[150:151] neg_lo:[0,1] neg_hi:[0,1]
	v_pk_add_f32 v[148:149], v[148:149], v[152:153] op_sel:[1,1] op_sel_hi:[0,0] neg_lo:[0,1] neg_hi:[1,0]
	v_pk_add_f32 v[72:73], v[72:73], v[102:103] neg_lo:[0,1] neg_hi:[0,1]
	v_pk_add_f32 v[120:121], v[120:121], v[128:129] op_sel:[1,1] op_sel_hi:[0,0] neg_lo:[0,1] neg_hi:[1,0]
	v_pk_add_f32 v[94:95], v[154:155], v[166:167]
	v_pk_add_f32 v[96:97], v[114:115], v[116:117]
	v_pk_add_f32 v[88:89], v[98:99], v[74:75]
	v_pk_add_f32 v[82:83], v[80:81], v[108:109]
	v_pk_add_f32 v[154:155], v[154:155], v[166:167] neg_lo:[0,1] neg_hi:[0,1]
	v_pk_add_f32 v[114:115], v[114:115], v[116:117] neg_lo:[0,1] neg_hi:[0,1]
	v_pk_add_f32 v[98:99], v[98:99], v[74:75] neg_lo:[0,1] neg_hi:[0,1]
	v_pk_add_f32 v[80:81], v[80:81], v[108:109] neg_lo:[0,1] neg_hi:[0,1]
	v_pk_add_f32 v[110:111], v[76:77], v[78:79]
	v_pk_add_f32 v[86:87], v[132:133], v[148:149]
	v_pk_add_f32 v[90:91], v[118:119], v[92:93]
	v_pk_add_f32 v[100:101], v[72:73], v[120:121]
	v_pk_add_f32 v[76:77], v[76:77], v[78:79] neg_lo:[0,1] neg_hi:[0,1]
	v_pk_add_f32 v[132:133], v[132:133], v[148:149] neg_lo:[0,1] neg_hi:[0,1]
	v_pk_add_f32 v[118:119], v[118:119], v[92:93] neg_lo:[0,1] neg_hi:[0,1]
	v_pk_add_f32 v[72:73], v[72:73], v[120:121] neg_lo:[0,1] neg_hi:[0,1]
	s_waitcnt lgkmcnt(0)
; __device__ __forceinline__ int otid() { int t = threadIdx.x; asm volatile("" : "+v"(t)); return t; }
; __device__ __forceinline__ void fft_conv(ldsf2 buf, const LAS unsigned* spec) {
;     ...
;     { const int tid = otid(); cf x[16];
; #pragma unroll
;       for (int m = 0; m < 16; ++m) { const v2f v = buf[tid * 17 + m]; x[m] = cf{v.x, v.y}; }
;       dif_reg<4>(x, cf{1.0f, 0.0f});
; #pragma unroll
;       for (int m = 0; m < 16; ++m) { const h2_t hv = __builtin_bit_cast(h2_t, spec[tid * 17 + m]); x[m] = cmul(x[m], cf{(float)hv.x, (float)hv.y}); }
;       dit_reg<4>(x, cf{1.0f, 0.0f});
	v_cvt_f32_f16_e32 v126, v156
	v_cvt_f32_f16_e32 v122, v157
	v_cvt_f32_f16_e32 v84, v158
	v_cvt_f32_f16_e32 v150, v159
	v_cvt_f32_f16_sdwa v127, v156 dst_sel:DWORD dst_unused:UNUSED_PAD src0_sel:WORD_1
	v_cvt_f32_f16_sdwa v123, v157 dst_sel:DWORD dst_unused:UNUSED_PAD src0_sel:WORD_1
	v_cvt_f32_f16_sdwa v85, v158 dst_sel:DWORD dst_unused:UNUSED_PAD src0_sel:WORD_1
	v_cvt_f32_f16_sdwa v151, v159 dst_sel:DWORD dst_unused:UNUSED_PAD src0_sel:WORD_1
	v_pk_mul_f32 v[104:105], v[94:95], v[126:127] op_sel:[1,1] op_sel_hi:[1,0]
	v_pk_mul_f32 v[124:125], v[154:155], v[122:123] op_sel:[1,1] op_sel_hi:[1,0]
	v_pk_mul_f32 v[112:113], v[96:97], v[84:85] op_sel:[1,1] op_sel_hi:[1,0]
	v_pk_mul_f32 v[152:153], v[114:115], v[150:151] op_sel:[1,1] op_sel_hi:[1,0]
	v_pk_fma_f32 v[126:127], v[94:95], v[126:127], v[104:105] op_sel:[0,0,0] op_sel_hi:[0,1,1] neg_lo:[0,0,1] neg_hi:[0,0,0]
	v_pk_fma_f32 v[122:123], v[154:155], v[122:123], v[124:125] op_sel:[0,0,0] op_sel_hi:[0,1,1] neg_lo:[0,0,1] neg_hi:[0,0,0]
	v_pk_fma_f32 v[84:85], v[96:97], v[84:85], v[112:113] op_sel:[0,0,0] op_sel_hi:[0,1,1] neg_lo:[0,0,1] neg_hi:[0,0,0]
	v_pk_fma_f32 v[150:151], v[114:115], v[150:151], v[152:153] op_sel:[0,0,0] op_sel_hi:[0,1,1] neg_lo:[0,0,1] neg_hi:[0,0,0]
	v_cvt_f32_f16_e32 v102, v160
	v_cvt_f32_f16_e32 v166, v161
	v_cvt_f32_f16_e32 v74, v162
	v_cvt_f32_f16_e32 v78, v163
	v_cvt_f32_f16_sdwa v103, v160 dst_sel:DWORD dst_unused:UNUSED_PAD src0_sel:WORD_1
	v_cvt_f32_f16_sdwa v167, v161 dst_sel:DWORD dst_unused:UNUSED_PAD src0_sel:WORD_1
	v_cvt_f32_f16_sdwa v75, v162 dst_sel:DWORD dst_unused:UNUSED_PAD src0_sel:WORD_1
	v_cvt_f32_f16_sdwa v79, v163 dst_sel:DWORD dst_unused:UNUSED_PAD src0_sel:WORD_1
	v_pk_mul_f32 v[128:129], v[88:89], v[102:103] op_sel:[1,1] op_sel_hi:[1,0]
	v_pk_mul_f32 v[116:117], v[98:99], v[166:167] op_sel:[1,1] op_sel_hi:[1,0]
	v_pk_mul_f32 v[108:109], v[82:83], v[74:75] op_sel:[1,1] op_sel_hi:[1,0]
	v_pk_mul_f32 v[148:149], v[80:81], v[78:79] op_sel:[1,1] op_sel_hi:[1,0]
	v_pk_fma_f32 v[102:103], v[88:89], v[102:103], v[128:129] op_sel:[0,0,0] op_sel_hi:[0,1,1] neg_lo:[0,0,1] neg_hi:[0,0,0]
	v_pk_fma_f32 v[166:167], v[98:99], v[166:167], v[116:117] op_sel:[0,0,0] op_sel_hi:[0,1,1] neg_lo:[0,0,1] neg_hi:[0,0,0]
	v_pk_fma_f32 v[74:75], v[82:83], v[74:75], v[108:109] op_sel:[0,0,0] op_sel_hi:[0,1,1] neg_lo:[0,0,1] neg_hi:[0,0,0]
	v_pk_fma_f32 v[78:79], v[80:81], v[78:79], v[148:149] op_sel:[0,0,0] op_sel_hi:[0,1,1] neg_lo:[0,0,1] neg_hi:[0,0,0]
	v_cvt_f32_f16_e32 v92, v164
	v_cvt_f32_f16_e32 v104, v165
	v_cvt_f32_f16_e32 v124, v134
	v_cvt_f32_f16_e32 v112, v135
	v_cvt_f32_f16_sdwa v93, v164 dst_sel:DWORD dst_unused:UNUSED_PAD src0_sel:WORD_1
	v_cvt_f32_f16_sdwa v105, v165 dst_sel:DWORD dst_unused:UNUSED_PAD src0_sel:WORD_1
	v_cvt_f32_f16_sdwa v125, v134 dst_sel:DWORD dst_unused:UNUSED_PAD src0_sel:WORD_1
	v_cvt_f32_f16_sdwa v113, v135 dst_sel:DWORD dst_unused:UNUSED_PAD src0_sel:WORD_1
	v_pk_mul_f32 v[120:121], v[110:111], v[92:93] op_sel:[1,1] op_sel_hi:[1,0]
	v_pk_mul_f32 v[94:95], v[76:77], v[104:105] op_sel:[1,1] op_sel_hi:[1,0]
	v_pk_mul_f32 v[154:155], v[86:87], v[124:125] op_sel:[1,1] op_sel_hi:[1,0]
	v_pk_mul_f32 v[96:97], v[132:133], v[112:113] op_sel:[1,1] op_sel_hi:[1,0]
	v_pk_fma_f32 v[92:93], v[110:111], v[92:93], v[120:121] op_sel:[0,0,0] op_sel_hi:[0,1,1] neg_lo:[0,0,1] neg_hi:[0,0,0]
	v_pk_fma_f32 v[104:105], v[76:77], v[104:105], v[94:95] op_sel:[0,0,0] op_sel_hi:[0,1,1] neg_lo:[0,0,1] neg_hi:[0,0,0]
	v_pk_fma_f32 v[124:125], v[86:87], v[124:125], v[154:155] op_sel:[0,0,0] op_sel_hi:[0,1,1] neg_lo:[0,0,1] neg_hi:[0,0,0]
	v_pk_fma_f32 v[112:113], v[132:133], v[112:113], v[96:97] op_sel:[0,0,0] op_sel_hi:[0,1,1] neg_lo:[0,0,1] neg_hi:[0,0,0]
	v_cvt_f32_f16_e32 v152, v130
	v_cvt_f32_f16_e32 v128, v131
	v_cvt_f32_f16_e32 v116, v168
	v_cvt_f32_f16_e32 v108, v169
	v_cvt_f32_f16_sdwa v153, v130 dst_sel:DWORD dst_unused:UNUSED_PAD src0_sel:WORD_1
	v_cvt_f32_f16_sdwa v129, v131 dst_sel:DWORD dst_unused:UNUSED_PAD src0_sel:WORD_1
	v_cvt_f32_f16_sdwa v117, v168 dst_sel:DWORD dst_unused:UNUSED_PAD src0_sel:WORD_1
	v_cvt_f32_f16_sdwa v109, v169 dst_sel:DWORD dst_unused:UNUSED_PAD src0_sel:WORD_1
	v_pk_mul_f32 v[114:115], v[90:91], v[152:153] op_sel:[1,1] op_sel_hi:[1,0]
	v_pk_mul_f32 v[88:89], v[118:119], v[128:129] op_sel:[1,1] op_sel_hi:[1,0]
	v_pk_mul_f32 v[98:99], v[100:101], v[116:117] op_sel:[1,1] op_sel_hi:[1,0]
	v_pk_mul_f32 v[82:83], v[72:73], v[108:109] op_sel:[1,1] op_sel_hi:[1,0]
	v_pk_fma_f32 v[152:153], v[90:91], v[152:153], v[114:115] op_sel:[0,0,0] op_sel_hi:[0,1,1] neg_lo:[0,0,1] neg_hi:[0,0,0]
	v_pk_fma_f32 v[128:129], v[118:119], v[128:129], v[88:89] op_sel:[0,0,0] op_sel_hi:[0,1,1] neg_lo:[0,0,1] neg_hi:[0,0,0]
	v_pk_fma_f32 v[116:117], v[100:101], v[116:117], v[98:99] op_sel:[0,0,0] op_sel_hi:[0,1,1] neg_lo:[0,0,1] neg_hi:[0,0,0]
	v_pk_fma_f32 v[108:109], v[72:73], v[108:109], v[82:83] op_sel:[0,0,0] op_sel_hi:[0,1,1] neg_lo:[0,0,1] neg_hi:[0,0,0]
	v_pk_add_f32 v[148:149], v[126:127], v[122:123]
	v_pk_add_f32 v[80:81], v[84:85], v[150:151]
	v_pk_add_f32 v[120:121], v[102:103], v[166:167]
	v_pk_add_f32 v[110:111], v[74:75], v[78:79]
	v_pk_add_f32 v[126:127], v[126:127], v[122:123] neg_lo:[0,1] neg_hi:[0,1]
	v_pk_add_f32 v[84:85], v[84:85], v[150:151] neg_lo:[0,1] neg_hi:[0,1]
	v_pk_add_f32 v[102:103], v[102:103], v[166:167] neg_lo:[0,1] neg_hi:[0,1]
	v_pk_add_f32 v[74:75], v[74:75], v[78:79] neg_lo:[0,1] neg_hi:[0,1]
	v_pk_add_f32 v[94:95], v[92:93], v[104:105]
	v_pk_add_f32 v[76:77], v[124:125], v[112:113]
	v_pk_add_f32 v[154:155], v[152:153], v[128:129]
	v_pk_add_f32 v[86:87], v[116:117], v[108:109]
; __device__ __forceinline__ cf twc(cf ws, int k16) { if (k16 == 0) return ws; if (k16 == 4) return cf{ws.y, -ws.x}; return cmul(ws, cf{c16(k16), -s16(k16)}); }
; __device__ __forceinline__ void wave_lds_fence() { asm volatile("s_waitcnt lgkmcnt(0)" ::: "memory"); }
; template <int LR> __device__ __forceinline__ void dit_reg(cf (&x)[1 << LR], cf w) {
;     constexpr int R = 1 << LR; cf wsv[LR]; wsv[0] = w;
; #pragma unroll
;     for (int s = 1; s < LR; ++s) wsv[s] = cmul(wsv[s - 1], wsv[s - 1]);
; #pragma unroll
;     for (int s = LR - 1; s >= 0; --s) { const int half = R >> (s + 1);
; #pragma unroll
;         for (int m0 = 0; m0 < R; m0 += 2 * half)
; #pragma unroll
;             for (int mm = 0; mm < half; ++mm) { const int ia = m0 + mm, ib = ia + half; const cf a = x[ia];
;                 const cf b = cmulc(x[ib], twc(wsv[s], (mm << s) * (16 / R)));
;                 x[ia] = cf{a.x + b.x, a.y + b.y}; x[ib] = cf{a.x - b.x, a.y - b.y}; } }
; }
; __device__ __forceinline__ void fft_conv(ldsf2 buf, const LAS unsigned* spec) {
;     ...
;       dit_reg<4>(x, cf{1.0f, 0.0f});
; #pragma unroll
;       for (int m = 0; m < 16; ++m) buf[tid * 17 + m] = mkv2(x[m].x, x[m].y); }
;     wave_lds_fence();
;     fft_inv_cba(buf);
	v_pk_add_f32 v[92:93], v[92:93], v[104:105] neg_lo:[0,1] neg_hi:[0,1]
	v_pk_add_f32 v[124:125], v[124:125], v[112:113] neg_lo:[0,1] neg_hi:[0,1]
	v_pk_add_f32 v[152:153], v[152:153], v[128:129] neg_lo:[0,1] neg_hi:[0,1]
	v_pk_add_f32 v[116:117], v[116:117], v[108:109] neg_lo:[0,1] neg_hi:[0,1]
	v_pk_add_f32 v[96:97], v[148:149], v[80:81]
	v_pk_add_f32 v[132:133], v[126:127], v[84:85] op_sel:[0,1] op_sel_hi:[1,0] neg_lo:[0,1] neg_hi:[0,0]
	v_pk_add_f32 v[114:115], v[120:121], v[110:111]
	v_pk_add_f32 v[90:91], v[102:103], v[74:75] op_sel:[0,1] op_sel_hi:[1,0] neg_lo:[0,1] neg_hi:[0,0]
	v_pk_add_f32 v[148:149], v[148:149], v[80:81] neg_lo:[0,1] neg_hi:[0,1]
	v_pk_add_f32 v[126:127], v[126:127], v[84:85] op_sel:[0,1] op_sel_hi:[1,0] neg_lo:[0,0] neg_hi:[0,1]
	v_pk_add_f32 v[120:121], v[120:121], v[110:111] neg_lo:[0,1] neg_hi:[0,1]
	v_pk_add_f32 v[102:103], v[102:103], v[74:75] op_sel:[0,1] op_sel_hi:[1,0] neg_lo:[0,0] neg_hi:[0,1]
	v_pk_add_f32 v[88:89], v[94:95], v[76:77]
	v_pk_add_f32 v[118:119], v[92:93], v[124:125] op_sel:[0,1] op_sel_hi:[1,0] neg_lo:[0,1] neg_hi:[0,0]
	v_pk_add_f32 v[98:99], v[154:155], v[86:87]
	v_pk_add_f32 v[100:101], v[152:153], v[116:117] op_sel:[0,1] op_sel_hi:[1,0] neg_lo:[0,1] neg_hi:[0,0]
	v_pk_add_f32 v[94:95], v[94:95], v[76:77] neg_lo:[0,1] neg_hi:[0,1]
	v_pk_add_f32 v[92:93], v[92:93], v[124:125] op_sel:[0,1] op_sel_hi:[1,0] neg_lo:[0,0] neg_hi:[0,1]
	v_pk_add_f32 v[154:155], v[154:155], v[86:87] neg_lo:[0,1] neg_hi:[0,1]
	v_pk_add_f32 v[152:153], v[152:153], v[116:117] op_sel:[0,1] op_sel_hi:[1,0] neg_lo:[0,0] neg_hi:[0,1]
	v_pk_add_f32 v[82:83], v[96:97], v[114:115]
	v_pk_mul_f32 v[72:73], v[90:91], s[16:17] op_sel:[1,0] op_sel_hi:[1,0] neg_lo:[0,1] neg_hi:[0,0]
	v_pk_add_f32 v[122:123], v[148:149], v[120:121] op_sel:[0,1] op_sel_hi:[1,0] neg_lo:[0,1] neg_hi:[0,0]
	v_pk_mul_f32 v[150:151], v[102:103], s[16:17] op_sel:[1,0] op_sel_hi:[1,0] neg_lo:[0,1] neg_hi:[0,1]
	v_pk_add_f32 v[96:97], v[96:97], v[114:115] neg_lo:[0,1] neg_hi:[0,1]
	v_pk_fma_f32 v[72:73], v[90:91], s[16:17], v[72:73] op_sel:[0,0,0] op_sel_hi:[0,0,1] neg_lo:[0,0,0] neg_hi:[0,0,0]
	v_pk_add_f32 v[148:149], v[148:149], v[120:121] op_sel:[0,1] op_sel_hi:[1,0] neg_lo:[0,0] neg_hi:[0,1]
	v_pk_fma_f32 v[150:151], v[102:103], s[16:17], v[150:151] op_sel:[0,0,0] op_sel_hi:[0,0,1] neg_lo:[0,1,0] neg_hi:[0,0,0]
	v_pk_add_f32 v[90:91], v[132:133], v[72:73] neg_lo:[0,1] neg_hi:[0,1]
	v_pk_add_f32 v[102:103], v[126:127], v[150:151] neg_lo:[0,1] neg_hi:[0,1]
	v_pk_add_f32 v[132:133], v[132:133], v[72:73]
	v_pk_add_f32 v[126:127], v[126:127], v[150:151]
	v_pk_add_f32 v[166:167], v[88:89], v[98:99]
	v_pk_mul_f32 v[78:79], v[100:101], s[16:17] op_sel:[1,0] op_sel_hi:[1,0] neg_lo:[0,1] neg_hi:[0,0]
	v_pk_add_f32 v[104:105], v[94:95], v[154:155] op_sel:[0,1] op_sel_hi:[1,0] neg_lo:[0,1] neg_hi:[0,0]
	v_pk_mul_f32 v[112:113], v[152:153], s[16:17] op_sel:[1,0] op_sel_hi:[1,0] neg_lo:[0,1] neg_hi:[0,1]
	v_pk_add_f32 v[88:89], v[88:89], v[98:99] neg_lo:[0,1] neg_hi:[0,1]
	v_pk_fma_f32 v[78:79], v[100:101], s[16:17], v[78:79] op_sel:[0,0,0] op_sel_hi:[0,0,1] neg_lo:[0,0,0] neg_hi:[0,0,0]
	v_pk_add_f32 v[94:95], v[94:95], v[154:155] op_sel:[0,1] op_sel_hi:[1,0] neg_lo:[0,0] neg_hi:[0,1]
	v_pk_fma_f32 v[112:113], v[152:153], s[16:17], v[112:113] op_sel:[0,0,0] op_sel_hi:[0,0,1] neg_lo:[0,1,0] neg_hi:[0,0,0]
	v_pk_add_f32 v[100:101], v[118:119], v[78:79] neg_lo:[0,1] neg_hi:[0,1]
	v_pk_add_f32 v[152:153], v[92:93], v[112:113] neg_lo:[0,1] neg_hi:[0,1]
	v_pk_add_f32 v[118:119], v[118:119], v[78:79]
	v_pk_add_f32 v[92:93], v[92:93], v[112:113]
	v_pk_add_f32 v[128:129], v[82:83], v[166:167]
	v_pk_mul_f32 v[108:109], v[118:119], s[4:5] op_sel:[1,1] op_sel_hi:[1,0] neg_lo:[0,1] neg_hi:[0,0]
	v_pk_mul_f32 v[80:81], v[104:105], s[16:17] op_sel:[1,0] op_sel_hi:[1,0] neg_lo:[0,1] neg_hi:[0,0]
	v_pk_mul_f32 v[84:85], v[92:93], s[4:5] op_sel:[1,0] op_sel_hi:[1,1] neg_lo:[0,1] neg_hi:[0,0]
	v_pk_add_f32 v[82:83], v[82:83], v[166:167] neg_lo:[0,1] neg_hi:[0,1]
	v_pk_fma_f32 v[108:109], v[118:119], s[4:5], v[108:109] op_sel:[0,0,0] op_sel_hi:[0,1,1] neg_lo:[0,0,0] neg_hi:[0,0,0]
	v_pk_fma_f32 v[80:81], v[104:105], s[16:17], v[80:81] op_sel:[0,0,0] op_sel_hi:[0,0,1] neg_lo:[0,0,0] neg_hi:[0,0,0]
	v_pk_fma_f32 v[84:85], v[92:93], s[4:5], v[84:85] op_sel:[0,1,0] op_sel_hi:[0,0,1] neg_lo:[0,0,0] neg_hi:[0,0,0]
	v_pk_add_f32 v[118:119], v[132:133], v[108:109] neg_lo:[0,1] neg_hi:[0,1]
	v_pk_add_f32 v[104:105], v[122:123], v[80:81] neg_lo:[0,1] neg_hi:[0,1]
	v_pk_add_f32 v[92:93], v[126:127], v[84:85] neg_lo:[0,1] neg_hi:[0,1]
	v_pk_add_f32 v[132:133], v[132:133], v[108:109]
	v_pk_add_f32 v[122:123], v[122:123], v[80:81]
	v_pk_add_f32 v[126:127], v[126:127], v[84:85]
	v_pk_add_f32 v[110:111], v[96:97], v[88:89] op_sel:[0,1] op_sel_hi:[1,0] neg_lo:[0,1] neg_hi:[0,0]
	v_pk_mul_f32 v[74:75], v[100:101], s[4:5] op_sel:[1,0] op_sel_hi:[1,1] neg_lo:[0,1] neg_hi:[0,1]
	v_pk_mul_f32 v[76:77], v[94:95], s[16:17] op_sel:[1,0] op_sel_hi:[1,0] neg_lo:[0,1] neg_hi:[0,1]
	v_pk_mul_f32 v[124:125], v[152:153], s[4:5] op_sel:[1,1] op_sel_hi:[1,0] neg_lo:[0,1] neg_hi:[0,1]
	v_pk_add_f32 v[96:97], v[96:97], v[88:89] op_sel:[0,1] op_sel_hi:[1,0] neg_lo:[0,0] neg_hi:[0,1]
	v_pk_fma_f32 v[74:75], v[100:101], s[4:5], v[74:75] op_sel:[0,1,0] op_sel_hi:[0,0,1] neg_lo:[0,1,0] neg_hi:[0,0,0]
	v_pk_fma_f32 v[76:77], v[94:95], s[16:17], v[76:77] op_sel:[0,0,0] op_sel_hi:[0,0,1] neg_lo:[0,1,0] neg_hi:[0,0,0]
	v_pk_fma_f32 v[124:125], v[152:153], s[4:5], v[124:125] op_sel:[0,0,0] op_sel_hi:[0,1,1] neg_lo:[0,1,0] neg_hi:[0,0,0]
	v_pk_add_f32 v[100:101], v[90:91], v[74:75] neg_lo:[0,1] neg_hi:[0,1]
	v_pk_add_f32 v[94:95], v[148:149], v[76:77] neg_lo:[0,1] neg_hi:[0,1]
	v_pk_add_f32 v[152:153], v[102:103], v[124:125] neg_lo:[0,1] neg_hi:[0,1]
	v_pk_add_f32 v[90:91], v[90:91], v[74:75]
	v_pk_add_f32 v[148:149], v[148:149], v[76:77]
	v_pk_add_f32 v[102:103], v[102:103], v[124:125]
	ds_write2_b64 v147, v[128:129], v[132:133] offset1:1
	ds_write2_b64 v147, v[122:123], v[126:127] offset0:2 offset1:3
	ds_write2_b64 v147, v[110:111], v[90:91] offset0:4 offset1:5
	ds_write2_b64 v147, v[148:149], v[102:103] offset0:6 offset1:7
	ds_write2_b64 v147, v[82:83], v[118:119] offset0:8 offset1:9
	ds_write2_b64 v147, v[104:105], v[92:93] offset0:10 offset1:11
	ds_write2_b64 v147, v[96:97], v[100:101] offset0:12 offset1:13
	ds_write2_b64 v147, v[94:95], v[152:153] offset0:14 offset1:15
	v_mov_b32_e32 v68, v195
	s_waitcnt lgkmcnt(0)
	s_mov_b32 s0, 0
	v_and_b32_e32 v73, 15, v68
	v_lshlrev_b32_e32 v72, 4, v68
	v_lshlrev_b32_e32 v75, 9, v73
	v_and_b32_e32 v72, 0xfffffc00, v72
	v_lshlrev_b32_e32 v74, 3, v68
	v_add_u32_e32 v75, 0, v75
	v_and_b32_e32 v69, 63, v68
	v_lshl_add_u32 v73, v73, 3, 0
	v_and_or_b32 v74, v74, s90, v72
	v_add_u32_e32 v75, 0x22000, v75
; #define LAS __attribute__((address_space(3)))
; __device__ __forceinline__ cf twc(cf ws, int k16) { if (k16 == 0) return ws; if (k16 == 4) return cf{ws.y, -ws.x}; return cmul(ws, cf{c16(k16), -s16(k16)}); }
; template <int LR> __device__ __forceinline__ void dit_reg(cf (&x)[1 << LR], cf w) {
;     constexpr int R = 1 << LR; cf wsv[LR]; wsv[0] = w;
; #pragma unroll
;     for (int s = 1; s < LR; ++s) wsv[s] = cmul(wsv[s - 1], wsv[s - 1]);
; #pragma unroll
;     for (int s = LR - 1; s >= 0; --s) { const int half = R >> (s + 1);
; #pragma unroll
;         for (int m0 = 0; m0 < R; m0 += 2 * half)
; #pragma unroll
;             for (int mm = 0; mm < half; ++mm) { const int ia = m0 + mm, ib = ia + half; const cf a = x[ia];
;                 const cf b = cmulc(x[ib], twc(wsv[s], (mm << s) * (16 / R)));
;                 x[ia] = cf{a.x + b.x, a.y + b.y}; x[ib] = cf{a.x - b.x, a.y - b.y}; } }
; }
; template <int LR, bool INV> __device__ __forceinline__ void fft_pass(ldsf2 buf, int base, int stride, int twi) {
;     constexpr int R = 1 << LR; cf x[R];
;     const v2f wv = ((ldsf2)((LAS unsigned char*)buf + 139264))[twi];
; #pragma unroll
;     for (int m = 0; m < R; ++m) { const v2f v = buf[base + m * stride]; x[m] = cf{v.x, v.y}; }
;     const cf w{wv.x, wv.y};
;     if (INV) dit_reg<LR>(x, w); else dif_reg<LR>(x, w);
; #pragma unroll
;     for (int m = 0; m < R; ++m) buf[base + m * stride] = mkv2(x[m].x, x[m].y);
; }
.LBB0_353:
	ds_read_b64 v[92:93], v75
	v_or_b32_e32 v76, s0, v74
	v_lshlrev_b32_e32 v77, 3, v76
	v_ashrrev_i32_e32 v76, 1, v76
	v_add3_u32 v122, v73, v77, v76
	ds_read2_b64 v[76:79], v122 offset1:17
	ds_read2_b64 v[80:83], v122 offset0:34 offset1:51
	ds_read2_b64 v[84:87], v122 offset0:68 offset1:85
	ds_read2_b64 v[88:91], v122 offset0:102 offset1:119
	s_movk_i32 s0, 0x200
	ds_read_b64 v[124:125], v75
	v_or_b32_e32 v126, s0, v74
	v_lshlrev_b32_e32 v128, 3, v126
	v_ashrrev_i32_e32 v126, 1, v126
	v_add3_u32 v130, v73, v128, v126
	ds_read2_b64 v[132:135], v130 offset1:17
	ds_read2_b64 v[148:151], v130 offset0:34 offset1:51
	ds_read2_b64 v[152:155], v130 offset0:68 offset1:85
	ds_read2_b64 v[156:159], v130 offset0:102 offset1:119
	s_waitcnt lgkmcnt(5)
	v_pk_add_f32 v[94:95], v[92:93], v[92:93] op_sel:[0,1] op_sel_hi:[1,0] neg_lo:[0,0] neg_hi:[0,1]
	v_pk_mul_f32 v[100:101], v[92:93], v[92:93] op_sel:[1,1] op_sel_hi:[1,0]
	v_pk_mul_f32 v[96:97], v[94:95], s[16:17] op_sel:[0,0] op_sel_hi:[1,0]
	v_pk_fma_f32 v[100:101], v[92:93], v[92:93], v[100:101] op_sel:[0,0,0] op_sel_hi:[0,1,1] neg_lo:[0,0,1] neg_hi:[0,0,0]
	v_pk_mul_f32 v[98:99], v[94:95], s[16:17] op_sel:[1,0] op_sel_hi:[0,0] neg_lo:[0,0] neg_hi:[1,0]
	s_nop 0
	v_pk_mul_f32 v[102:103], v[100:101], v[100:101] op_sel:[1,1] op_sel_hi:[1,0]
	s_nop 0
	v_pk_fma_f32 v[102:103], v[100:101], v[100:101], v[102:103] op_sel:[0,0,0] op_sel_hi:[0,1,1] neg_lo:[0,0,1] neg_hi:[0,0,0]
	v_pk_mul_f32 v[104:105], v[78:79], v[102:103] op_sel:[1,1] op_sel_hi:[1,0]
	v_pk_mul_f32 v[106:107], v[82:83], v[102:103] op_sel:[1,1] op_sel_hi:[1,0]
	v_pk_mul_f32 v[108:109], v[86:87], v[102:103] op_sel:[1,1] op_sel_hi:[1,0]
	v_pk_mul_f32 v[110:111], v[90:91], v[102:103] op_sel:[1,1] op_sel_hi:[1,0]
	v_pk_fma_f32 v[104:105], v[78:79], v[102:103], v[104:105] op_sel:[0,0,0] op_sel_hi:[0,1,1] neg_lo:[0,0,0] neg_hi:[0,1,0]
	v_pk_fma_f32 v[106:107], v[82:83], v[102:103], v[106:107] op_sel:[0,0,0] op_sel_hi:[0,1,1] neg_lo:[0,0,0] neg_hi:[0,1,0]
	v_pk_fma_f32 v[108:109], v[86:87], v[102:103], v[108:109] op_sel:[0,0,0] op_sel_hi:[0,1,1] neg_lo:[0,0,0] neg_hi:[0,1,0]
	v_pk_fma_f32 v[110:111], v[90:91], v[102:103], v[110:111] op_sel:[0,0,0] op_sel_hi:[0,1,1] neg_lo:[0,0,0] neg_hi:[0,1,0]
	v_pk_add_f32 v[78:79], v[76:77], v[104:105] neg_lo:[0,1] neg_hi:[0,1]
	v_pk_add_f32 v[82:83], v[80:81], v[106:107] neg_lo:[0,1] neg_hi:[0,1]
	v_pk_add_f32 v[86:87], v[84:85], v[108:109] neg_lo:[0,1] neg_hi:[0,1]
	v_pk_add_f32 v[90:91], v[88:89], v[110:111] neg_lo:[0,1] neg_hi:[0,1]
	v_pk_add_f32 v[76:77], v[76:77], v[104:105]
	v_pk_add_f32 v[80:81], v[80:81], v[106:107]
	v_pk_add_f32 v[84:85], v[84:85], v[108:109]
	v_pk_add_f32 v[88:89], v[88:89], v[110:111]
	v_pk_mul_f32 v[104:105], v[80:81], v[100:101] op_sel:[1,1] op_sel_hi:[1,0]
	v_pk_mul_f32 v[106:107], v[82:83], v[100:101] op_sel:[1,0] op_sel_hi:[1,1]
	v_pk_mul_f32 v[108:109], v[88:89], v[100:101] op_sel:[1,1] op_sel_hi:[1,0]
	v_pk_mul_f32 v[110:111], v[90:91], v[100:101] op_sel:[1,0] op_sel_hi:[1,1]
	v_pk_fma_f32 v[104:105], v[80:81], v[100:101], v[104:105] op_sel:[0,0,0] op_sel_hi:[0,1,1] neg_lo:[0,0,0] neg_hi:[0,1,0]
	v_pk_fma_f32 v[106:107], v[82:83], v[100:101], v[106:107] op_sel:[0,1,0] op_sel_hi:[0,0,1] neg_lo:[0,0,1] neg_hi:[0,0,0]
	v_pk_fma_f32 v[108:109], v[88:89], v[100:101], v[108:109] op_sel:[0,0,0] op_sel_hi:[0,1,1] neg_lo:[0,0,0] neg_hi:[0,1,0]
	v_pk_fma_f32 v[110:111], v[90:91], v[100:101], v[110:111] op_sel:[0,1,0] op_sel_hi:[0,0,1] neg_lo:[0,0,1] neg_hi:[0,0,0]
	v_pk_add_f32 v[80:81], v[76:77], v[104:105] neg_lo:[0,1] neg_hi:[0,1]
	v_pk_add_f32 v[82:83], v[78:79], v[106:107] neg_lo:[0,1] neg_hi:[0,1]
	v_pk_add_f32 v[88:89], v[84:85], v[108:109] neg_lo:[0,1] neg_hi:[0,1]
	v_pk_add_f32 v[90:91], v[86:87], v[110:111] neg_lo:[0,1] neg_hi:[0,1]
	v_pk_add_f32 v[76:77], v[76:77], v[104:105]
	v_pk_add_f32 v[78:79], v[78:79], v[106:107]
	v_pk_add_f32 v[84:85], v[84:85], v[108:109]
	v_pk_add_f32 v[86:87], v[86:87], v[110:111]
	v_pk_mul_f32 v[104:105], v[84:85], v[92:93] op_sel:[1,1] op_sel_hi:[1,0]
	v_pk_mul_f32 v[106:107], v[86:87], v[96:97] op_sel:[1,1] op_sel_hi:[1,0]
	v_pk_mul_f32 v[108:109], v[88:89], v[92:93] op_sel:[1,0] op_sel_hi:[1,1]
	v_pk_mul_f32 v[110:111], v[90:91], v[98:99] op_sel:[1,1] op_sel_hi:[1,0]
	v_pk_fma_f32 v[104:105], v[84:85], v[92:93], v[104:105] op_sel:[0,0,0] op_sel_hi:[0,1,1] neg_lo:[0,0,0] neg_hi:[0,1,0]
	v_pk_fma_f32 v[106:107], v[86:87], v[96:97], v[106:107] op_sel:[0,0,0] op_sel_hi:[0,1,1] neg_lo:[0,0,0] neg_hi:[0,1,0]
	v_pk_fma_f32 v[108:109], v[88:89], v[92:93], v[108:109] op_sel:[0,1,0] op_sel_hi:[0,0,1] neg_lo:[0,0,1] neg_hi:[0,0,0]
	v_pk_fma_f32 v[110:111], v[90:91], v[98:99], v[110:111] op_sel:[0,0,0] op_sel_hi:[0,1,1] neg_lo:[0,0,0] neg_hi:[0,1,0]
	v_pk_add_f32 v[84:85], v[76:77], v[104:105] neg_lo:[0,1] neg_hi:[0,1]
	v_pk_add_f32 v[86:87], v[78:79], v[106:107] neg_lo:[0,1] neg_hi:[0,1]
	v_pk_add_f32 v[88:89], v[80:81], v[108:109] neg_lo:[0,1] neg_hi:[0,1]
	v_pk_add_f32 v[90:91], v[82:83], v[110:111] neg_lo:[0,1] neg_hi:[0,1]
	v_pk_add_f32 v[76:77], v[76:77], v[104:105]
	v_pk_add_f32 v[78:79], v[78:79], v[106:107]
	v_pk_add_f32 v[80:81], v[80:81], v[108:109]
	v_pk_add_f32 v[82:83], v[82:83], v[110:111]
	ds_write2_b64 v122, v[76:77], v[78:79] offset1:17
	ds_write2_b64 v122, v[80:81], v[82:83] offset0:34 offset1:51
	ds_write2_b64 v122, v[84:85], v[86:87] offset0:68 offset1:85
	ds_write2_b64 v122, v[88:89], v[90:91] offset0:102 offset1:119
	s_waitcnt lgkmcnt(4)
; #define LAS __attribute__((address_space(3)))
; __device__ __forceinline__ cf twc(cf ws, int k16) { if (k16 == 0) return ws; if (k16 == 4) return cf{ws.y, -ws.x}; return cmul(ws, cf{c16(k16), -s16(k16)}); }
; template <int LR> __device__ __forceinline__ void dit_reg(cf (&x)[1 << LR], cf w) {
;     constexpr int R = 1 << LR; cf wsv[LR]; wsv[0] = w;
; #pragma unroll
;     for (int s = 1; s < LR; ++s) wsv[s] = cmul(wsv[s - 1], wsv[s - 1]);
; #pragma unroll
;     for (int s = LR - 1; s >= 0; --s) { const int half = R >> (s + 1);
; #pragma unroll
;         for (int m0 = 0; m0 < R; m0 += 2 * half)
; #pragma unroll
;             for (int mm = 0; mm < half; ++mm) { const int ia = m0 + mm, ib = ia + half; const cf a = x[ia];
;                 const cf b = cmulc(x[ib], twc(wsv[s], (mm << s) * (16 / R)));
;                 x[ia] = cf{a.x + b.x, a.y + b.y}; x[ib] = cf{a.x - b.x, a.y - b.y}; } }
; }
; template <int LR, bool INV> __device__ __forceinline__ void fft_pass(ldsf2 buf, int base, int stride, int twi) {
;     constexpr int R = 1 << LR; cf x[R];
;     const v2f wv = ((ldsf2)((LAS unsigned char*)buf + 139264))[twi];
; #pragma unroll
;     for (int m = 0; m < R; ++m) { const v2f v = buf[base + m * stride]; x[m] = cf{v.x, v.y}; }
;     const cf w{wv.x, wv.y};
;     if (INV) dit_reg<LR>(x, w); else dif_reg<LR>(x, w);
; #pragma unroll
;     for (int m = 0; m < R; ++m) buf[base + m * stride] = mkv2(x[m].x, x[m].y);
; }
	v_pk_add_f32 v[160:161], v[124:125], v[124:125] op_sel:[0,1] op_sel_hi:[1,0] neg_lo:[0,0] neg_hi:[0,1]
	v_pk_mul_f32 v[166:167], v[124:125], v[124:125] op_sel:[1,1] op_sel_hi:[1,0]
	v_pk_mul_f32 v[162:163], v[160:161], s[16:17] op_sel:[0,0] op_sel_hi:[1,0]
	v_pk_fma_f32 v[166:167], v[124:125], v[124:125], v[166:167] op_sel:[0,0,0] op_sel_hi:[0,1,1] neg_lo:[0,0,1] neg_hi:[0,0,0]
	v_pk_mul_f32 v[164:165], v[160:161], s[16:17] op_sel:[1,0] op_sel_hi:[0,0] neg_lo:[0,0] neg_hi:[1,0]
	s_nop 0
	v_pk_mul_f32 v[168:169], v[166:167], v[166:167] op_sel:[1,1] op_sel_hi:[1,0]
	s_nop 0
	v_pk_fma_f32 v[168:169], v[166:167], v[166:167], v[168:169] op_sel:[0,0,0] op_sel_hi:[0,1,1] neg_lo:[0,0,1] neg_hi:[0,0,0]
	v_pk_mul_f32 v[170:171], v[134:135], v[168:169] op_sel:[1,1] op_sel_hi:[1,0]
	v_pk_mul_f32 v[172:173], v[150:151], v[168:169] op_sel:[1,1] op_sel_hi:[1,0]
	v_pk_mul_f32 v[174:175], v[154:155], v[168:169] op_sel:[1,1] op_sel_hi:[1,0]
	v_pk_mul_f32 v[188:189], v[158:159], v[168:169] op_sel:[1,1] op_sel_hi:[1,0]
	v_pk_fma_f32 v[170:171], v[134:135], v[168:169], v[170:171] op_sel:[0,0,0] op_sel_hi:[0,1,1] neg_lo:[0,0,0] neg_hi:[0,1,0]
	v_pk_fma_f32 v[172:173], v[150:151], v[168:169], v[172:173] op_sel:[0,0,0] op_sel_hi:[0,1,1] neg_lo:[0,0,0] neg_hi:[0,1,0]
	v_pk_fma_f32 v[174:175], v[154:155], v[168:169], v[174:175] op_sel:[0,0,0] op_sel_hi:[0,1,1] neg_lo:[0,0,0] neg_hi:[0,1,0]
	v_pk_fma_f32 v[188:189], v[158:159], v[168:169], v[188:189] op_sel:[0,0,0] op_sel_hi:[0,1,1] neg_lo:[0,0,0] neg_hi:[0,1,0]
	v_pk_add_f32 v[134:135], v[132:133], v[170:171] neg_lo:[0,1] neg_hi:[0,1]
	v_pk_add_f32 v[150:151], v[148:149], v[172:173] neg_lo:[0,1] neg_hi:[0,1]
	v_pk_add_f32 v[154:155], v[152:153], v[174:175] neg_lo:[0,1] neg_hi:[0,1]
	v_pk_add_f32 v[158:159], v[156:157], v[188:189] neg_lo:[0,1] neg_hi:[0,1]
	v_pk_add_f32 v[132:133], v[132:133], v[170:171]
	v_pk_add_f32 v[148:149], v[148:149], v[172:173]
	v_pk_add_f32 v[152:153], v[152:153], v[174:175]
	v_pk_add_f32 v[156:157], v[156:157], v[188:189]
	v_pk_mul_f32 v[170:171], v[148:149], v[166:167] op_sel:[1,1] op_sel_hi:[1,0]
	v_pk_mul_f32 v[172:173], v[150:151], v[166:167] op_sel:[1,0] op_sel_hi:[1,1]
	v_pk_mul_f32 v[174:175], v[156:157], v[166:167] op_sel:[1,1] op_sel_hi:[1,0]
	v_pk_mul_f32 v[188:189], v[158:159], v[166:167] op_sel:[1,0] op_sel_hi:[1,1]
	v_pk_fma_f32 v[170:171], v[148:149], v[166:167], v[170:171] op_sel:[0,0,0] op_sel_hi:[0,1,1] neg_lo:[0,0,0] neg_hi:[0,1,0]
	v_pk_fma_f32 v[172:173], v[150:151], v[166:167], v[172:173] op_sel:[0,1,0] op_sel_hi:[0,0,1] neg_lo:[0,0,1] neg_hi:[0,0,0]
	v_pk_fma_f32 v[174:175], v[156:157], v[166:167], v[174:175] op_sel:[0,0,0] op_sel_hi:[0,1,1] neg_lo:[0,0,0] neg_hi:[0,1,0]
	v_pk_fma_f32 v[188:189], v[158:159], v[166:167], v[188:189] op_sel:[0,1,0] op_sel_hi:[0,0,1] neg_lo:[0,0,1] neg_hi:[0,0,0]
	v_pk_add_f32 v[148:149], v[132:133], v[170:171] neg_lo:[0,1] neg_hi:[0,1]
	v_pk_add_f32 v[150:151], v[134:135], v[172:173] neg_lo:[0,1] neg_hi:[0,1]
	v_pk_add_f32 v[156:157], v[152:153], v[174:175] neg_lo:[0,1] neg_hi:[0,1]
	v_pk_add_f32 v[158:159], v[154:155], v[188:189] neg_lo:[0,1] neg_hi:[0,1]
	v_pk_add_f32 v[132:133], v[132:133], v[170:171]
	v_pk_add_f32 v[134:135], v[134:135], v[172:173]
	v_pk_add_f32 v[152:153], v[152:153], v[174:175]
	v_pk_add_f32 v[154:155], v[154:155], v[188:189]
	v_pk_mul_f32 v[170:171], v[152:153], v[124:125] op_sel:[1,1] op_sel_hi:[1,0]
	v_pk_mul_f32 v[172:173], v[154:155], v[162:163] op_sel:[1,1] op_sel_hi:[1,0]
	v_pk_mul_f32 v[174:175], v[156:157], v[124:125] op_sel:[1,0] op_sel_hi:[1,1]
	v_pk_mul_f32 v[188:189], v[158:159], v[164:165] op_sel:[1,1] op_sel_hi:[1,0]
	v_pk_fma_f32 v[170:171], v[152:153], v[124:125], v[170:171] op_sel:[0,0,0] op_sel_hi:[0,1,1] neg_lo:[0,0,0] neg_hi:[0,1,0]
	v_pk_fma_f32 v[172:173], v[154:155], v[162:163], v[172:173] op_sel:[0,0,0] op_sel_hi:[0,1,1] neg_lo:[0,0,0] neg_hi:[0,1,0]
	v_pk_fma_f32 v[174:175], v[156:157], v[124:125], v[174:175] op_sel:[0,1,0] op_sel_hi:[0,0,1] neg_lo:[0,0,1] neg_hi:[0,0,0]
	v_pk_fma_f32 v[188:189], v[158:159], v[164:165], v[188:189] op_sel:[0,0,0] op_sel_hi:[0,1,1] neg_lo:[0,0,0] neg_hi:[0,1,0]
	v_pk_add_f32 v[152:153], v[132:133], v[170:171] neg_lo:[0,1] neg_hi:[0,1]
	v_pk_add_f32 v[154:155], v[134:135], v[172:173] neg_lo:[0,1] neg_hi:[0,1]
	v_pk_add_f32 v[156:157], v[148:149], v[174:175] neg_lo:[0,1] neg_hi:[0,1]
	v_pk_add_f32 v[158:159], v[150:151], v[188:189] neg_lo:[0,1] neg_hi:[0,1]
	v_pk_add_f32 v[132:133], v[132:133], v[170:171]
	v_pk_add_f32 v[134:135], v[134:135], v[172:173]
	v_pk_add_f32 v[148:149], v[148:149], v[174:175]
	v_pk_add_f32 v[150:151], v[150:151], v[188:189]
	ds_write2_b64 v130, v[132:133], v[134:135] offset1:17
	ds_write2_b64 v130, v[148:149], v[150:151] offset0:34 offset1:51
	ds_write2_b64 v130, v[152:153], v[154:155] offset0:68 offset1:85
	ds_write2_b64 v130, v[156:157], v[158:159] offset0:102 offset1:119
	s_mov_b64 s[6:7], 0
	s_waitcnt lgkmcnt(0)
	s_mov_b32 s0, 0
	s_mov_b64 s[6:7], -1
; #define LAS __attribute__((address_space(3)))
; __device__ __forceinline__ cf twc(cf ws, int k16) { if (k16 == 0) return ws; if (k16 == 4) return cf{ws.y, -ws.x}; return cmul(ws, cf{c16(k16), -s16(k16)}); }
; template <int LR> __device__ __forceinline__ void dit_reg(cf (&x)[1 << LR], cf w) {
;     constexpr int R = 1 << LR; cf wsv[LR]; wsv[0] = w;
; #pragma unroll
;     for (int s = 1; s < LR; ++s) wsv[s] = cmul(wsv[s - 1], wsv[s - 1]);
; #pragma unroll
;     for (int s = LR - 1; s >= 0; --s) { const int half = R >> (s + 1);
; #pragma unroll
;         for (int m0 = 0; m0 < R; m0 += 2 * half)
; #pragma unroll
;             for (int mm = 0; mm < half; ++mm) { const int ia = m0 + mm, ib = ia + half; const cf a = x[ia];
;                 const cf b = cmulc(x[ib], twc(wsv[s], (mm << s) * (16 / R)));
;                 x[ia] = cf{a.x + b.x, a.y + b.y}; x[ib] = cf{a.x - b.x, a.y - b.y}; } }
; }
; template <int LR, bool INV> __device__ __forceinline__ void fft_pass(ldsf2 buf, int base, int stride, int twi) {
;     constexpr int R = 1 << LR; cf x[R];
;     const v2f wv = ((ldsf2)((LAS unsigned char*)buf + 139264))[twi];
; #pragma unroll
;     for (int m = 0; m < R; ++m) { const v2f v = buf[base + m * stride]; x[m] = cf{v.x, v.y}; }
;     const cf w{wv.x, wv.y};
;     if (INV) dit_reg<LR>(x, w); else dif_reg<LR>(x, w);
; #pragma unroll
;     for (int m = 0; m < R; ++m) buf[base + m * stride] = mkv2(x[m].x, x[m].y);
; }
.LBB0_355:
	v_or_b32_e32 v73, s0, v69
	v_or_b32_e32 v74, v73, v72
	v_lshl_add_u32 v73, v73, 6, 0
	v_add_u32_e32 v73, 0x22000, v73
	ds_read_b64 v[90:91], v73
	v_ashrrev_i32_e32 v75, 4, v74
	v_lshlrev_b32_e32 v73, 3, v74
	v_lshlrev_b32_e32 v74, 3, v75
	v_add3_u32 v73, 0, v73, v74
	v_add_u32_e32 v122, 0x1800, v73
	v_add_u32_e32 v121, 0x1000, v73
	ds_read2_b64 v[86:89], v122 offset0:48 offset1:184
	ds_read2_b64 v[82:85], v121 offset0:32 offset1:168
	v_add_u32_e32 v120, 0x800, v73
	ds_read2_b64 v[74:77], v73 offset1:136
	ds_read2_b64 v[78:81], v120 offset0:16 offset1:152
	s_mov_b32 s0, 64
	v_or_b32_e32 v124, s0, v69
	v_or_b32_e32 v126, v124, v72
	v_lshl_add_u32 v124, v124, 6, 0
	v_add_u32_e32 v124, 0x22000, v124
	ds_read_b64 v[128:129], v124
	v_ashrrev_i32_e32 v130, 4, v126
	v_lshlrev_b32_e32 v124, 3, v126
	v_lshlrev_b32_e32 v126, 3, v130
	v_add3_u32 v124, 0, v124, v126
	v_add_u32_e32 v132, 0x1800, v124
	v_add_u32_e32 v134, 0x1000, v124
	ds_read2_b64 v[148:151], v132 offset0:48 offset1:184
	ds_read2_b64 v[152:155], v134 offset0:32 offset1:168
	v_add_u32_e32 v156, 0x800, v124
	ds_read2_b64 v[158:161], v124 offset1:136
	ds_read2_b64 v[162:165], v156 offset0:16 offset1:152
	s_waitcnt lgkmcnt(5)
	v_pk_add_f32 v[92:93], v[90:91], v[90:91] op_sel:[0,1] op_sel_hi:[1,0] neg_lo:[0,0] neg_hi:[0,1]
	v_pk_mul_f32 v[98:99], v[90:91], v[90:91] op_sel:[1,1] op_sel_hi:[1,0]
	v_pk_mul_f32 v[94:95], v[92:93], s[16:17] op_sel:[0,0] op_sel_hi:[1,0]
	v_pk_fma_f32 v[98:99], v[90:91], v[90:91], v[98:99] op_sel:[0,0,0] op_sel_hi:[0,1,1] neg_lo:[0,0,1] neg_hi:[0,0,0]
	v_pk_mul_f32 v[96:97], v[92:93], s[16:17] op_sel:[1,0] op_sel_hi:[0,0] neg_lo:[0,0] neg_hi:[1,0]
	s_nop 0
	v_pk_mul_f32 v[100:101], v[98:99], v[98:99] op_sel:[1,1] op_sel_hi:[1,0]
	s_nop 0
	v_pk_fma_f32 v[100:101], v[98:99], v[98:99], v[100:101] op_sel:[0,0,0] op_sel_hi:[0,1,1] neg_lo:[0,0,1] neg_hi:[0,0,0]
	v_pk_mul_f32 v[102:103], v[76:77], v[100:101] op_sel:[1,1] op_sel_hi:[1,0]
	v_pk_mul_f32 v[104:105], v[80:81], v[100:101] op_sel:[1,1] op_sel_hi:[1,0]
	v_pk_mul_f32 v[106:107], v[84:85], v[100:101] op_sel:[1,1] op_sel_hi:[1,0]
	v_pk_mul_f32 v[108:109], v[88:89], v[100:101] op_sel:[1,1] op_sel_hi:[1,0]
	v_pk_fma_f32 v[102:103], v[76:77], v[100:101], v[102:103] op_sel:[0,0,0] op_sel_hi:[0,1,1] neg_lo:[0,0,0] neg_hi:[0,1,0]
	v_pk_fma_f32 v[104:105], v[80:81], v[100:101], v[104:105] op_sel:[0,0,0] op_sel_hi:[0,1,1] neg_lo:[0,0,0] neg_hi:[0,1,0]
	v_pk_fma_f32 v[106:107], v[84:85], v[100:101], v[106:107] op_sel:[0,0,0] op_sel_hi:[0,1,1] neg_lo:[0,0,0] neg_hi:[0,1,0]
	v_pk_fma_f32 v[108:109], v[88:89], v[100:101], v[108:109] op_sel:[0,0,0] op_sel_hi:[0,1,1] neg_lo:[0,0,0] neg_hi:[0,1,0]
	v_pk_add_f32 v[76:77], v[74:75], v[102:103] neg_lo:[0,1] neg_hi:[0,1]
	v_pk_add_f32 v[80:81], v[78:79], v[104:105] neg_lo:[0,1] neg_hi:[0,1]
	v_pk_add_f32 v[84:85], v[82:83], v[106:107] neg_lo:[0,1] neg_hi:[0,1]
	v_pk_add_f32 v[88:89], v[86:87], v[108:109] neg_lo:[0,1] neg_hi:[0,1]
	v_pk_add_f32 v[74:75], v[74:75], v[102:103]
	v_pk_add_f32 v[78:79], v[78:79], v[104:105]
	v_pk_add_f32 v[82:83], v[82:83], v[106:107]
	v_pk_add_f32 v[86:87], v[86:87], v[108:109]
	v_pk_mul_f32 v[102:103], v[78:79], v[98:99] op_sel:[1,1] op_sel_hi:[1,0]
	v_pk_mul_f32 v[104:105], v[80:81], v[98:99] op_sel:[1,0] op_sel_hi:[1,1]
	v_pk_mul_f32 v[106:107], v[86:87], v[98:99] op_sel:[1,1] op_sel_hi:[1,0]
	v_pk_mul_f32 v[108:109], v[88:89], v[98:99] op_sel:[1,0] op_sel_hi:[1,1]
	v_pk_fma_f32 v[102:103], v[78:79], v[98:99], v[102:103] op_sel:[0,0,0] op_sel_hi:[0,1,1] neg_lo:[0,0,0] neg_hi:[0,1,0]
	v_pk_fma_f32 v[104:105], v[80:81], v[98:99], v[104:105] op_sel:[0,1,0] op_sel_hi:[0,0,1] neg_lo:[0,0,1] neg_hi:[0,0,0]
	v_pk_fma_f32 v[106:107], v[86:87], v[98:99], v[106:107] op_sel:[0,0,0] op_sel_hi:[0,1,1] neg_lo:[0,0,0] neg_hi:[0,1,0]
	v_pk_fma_f32 v[108:109], v[88:89], v[98:99], v[108:109] op_sel:[0,1,0] op_sel_hi:[0,0,1] neg_lo:[0,0,1] neg_hi:[0,0,0]
	v_pk_add_f32 v[78:79], v[74:75], v[102:103] neg_lo:[0,1] neg_hi:[0,1]
	v_pk_add_f32 v[80:81], v[76:77], v[104:105] neg_lo:[0,1] neg_hi:[0,1]
	v_pk_add_f32 v[86:87], v[82:83], v[106:107] neg_lo:[0,1] neg_hi:[0,1]
	v_pk_add_f32 v[88:89], v[84:85], v[108:109] neg_lo:[0,1] neg_hi:[0,1]
	v_pk_add_f32 v[74:75], v[74:75], v[102:103]
	v_pk_add_f32 v[76:77], v[76:77], v[104:105]
	v_pk_add_f32 v[82:83], v[82:83], v[106:107]
	v_pk_add_f32 v[84:85], v[84:85], v[108:109]
	v_pk_mul_f32 v[102:103], v[82:83], v[90:91] op_sel:[1,1] op_sel_hi:[1,0]
	v_pk_mul_f32 v[104:105], v[84:85], v[94:95] op_sel:[1,1] op_sel_hi:[1,0]
	v_pk_mul_f32 v[106:107], v[86:87], v[90:91] op_sel:[1,0] op_sel_hi:[1,1]
	v_pk_mul_f32 v[108:109], v[88:89], v[96:97] op_sel:[1,1] op_sel_hi:[1,0]
	v_pk_fma_f32 v[102:103], v[82:83], v[90:91], v[102:103] op_sel:[0,0,0] op_sel_hi:[0,1,1] neg_lo:[0,0,0] neg_hi:[0,1,0]
	v_pk_fma_f32 v[104:105], v[84:85], v[94:95], v[104:105] op_sel:[0,0,0] op_sel_hi:[0,1,1] neg_lo:[0,0,0] neg_hi:[0,1,0]
	v_pk_fma_f32 v[106:107], v[86:87], v[90:91], v[106:107] op_sel:[0,1,0] op_sel_hi:[0,0,1] neg_lo:[0,0,1] neg_hi:[0,0,0]
	v_pk_fma_f32 v[108:109], v[88:89], v[96:97], v[108:109] op_sel:[0,0,0] op_sel_hi:[0,1,1] neg_lo:[0,0,0] neg_hi:[0,1,0]
	v_pk_add_f32 v[82:83], v[74:75], v[102:103] neg_lo:[0,1] neg_hi:[0,1]
	v_pk_add_f32 v[84:85], v[76:77], v[104:105] neg_lo:[0,1] neg_hi:[0,1]
	v_pk_add_f32 v[86:87], v[78:79], v[106:107] neg_lo:[0,1] neg_hi:[0,1]
	v_pk_add_f32 v[88:89], v[80:81], v[108:109] neg_lo:[0,1] neg_hi:[0,1]
	v_pk_add_f32 v[74:75], v[74:75], v[102:103]
	v_pk_add_f32 v[76:77], v[76:77], v[104:105]
	v_pk_add_f32 v[78:79], v[78:79], v[106:107]
	v_pk_add_f32 v[80:81], v[80:81], v[108:109]
	ds_write2_b64 v73, v[74:75], v[76:77] offset1:136
	ds_write2_b64 v120, v[78:79], v[80:81] offset0:16 offset1:152
	ds_write2_b64 v121, v[82:83], v[84:85] offset0:32 offset1:168
	ds_write2_b64 v122, v[86:87], v[88:89] offset0:48 offset1:184
	s_waitcnt lgkmcnt(4)
; #define LAS __attribute__((address_space(3)))
; __device__ __forceinline__ cf twc(cf ws, int k16) { if (k16 == 0) return ws; if (k16 == 4) return cf{ws.y, -ws.x}; return cmul(ws, cf{c16(k16), -s16(k16)}); }
; template <int LR> __device__ __forceinline__ void dit_reg(cf (&x)[1 << LR], cf w) {
;     constexpr int R = 1 << LR; cf wsv[LR]; wsv[0] = w;
; #pragma unroll
;     for (int s = 1; s < LR; ++s) wsv[s] = cmul(wsv[s - 1], wsv[s - 1]);
; #pragma unroll
;     for (int s = LR - 1; s >= 0; --s) { const int half = R >> (s + 1);
; #pragma unroll
;         for (int m0 = 0; m0 < R; m0 += 2 * half)
; #pragma unroll
;             for (int mm = 0; mm < half; ++mm) { const int ia = m0 + mm, ib = ia + half; const cf a = x[ia];
;                 const cf b = cmulc(x[ib], twc(wsv[s], (mm << s) * (16 / R)));
;                 x[ia] = cf{a.x + b.x, a.y + b.y}; x[ib] = cf{a.x - b.x, a.y - b.y}; } }
; }
; template <int LR, bool INV> __device__ __forceinline__ void fft_pass(ldsf2 buf, int base, int stride, int twi) {
;     constexpr int R = 1 << LR; cf x[R];
;     const v2f wv = ((ldsf2)((LAS unsigned char*)buf + 139264))[twi];
; #pragma unroll
;     for (int m = 0; m < R; ++m) { const v2f v = buf[base + m * stride]; x[m] = cf{v.x, v.y}; }
;     const cf w{wv.x, wv.y};
;     if (INV) dit_reg<LR>(x, w); else dif_reg<LR>(x, w);
; #pragma unroll
;     for (int m = 0; m < R; ++m) buf[base + m * stride] = mkv2(x[m].x, x[m].y);
; }
	v_pk_add_f32 v[166:167], v[128:129], v[128:129] op_sel:[0,1] op_sel_hi:[1,0] neg_lo:[0,0] neg_hi:[0,1]
	v_pk_mul_f32 v[172:173], v[128:129], v[128:129] op_sel:[1,1] op_sel_hi:[1,0]
	v_pk_mul_f32 v[168:169], v[166:167], s[16:17] op_sel:[0,0] op_sel_hi:[1,0]
	v_pk_fma_f32 v[172:173], v[128:129], v[128:129], v[172:173] op_sel:[0,0,0] op_sel_hi:[0,1,1] neg_lo:[0,0,1] neg_hi:[0,0,0]
	v_pk_mul_f32 v[170:171], v[166:167], s[16:17] op_sel:[1,0] op_sel_hi:[0,0] neg_lo:[0,0] neg_hi:[1,0]
	s_nop 0
	v_pk_mul_f32 v[174:175], v[172:173], v[172:173] op_sel:[1,1] op_sel_hi:[1,0]
	s_nop 0
	v_pk_fma_f32 v[174:175], v[172:173], v[172:173], v[174:175] op_sel:[0,0,0] op_sel_hi:[0,1,1] neg_lo:[0,0,1] neg_hi:[0,0,0]
	v_pk_mul_f32 v[188:189], v[160:161], v[174:175] op_sel:[1,1] op_sel_hi:[1,0]
	v_pk_mul_f32 v[190:191], v[164:165], v[174:175] op_sel:[1,1] op_sel_hi:[1,0]
	v_pk_mul_f32 v[196:197], v[154:155], v[174:175] op_sel:[1,1] op_sel_hi:[1,0]
	v_pk_mul_f32 v[198:199], v[150:151], v[174:175] op_sel:[1,1] op_sel_hi:[1,0]
	v_pk_fma_f32 v[188:189], v[160:161], v[174:175], v[188:189] op_sel:[0,0,0] op_sel_hi:[0,1,1] neg_lo:[0,0,0] neg_hi:[0,1,0]
	v_pk_fma_f32 v[190:191], v[164:165], v[174:175], v[190:191] op_sel:[0,0,0] op_sel_hi:[0,1,1] neg_lo:[0,0,0] neg_hi:[0,1,0]
	v_pk_fma_f32 v[196:197], v[154:155], v[174:175], v[196:197] op_sel:[0,0,0] op_sel_hi:[0,1,1] neg_lo:[0,0,0] neg_hi:[0,1,0]
	v_pk_fma_f32 v[198:199], v[150:151], v[174:175], v[198:199] op_sel:[0,0,0] op_sel_hi:[0,1,1] neg_lo:[0,0,0] neg_hi:[0,1,0]
	v_pk_add_f32 v[160:161], v[158:159], v[188:189] neg_lo:[0,1] neg_hi:[0,1]
	v_pk_add_f32 v[164:165], v[162:163], v[190:191] neg_lo:[0,1] neg_hi:[0,1]
	v_pk_add_f32 v[154:155], v[152:153], v[196:197] neg_lo:[0,1] neg_hi:[0,1]
	v_pk_add_f32 v[150:151], v[148:149], v[198:199] neg_lo:[0,1] neg_hi:[0,1]
	v_pk_add_f32 v[158:159], v[158:159], v[188:189]
	v_pk_add_f32 v[162:163], v[162:163], v[190:191]
	v_pk_add_f32 v[152:153], v[152:153], v[196:197]
	v_pk_add_f32 v[148:149], v[148:149], v[198:199]
	v_pk_mul_f32 v[188:189], v[162:163], v[172:173] op_sel:[1,1] op_sel_hi:[1,0]
	v_pk_mul_f32 v[190:191], v[164:165], v[172:173] op_sel:[1,0] op_sel_hi:[1,1]
	v_pk_mul_f32 v[196:197], v[148:149], v[172:173] op_sel:[1,1] op_sel_hi:[1,0]
	v_pk_mul_f32 v[198:199], v[150:151], v[172:173] op_sel:[1,0] op_sel_hi:[1,1]
	v_pk_fma_f32 v[188:189], v[162:163], v[172:173], v[188:189] op_sel:[0,0,0] op_sel_hi:[0,1,1] neg_lo:[0,0,0] neg_hi:[0,1,0]
	v_pk_fma_f32 v[190:191], v[164:165], v[172:173], v[190:191] op_sel:[0,1,0] op_sel_hi:[0,0,1] neg_lo:[0,0,1] neg_hi:[0,0,0]
	v_pk_fma_f32 v[196:197], v[148:149], v[172:173], v[196:197] op_sel:[0,0,0] op_sel_hi:[0,1,1] neg_lo:[0,0,0] neg_hi:[0,1,0]
	v_pk_fma_f32 v[198:199], v[150:151], v[172:173], v[198:199] op_sel:[0,1,0] op_sel_hi:[0,0,1] neg_lo:[0,0,1] neg_hi:[0,0,0]
	v_pk_add_f32 v[162:163], v[158:159], v[188:189] neg_lo:[0,1] neg_hi:[0,1]
	v_pk_add_f32 v[164:165], v[160:161], v[190:191] neg_lo:[0,1] neg_hi:[0,1]
	v_pk_add_f32 v[148:149], v[152:153], v[196:197] neg_lo:[0,1] neg_hi:[0,1]
	v_pk_add_f32 v[150:151], v[154:155], v[198:199] neg_lo:[0,1] neg_hi:[0,1]
	v_pk_add_f32 v[158:159], v[158:159], v[188:189]
	v_pk_add_f32 v[160:161], v[160:161], v[190:191]
	v_pk_add_f32 v[152:153], v[152:153], v[196:197]
	v_pk_add_f32 v[154:155], v[154:155], v[198:199]
	v_pk_mul_f32 v[188:189], v[152:153], v[128:129] op_sel:[1,1] op_sel_hi:[1,0]
	v_pk_mul_f32 v[190:191], v[154:155], v[168:169] op_sel:[1,1] op_sel_hi:[1,0]
	v_pk_mul_f32 v[196:197], v[148:149], v[128:129] op_sel:[1,0] op_sel_hi:[1,1]
	v_pk_mul_f32 v[198:199], v[150:151], v[170:171] op_sel:[1,1] op_sel_hi:[1,0]
	v_pk_fma_f32 v[188:189], v[152:153], v[128:129], v[188:189] op_sel:[0,0,0] op_sel_hi:[0,1,1] neg_lo:[0,0,0] neg_hi:[0,1,0]
	v_pk_fma_f32 v[190:191], v[154:155], v[168:169], v[190:191] op_sel:[0,0,0] op_sel_hi:[0,1,1] neg_lo:[0,0,0] neg_hi:[0,1,0]
	v_pk_fma_f32 v[196:197], v[148:149], v[128:129], v[196:197] op_sel:[0,1,0] op_sel_hi:[0,0,1] neg_lo:[0,0,1] neg_hi:[0,0,0]
	v_pk_fma_f32 v[198:199], v[150:151], v[170:171], v[198:199] op_sel:[0,0,0] op_sel_hi:[0,1,1] neg_lo:[0,0,0] neg_hi:[0,1,0]
	v_pk_add_f32 v[152:153], v[158:159], v[188:189] neg_lo:[0,1] neg_hi:[0,1]
	v_pk_add_f32 v[154:155], v[160:161], v[190:191] neg_lo:[0,1] neg_hi:[0,1]
	v_pk_add_f32 v[148:149], v[162:163], v[196:197] neg_lo:[0,1] neg_hi:[0,1]
	v_pk_add_f32 v[150:151], v[164:165], v[198:199] neg_lo:[0,1] neg_hi:[0,1]
	v_pk_add_f32 v[158:159], v[158:159], v[188:189]
	v_pk_add_f32 v[160:161], v[160:161], v[190:191]
	v_pk_add_f32 v[162:163], v[162:163], v[196:197]
	v_pk_add_f32 v[164:165], v[164:165], v[198:199]
	ds_write2_b64 v124, v[158:159], v[160:161] offset1:136
	ds_write2_b64 v156, v[162:163], v[164:165] offset0:16 offset1:152
	ds_write2_b64 v134, v[152:153], v[154:155] offset0:32 offset1:168
	ds_write2_b64 v132, v[148:149], v[150:151] offset0:48 offset1:184
	s_mov_b64 s[6:7], 0
	s_waitcnt lgkmcnt(0)
	s_barrier
	s_mov_b32 s0, 0
	s_mov_b64 s[6:7], -1
; #define LAS __attribute__((address_space(3)))
; __device__ __forceinline__ cf twc(cf ws, int k16) { if (k16 == 0) return ws; if (k16 == 4) return cf{ws.y, -ws.x}; return cmul(ws, cf{c16(k16), -s16(k16)}); }
; template <int LR> __device__ __forceinline__ void dit_reg(cf (&x)[1 << LR], cf w) {
;     constexpr int R = 1 << LR; cf wsv[LR]; wsv[0] = w;
; #pragma unroll
;     for (int s = 1; s < LR; ++s) wsv[s] = cmul(wsv[s - 1], wsv[s - 1]);
; #pragma unroll
;     for (int s = LR - 1; s >= 0; --s) { const int half = R >> (s + 1);
; #pragma unroll
;         for (int m0 = 0; m0 < R; m0 += 2 * half)
; #pragma unroll
;             for (int mm = 0; mm < half; ++mm) { const int ia = m0 + mm, ib = ia + half; const cf a = x[ia];
;                 const cf b = cmulc(x[ib], twc(wsv[s], (mm << s) * (16 / R)));
;                 x[ia] = cf{a.x + b.x, a.y + b.y}; x[ib] = cf{a.x - b.x, a.y - b.y}; } }
; }
; template <int LR, bool INV> __device__ __forceinline__ void fft_pass(ldsf2 buf, int base, int stride, int twi) {
;     constexpr int R = 1 << LR; cf x[R];
;     const v2f wv = ((ldsf2)((LAS unsigned char*)buf + 139264))[twi];
; #pragma unroll
;     for (int m = 0; m < R; ++m) { const v2f v = buf[base + m * stride]; x[m] = cf{v.x, v.y}; }
;     const cf w{wv.x, wv.y};
;     if (INV) dit_reg<LR>(x, w); else dif_reg<LR>(x, w);
; #pragma unroll
;     for (int m = 0; m < R; ++m) buf[base + m * stride] = mkv2(x[m].x, x[m].y);
; }
.LBB0_357:
	v_add_u32_e32 v69, s0, v68
	v_ashrrev_i32_e32 v72, 4, v69
	v_lshl_add_u32 v69, v69, 3, 0
	v_add_u32_e32 v73, 0x22000, v69
	ds_read_b64 v[88:89], v73
	v_lshl_add_u32 v69, v72, 3, v69
	ds_read2st64_b64 v[72:75], v69 offset1:17
	ds_read2st64_b64 v[76:79], v69 offset0:34 offset1:51
	ds_read2st64_b64 v[80:83], v69 offset0:68 offset1:85
	ds_read2st64_b64 v[84:87], v69 offset0:102 offset1:119
	s_movk_i32 s0, 0x200
	v_add_u32_e32 v118, s0, v68
	v_ashrrev_i32_e32 v120, 4, v118
	v_lshl_add_u32 v118, v118, 3, 0
	v_add_u32_e32 v122, 0x22000, v118
	ds_read_b64 v[124:125], v122
	v_lshl_add_u32 v118, v120, 3, v118
	ds_read2st64_b64 v[126:129], v118 offset1:17
	ds_read2st64_b64 v[130:133], v118 offset0:34 offset1:51
	ds_read2st64_b64 v[148:151], v118 offset0:68 offset1:85
	ds_read2st64_b64 v[152:155], v118 offset0:102 offset1:119
	s_waitcnt lgkmcnt(5)
	v_pk_add_f32 v[90:91], v[88:89], v[88:89] op_sel:[0,1] op_sel_hi:[1,0] neg_lo:[0,0] neg_hi:[0,1]
	v_pk_mul_f32 v[96:97], v[88:89], v[88:89] op_sel:[1,1] op_sel_hi:[1,0]
	v_pk_mul_f32 v[92:93], v[90:91], s[16:17] op_sel:[0,0] op_sel_hi:[1,0]
	v_pk_fma_f32 v[96:97], v[88:89], v[88:89], v[96:97] op_sel:[0,0,0] op_sel_hi:[0,1,1] neg_lo:[0,0,1] neg_hi:[0,0,0]
	v_pk_mul_f32 v[94:95], v[90:91], s[16:17] op_sel:[1,0] op_sel_hi:[0,0] neg_lo:[0,0] neg_hi:[1,0]
	s_nop 0
	v_pk_mul_f32 v[98:99], v[96:97], v[96:97] op_sel:[1,1] op_sel_hi:[1,0]
	s_nop 0
	v_pk_fma_f32 v[98:99], v[96:97], v[96:97], v[98:99] op_sel:[0,0,0] op_sel_hi:[0,1,1] neg_lo:[0,0,1] neg_hi:[0,0,0]
	v_pk_mul_f32 v[100:101], v[74:75], v[98:99] op_sel:[1,1] op_sel_hi:[1,0]
	v_pk_mul_f32 v[102:103], v[78:79], v[98:99] op_sel:[1,1] op_sel_hi:[1,0]
	v_pk_mul_f32 v[104:105], v[82:83], v[98:99] op_sel:[1,1] op_sel_hi:[1,0]
	v_pk_mul_f32 v[106:107], v[86:87], v[98:99] op_sel:[1,1] op_sel_hi:[1,0]
	v_pk_fma_f32 v[100:101], v[74:75], v[98:99], v[100:101] op_sel:[0,0,0] op_sel_hi:[0,1,1] neg_lo:[0,0,0] neg_hi:[0,1,0]
	v_pk_fma_f32 v[102:103], v[78:79], v[98:99], v[102:103] op_sel:[0,0,0] op_sel_hi:[0,1,1] neg_lo:[0,0,0] neg_hi:[0,1,0]
	v_pk_fma_f32 v[104:105], v[82:83], v[98:99], v[104:105] op_sel:[0,0,0] op_sel_hi:[0,1,1] neg_lo:[0,0,0] neg_hi:[0,1,0]
	v_pk_fma_f32 v[106:107], v[86:87], v[98:99], v[106:107] op_sel:[0,0,0] op_sel_hi:[0,1,1] neg_lo:[0,0,0] neg_hi:[0,1,0]
	v_pk_add_f32 v[74:75], v[72:73], v[100:101] neg_lo:[0,1] neg_hi:[0,1]
	v_pk_add_f32 v[78:79], v[76:77], v[102:103] neg_lo:[0,1] neg_hi:[0,1]
	v_pk_add_f32 v[82:83], v[80:81], v[104:105] neg_lo:[0,1] neg_hi:[0,1]
	v_pk_add_f32 v[86:87], v[84:85], v[106:107] neg_lo:[0,1] neg_hi:[0,1]
	v_pk_add_f32 v[72:73], v[72:73], v[100:101]
	v_pk_add_f32 v[76:77], v[76:77], v[102:103]
	v_pk_add_f32 v[80:81], v[80:81], v[104:105]
	v_pk_add_f32 v[84:85], v[84:85], v[106:107]
	v_pk_mul_f32 v[100:101], v[76:77], v[96:97] op_sel:[1,1] op_sel_hi:[1,0]
	v_pk_mul_f32 v[102:103], v[78:79], v[96:97] op_sel:[1,0] op_sel_hi:[1,1]
	v_pk_mul_f32 v[104:105], v[84:85], v[96:97] op_sel:[1,1] op_sel_hi:[1,0]
	v_pk_mul_f32 v[106:107], v[86:87], v[96:97] op_sel:[1,0] op_sel_hi:[1,1]
	v_pk_fma_f32 v[100:101], v[76:77], v[96:97], v[100:101] op_sel:[0,0,0] op_sel_hi:[0,1,1] neg_lo:[0,0,0] neg_hi:[0,1,0]
	v_pk_fma_f32 v[102:103], v[78:79], v[96:97], v[102:103] op_sel:[0,1,0] op_sel_hi:[0,0,1] neg_lo:[0,0,1] neg_hi:[0,0,0]
	v_pk_fma_f32 v[104:105], v[84:85], v[96:97], v[104:105] op_sel:[0,0,0] op_sel_hi:[0,1,1] neg_lo:[0,0,0] neg_hi:[0,1,0]
	v_pk_fma_f32 v[106:107], v[86:87], v[96:97], v[106:107] op_sel:[0,1,0] op_sel_hi:[0,0,1] neg_lo:[0,0,1] neg_hi:[0,0,0]
	v_pk_add_f32 v[76:77], v[72:73], v[100:101] neg_lo:[0,1] neg_hi:[0,1]
	v_pk_add_f32 v[78:79], v[74:75], v[102:103] neg_lo:[0,1] neg_hi:[0,1]
	v_pk_add_f32 v[84:85], v[80:81], v[104:105] neg_lo:[0,1] neg_hi:[0,1]
	v_pk_add_f32 v[86:87], v[82:83], v[106:107] neg_lo:[0,1] neg_hi:[0,1]
	v_pk_add_f32 v[72:73], v[72:73], v[100:101]
	v_pk_add_f32 v[74:75], v[74:75], v[102:103]
	v_pk_add_f32 v[80:81], v[80:81], v[104:105]
	v_pk_add_f32 v[82:83], v[82:83], v[106:107]
	v_pk_mul_f32 v[100:101], v[80:81], v[88:89] op_sel:[1,1] op_sel_hi:[1,0]
	v_pk_mul_f32 v[102:103], v[82:83], v[92:93] op_sel:[1,1] op_sel_hi:[1,0]
	v_pk_mul_f32 v[104:105], v[84:85], v[88:89] op_sel:[1,0] op_sel_hi:[1,1]
	v_pk_mul_f32 v[106:107], v[86:87], v[94:95] op_sel:[1,1] op_sel_hi:[1,0]
	v_pk_fma_f32 v[100:101], v[80:81], v[88:89], v[100:101] op_sel:[0,0,0] op_sel_hi:[0,1,1] neg_lo:[0,0,0] neg_hi:[0,1,0]
	v_pk_fma_f32 v[102:103], v[82:83], v[92:93], v[102:103] op_sel:[0,0,0] op_sel_hi:[0,1,1] neg_lo:[0,0,0] neg_hi:[0,1,0]
	v_pk_fma_f32 v[104:105], v[84:85], v[88:89], v[104:105] op_sel:[0,1,0] op_sel_hi:[0,0,1] neg_lo:[0,0,1] neg_hi:[0,0,0]
	v_pk_fma_f32 v[106:107], v[86:87], v[94:95], v[106:107] op_sel:[0,0,0] op_sel_hi:[0,1,1] neg_lo:[0,0,0] neg_hi:[0,1,0]
	v_pk_add_f32 v[80:81], v[72:73], v[100:101] neg_lo:[0,1] neg_hi:[0,1]
	v_pk_add_f32 v[82:83], v[74:75], v[102:103] neg_lo:[0,1] neg_hi:[0,1]
	v_pk_add_f32 v[84:85], v[76:77], v[104:105] neg_lo:[0,1] neg_hi:[0,1]
	v_pk_add_f32 v[86:87], v[78:79], v[106:107] neg_lo:[0,1] neg_hi:[0,1]
	v_pk_add_f32 v[72:73], v[72:73], v[100:101]
	v_pk_add_f32 v[74:75], v[74:75], v[102:103]
	v_pk_add_f32 v[76:77], v[76:77], v[104:105]
	v_pk_add_f32 v[78:79], v[78:79], v[106:107]
	ds_write2st64_b64 v69, v[72:73], v[74:75] offset1:17
	ds_write2st64_b64 v69, v[76:77], v[78:79] offset0:34 offset1:51
	ds_write2st64_b64 v69, v[80:81], v[82:83] offset0:68 offset1:85
	ds_write2st64_b64 v69, v[84:85], v[86:87] offset0:102 offset1:119
	s_waitcnt lgkmcnt(4)
; __device__ __forceinline__ float bf2f(bf16_t b) { return __uint_as_float(((unsigned)b) << 16); }
; __device__ __forceinline__ cf twc(cf ws, int k16) { if (k16 == 0) return ws; if (k16 == 4) return cf{ws.y, -ws.x}; return cmul(ws, cf{c16(k16), -s16(k16)}); }
; template <int LR> __device__ __forceinline__ void dit_reg(cf (&x)[1 << LR], cf w) {
;     constexpr int R = 1 << LR; cf wsv[LR]; wsv[0] = w;
; #pragma unroll
;     for (int s = 1; s < LR; ++s) wsv[s] = cmul(wsv[s - 1], wsv[s - 1]);
; #pragma unroll
;     for (int s = LR - 1; s >= 0; --s) { const int half = R >> (s + 1);
; #pragma unroll
;         for (int m0 = 0; m0 < R; m0 += 2 * half)
; #pragma unroll
;             for (int mm = 0; mm < half; ++mm) { const int ia = m0 + mm, ib = ia + half; const cf a = x[ia];
;                 const cf b = cmulc(x[ib], twc(wsv[s], (mm << s) * (16 / R)));
;                 x[ia] = cf{a.x + b.x, a.y + b.y}; x[ib] = cf{a.x - b.x, a.y - b.y}; } }
; }
; __device__ __forceinline__ void sconv8(const Raw8& r, int n0, float w0, float w1, float w2, float b, float (&out)[8]) {
;     float a[10]; a[0] = n0 > 0 ? bf2f(r.eL) : 0.f; a[9] = n0 + 8 < SEQ ? bf2f(r.eR) : 0.f;
;     a[1] = __uint_as_float(r.body.x << 16); a[2] = __uint_as_float(r.body.x & 0xffff0000u); a[3] = __uint_as_float(r.body.y << 16); a[4] = __uint_as_float(r.body.y & 0xffff0000u);
;     a[5] = __uint_as_float(r.body.z << 16); a[6] = __uint_as_float(r.body.z & 0xffff0000u); a[7] = __uint_as_float(r.body.w << 16); a[8] = __uint_as_float(r.body.w & 0xffff0000u);
; #pragma unroll
;     for (int k = 0; k < 8; ++k) out[k] = w0 * a[k] + w1 * a[k + 1] + w2 * a[k + 2] + b;
; }
	v_pk_add_f32 v[134:135], v[124:125], v[124:125] op_sel:[0,1] op_sel_hi:[1,0] neg_lo:[0,0] neg_hi:[0,1]
	v_pk_mul_f32 v[160:161], v[124:125], v[124:125] op_sel:[1,1] op_sel_hi:[1,0]
	v_pk_mul_f32 v[156:157], v[134:135], s[16:17] op_sel:[0,0] op_sel_hi:[1,0]
	v_pk_fma_f32 v[160:161], v[124:125], v[124:125], v[160:161] op_sel:[0,0,0] op_sel_hi:[0,1,1] neg_lo:[0,0,1] neg_hi:[0,0,0]
	v_pk_mul_f32 v[158:159], v[134:135], s[16:17] op_sel:[1,0] op_sel_hi:[0,0] neg_lo:[0,0] neg_hi:[1,0]
	s_nop 0
	v_pk_mul_f32 v[162:163], v[160:161], v[160:161] op_sel:[1,1] op_sel_hi:[1,0]
	s_nop 0
	v_pk_fma_f32 v[162:163], v[160:161], v[160:161], v[162:163] op_sel:[0,0,0] op_sel_hi:[0,1,1] neg_lo:[0,0,1] neg_hi:[0,0,0]
	v_pk_mul_f32 v[164:165], v[128:129], v[162:163] op_sel:[1,1] op_sel_hi:[1,0]
	v_pk_mul_f32 v[166:167], v[132:133], v[162:163] op_sel:[1,1] op_sel_hi:[1,0]
	v_pk_mul_f32 v[168:169], v[150:151], v[162:163] op_sel:[1,1] op_sel_hi:[1,0]
	v_pk_mul_f32 v[170:171], v[154:155], v[162:163] op_sel:[1,1] op_sel_hi:[1,0]
	v_pk_fma_f32 v[164:165], v[128:129], v[162:163], v[164:165] op_sel:[0,0,0] op_sel_hi:[0,1,1] neg_lo:[0,0,0] neg_hi:[0,1,0]
	v_pk_fma_f32 v[166:167], v[132:133], v[162:163], v[166:167] op_sel:[0,0,0] op_sel_hi:[0,1,1] neg_lo:[0,0,0] neg_hi:[0,1,0]
	v_pk_fma_f32 v[168:169], v[150:151], v[162:163], v[168:169] op_sel:[0,0,0] op_sel_hi:[0,1,1] neg_lo:[0,0,0] neg_hi:[0,1,0]
	v_pk_fma_f32 v[170:171], v[154:155], v[162:163], v[170:171] op_sel:[0,0,0] op_sel_hi:[0,1,1] neg_lo:[0,0,0] neg_hi:[0,1,0]
	v_pk_add_f32 v[128:129], v[126:127], v[164:165] neg_lo:[0,1] neg_hi:[0,1]
	v_pk_add_f32 v[132:133], v[130:131], v[166:167] neg_lo:[0,1] neg_hi:[0,1]
	v_pk_add_f32 v[150:151], v[148:149], v[168:169] neg_lo:[0,1] neg_hi:[0,1]
	v_pk_add_f32 v[154:155], v[152:153], v[170:171] neg_lo:[0,1] neg_hi:[0,1]
	v_pk_add_f32 v[126:127], v[126:127], v[164:165]
	v_pk_add_f32 v[130:131], v[130:131], v[166:167]
	v_pk_add_f32 v[148:149], v[148:149], v[168:169]
	v_pk_add_f32 v[152:153], v[152:153], v[170:171]
	v_pk_mul_f32 v[164:165], v[130:131], v[160:161] op_sel:[1,1] op_sel_hi:[1,0]
	v_pk_mul_f32 v[166:167], v[132:133], v[160:161] op_sel:[1,0] op_sel_hi:[1,1]
	v_pk_mul_f32 v[168:169], v[152:153], v[160:161] op_sel:[1,1] op_sel_hi:[1,0]
	v_pk_mul_f32 v[170:171], v[154:155], v[160:161] op_sel:[1,0] op_sel_hi:[1,1]
	v_pk_fma_f32 v[164:165], v[130:131], v[160:161], v[164:165] op_sel:[0,0,0] op_sel_hi:[0,1,1] neg_lo:[0,0,0] neg_hi:[0,1,0]
	v_pk_fma_f32 v[166:167], v[132:133], v[160:161], v[166:167] op_sel:[0,1,0] op_sel_hi:[0,0,1] neg_lo:[0,0,1] neg_hi:[0,0,0]
	v_pk_fma_f32 v[168:169], v[152:153], v[160:161], v[168:169] op_sel:[0,0,0] op_sel_hi:[0,1,1] neg_lo:[0,0,0] neg_hi:[0,1,0]
	v_pk_fma_f32 v[170:171], v[154:155], v[160:161], v[170:171] op_sel:[0,1,0] op_sel_hi:[0,0,1] neg_lo:[0,0,1] neg_hi:[0,0,0]
	v_pk_add_f32 v[130:131], v[126:127], v[164:165] neg_lo:[0,1] neg_hi:[0,1]
	v_pk_add_f32 v[132:133], v[128:129], v[166:167] neg_lo:[0,1] neg_hi:[0,1]
	v_pk_add_f32 v[152:153], v[148:149], v[168:169] neg_lo:[0,1] neg_hi:[0,1]
	v_pk_add_f32 v[154:155], v[150:151], v[170:171] neg_lo:[0,1] neg_hi:[0,1]
	v_pk_add_f32 v[126:127], v[126:127], v[164:165]
	v_pk_add_f32 v[128:129], v[128:129], v[166:167]
	v_pk_add_f32 v[148:149], v[148:149], v[168:169]
	v_pk_add_f32 v[150:151], v[150:151], v[170:171]
	v_pk_mul_f32 v[164:165], v[148:149], v[124:125] op_sel:[1,1] op_sel_hi:[1,0]
	v_pk_mul_f32 v[166:167], v[150:151], v[156:157] op_sel:[1,1] op_sel_hi:[1,0]
	v_pk_mul_f32 v[168:169], v[152:153], v[124:125] op_sel:[1,0] op_sel_hi:[1,1]
	v_pk_mul_f32 v[170:171], v[154:155], v[158:159] op_sel:[1,1] op_sel_hi:[1,0]
	v_pk_fma_f32 v[164:165], v[148:149], v[124:125], v[164:165] op_sel:[0,0,0] op_sel_hi:[0,1,1] neg_lo:[0,0,0] neg_hi:[0,1,0]
	v_pk_fma_f32 v[166:167], v[150:151], v[156:157], v[166:167] op_sel:[0,0,0] op_sel_hi:[0,1,1] neg_lo:[0,0,0] neg_hi:[0,1,0]
	v_pk_fma_f32 v[168:169], v[152:153], v[124:125], v[168:169] op_sel:[0,1,0] op_sel_hi:[0,0,1] neg_lo:[0,0,1] neg_hi:[0,0,0]
	v_pk_fma_f32 v[170:171], v[154:155], v[158:159], v[170:171] op_sel:[0,0,0] op_sel_hi:[0,1,1] neg_lo:[0,0,0] neg_hi:[0,1,0]
	v_pk_add_f32 v[148:149], v[126:127], v[164:165] neg_lo:[0,1] neg_hi:[0,1]
	v_pk_add_f32 v[150:151], v[128:129], v[166:167] neg_lo:[0,1] neg_hi:[0,1]
	v_pk_add_f32 v[152:153], v[130:131], v[168:169] neg_lo:[0,1] neg_hi:[0,1]
	v_pk_add_f32 v[154:155], v[132:133], v[170:171] neg_lo:[0,1] neg_hi:[0,1]
	v_pk_add_f32 v[126:127], v[126:127], v[164:165]
	v_pk_add_f32 v[128:129], v[128:129], v[166:167]
	v_pk_add_f32 v[130:131], v[130:131], v[168:169]
	v_pk_add_f32 v[132:133], v[132:133], v[170:171]
	ds_write2st64_b64 v118, v[126:127], v[128:129] offset1:17
	ds_write2st64_b64 v118, v[130:131], v[132:133] offset0:34 offset1:51
	ds_write2st64_b64 v118, v[148:149], v[150:151] offset0:68 offset1:85
	ds_write2st64_b64 v118, v[152:153], v[154:155] offset0:102 offset1:119
	s_mov_b64 s[6:7], 0
	s_waitcnt vmcnt(5)
	v_lshlrev_b32_e32 v68, 16, v143
	v_cndmask_b32_e64 v69, 0, v68, s[42:43]
	s_waitcnt vmcnt(3)
; __device__ __forceinline__ uint4 ntld_u4(const void* p) { const ntu4_t v = __builtin_nontemporal_load((const ntu4_t*)p); return make_uint4(v.x, v.y, v.z, v.w); }
; __device__ __forceinline__ float bf2f(bf16_t b) { return __uint_as_float(((unsigned)b) << 16); }
; __device__ __forceinline__ Raw8 load_raw8(const bf16_t* __restrict__ row, int n0) {
;     Raw8 r; r.body = ntld_u4(row + n0); r.eL = row[n0 > 0 ? n0 - 1 : 0]; r.eR = row[n0 + 8 < SEQ ? n0 + 8 : SEQ - 1]; return r; }
; __device__ __forceinline__ void sconv8(const Raw8& r, int n0, float w0, float w1, float w2, float b, float (&out)[8]) {
;     float a[10]; a[0] = n0 > 0 ? bf2f(r.eL) : 0.f; a[9] = n0 + 8 < SEQ ? bf2f(r.eR) : 0.f;
;     a[1] = __uint_as_float(r.body.x << 16); a[2] = __uint_as_float(r.body.x & 0xffff0000u); a[3] = __uint_as_float(r.body.y << 16); a[4] = __uint_as_float(r.body.y & 0xffff0000u);
;     a[5] = __uint_as_float(r.body.z << 16); a[6] = __uint_as_float(r.body.z & 0xffff0000u); a[7] = __uint_as_float(r.body.w << 16); a[8] = __uint_as_float(r.body.w & 0xffff0000u);
; #pragma unroll
;     for (int k = 0; k < 8; ++k) out[k] = w0 * a[k] + w1 * a[k + 1] + w2 * a[k + 2] + b;
; }
; __device__ void ph_hyena_fft(const Params& P, int j, const bf16_t* __restrict__ projAT, const float* __restrict__ kf, bf16_t* __restrict__ yaT, unsigned char* lds_raw) {
;     ...
;             { float xa[8], xb[8]; sconv8(xa0, n0, wa0, wa1, wa2, ba, xa); sconv8(xa1, n0, wa0, wa1, wa2, ba, xb);
	v_lshlrev_b32_e32 v68, 16, v144
	v_lshlrev_b32_e32 v75, 16, v5
	v_cndmask_b32_e64 v73, 0, v68, s[44:45]
	v_lshlrev_b32_e32 v74, 16, v4
	v_and_b32_e32 v76, 0xffff0000, v4
	v_mov_b32_e32 v68, v75
	v_and_b32_e32 v77, 0xffff0000, v5
	v_mov_b32_e32 v80, v74
	v_mov_b32_e32 v81, v76
	v_pk_mul_f32 v[68:69], v[56:57], v[68:69]
	v_lshlrev_b32_e32 v79, 16, v6
	v_pk_fma_f32 v[68:69], v[56:57], v[80:81], v[68:69] op_sel:[0,0,1] op_sel_hi:[1,1,0]
	v_pk_mul_f32 v[80:81], v[32:33], v[76:77]
	v_and_b32_e32 v5, 0xffff0000, v7
	v_mov_b32_e32 v78, v75
	v_pk_fma_f32 v[74:75], v[30:31], v[74:75], v[80:81]
	v_and_b32_e32 v81, 16, v7
	v_and_b32_e32 v80, 0xffff0000, v6
	v_lshlrev_b32_e32 v7, 16, v7
	v_pk_fma_f32 v[68:69], v[34:35], v[76:77], v[68:69]
	v_mov_b32_e32 v6, v80
	v_mov_b32_e32 v4, v80
	v_pk_mov_b32 v[76:77], v[76:77], v[80:81] op_sel:[1,0]
	v_mov_b32_e32 v80, v79
	v_mov_b32_e32 v81, v7
	v_pk_mul_f32 v[80:81], v[32:33], v[80:81]
	v_pk_fma_f32 v[74:75], v[34:35], v[78:79], v[74:75]
	v_pk_fma_f32 v[76:77], v[30:31], v[76:77], v[80:81]
	v_mov_b32_e32 v78, v5
	v_pk_fma_f32 v[80:81], v[34:35], v[4:5], v[76:77]
	v_pk_mul_f32 v[4:5], v[56:57], v[78:79]
	v_mov_b32_e32 v72, v7
	v_pk_fma_f32 v[4:5], v[56:57], v[6:7], v[4:5] op_sel:[0,0,1] op_sel_hi:[1,1,0]
	s_waitcnt vmcnt(1)
	v_lshlrev_b32_e32 v77, 16, v1
	v_pk_fma_f32 v[72:73], v[34:35], v[72:73], v[4:5]
	v_lshlrev_b32_e32 v4, 16, v139
	v_cndmask_b32_e64 v5, 0, v4, s[42:43]
	s_waitcnt vmcnt(0)
	v_lshlrev_b32_e32 v4, 16, v141
	v_cndmask_b32_e64 v7, 0, v4, s[44:45]
	v_lshlrev_b32_e32 v76, 16, v0
	v_and_b32_e32 v78, 0xffff0000, v0
	v_mov_b32_e32 v4, v77
	v_mov_b32_e32 v84, v76
	v_mov_b32_e32 v85, v78
	v_pk_mul_f32 v[4:5], v[56:57], v[4:5]
	v_and_b32_e32 v79, 0xffff0000, v1
	v_pk_fma_f32 v[4:5], v[56:57], v[84:85], v[4:5] op_sel:[0,0,1] op_sel_hi:[1,1,0]
	v_lshlrev_b32_e32 v83, 16, v2
	v_pk_fma_f32 v[84:85], v[34:35], v[78:79], v[4:5]
	v_pk_mul_f32 v[4:5], v[32:33], v[78:79]
	v_mov_b32_e32 v82, v77
	v_pk_fma_f32 v[4:5], v[30:31], v[76:77], v[4:5]
	v_and_b32_e32 v1, 0xffff0000, v3
	v_pk_fma_f32 v[86:87], v[34:35], v[82:83], v[4:5]
	v_and_b32_e32 v5, 16, v3
	v_lshlrev_b32_e32 v3, 16, v3
	v_and_b32_e32 v4, 0xffff0000, v2
	v_mov_b32_e32 v76, v83
	v_mov_b32_e32 v77, v3
	v_mov_b32_e32 v2, v4
	v_mov_b32_e32 v0, v4
	v_pk_mov_b32 v[4:5], v[78:79], v[4:5] op_sel:[1,0]
	v_pk_mul_f32 v[76:77], v[32:33], v[76:77]
	v_mov_b32_e32 v82, v1
	v_pk_fma_f32 v[4:5], v[30:31], v[4:5], v[76:77]
	s_waitcnt lgkmcnt(0)
	s_barrier
; __device__ __forceinline__ uint4 ntld_u4(const void* p) { const ntu4_t v = __builtin_nontemporal_load((const ntu4_t*)p); return make_uint4(v.x, v.y, v.z, v.w); }
; __device__ __forceinline__ void lds_barrier() { asm volatile("s_waitcnt lgkmcnt(0)\n\ts_barrier" ::: "memory"); }
; __device__ void ph_hyena_fft(const Params& P, int j, const bf16_t* __restrict__ projAT, const float* __restrict__ kf, bf16_t* __restrict__ yaT, unsigned char* lds_raw) {
;     ...
;             const size_t o0 = (size_t)(2 * bp) * SEQ, o1 = o0 + SEQ;
;             float va[8], vb[8];
;             { const Raw8 r0 = load_raw8(vrow + o0, n0), r1 = load_raw8(vrow + o1, n0); sconv8(r0, n0, wv0, wv1, wv2, bv, va); sconv8(r1, n0, wv0, wv1, wv2, bv, vb); }
; #pragma unroll
;             for (int k = 0; k < 8; ++k) { buf[ph0 + k] = mkv2(va[k], vb[k]); buf[ph0 + 4352 + k] = mkv2(0.f, 0.f); }
;             const Raw8 xa0 = load_raw8(x1row + o0, n0), xa1 = load_raw8(x1row + o1, n0);
;             lds_barrier();
;             fft_conv(buf, spec1);
;             { float xa[8], xb[8]; sconv8(xa0, n0, wa0, wa1, wa2, ba, xa); sconv8(xa1, n0, wa0, wa1, wa2, ba, xb);
; #pragma unroll
;               for (int k = 0; k < 8; ++k) { const v2f y = buf[ph0 + k]; va[k] = xa[k] * (y.x * invN + sk0 * va[k]); vb[k] = xb[k] * (y.y * invN + sk0 * vb[k]);
;                   buf[ph0 + k] = mkv2(va[k], vb[k]); buf[ph0 + 4352 + k] = mkv2(0.f, 0.f); } }
;             const Raw8 xb0 = load_raw8(x2row + o0, n0), xb1 = load_raw8(x2row + o1, n0);
;             const uint4 g0 = ntld_u4(grow + o0 + n0), g1 = ntld_u4(grow + o1 + n0);
	v_mov_b32_e32 v6, v3
	v_pk_fma_f32 v[78:79], v[34:35], v[0:1], v[4:5]
	v_pk_mul_f32 v[0:1], v[56:57], v[82:83]
	v_pk_add_f32 v[74:75], v[36:37], v[74:75]
	v_pk_fma_f32 v[0:1], v[56:57], v[2:3], v[0:1] op_sel:[0,0,1] op_sel_hi:[1,1,0]
	v_pk_add_f32 v[68:69], v[36:37], v[68:69]
	v_pk_fma_f32 v[82:83], v[34:35], v[6:7], v[0:1]
	ds_read2_b64 v[0:3], v145 offset1:1
	ds_read2_b64 v[4:7], v145 offset0:2 offset1:3
	s_mov_b32 s14, 0
	s_mov_b32 s15, s14
	s_mov_b32 s0, s14
	s_waitcnt lgkmcnt(1)
	v_mov_b32_e32 v76, v0
	s_waitcnt lgkmcnt(0)
	v_mov_b32_e32 v77, v4
	v_mov_b32_e32 v4, v1
	v_pk_mul_f32 v[0:1], v[4:5], s[80:81] op_sel_hi:[1,0]
	v_mov_b32_e32 v4, v2
	v_mov_b32_e32 v5, v6
	v_pk_mul_f32 v[4:5], v[4:5], s[80:81] op_sel_hi:[1,0]
	v_pk_mul_f32 v[76:77], v[76:77], s[80:81] op_sel_hi:[1,0]
	v_pk_fma_f32 v[4:5], v[44:45], v[62:63], v[4:5]
	v_mov_b32_e32 v6, v3
	v_pk_fma_f32 v[64:65], v[44:45], v[64:65], v[76:77]
	v_pk_mul_f32 v[74:75], v[74:75], v[4:5]
	v_pk_mul_f32 v[2:3], v[6:7], s[80:81] op_sel_hi:[1,0]
	v_pk_add_f32 v[4:5], v[36:37], v[84:85]
	v_pk_fma_f32 v[0:1], v[44:45], v[66:67], v[0:1]
	v_pk_mul_f32 v[76:77], v[68:69], v[64:65]
	v_pk_add_f32 v[6:7], v[36:37], v[86:87]
	v_pk_mul_f32 v[68:69], v[4:5], v[0:1]
	v_pk_fma_f32 v[0:1], v[44:45], v[70:71], v[2:3]
	s_mov_b32 s1, s14
	v_pk_mul_f32 v[66:67], v[6:7], v[0:1]
	v_mov_b32_e32 v0, v76
	v_mov_b32_e32 v1, v68
	v_mov_b32_e32 v2, v74
	v_mov_b32_e32 v3, v66
	v_mov_b64_e32 v[88:89], s[14:15]
	v_mov_b64_e32 v[90:91], s[0:1]
	ds_write2_b64 v145, v[0:1], v[2:3] offset1:1
	v_mov_b32_e32 v0, v77
	v_mov_b32_e32 v1, v69
	v_mov_b32_e32 v2, v75
	v_mov_b32_e32 v3, v67
	ds_write2_b64 v142, v[88:89], v[90:91] offset1:1
	ds_write2_b64 v145, v[0:1], v[2:3] offset0:2 offset1:3
	ds_write2_b64 v138, v[88:89], v[90:91] offset1:1
	ds_read2_b64 v[0:3], v145 offset0:4 offset1:5
	ds_read2_b64 v[4:7], v145 offset0:6 offset1:7
	v_pk_add_f32 v[70:71], v[36:37], v[72:73]
	v_pk_add_f32 v[64:65], v[36:37], v[80:81]
	s_lshl_b32 s62, s11, 1
	s_waitcnt lgkmcnt(1)
	v_mov_b32_e32 v62, v0
	s_waitcnt lgkmcnt(0)
	v_mov_b32_e32 v63, v4
	v_mov_b32_e32 v4, v1
	v_pk_mul_f32 v[0:1], v[4:5], s[80:81] op_sel_hi:[1,0]
	v_mov_b32_e32 v4, v2
	v_mov_b32_e32 v5, v6
	v_pk_mul_f32 v[4:5], v[4:5], s[80:81] op_sel_hi:[1,0]
	v_pk_mul_f32 v[62:63], v[62:63], s[80:81] op_sel_hi:[1,0]
	v_pk_fma_f32 v[4:5], v[44:45], v[10:11], v[4:5]
	v_mov_b32_e32 v6, v3
	v_pk_fma_f32 v[8:9], v[44:45], v[8:9], v[62:63]
	v_pk_mul_f32 v[70:71], v[70:71], v[4:5]
	v_pk_mul_f32 v[2:3], v[6:7], s[80:81] op_sel_hi:[1,0]
	v_pk_add_f32 v[4:5], v[36:37], v[78:79]
	v_pk_fma_f32 v[0:1], v[44:45], v[12:13], v[0:1]
	v_pk_mul_f32 v[72:73], v[64:65], v[8:9]
	v_pk_add_f32 v[6:7], v[36:37], v[82:83]
	v_pk_mul_f32 v[64:65], v[4:5], v[0:1]
	v_pk_fma_f32 v[0:1], v[44:45], v[14:15], v[2:3]
	v_mov_b32_e32 v2, v70
	v_pk_mul_f32 v[62:63], v[6:7], v[0:1]
	v_mov_b32_e32 v0, v72
	v_mov_b32_e32 v1, v64
	v_mov_b32_e32 v3, v62
	s_add_u32 s0, s61, s62
	ds_write2_b64 v145, v[0:1], v[2:3] offset0:4 offset1:5
	v_mov_b32_e32 v0, v73
	v_mov_b32_e32 v1, v65
	v_mov_b32_e32 v2, v71
	v_mov_b32_e32 v3, v63
	s_addc_u32 s1, s52, 0
	ds_write2_b64 v140, v[88:89], v[90:91] offset1:1
	ds_write2_b64 v145, v[0:1], v[2:3] offset0:6 offset1:7
	ds_write2_b64 v137, v[88:89], v[90:91] offset1:1
	v_lshl_add_u64 v[0:1], s[0:1], 0, v[16:17]
	s_lshl_b32 s6, s10, 1
	global_load_dwordx4 v[4:7], v[0:1], off nt
	global_load_ushort v147, v146, s[0:1] offset:-2
	v_lshl_add_u64 v[0:1], s[0:1], 0, v[22:23]
	s_add_u32 s0, s61, s6
	s_addc_u32 s1, s52, 0
	global_load_ushort v148, v[0:1], off offset:16
	v_lshl_add_u64 v[0:1], s[0:1], 0, v[16:17]
	global_load_dwordx4 v[8:11], v[0:1], off nt
	global_load_ushort v149, v146, s[0:1] offset:-2
	v_lshl_add_u64 v[0:1], s[0:1], 0, v[22:23]
	s_mov_b32 s7, s63
	global_load_ushort v150, v[0:1], off offset:16
	v_lshl_add_u64 v[0:1], v[48:49], 0, s[62:63]
	global_load_dwordx4 v[12:15], v[0:1], off nt
	v_lshl_add_u64 v[0:1], v[48:49], 0, s[6:7]
	global_load_dwordx4 v[0:3], v[0:1], off nt
	s_cmp_eq_u32 s53, 3
	s_cbranch_scc1 .Lhy_nopf
	s_add_i32 s100, s53, 1
	s_lshl_b32 s100, s100, 14
	s_add_u32 s100, s47, s100
	s_addc_u32 s101, s58, 0
	v_lshl_add_u64 v[188:189], s[100:101], 0, v[16:17]
	v_lshl_add_u64 v[190:191], s[100:101], 0, v[22:23]
	global_load_ushort v184, v146, s[100:101] offset:-2
	global_load_dwordx4 v[176:179], v[188:189], off nt
	s_add_u32 s100, s100, 0x2000
	s_addc_u32 s101, s101, 0
	v_lshl_add_u64 v[188:189], s[100:101], 0, v[22:23]
	global_load_ushort v185, v146, s[100:101] offset:-2
	global_load_ushort v186, v[188:189], off offset:16
	global_load_ushort v187, v[190:191], off offset:16
	v_lshl_add_u64 v[188:189], s[100:101], 0, v[16:17]
	global_load_dwordx4 v[180:183], v[188:189], off nt

; #define LAS __attribute__((address_space(3)))
; __device__ __forceinline__ cf twc(cf ws, int k16) { if (k16 == 0) return ws; if (k16 == 4) return cf{ws.y, -ws.x}; return cmul(ws, cf{c16(k16), -s16(k16)}); }
; template <int LR> __device__ __forceinline__ void dif_reg(cf (&x)[1 << LR], cf w) {
;     constexpr int R = 1 << LR; cf ws = w;
; #pragma unroll
;     for (int s = 0; s < LR; ++s) { const int half = R >> (s + 1);
; #pragma unroll
;         for (int m0 = 0; m0 < R; m0 += 2 * half)
; #pragma unroll
;             for (int mm = 0; mm < half; ++mm) { const int ia = m0 + mm, ib = ia + half; const cf a = x[ia], b = x[ib];
;                 x[ia] = cf{a.x + b.x, a.y + b.y}; const cf d{a.x - b.x, a.y - b.y};
;                 x[ib] = cmul(d, twc(ws, (mm << s) * (16 / R))); }
;         ws = cmul(ws, ws); }
; }
; template <int LR, bool INV> __device__ __forceinline__ void fft_pass(ldsf2 buf, int base, int stride, int twi) {
;     constexpr int R = 1 << LR; cf x[R];
;     const v2f wv = ((ldsf2)((LAS unsigned char*)buf + 139264))[twi];
; #pragma unroll
;     for (int m = 0; m < R; ++m) { const v2f v = buf[base + m * stride]; x[m] = cf{v.x, v.y}; }
;     const cf w{wv.x, wv.y};
;     if (INV) dit_reg<LR>(x, w); else dif_reg<LR>(x, w);
; #pragma unroll
;     for (int m = 0; m < R; ++m) buf[base + m * stride] = mkv2(x[m].x, x[m].y);
; }
.LBB0_359:
	v_add_u32_e32 v80, s14, v78
	v_ashrrev_i32_e32 v79, 4, v80
	v_lshl_add_u32 v80, v80, 3, 0
	v_add_u32_e32 v81, 0x22000, v80
	v_lshl_add_u32 v79, v79, 3, v80
	ds_read_b64 v[96:97], v81
	ds_read2st64_b64 v[80:83], v79 offset1:17
	ds_read2st64_b64 v[84:87], v79 offset0:68 offset1:85
	ds_read2st64_b64 v[88:91], v79 offset0:34 offset1:51
	ds_read2st64_b64 v[92:95], v79 offset0:102 offset1:119
	s_movk_i32 s14, 0x200
	v_add_u32_e32 v120, s14, v78
	v_ashrrev_i32_e32 v122, 4, v120
	v_lshl_add_u32 v120, v120, 3, 0
	v_add_u32_e32 v124, 0x22000, v120
	v_lshl_add_u32 v122, v122, 3, v120
	ds_read_b64 v[126:127], v124
	ds_read2st64_b64 v[128:131], v122 offset1:17
	ds_read2st64_b64 v[132:135], v122 offset0:68 offset1:85
	ds_read2st64_b64 v[136:139], v122 offset0:34 offset1:51
	ds_read2st64_b64 v[140:143], v122 offset0:102 offset1:119
	s_waitcnt lgkmcnt(5)
	v_pk_add_f32 v[98:99], v[96:97], v[96:97] op_sel:[0,1] op_sel_hi:[1,0] neg_lo:[0,0] neg_hi:[0,1]
	v_pk_mul_f32 v[104:105], v[96:97], v[96:97] op_sel:[1,1] op_sel_hi:[1,0]
	v_pk_mul_f32 v[100:101], v[98:99], s[16:17] op_sel:[0,0] op_sel_hi:[1,0]
	v_pk_fma_f32 v[104:105], v[96:97], v[96:97], v[104:105] op_sel:[0,0,0] op_sel_hi:[0,1,1] neg_lo:[0,0,1] neg_hi:[0,0,0]
	v_pk_mul_f32 v[102:103], v[98:99], s[16:17] op_sel:[1,0] op_sel_hi:[0,0] neg_lo:[0,0] neg_hi:[1,0]
	s_nop 0
	v_pk_mul_f32 v[106:107], v[104:105], v[104:105] op_sel:[1,1] op_sel_hi:[1,0]
	s_nop 0
	v_pk_fma_f32 v[106:107], v[104:105], v[104:105], v[106:107] op_sel:[0,0,0] op_sel_hi:[0,1,1] neg_lo:[0,0,1] neg_hi:[0,0,0]
	v_pk_add_f32 v[108:109], v[80:81], v[84:85] neg_lo:[0,1] neg_hi:[0,1]
	v_pk_add_f32 v[110:111], v[82:83], v[86:87] neg_lo:[0,1] neg_hi:[0,1]
	v_pk_add_f32 v[112:113], v[88:89], v[92:93] neg_lo:[0,1] neg_hi:[0,1]
	v_pk_add_f32 v[114:115], v[90:91], v[94:95] neg_lo:[0,1] neg_hi:[0,1]
	v_pk_add_f32 v[80:81], v[80:81], v[84:85]
	v_pk_add_f32 v[82:83], v[82:83], v[86:87]
	v_pk_add_f32 v[88:89], v[88:89], v[92:93]
	v_pk_add_f32 v[90:91], v[90:91], v[94:95]
	v_pk_mul_f32 v[84:85], v[108:109], v[96:97] op_sel:[1,1] op_sel_hi:[1,0]
	v_pk_mul_f32 v[86:87], v[110:111], v[100:101] op_sel:[1,1] op_sel_hi:[1,0]
	v_pk_mul_f32 v[92:93], v[112:113], v[96:97] op_sel:[1,0] op_sel_hi:[1,1]
	v_pk_mul_f32 v[94:95], v[114:115], v[102:103] op_sel:[1,1] op_sel_hi:[1,0]
	v_pk_fma_f32 v[84:85], v[108:109], v[96:97], v[84:85] op_sel:[0,0,0] op_sel_hi:[0,1,1] neg_lo:[0,0,1] neg_hi:[0,0,0]
	v_pk_fma_f32 v[86:87], v[110:111], v[100:101], v[86:87] op_sel:[0,0,0] op_sel_hi:[0,1,1] neg_lo:[0,0,1] neg_hi:[0,0,0]
	v_pk_fma_f32 v[92:93], v[112:113], v[96:97], v[92:93] op_sel:[0,1,0] op_sel_hi:[0,0,1] neg_lo:[0,0,0] neg_hi:[0,1,0]
	v_pk_fma_f32 v[94:95], v[114:115], v[102:103], v[94:95] op_sel:[0,0,0] op_sel_hi:[0,1,1] neg_lo:[0,0,1] neg_hi:[0,0,0]
	v_pk_add_f32 v[108:109], v[80:81], v[88:89] neg_lo:[0,1] neg_hi:[0,1]
	v_pk_add_f32 v[110:111], v[82:83], v[90:91] neg_lo:[0,1] neg_hi:[0,1]
	v_pk_add_f32 v[112:113], v[84:85], v[92:93] neg_lo:[0,1] neg_hi:[0,1]
	v_pk_add_f32 v[114:115], v[86:87], v[94:95] neg_lo:[0,1] neg_hi:[0,1]
	v_pk_add_f32 v[80:81], v[80:81], v[88:89]
	v_pk_add_f32 v[82:83], v[82:83], v[90:91]
	v_pk_add_f32 v[84:85], v[84:85], v[92:93]
	v_pk_add_f32 v[86:87], v[86:87], v[94:95]
	v_pk_mul_f32 v[88:89], v[108:109], v[104:105] op_sel:[1,1] op_sel_hi:[1,0]
	v_pk_mul_f32 v[90:91], v[110:111], v[104:105] op_sel:[1,0] op_sel_hi:[1,1]
	v_pk_mul_f32 v[92:93], v[112:113], v[104:105] op_sel:[1,1] op_sel_hi:[1,0]
	v_pk_mul_f32 v[94:95], v[114:115], v[104:105] op_sel:[1,0] op_sel_hi:[1,1]
	v_pk_fma_f32 v[88:89], v[108:109], v[104:105], v[88:89] op_sel:[0,0,0] op_sel_hi:[0,1,1] neg_lo:[0,0,1] neg_hi:[0,0,0]
	v_pk_fma_f32 v[90:91], v[110:111], v[104:105], v[90:91] op_sel:[0,1,0] op_sel_hi:[0,0,1] neg_lo:[0,0,0] neg_hi:[0,1,0]
	v_pk_fma_f32 v[92:93], v[112:113], v[104:105], v[92:93] op_sel:[0,0,0] op_sel_hi:[0,1,1] neg_lo:[0,0,1] neg_hi:[0,0,0]
	v_pk_fma_f32 v[94:95], v[114:115], v[104:105], v[94:95] op_sel:[0,1,0] op_sel_hi:[0,0,1] neg_lo:[0,0,0] neg_hi:[0,1,0]
	v_pk_add_f32 v[108:109], v[80:81], v[82:83] neg_lo:[0,1] neg_hi:[0,1]
	v_pk_add_f32 v[110:111], v[88:89], v[90:91] neg_lo:[0,1] neg_hi:[0,1]
	v_pk_add_f32 v[112:113], v[84:85], v[86:87] neg_lo:[0,1] neg_hi:[0,1]
	v_pk_add_f32 v[114:115], v[92:93], v[94:95] neg_lo:[0,1] neg_hi:[0,1]
	v_pk_add_f32 v[80:81], v[80:81], v[82:83]
	v_pk_add_f32 v[88:89], v[88:89], v[90:91]
	v_pk_add_f32 v[84:85], v[84:85], v[86:87]
	v_pk_add_f32 v[92:93], v[92:93], v[94:95]
	v_pk_mul_f32 v[82:83], v[108:109], v[106:107] op_sel:[1,1] op_sel_hi:[1,0]
	v_pk_mul_f32 v[90:91], v[110:111], v[106:107] op_sel:[1,1] op_sel_hi:[1,0]
	v_pk_mul_f32 v[86:87], v[112:113], v[106:107] op_sel:[1,1] op_sel_hi:[1,0]
	v_pk_mul_f32 v[94:95], v[114:115], v[106:107] op_sel:[1,1] op_sel_hi:[1,0]
	v_pk_fma_f32 v[82:83], v[108:109], v[106:107], v[82:83] op_sel:[0,0,0] op_sel_hi:[0,1,1] neg_lo:[0,0,1] neg_hi:[0,0,0]
	v_pk_fma_f32 v[90:91], v[110:111], v[106:107], v[90:91] op_sel:[0,0,0] op_sel_hi:[0,1,1] neg_lo:[0,0,1] neg_hi:[0,0,0]
	v_pk_fma_f32 v[86:87], v[112:113], v[106:107], v[86:87] op_sel:[0,0,0] op_sel_hi:[0,1,1] neg_lo:[0,0,1] neg_hi:[0,0,0]
	v_pk_fma_f32 v[94:95], v[114:115], v[106:107], v[94:95] op_sel:[0,0,0] op_sel_hi:[0,1,1] neg_lo:[0,0,1] neg_hi:[0,0,0]
	ds_write2st64_b64 v79, v[80:81], v[82:83] offset1:17
	ds_write2st64_b64 v79, v[88:89], v[90:91] offset0:34 offset1:51
	ds_write2st64_b64 v79, v[84:85], v[86:87] offset0:68 offset1:85
	ds_write2st64_b64 v79, v[92:93], v[94:95] offset0:102 offset1:119
	s_waitcnt lgkmcnt(4)
; #define LAS __attribute__((address_space(3)))
; __device__ __forceinline__ int otid() { int t = threadIdx.x; asm volatile("" : "+v"(t)); return t; }
; __device__ __forceinline__ cf twc(cf ws, int k16) { if (k16 == 0) return ws; if (k16 == 4) return cf{ws.y, -ws.x}; return cmul(ws, cf{c16(k16), -s16(k16)}); }
; __device__ __forceinline__ void lds_barrier() { asm volatile("s_waitcnt lgkmcnt(0)\n\ts_barrier" ::: "memory"); }
; template <int LR> __device__ __forceinline__ void dif_reg(cf (&x)[1 << LR], cf w) {
;     constexpr int R = 1 << LR; cf ws = w;
; #pragma unroll
;     for (int s = 0; s < LR; ++s) { const int half = R >> (s + 1);
; #pragma unroll
;         for (int m0 = 0; m0 < R; m0 += 2 * half)
; #pragma unroll
;             for (int mm = 0; mm < half; ++mm) { const int ia = m0 + mm, ib = ia + half; const cf a = x[ia], b = x[ib];
;                 x[ia] = cf{a.x + b.x, a.y + b.y}; const cf d{a.x - b.x, a.y - b.y};
;                 x[ib] = cmul(d, twc(ws, (mm << s) * (16 / R))); }
;         ws = cmul(ws, ws); }
; }
; template <int LR, bool INV> __device__ __forceinline__ void fft_pass(ldsf2 buf, int base, int stride, int twi) {
;     constexpr int R = 1 << LR; cf x[R];
;     const v2f wv = ((ldsf2)((LAS unsigned char*)buf + 139264))[twi];
; #pragma unroll
;     for (int m = 0; m < R; ++m) { const v2f v = buf[base + m * stride]; x[m] = cf{v.x, v.y}; }
;     const cf w{wv.x, wv.y};
;     if (INV) dit_reg<LR>(x, w); else dif_reg<LR>(x, w);
; #pragma unroll
;     for (int m = 0; m < R; ++m) buf[base + m * stride] = mkv2(x[m].x, x[m].y);
; }
; __device__ __forceinline__ void wave_lds_fence() { asm volatile("s_waitcnt lgkmcnt(0)" ::: "memory"); }
; __device__ __forceinline__ void fft_fwd_abc(ldsf2 buf) {
;     const int tid = otid(); const int wv = tid >> 6, l = tid & 63;
; #pragma unroll 1
;     for (int u = 0; u < 2; ++u) { const int bf = tid + NT * u; fft_pass<3, false>(buf, bf + (bf >> 4), 1088, bf); }
;     lds_barrier();
	v_pk_add_f32 v[152:153], v[126:127], v[126:127] op_sel:[0,1] op_sel_hi:[1,0] neg_lo:[0,0] neg_hi:[0,1]
	v_pk_mul_f32 v[158:159], v[126:127], v[126:127] op_sel:[1,1] op_sel_hi:[1,0]
	v_pk_mul_f32 v[154:155], v[152:153], s[16:17] op_sel:[0,0] op_sel_hi:[1,0]
	v_pk_fma_f32 v[158:159], v[126:127], v[126:127], v[158:159] op_sel:[0,0,0] op_sel_hi:[0,1,1] neg_lo:[0,0,1] neg_hi:[0,0,0]
	v_pk_mul_f32 v[156:157], v[152:153], s[16:17] op_sel:[1,0] op_sel_hi:[0,0] neg_lo:[0,0] neg_hi:[1,0]
	s_nop 0
	v_pk_mul_f32 v[160:161], v[158:159], v[158:159] op_sel:[1,1] op_sel_hi:[1,0]
	s_nop 0
	v_pk_fma_f32 v[160:161], v[158:159], v[158:159], v[160:161] op_sel:[0,0,0] op_sel_hi:[0,1,1] neg_lo:[0,0,1] neg_hi:[0,0,0]
	v_pk_add_f32 v[162:163], v[128:129], v[132:133] neg_lo:[0,1] neg_hi:[0,1]
	v_pk_add_f32 v[164:165], v[130:131], v[134:135] neg_lo:[0,1] neg_hi:[0,1]
	v_pk_add_f32 v[166:167], v[136:137], v[140:141] neg_lo:[0,1] neg_hi:[0,1]
	v_pk_add_f32 v[168:169], v[138:139], v[142:143] neg_lo:[0,1] neg_hi:[0,1]
	v_pk_add_f32 v[128:129], v[128:129], v[132:133]
	v_pk_add_f32 v[130:131], v[130:131], v[134:135]
	v_pk_add_f32 v[136:137], v[136:137], v[140:141]
	v_pk_add_f32 v[138:139], v[138:139], v[142:143]
	v_pk_mul_f32 v[132:133], v[162:163], v[126:127] op_sel:[1,1] op_sel_hi:[1,0]
	v_pk_mul_f32 v[134:135], v[164:165], v[154:155] op_sel:[1,1] op_sel_hi:[1,0]
	v_pk_mul_f32 v[140:141], v[166:167], v[126:127] op_sel:[1,0] op_sel_hi:[1,1]
	v_pk_mul_f32 v[142:143], v[168:169], v[156:157] op_sel:[1,1] op_sel_hi:[1,0]
	v_pk_fma_f32 v[132:133], v[162:163], v[126:127], v[132:133] op_sel:[0,0,0] op_sel_hi:[0,1,1] neg_lo:[0,0,1] neg_hi:[0,0,0]
	v_pk_fma_f32 v[134:135], v[164:165], v[154:155], v[134:135] op_sel:[0,0,0] op_sel_hi:[0,1,1] neg_lo:[0,0,1] neg_hi:[0,0,0]
	v_pk_fma_f32 v[140:141], v[166:167], v[126:127], v[140:141] op_sel:[0,1,0] op_sel_hi:[0,0,1] neg_lo:[0,0,0] neg_hi:[0,1,0]
	v_pk_fma_f32 v[142:143], v[168:169], v[156:157], v[142:143] op_sel:[0,0,0] op_sel_hi:[0,1,1] neg_lo:[0,0,1] neg_hi:[0,0,0]
	v_pk_add_f32 v[162:163], v[128:129], v[136:137] neg_lo:[0,1] neg_hi:[0,1]
	v_pk_add_f32 v[164:165], v[130:131], v[138:139] neg_lo:[0,1] neg_hi:[0,1]
	v_pk_add_f32 v[166:167], v[132:133], v[140:141] neg_lo:[0,1] neg_hi:[0,1]
	v_pk_add_f32 v[168:169], v[134:135], v[142:143] neg_lo:[0,1] neg_hi:[0,1]
	v_pk_add_f32 v[128:129], v[128:129], v[136:137]
	v_pk_add_f32 v[130:131], v[130:131], v[138:139]
	v_pk_add_f32 v[132:133], v[132:133], v[140:141]
	v_pk_add_f32 v[134:135], v[134:135], v[142:143]
	v_pk_mul_f32 v[136:137], v[162:163], v[158:159] op_sel:[1,1] op_sel_hi:[1,0]
	v_pk_mul_f32 v[138:139], v[164:165], v[158:159] op_sel:[1,0] op_sel_hi:[1,1]
	v_pk_mul_f32 v[140:141], v[166:167], v[158:159] op_sel:[1,1] op_sel_hi:[1,0]
	v_pk_mul_f32 v[142:143], v[168:169], v[158:159] op_sel:[1,0] op_sel_hi:[1,1]
	v_pk_fma_f32 v[136:137], v[162:163], v[158:159], v[136:137] op_sel:[0,0,0] op_sel_hi:[0,1,1] neg_lo:[0,0,1] neg_hi:[0,0,0]
	v_pk_fma_f32 v[138:139], v[164:165], v[158:159], v[138:139] op_sel:[0,1,0] op_sel_hi:[0,0,1] neg_lo:[0,0,0] neg_hi:[0,1,0]
	v_pk_fma_f32 v[140:141], v[166:167], v[158:159], v[140:141] op_sel:[0,0,0] op_sel_hi:[0,1,1] neg_lo:[0,0,1] neg_hi:[0,0,0]
	v_pk_fma_f32 v[142:143], v[168:169], v[158:159], v[142:143] op_sel:[0,1,0] op_sel_hi:[0,0,1] neg_lo:[0,0,0] neg_hi:[0,1,0]
	v_pk_add_f32 v[162:163], v[128:129], v[130:131] neg_lo:[0,1] neg_hi:[0,1]
	v_pk_add_f32 v[164:165], v[136:137], v[138:139] neg_lo:[0,1] neg_hi:[0,1]
	v_pk_add_f32 v[166:167], v[132:133], v[134:135] neg_lo:[0,1] neg_hi:[0,1]
	v_pk_add_f32 v[168:169], v[140:141], v[142:143] neg_lo:[0,1] neg_hi:[0,1]
	v_pk_add_f32 v[128:129], v[128:129], v[130:131]
	v_pk_add_f32 v[136:137], v[136:137], v[138:139]
	v_pk_add_f32 v[132:133], v[132:133], v[134:135]
	v_pk_add_f32 v[140:141], v[140:141], v[142:143]
	v_pk_mul_f32 v[130:131], v[162:163], v[160:161] op_sel:[1,1] op_sel_hi:[1,0]
	v_pk_mul_f32 v[138:139], v[164:165], v[160:161] op_sel:[1,1] op_sel_hi:[1,0]
	v_pk_mul_f32 v[134:135], v[166:167], v[160:161] op_sel:[1,1] op_sel_hi:[1,0]
	v_pk_mul_f32 v[142:143], v[168:169], v[160:161] op_sel:[1,1] op_sel_hi:[1,0]
	v_pk_fma_f32 v[130:131], v[162:163], v[160:161], v[130:131] op_sel:[0,0,0] op_sel_hi:[0,1,1] neg_lo:[0,0,1] neg_hi:[0,0,0]
	v_pk_fma_f32 v[138:139], v[164:165], v[160:161], v[138:139] op_sel:[0,0,0] op_sel_hi:[0,1,1] neg_lo:[0,0,1] neg_hi:[0,0,0]
	v_pk_fma_f32 v[134:135], v[166:167], v[160:161], v[134:135] op_sel:[0,0,0] op_sel_hi:[0,1,1] neg_lo:[0,0,1] neg_hi:[0,0,0]
	v_pk_fma_f32 v[142:143], v[168:169], v[160:161], v[142:143] op_sel:[0,0,0] op_sel_hi:[0,1,1] neg_lo:[0,0,1] neg_hi:[0,0,0]
	ds_write2st64_b64 v122, v[128:129], v[130:131] offset1:17
	ds_write2st64_b64 v122, v[136:137], v[138:139] offset0:34 offset1:51
	ds_write2st64_b64 v122, v[132:133], v[134:135] offset0:68 offset1:85
	ds_write2st64_b64 v122, v[140:141], v[142:143] offset0:102 offset1:119
	s_mov_b64 s[10:11], 0
	s_waitcnt lgkmcnt(0)
	s_barrier
	v_lshlrev_b32_e32 v80, 4, v78
	v_and_b32_e32 v79, 63, v78
	v_and_b32_e32 v80, 0xfffffc00, v80
	s_mov_b32 s0, 0
	s_mov_b64 s[10:11], -1
; #define LAS __attribute__((address_space(3)))
; __device__ __forceinline__ cf twc(cf ws, int k16) { if (k16 == 0) return ws; if (k16 == 4) return cf{ws.y, -ws.x}; return cmul(ws, cf{c16(k16), -s16(k16)}); }
; template <int LR> __device__ __forceinline__ void dif_reg(cf (&x)[1 << LR], cf w) {
;     constexpr int R = 1 << LR; cf ws = w;
; #pragma unroll
;     for (int s = 0; s < LR; ++s) { const int half = R >> (s + 1);
; #pragma unroll
;         for (int m0 = 0; m0 < R; m0 += 2 * half)
; #pragma unroll
;             for (int mm = 0; mm < half; ++mm) { const int ia = m0 + mm, ib = ia + half; const cf a = x[ia], b = x[ib];
;                 x[ia] = cf{a.x + b.x, a.y + b.y}; const cf d{a.x - b.x, a.y - b.y};
;                 x[ib] = cmul(d, twc(ws, (mm << s) * (16 / R))); }
;         ws = cmul(ws, ws); }
; }
; template <int LR, bool INV> __device__ __forceinline__ void fft_pass(ldsf2 buf, int base, int stride, int twi) {
;     constexpr int R = 1 << LR; cf x[R];
;     const v2f wv = ((ldsf2)((LAS unsigned char*)buf + 139264))[twi];
; #pragma unroll
;     for (int m = 0; m < R; ++m) { const v2f v = buf[base + m * stride]; x[m] = cf{v.x, v.y}; }
;     const cf w{wv.x, wv.y};
;     if (INV) dit_reg<LR>(x, w); else dif_reg<LR>(x, w);
; #pragma unroll
;     for (int m = 0; m < R; ++m) buf[base + m * stride] = mkv2(x[m].x, x[m].y);
; }
.LBB0_361:
	v_or_b32_e32 v82, s0, v79
	v_or_b32_e32 v81, v82, v80
	v_lshl_add_u32 v82, v82, 6, 0
	v_ashrrev_i32_e32 v83, 4, v81
	v_add_u32_e32 v82, 0x22000, v82
	v_lshlrev_b32_e32 v81, 3, v81
	ds_read_b64 v[98:99], v82
	v_lshlrev_b32_e32 v82, 3, v83
	v_add3_u32 v81, 0, v81, v82
	v_add_u32_e32 v121, 0x800, v81
	ds_read2_b64 v[82:85], v81 offset1:136
	v_add_u32_e32 v126, 0x1000, v81
	v_add_u32_e32 v127, 0x1800, v81
	ds_read2_b64 v[86:89], v121 offset0:16 offset1:152
	ds_read2_b64 v[90:93], v126 offset0:32 offset1:168
	ds_read2_b64 v[94:97], v127 offset0:48 offset1:184
	s_mov_b32 s0, 64
	v_or_b32_e32 v128, s0, v79
	v_or_b32_e32 v130, v128, v80
	v_lshl_add_u32 v128, v128, 6, 0
	v_ashrrev_i32_e32 v132, 4, v130
	v_add_u32_e32 v128, 0x22000, v128
	v_lshlrev_b32_e32 v130, 3, v130
	ds_read_b64 v[134:135], v128
	v_lshlrev_b32_e32 v128, 3, v132
	v_add3_u32 v130, 0, v130, v128
	v_add_u32_e32 v136, 0x800, v130
	ds_read2_b64 v[138:141], v130 offset1:136
	v_add_u32_e32 v142, 0x1000, v130
	v_add_u32_e32 v152, 0x1800, v130
	ds_read2_b64 v[154:157], v136 offset0:16 offset1:152
	ds_read2_b64 v[158:161], v142 offset0:32 offset1:168
	ds_read2_b64 v[162:165], v152 offset0:48 offset1:184
	s_waitcnt lgkmcnt(5)
	v_pk_add_f32 v[100:101], v[98:99], v[98:99] op_sel:[0,1] op_sel_hi:[1,0] neg_lo:[0,0] neg_hi:[0,1]
	v_pk_mul_f32 v[106:107], v[98:99], v[98:99] op_sel:[1,1] op_sel_hi:[1,0]
	v_pk_mul_f32 v[102:103], v[100:101], s[16:17] op_sel:[0,0] op_sel_hi:[1,0]
	v_pk_fma_f32 v[106:107], v[98:99], v[98:99], v[106:107] op_sel:[0,0,0] op_sel_hi:[0,1,1] neg_lo:[0,0,1] neg_hi:[0,0,0]
	v_pk_mul_f32 v[104:105], v[100:101], s[16:17] op_sel:[1,0] op_sel_hi:[0,0] neg_lo:[0,0] neg_hi:[1,0]
	s_nop 0
	v_pk_mul_f32 v[108:109], v[106:107], v[106:107] op_sel:[1,1] op_sel_hi:[1,0]
	s_nop 0
	v_pk_fma_f32 v[108:109], v[106:107], v[106:107], v[108:109] op_sel:[0,0,0] op_sel_hi:[0,1,1] neg_lo:[0,0,1] neg_hi:[0,0,0]
	v_pk_add_f32 v[110:111], v[82:83], v[90:91] neg_lo:[0,1] neg_hi:[0,1]
	v_pk_add_f32 v[112:113], v[84:85], v[92:93] neg_lo:[0,1] neg_hi:[0,1]
	v_pk_add_f32 v[114:115], v[86:87], v[94:95] neg_lo:[0,1] neg_hi:[0,1]
	v_pk_add_f32 v[116:117], v[88:89], v[96:97] neg_lo:[0,1] neg_hi:[0,1]
	v_pk_add_f32 v[82:83], v[82:83], v[90:91]
	v_pk_add_f32 v[84:85], v[84:85], v[92:93]
	v_pk_add_f32 v[86:87], v[86:87], v[94:95]
	v_pk_add_f32 v[88:89], v[88:89], v[96:97]
	v_pk_mul_f32 v[90:91], v[110:111], v[98:99] op_sel:[1,1] op_sel_hi:[1,0]
	v_pk_mul_f32 v[92:93], v[112:113], v[102:103] op_sel:[1,1] op_sel_hi:[1,0]
	v_pk_mul_f32 v[94:95], v[114:115], v[98:99] op_sel:[1,0] op_sel_hi:[1,1]
	v_pk_mul_f32 v[96:97], v[116:117], v[104:105] op_sel:[1,1] op_sel_hi:[1,0]
	v_pk_fma_f32 v[90:91], v[110:111], v[98:99], v[90:91] op_sel:[0,0,0] op_sel_hi:[0,1,1] neg_lo:[0,0,1] neg_hi:[0,0,0]
	v_pk_fma_f32 v[92:93], v[112:113], v[102:103], v[92:93] op_sel:[0,0,0] op_sel_hi:[0,1,1] neg_lo:[0,0,1] neg_hi:[0,0,0]
	v_pk_fma_f32 v[94:95], v[114:115], v[98:99], v[94:95] op_sel:[0,1,0] op_sel_hi:[0,0,1] neg_lo:[0,0,0] neg_hi:[0,1,0]
	v_pk_fma_f32 v[96:97], v[116:117], v[104:105], v[96:97] op_sel:[0,0,0] op_sel_hi:[0,1,1] neg_lo:[0,0,1] neg_hi:[0,0,0]
	v_pk_add_f32 v[110:111], v[82:83], v[86:87] neg_lo:[0,1] neg_hi:[0,1]
	v_pk_add_f32 v[112:113], v[84:85], v[88:89] neg_lo:[0,1] neg_hi:[0,1]
	v_pk_add_f32 v[114:115], v[90:91], v[94:95] neg_lo:[0,1] neg_hi:[0,1]
	v_pk_add_f32 v[116:117], v[92:93], v[96:97] neg_lo:[0,1] neg_hi:[0,1]
	v_pk_add_f32 v[82:83], v[82:83], v[86:87]
	v_pk_add_f32 v[84:85], v[84:85], v[88:89]
	v_pk_add_f32 v[90:91], v[90:91], v[94:95]
	v_pk_add_f32 v[92:93], v[92:93], v[96:97]
	v_pk_mul_f32 v[86:87], v[110:111], v[106:107] op_sel:[1,1] op_sel_hi:[1,0]
	v_pk_mul_f32 v[88:89], v[112:113], v[106:107] op_sel:[1,0] op_sel_hi:[1,1]
	v_pk_mul_f32 v[94:95], v[114:115], v[106:107] op_sel:[1,1] op_sel_hi:[1,0]
	v_pk_mul_f32 v[96:97], v[116:117], v[106:107] op_sel:[1,0] op_sel_hi:[1,1]
	v_pk_fma_f32 v[86:87], v[110:111], v[106:107], v[86:87] op_sel:[0,0,0] op_sel_hi:[0,1,1] neg_lo:[0,0,1] neg_hi:[0,0,0]
	v_pk_fma_f32 v[88:89], v[112:113], v[106:107], v[88:89] op_sel:[0,1,0] op_sel_hi:[0,0,1] neg_lo:[0,0,0] neg_hi:[0,1,0]
	v_pk_fma_f32 v[94:95], v[114:115], v[106:107], v[94:95] op_sel:[0,0,0] op_sel_hi:[0,1,1] neg_lo:[0,0,1] neg_hi:[0,0,0]
	v_pk_fma_f32 v[96:97], v[116:117], v[106:107], v[96:97] op_sel:[0,1,0] op_sel_hi:[0,0,1] neg_lo:[0,0,0] neg_hi:[0,1,0]
	v_pk_add_f32 v[110:111], v[82:83], v[84:85] neg_lo:[0,1] neg_hi:[0,1]
	v_pk_add_f32 v[112:113], v[86:87], v[88:89] neg_lo:[0,1] neg_hi:[0,1]
	v_pk_add_f32 v[114:115], v[90:91], v[92:93] neg_lo:[0,1] neg_hi:[0,1]
	v_pk_add_f32 v[116:117], v[94:95], v[96:97] neg_lo:[0,1] neg_hi:[0,1]
	v_pk_add_f32 v[82:83], v[82:83], v[84:85]
	v_pk_add_f32 v[86:87], v[86:87], v[88:89]
	v_pk_add_f32 v[90:91], v[90:91], v[92:93]
	v_pk_add_f32 v[94:95], v[94:95], v[96:97]
	v_pk_mul_f32 v[84:85], v[110:111], v[108:109] op_sel:[1,1] op_sel_hi:[1,0]
	v_pk_mul_f32 v[88:89], v[112:113], v[108:109] op_sel:[1,1] op_sel_hi:[1,0]
	v_pk_mul_f32 v[92:93], v[114:115], v[108:109] op_sel:[1,1] op_sel_hi:[1,0]
	v_pk_mul_f32 v[96:97], v[116:117], v[108:109] op_sel:[1,1] op_sel_hi:[1,0]
	v_pk_fma_f32 v[84:85], v[110:111], v[108:109], v[84:85] op_sel:[0,0,0] op_sel_hi:[0,1,1] neg_lo:[0,0,1] neg_hi:[0,0,0]
	v_pk_fma_f32 v[88:89], v[112:113], v[108:109], v[88:89] op_sel:[0,0,0] op_sel_hi:[0,1,1] neg_lo:[0,0,1] neg_hi:[0,0,0]
	v_pk_fma_f32 v[92:93], v[114:115], v[108:109], v[92:93] op_sel:[0,0,0] op_sel_hi:[0,1,1] neg_lo:[0,0,1] neg_hi:[0,0,0]
	v_pk_fma_f32 v[96:97], v[116:117], v[108:109], v[96:97] op_sel:[0,0,0] op_sel_hi:[0,1,1] neg_lo:[0,0,1] neg_hi:[0,0,0]
	ds_write2_b64 v81, v[82:83], v[84:85] offset1:136
	ds_write2_b64 v121, v[86:87], v[88:89] offset0:16 offset1:152
	ds_write2_b64 v126, v[90:91], v[92:93] offset0:32 offset1:168
	ds_write2_b64 v127, v[94:95], v[96:97] offset0:48 offset1:184
	s_waitcnt lgkmcnt(4)
; #define LAS __attribute__((address_space(3)))
; __device__ __forceinline__ int otid() { int t = threadIdx.x; asm volatile("" : "+v"(t)); return t; }
; __device__ __forceinline__ cf twc(cf ws, int k16) { if (k16 == 0) return ws; if (k16 == 4) return cf{ws.y, -ws.x}; return cmul(ws, cf{c16(k16), -s16(k16)}); }
; __device__ __forceinline__ void lds_barrier() { asm volatile("s_waitcnt lgkmcnt(0)\n\ts_barrier" ::: "memory"); }
; template <int LR> __device__ __forceinline__ void dif_reg(cf (&x)[1 << LR], cf w) {
;     constexpr int R = 1 << LR; cf ws = w;
; #pragma unroll
;     for (int s = 0; s < LR; ++s) { const int half = R >> (s + 1);
; #pragma unroll
;         for (int m0 = 0; m0 < R; m0 += 2 * half)
; #pragma unroll
;             for (int mm = 0; mm < half; ++mm) { const int ia = m0 + mm, ib = ia + half; const cf a = x[ia], b = x[ib];
;                 x[ia] = cf{a.x + b.x, a.y + b.y}; const cf d{a.x - b.x, a.y - b.y};
;                 x[ib] = cmul(d, twc(ws, (mm << s) * (16 / R))); }
;         ws = cmul(ws, ws); }
; }
; template <int LR, bool INV> __device__ __forceinline__ void fft_pass(ldsf2 buf, int base, int stride, int twi) {
;     constexpr int R = 1 << LR; cf x[R];
;     const v2f wv = ((ldsf2)((LAS unsigned char*)buf + 139264))[twi];
; #pragma unroll
;     for (int m = 0; m < R; ++m) { const v2f v = buf[base + m * stride]; x[m] = cf{v.x, v.y}; }
;     const cf w{wv.x, wv.y};
;     if (INV) dit_reg<LR>(x, w); else dif_reg<LR>(x, w);
; #pragma unroll
;     for (int m = 0; m < R; ++m) buf[base + m * stride] = mkv2(x[m].x, x[m].y);
; }
; __device__ __forceinline__ void wave_lds_fence() { asm volatile("s_waitcnt lgkmcnt(0)" ::: "memory"); }
; __device__ __forceinline__ void fft_fwd_abc(ldsf2 buf) {
;     const int tid = otid(); const int wv = tid >> 6, l = tid & 63;
; #pragma unroll 1
;     for (int u = 0; u < 2; ++u) { const int bf = tid + NT * u; fft_pass<3, false>(buf, bf + (bf >> 4), 1088, bf); }
;     lds_barrier();
; #pragma unroll 1
;     for (int u = 0; u < 2; ++u) { const int o = l + 64 * u, e0 = wv * 1024 + o; fft_pass<3, false>(buf, e0 + (e0 >> 4), 136, o * 8); }
	v_pk_add_f32 v[166:167], v[134:135], v[134:135] op_sel:[0,1] op_sel_hi:[1,0] neg_lo:[0,0] neg_hi:[0,1]
	v_pk_mul_f32 v[172:173], v[134:135], v[134:135] op_sel:[1,1] op_sel_hi:[1,0]
	v_pk_mul_f32 v[168:169], v[166:167], s[16:17] op_sel:[0,0] op_sel_hi:[1,0]
	v_pk_fma_f32 v[172:173], v[134:135], v[134:135], v[172:173] op_sel:[0,0,0] op_sel_hi:[0,1,1] neg_lo:[0,0,1] neg_hi:[0,0,0]
	v_pk_mul_f32 v[170:171], v[166:167], s[16:17] op_sel:[1,0] op_sel_hi:[0,0] neg_lo:[0,0] neg_hi:[1,0]
	s_nop 0
	v_pk_mul_f32 v[174:175], v[172:173], v[172:173] op_sel:[1,1] op_sel_hi:[1,0]
	s_nop 0
	v_pk_fma_f32 v[174:175], v[172:173], v[172:173], v[174:175] op_sel:[0,0,0] op_sel_hi:[0,1,1] neg_lo:[0,0,1] neg_hi:[0,0,0]
	v_pk_add_f32 v[188:189], v[138:139], v[158:159] neg_lo:[0,1] neg_hi:[0,1]
	v_pk_add_f32 v[190:191], v[140:141], v[160:161] neg_lo:[0,1] neg_hi:[0,1]
	v_pk_add_f32 v[196:197], v[154:155], v[162:163] neg_lo:[0,1] neg_hi:[0,1]
	v_pk_add_f32 v[198:199], v[156:157], v[164:165] neg_lo:[0,1] neg_hi:[0,1]
	v_pk_add_f32 v[138:139], v[138:139], v[158:159]
	v_pk_add_f32 v[140:141], v[140:141], v[160:161]
	v_pk_add_f32 v[154:155], v[154:155], v[162:163]
	v_pk_add_f32 v[156:157], v[156:157], v[164:165]
	v_pk_mul_f32 v[158:159], v[188:189], v[134:135] op_sel:[1,1] op_sel_hi:[1,0]
	v_pk_mul_f32 v[160:161], v[190:191], v[168:169] op_sel:[1,1] op_sel_hi:[1,0]
	v_pk_mul_f32 v[162:163], v[196:197], v[134:135] op_sel:[1,0] op_sel_hi:[1,1]
	v_pk_mul_f32 v[164:165], v[198:199], v[170:171] op_sel:[1,1] op_sel_hi:[1,0]
	v_pk_fma_f32 v[158:159], v[188:189], v[134:135], v[158:159] op_sel:[0,0,0] op_sel_hi:[0,1,1] neg_lo:[0,0,1] neg_hi:[0,0,0]
	v_pk_fma_f32 v[160:161], v[190:191], v[168:169], v[160:161] op_sel:[0,0,0] op_sel_hi:[0,1,1] neg_lo:[0,0,1] neg_hi:[0,0,0]
	v_pk_fma_f32 v[162:163], v[196:197], v[134:135], v[162:163] op_sel:[0,1,0] op_sel_hi:[0,0,1] neg_lo:[0,0,0] neg_hi:[0,1,0]
	v_pk_fma_f32 v[164:165], v[198:199], v[170:171], v[164:165] op_sel:[0,0,0] op_sel_hi:[0,1,1] neg_lo:[0,0,1] neg_hi:[0,0,0]
	v_pk_add_f32 v[188:189], v[138:139], v[154:155] neg_lo:[0,1] neg_hi:[0,1]
	v_pk_add_f32 v[190:191], v[140:141], v[156:157] neg_lo:[0,1] neg_hi:[0,1]
	v_pk_add_f32 v[196:197], v[158:159], v[162:163] neg_lo:[0,1] neg_hi:[0,1]
	v_pk_add_f32 v[198:199], v[160:161], v[164:165] neg_lo:[0,1] neg_hi:[0,1]
	v_pk_add_f32 v[138:139], v[138:139], v[154:155]
	v_pk_add_f32 v[140:141], v[140:141], v[156:157]
	v_pk_add_f32 v[158:159], v[158:159], v[162:163]
	v_pk_add_f32 v[160:161], v[160:161], v[164:165]
	v_pk_mul_f32 v[154:155], v[188:189], v[172:173] op_sel:[1,1] op_sel_hi:[1,0]
	v_pk_mul_f32 v[156:157], v[190:191], v[172:173] op_sel:[1,0] op_sel_hi:[1,1]
	v_pk_mul_f32 v[162:163], v[196:197], v[172:173] op_sel:[1,1] op_sel_hi:[1,0]
	v_pk_mul_f32 v[164:165], v[198:199], v[172:173] op_sel:[1,0] op_sel_hi:[1,1]
	v_pk_fma_f32 v[154:155], v[188:189], v[172:173], v[154:155] op_sel:[0,0,0] op_sel_hi:[0,1,1] neg_lo:[0,0,1] neg_hi:[0,0,0]
	v_pk_fma_f32 v[156:157], v[190:191], v[172:173], v[156:157] op_sel:[0,1,0] op_sel_hi:[0,0,1] neg_lo:[0,0,0] neg_hi:[0,1,0]
	v_pk_fma_f32 v[162:163], v[196:197], v[172:173], v[162:163] op_sel:[0,0,0] op_sel_hi:[0,1,1] neg_lo:[0,0,1] neg_hi:[0,0,0]
	v_pk_fma_f32 v[164:165], v[198:199], v[172:173], v[164:165] op_sel:[0,1,0] op_sel_hi:[0,0,1] neg_lo:[0,0,0] neg_hi:[0,1,0]
	v_pk_add_f32 v[188:189], v[138:139], v[140:141] neg_lo:[0,1] neg_hi:[0,1]
	v_pk_add_f32 v[190:191], v[154:155], v[156:157] neg_lo:[0,1] neg_hi:[0,1]
	v_pk_add_f32 v[196:197], v[158:159], v[160:161] neg_lo:[0,1] neg_hi:[0,1]
	v_pk_add_f32 v[198:199], v[162:163], v[164:165] neg_lo:[0,1] neg_hi:[0,1]
	v_pk_add_f32 v[138:139], v[138:139], v[140:141]
	v_pk_add_f32 v[154:155], v[154:155], v[156:157]
	v_pk_add_f32 v[158:159], v[158:159], v[160:161]
	v_pk_add_f32 v[162:163], v[162:163], v[164:165]
	v_pk_mul_f32 v[140:141], v[188:189], v[174:175] op_sel:[1,1] op_sel_hi:[1,0]
	v_pk_mul_f32 v[156:157], v[190:191], v[174:175] op_sel:[1,1] op_sel_hi:[1,0]
	v_pk_mul_f32 v[160:161], v[196:197], v[174:175] op_sel:[1,1] op_sel_hi:[1,0]
	v_pk_mul_f32 v[164:165], v[198:199], v[174:175] op_sel:[1,1] op_sel_hi:[1,0]
	v_pk_fma_f32 v[140:141], v[188:189], v[174:175], v[140:141] op_sel:[0,0,0] op_sel_hi:[0,1,1] neg_lo:[0,0,1] neg_hi:[0,0,0]
	v_pk_fma_f32 v[156:157], v[190:191], v[174:175], v[156:157] op_sel:[0,0,0] op_sel_hi:[0,1,1] neg_lo:[0,0,1] neg_hi:[0,0,0]
	v_pk_fma_f32 v[160:161], v[196:197], v[174:175], v[160:161] op_sel:[0,0,0] op_sel_hi:[0,1,1] neg_lo:[0,0,1] neg_hi:[0,0,0]
	v_pk_fma_f32 v[164:165], v[198:199], v[174:175], v[164:165] op_sel:[0,0,0] op_sel_hi:[0,1,1] neg_lo:[0,0,1] neg_hi:[0,0,0]
	ds_write2_b64 v130, v[138:139], v[140:141] offset1:136
	ds_write2_b64 v136, v[154:155], v[156:157] offset0:16 offset1:152
	ds_write2_b64 v142, v[158:159], v[160:161] offset0:32 offset1:168
	ds_write2_b64 v152, v[162:163], v[164:165] offset0:48 offset1:184
	s_mov_b64 s[10:11], 0
	v_and_b32_e32 v78, 15, v78
	s_waitcnt lgkmcnt(0)
	v_lshlrev_b32_e32 v79, 3, v79
	v_lshlrev_b32_e32 v81, 9, v78
	v_and_or_b32 v79, v79, s90, v80
	v_add_u32_e32 v80, 0, v81
	v_lshl_add_u32 v78, v78, 3, 0
	s_mov_b32 s0, 0
	s_mov_b64 s[10:11], -1
	v_add_u32_e32 v80, 0x22000, v80
; #define LAS __attribute__((address_space(3)))
; __device__ __forceinline__ cf twc(cf ws, int k16) { if (k16 == 0) return ws; if (k16 == 4) return cf{ws.y, -ws.x}; return cmul(ws, cf{c16(k16), -s16(k16)}); }
; template <int LR> __device__ __forceinline__ void dif_reg(cf (&x)[1 << LR], cf w) {
;     constexpr int R = 1 << LR; cf ws = w;
; #pragma unroll
;     for (int s = 0; s < LR; ++s) { const int half = R >> (s + 1);
; #pragma unroll
;         for (int m0 = 0; m0 < R; m0 += 2 * half)
; #pragma unroll
;             for (int mm = 0; mm < half; ++mm) { const int ia = m0 + mm, ib = ia + half; const cf a = x[ia], b = x[ib];
;                 x[ia] = cf{a.x + b.x, a.y + b.y}; const cf d{a.x - b.x, a.y - b.y};
;                 x[ib] = cmul(d, twc(ws, (mm << s) * (16 / R))); }
;         ws = cmul(ws, ws); }
; }
; template <int LR, bool INV> __device__ __forceinline__ void fft_pass(ldsf2 buf, int base, int stride, int twi) {
;     constexpr int R = 1 << LR; cf x[R];
;     const v2f wv = ((ldsf2)((LAS unsigned char*)buf + 139264))[twi];
; #pragma unroll
;     for (int m = 0; m < R; ++m) { const v2f v = buf[base + m * stride]; x[m] = cf{v.x, v.y}; }
;     const cf w{wv.x, wv.y};
;     if (INV) dit_reg<LR>(x, w); else dif_reg<LR>(x, w);
; #pragma unroll
;     for (int m = 0; m < R; ++m) buf[base + m * stride] = mkv2(x[m].x, x[m].y);
; }
.LBB0_363:
	v_or_b32_e32 v81, s0, v79
	ds_read_b64 v[98:99], v80
	v_lshlrev_b32_e32 v82, 3, v81
	v_ashrrev_i32_e32 v81, 1, v81
	v_add3_u32 v81, v78, v82, v81
	ds_read2_b64 v[82:85], v81 offset1:17
	ds_read2_b64 v[86:89], v81 offset0:34 offset1:51
	ds_read2_b64 v[90:93], v81 offset0:68 offset1:85
	ds_read2_b64 v[94:97], v81 offset0:102 offset1:119
	s_movk_i32 s0, 0x200
	v_or_b32_e32 v126, s0, v79
	ds_read_b64 v[128:129], v80
	v_lshlrev_b32_e32 v130, 3, v126
	v_ashrrev_i32_e32 v126, 1, v126
	v_add3_u32 v126, v78, v130, v126
	ds_read2_b64 v[132:135], v126 offset1:17
	ds_read2_b64 v[136:139], v126 offset0:34 offset1:51
	ds_read2_b64 v[140:143], v126 offset0:68 offset1:85
	ds_read2_b64 v[152:155], v126 offset0:102 offset1:119
	s_waitcnt lgkmcnt(5)
	v_pk_add_f32 v[100:101], v[98:99], v[98:99] op_sel:[0,1] op_sel_hi:[1,0] neg_lo:[0,0] neg_hi:[0,1]
	v_pk_mul_f32 v[106:107], v[98:99], v[98:99] op_sel:[1,1] op_sel_hi:[1,0]
	v_pk_mul_f32 v[102:103], v[100:101], s[16:17] op_sel:[0,0] op_sel_hi:[1,0]
	v_pk_fma_f32 v[106:107], v[98:99], v[98:99], v[106:107] op_sel:[0,0,0] op_sel_hi:[0,1,1] neg_lo:[0,0,1] neg_hi:[0,0,0]
	v_pk_mul_f32 v[104:105], v[100:101], s[16:17] op_sel:[1,0] op_sel_hi:[0,0] neg_lo:[0,0] neg_hi:[1,0]
	s_nop 0
	v_pk_mul_f32 v[108:109], v[106:107], v[106:107] op_sel:[1,1] op_sel_hi:[1,0]
	s_nop 0
	v_pk_fma_f32 v[108:109], v[106:107], v[106:107], v[108:109] op_sel:[0,0,0] op_sel_hi:[0,1,1] neg_lo:[0,0,1] neg_hi:[0,0,0]
	v_pk_add_f32 v[110:111], v[82:83], v[90:91] neg_lo:[0,1] neg_hi:[0,1]
	v_pk_add_f32 v[112:113], v[84:85], v[92:93] neg_lo:[0,1] neg_hi:[0,1]
	v_pk_add_f32 v[114:115], v[86:87], v[94:95] neg_lo:[0,1] neg_hi:[0,1]
	v_pk_add_f32 v[116:117], v[88:89], v[96:97] neg_lo:[0,1] neg_hi:[0,1]
	v_pk_add_f32 v[82:83], v[82:83], v[90:91]
	v_pk_add_f32 v[84:85], v[84:85], v[92:93]
	v_pk_add_f32 v[86:87], v[86:87], v[94:95]
	v_pk_add_f32 v[88:89], v[88:89], v[96:97]
	v_pk_mul_f32 v[90:91], v[110:111], v[98:99] op_sel:[1,1] op_sel_hi:[1,0]
	v_pk_mul_f32 v[92:93], v[112:113], v[102:103] op_sel:[1,1] op_sel_hi:[1,0]
	v_pk_mul_f32 v[94:95], v[114:115], v[98:99] op_sel:[1,0] op_sel_hi:[1,1]
	v_pk_mul_f32 v[96:97], v[116:117], v[104:105] op_sel:[1,1] op_sel_hi:[1,0]
	v_pk_fma_f32 v[90:91], v[110:111], v[98:99], v[90:91] op_sel:[0,0,0] op_sel_hi:[0,1,1] neg_lo:[0,0,1] neg_hi:[0,0,0]
	v_pk_fma_f32 v[92:93], v[112:113], v[102:103], v[92:93] op_sel:[0,0,0] op_sel_hi:[0,1,1] neg_lo:[0,0,1] neg_hi:[0,0,0]
	v_pk_fma_f32 v[94:95], v[114:115], v[98:99], v[94:95] op_sel:[0,1,0] op_sel_hi:[0,0,1] neg_lo:[0,0,0] neg_hi:[0,1,0]
	v_pk_fma_f32 v[96:97], v[116:117], v[104:105], v[96:97] op_sel:[0,0,0] op_sel_hi:[0,1,1] neg_lo:[0,0,1] neg_hi:[0,0,0]
	v_pk_add_f32 v[110:111], v[82:83], v[86:87] neg_lo:[0,1] neg_hi:[0,1]
	v_pk_add_f32 v[112:113], v[84:85], v[88:89] neg_lo:[0,1] neg_hi:[0,1]
	v_pk_add_f32 v[114:115], v[90:91], v[94:95] neg_lo:[0,1] neg_hi:[0,1]
	v_pk_add_f32 v[116:117], v[92:93], v[96:97] neg_lo:[0,1] neg_hi:[0,1]
	v_pk_add_f32 v[82:83], v[82:83], v[86:87]
	v_pk_add_f32 v[84:85], v[84:85], v[88:89]
	v_pk_add_f32 v[90:91], v[90:91], v[94:95]
	v_pk_add_f32 v[92:93], v[92:93], v[96:97]
	v_pk_mul_f32 v[86:87], v[110:111], v[106:107] op_sel:[1,1] op_sel_hi:[1,0]
	v_pk_mul_f32 v[88:89], v[112:113], v[106:107] op_sel:[1,0] op_sel_hi:[1,1]
	v_pk_mul_f32 v[94:95], v[114:115], v[106:107] op_sel:[1,1] op_sel_hi:[1,0]
	v_pk_mul_f32 v[96:97], v[116:117], v[106:107] op_sel:[1,0] op_sel_hi:[1,1]
	v_pk_fma_f32 v[86:87], v[110:111], v[106:107], v[86:87] op_sel:[0,0,0] op_sel_hi:[0,1,1] neg_lo:[0,0,1] neg_hi:[0,0,0]
	v_pk_fma_f32 v[88:89], v[112:113], v[106:107], v[88:89] op_sel:[0,1,0] op_sel_hi:[0,0,1] neg_lo:[0,0,0] neg_hi:[0,1,0]
	v_pk_fma_f32 v[94:95], v[114:115], v[106:107], v[94:95] op_sel:[0,0,0] op_sel_hi:[0,1,1] neg_lo:[0,0,1] neg_hi:[0,0,0]
	v_pk_fma_f32 v[96:97], v[116:117], v[106:107], v[96:97] op_sel:[0,1,0] op_sel_hi:[0,0,1] neg_lo:[0,0,0] neg_hi:[0,1,0]
	v_pk_add_f32 v[110:111], v[82:83], v[84:85] neg_lo:[0,1] neg_hi:[0,1]
	v_pk_add_f32 v[112:113], v[86:87], v[88:89] neg_lo:[0,1] neg_hi:[0,1]
	v_pk_add_f32 v[114:115], v[90:91], v[92:93] neg_lo:[0,1] neg_hi:[0,1]
	v_pk_add_f32 v[116:117], v[94:95], v[96:97] neg_lo:[0,1] neg_hi:[0,1]
	v_pk_add_f32 v[82:83], v[82:83], v[84:85]
	v_pk_add_f32 v[86:87], v[86:87], v[88:89]
	v_pk_add_f32 v[90:91], v[90:91], v[92:93]
	v_pk_add_f32 v[94:95], v[94:95], v[96:97]
	v_pk_mul_f32 v[84:85], v[110:111], v[108:109] op_sel:[1,1] op_sel_hi:[1,0]
	v_pk_mul_f32 v[88:89], v[112:113], v[108:109] op_sel:[1,1] op_sel_hi:[1,0]
	v_pk_mul_f32 v[92:93], v[114:115], v[108:109] op_sel:[1,1] op_sel_hi:[1,0]
	v_pk_mul_f32 v[96:97], v[116:117], v[108:109] op_sel:[1,1] op_sel_hi:[1,0]
	v_pk_fma_f32 v[84:85], v[110:111], v[108:109], v[84:85] op_sel:[0,0,0] op_sel_hi:[0,1,1] neg_lo:[0,0,1] neg_hi:[0,0,0]
	v_pk_fma_f32 v[88:89], v[112:113], v[108:109], v[88:89] op_sel:[0,0,0] op_sel_hi:[0,1,1] neg_lo:[0,0,1] neg_hi:[0,0,0]
	v_pk_fma_f32 v[92:93], v[114:115], v[108:109], v[92:93] op_sel:[0,0,0] op_sel_hi:[0,1,1] neg_lo:[0,0,1] neg_hi:[0,0,0]
	v_pk_fma_f32 v[96:97], v[116:117], v[108:109], v[96:97] op_sel:[0,0,0] op_sel_hi:[0,1,1] neg_lo:[0,0,1] neg_hi:[0,0,0]
	ds_write2_b64 v81, v[82:83], v[84:85] offset1:17
	ds_write2_b64 v81, v[86:87], v[88:89] offset0:34 offset1:51
	ds_write2_b64 v81, v[90:91], v[92:93] offset0:68 offset1:85
	ds_write2_b64 v81, v[94:95], v[96:97] offset0:102 offset1:119
	s_waitcnt lgkmcnt(4)
; __device__ __forceinline__ int otid() { int t = threadIdx.x; asm volatile("" : "+v"(t)); return t; }
; __device__ __forceinline__ cf twc(cf ws, int k16) { if (k16 == 0) return ws; if (k16 == 4) return cf{ws.y, -ws.x}; return cmul(ws, cf{c16(k16), -s16(k16)}); }
; template <int LR> __device__ __forceinline__ void dif_reg(cf (&x)[1 << LR], cf w) {
;     constexpr int R = 1 << LR; cf ws = w;
; #pragma unroll
;     for (int s = 0; s < LR; ++s) { const int half = R >> (s + 1);
; #pragma unroll
;         for (int m0 = 0; m0 < R; m0 += 2 * half)
; #pragma unroll
;             for (int mm = 0; mm < half; ++mm) { const int ia = m0 + mm, ib = ia + half; const cf a = x[ia], b = x[ib];
;                 x[ia] = cf{a.x + b.x, a.y + b.y}; const cf d{a.x - b.x, a.y - b.y};
;                 x[ib] = cmul(d, twc(ws, (mm << s) * (16 / R))); }
;         ws = cmul(ws, ws); }
; }
; __device__ __forceinline__ void fft_conv(ldsf2 buf, const LAS unsigned* spec) {
;     ...
;     { const int tid = otid(); cf x[16];
; #pragma unroll
;       for (int m = 0; m < 16; ++m) { const v2f v = buf[tid * 17 + m]; x[m] = cf{v.x, v.y}; }
;       dif_reg<4>(x, cf{1.0f, 0.0f});
; #pragma unroll
;       for (int m = 0; m < 16; ++m) { const h2_t hv = __builtin_bit_cast(h2_t, spec[tid * 17 + m]); x[m] = cmul(x[m], cf{(float)hv.x, (float)hv.y}); }
	v_pk_add_f32 v[156:157], v[128:129], v[128:129] op_sel:[0,1] op_sel_hi:[1,0] neg_lo:[0,0] neg_hi:[0,1]
	v_pk_mul_f32 v[162:163], v[128:129], v[128:129] op_sel:[1,1] op_sel_hi:[1,0]
	v_pk_mul_f32 v[158:159], v[156:157], s[16:17] op_sel:[0,0] op_sel_hi:[1,0]
	v_pk_fma_f32 v[162:163], v[128:129], v[128:129], v[162:163] op_sel:[0,0,0] op_sel_hi:[0,1,1] neg_lo:[0,0,1] neg_hi:[0,0,0]
	v_pk_mul_f32 v[160:161], v[156:157], s[16:17] op_sel:[1,0] op_sel_hi:[0,0] neg_lo:[0,0] neg_hi:[1,0]
	s_nop 0
	v_pk_mul_f32 v[164:165], v[162:163], v[162:163] op_sel:[1,1] op_sel_hi:[1,0]
	s_nop 0
	v_pk_fma_f32 v[164:165], v[162:163], v[162:163], v[164:165] op_sel:[0,0,0] op_sel_hi:[0,1,1] neg_lo:[0,0,1] neg_hi:[0,0,0]
	v_pk_add_f32 v[166:167], v[132:133], v[140:141] neg_lo:[0,1] neg_hi:[0,1]
	v_pk_add_f32 v[168:169], v[134:135], v[142:143] neg_lo:[0,1] neg_hi:[0,1]
	v_pk_add_f32 v[170:171], v[136:137], v[152:153] neg_lo:[0,1] neg_hi:[0,1]
	v_pk_add_f32 v[172:173], v[138:139], v[154:155] neg_lo:[0,1] neg_hi:[0,1]
	v_pk_add_f32 v[132:133], v[132:133], v[140:141]
	v_pk_add_f32 v[134:135], v[134:135], v[142:143]
	v_pk_add_f32 v[136:137], v[136:137], v[152:153]
	v_pk_add_f32 v[138:139], v[138:139], v[154:155]
	v_pk_mul_f32 v[140:141], v[166:167], v[128:129] op_sel:[1,1] op_sel_hi:[1,0]
	v_pk_mul_f32 v[142:143], v[168:169], v[158:159] op_sel:[1,1] op_sel_hi:[1,0]
	v_pk_mul_f32 v[152:153], v[170:171], v[128:129] op_sel:[1,0] op_sel_hi:[1,1]
	v_pk_mul_f32 v[154:155], v[172:173], v[160:161] op_sel:[1,1] op_sel_hi:[1,0]
	v_pk_fma_f32 v[140:141], v[166:167], v[128:129], v[140:141] op_sel:[0,0,0] op_sel_hi:[0,1,1] neg_lo:[0,0,1] neg_hi:[0,0,0]
	v_pk_fma_f32 v[142:143], v[168:169], v[158:159], v[142:143] op_sel:[0,0,0] op_sel_hi:[0,1,1] neg_lo:[0,0,1] neg_hi:[0,0,0]
	v_pk_fma_f32 v[152:153], v[170:171], v[128:129], v[152:153] op_sel:[0,1,0] op_sel_hi:[0,0,1] neg_lo:[0,0,0] neg_hi:[0,1,0]
	v_pk_fma_f32 v[154:155], v[172:173], v[160:161], v[154:155] op_sel:[0,0,0] op_sel_hi:[0,1,1] neg_lo:[0,0,1] neg_hi:[0,0,0]
	v_pk_add_f32 v[166:167], v[132:133], v[136:137] neg_lo:[0,1] neg_hi:[0,1]
	v_pk_add_f32 v[168:169], v[134:135], v[138:139] neg_lo:[0,1] neg_hi:[0,1]
	v_pk_add_f32 v[170:171], v[140:141], v[152:153] neg_lo:[0,1] neg_hi:[0,1]
	v_pk_add_f32 v[172:173], v[142:143], v[154:155] neg_lo:[0,1] neg_hi:[0,1]
	v_pk_add_f32 v[132:133], v[132:133], v[136:137]
	v_pk_add_f32 v[134:135], v[134:135], v[138:139]
	v_pk_add_f32 v[140:141], v[140:141], v[152:153]
	v_pk_add_f32 v[142:143], v[142:143], v[154:155]
	v_pk_mul_f32 v[136:137], v[166:167], v[162:163] op_sel:[1,1] op_sel_hi:[1,0]
	v_pk_mul_f32 v[138:139], v[168:169], v[162:163] op_sel:[1,0] op_sel_hi:[1,1]
	v_pk_mul_f32 v[152:153], v[170:171], v[162:163] op_sel:[1,1] op_sel_hi:[1,0]
	v_pk_mul_f32 v[154:155], v[172:173], v[162:163] op_sel:[1,0] op_sel_hi:[1,1]
	v_pk_fma_f32 v[136:137], v[166:167], v[162:163], v[136:137] op_sel:[0,0,0] op_sel_hi:[0,1,1] neg_lo:[0,0,1] neg_hi:[0,0,0]
	v_pk_fma_f32 v[138:139], v[168:169], v[162:163], v[138:139] op_sel:[0,1,0] op_sel_hi:[0,0,1] neg_lo:[0,0,0] neg_hi:[0,1,0]
	v_pk_fma_f32 v[152:153], v[170:171], v[162:163], v[152:153] op_sel:[0,0,0] op_sel_hi:[0,1,1] neg_lo:[0,0,1] neg_hi:[0,0,0]
	v_pk_fma_f32 v[154:155], v[172:173], v[162:163], v[154:155] op_sel:[0,1,0] op_sel_hi:[0,0,1] neg_lo:[0,0,0] neg_hi:[0,1,0]
	v_pk_add_f32 v[166:167], v[132:133], v[134:135] neg_lo:[0,1] neg_hi:[0,1]
	v_pk_add_f32 v[168:169], v[136:137], v[138:139] neg_lo:[0,1] neg_hi:[0,1]
	v_pk_add_f32 v[170:171], v[140:141], v[142:143] neg_lo:[0,1] neg_hi:[0,1]
	v_pk_add_f32 v[172:173], v[152:153], v[154:155] neg_lo:[0,1] neg_hi:[0,1]
	v_pk_add_f32 v[132:133], v[132:133], v[134:135]
	v_pk_add_f32 v[136:137], v[136:137], v[138:139]
	v_pk_add_f32 v[140:141], v[140:141], v[142:143]
	v_pk_add_f32 v[152:153], v[152:153], v[154:155]
	v_pk_mul_f32 v[134:135], v[166:167], v[164:165] op_sel:[1,1] op_sel_hi:[1,0]
	v_pk_mul_f32 v[138:139], v[168:169], v[164:165] op_sel:[1,1] op_sel_hi:[1,0]
	v_pk_mul_f32 v[142:143], v[170:171], v[164:165] op_sel:[1,1] op_sel_hi:[1,0]
	v_pk_mul_f32 v[154:155], v[172:173], v[164:165] op_sel:[1,1] op_sel_hi:[1,0]
	v_pk_fma_f32 v[134:135], v[166:167], v[164:165], v[134:135] op_sel:[0,0,0] op_sel_hi:[0,1,1] neg_lo:[0,0,1] neg_hi:[0,0,0]
	v_pk_fma_f32 v[138:139], v[168:169], v[164:165], v[138:139] op_sel:[0,0,0] op_sel_hi:[0,1,1] neg_lo:[0,0,1] neg_hi:[0,0,0]
	v_pk_fma_f32 v[142:143], v[170:171], v[164:165], v[142:143] op_sel:[0,0,0] op_sel_hi:[0,1,1] neg_lo:[0,0,1] neg_hi:[0,0,0]
	v_pk_fma_f32 v[154:155], v[172:173], v[164:165], v[154:155] op_sel:[0,0,0] op_sel_hi:[0,1,1] neg_lo:[0,0,1] neg_hi:[0,0,0]
	ds_write2_b64 v126, v[132:133], v[134:135] offset1:17
	ds_write2_b64 v126, v[136:137], v[138:139] offset0:34 offset1:51
	ds_write2_b64 v126, v[140:141], v[142:143] offset0:68 offset1:85
	ds_write2_b64 v126, v[152:153], v[154:155] offset0:102 offset1:119
	s_mov_b64 s[10:11], 0
	v_mov_b32_e32 v162, v195
	s_movk_i32 s0, 0x88
	s_waitcnt lgkmcnt(0)
	s_mov_b32 s86, s63
	v_mul_lo_u32 v78, v162, s0
	v_add_u32_e32 v151, 0, v78
	ds_read2_b64 v[80:83], v151 offset1:1
	ds_read2_b64 v[84:87], v151 offset0:2 offset1:3
	ds_read2_b64 v[98:101], v151 offset0:4 offset1:5
	ds_read2_b64 v[102:105], v151 offset0:6 offset1:7
	ds_read2_b64 v[106:109], v151 offset0:8 offset1:9
	ds_read2_b64 v[110:113], v151 offset0:10 offset1:11
	ds_read2_b64 v[126:129], v151 offset0:12 offset1:13
	ds_read2_b64 v[134:137], v151 offset0:14 offset1:15
	s_mov_b32 s10, s63
	s_mov_b32 s11, s16
	s_mov_b32 s17, s5
	s_mov_b32 s0, s16
	s_mov_b32 s1, s4
	s_mov_b32 s0, s63
	s_mov_b32 s1, s5
	s_mov_b32 s0, s87
	s_mov_b32 s1, s4
	s_mov_b32 s1, s5
	s_mov_b32 s35, s4
	s_mov_b32 s12, s63
	s_movk_i32 s0, 0x44
	v_mul_lo_u32 v114, v162, s0
	v_add_u32_e32 v114, 0, v114
	v_add_u32_e32 v114, 0x19800, v114
	ds_read2_b32 v[160:161], v114 offset1:1
	ds_read2_b32 v[162:163], v114 offset0:2 offset1:3
	ds_read2_b32 v[164:165], v114 offset0:4 offset1:5
	ds_read2_b32 v[166:167], v114 offset0:6 offset1:7
	ds_read2_b32 v[168:169], v114 offset0:8 offset1:9
	ds_read2_b32 v[142:143], v114 offset0:10 offset1:11
	ds_read2_b32 v[138:139], v114 offset0:12 offset1:13
	ds_read2_b32 v[172:173], v114 offset0:14 offset1:15
	s_mov_b32 s0, s5
	s_mov_b64 s[14:15], -1
	s_mov_b32 s35, s13
	s_mov_b32 s0, s13
	s_waitcnt lgkmcnt(8)
; __device__ __forceinline__ cf twc(cf ws, int k16) { if (k16 == 0) return ws; if (k16 == 4) return cf{ws.y, -ws.x}; return cmul(ws, cf{c16(k16), -s16(k16)}); }
; template <int LR> __device__ __forceinline__ void dif_reg(cf (&x)[1 << LR], cf w) {
;     constexpr int R = 1 << LR; cf ws = w;
; #pragma unroll
;     for (int s = 0; s < LR; ++s) { const int half = R >> (s + 1);
; #pragma unroll
;         for (int m0 = 0; m0 < R; m0 += 2 * half)
; #pragma unroll
;             for (int mm = 0; mm < half; ++mm) { const int ia = m0 + mm, ib = ia + half; const cf a = x[ia], b = x[ib];
;                 x[ia] = cf{a.x + b.x, a.y + b.y}; const cf d{a.x - b.x, a.y - b.y};
;                 x[ib] = cmul(d, twc(ws, (mm << s) * (16 / R))); }
;         ws = cmul(ws, ws); }
; }
	v_pk_add_f32 v[88:89], v[80:81], v[106:107]
	v_pk_add_f32 v[90:91], v[82:83], v[108:109]
	v_pk_add_f32 v[92:93], v[84:85], v[110:111]
	v_pk_add_f32 v[94:95], v[86:87], v[112:113]
	v_pk_add_f32 v[80:81], v[80:81], v[106:107] neg_lo:[0,1] neg_hi:[0,1]
	v_pk_add_f32 v[82:83], v[82:83], v[108:109] neg_lo:[0,1] neg_hi:[0,1]
	v_pk_add_f32 v[84:85], v[84:85], v[110:111] neg_lo:[0,1] neg_hi:[0,1]
	v_pk_add_f32 v[86:87], v[86:87], v[112:113] neg_lo:[0,1] neg_hi:[0,1]
	v_pk_mul_f32 v[108:109], v[82:83], s[4:5] op_sel:[1,1] op_sel_hi:[1,0] neg_lo:[0,1] neg_hi:[0,0]
	v_pk_mul_f32 v[110:111], v[84:85], s[16:17] op_sel:[1,0] op_sel_hi:[1,0] neg_lo:[0,1] neg_hi:[0,0]
	v_pk_mul_f32 v[112:113], v[86:87], s[4:5] op_sel:[1,0] op_sel_hi:[1,1] neg_lo:[0,1] neg_hi:[0,0]
	v_pk_fma_f32 v[108:109], v[82:83], s[4:5], v[108:109] op_sel:[0,0,0] op_sel_hi:[0,1,1] neg_lo:[0,0,1] neg_hi:[0,1,0]
	v_pk_fma_f32 v[110:111], v[84:85], s[16:17], v[110:111] op_sel:[0,0,0] op_sel_hi:[0,0,1] neg_lo:[0,0,1] neg_hi:[0,1,0]
	v_pk_fma_f32 v[112:113], v[86:87], s[4:5], v[112:113] op_sel:[0,1,0] op_sel_hi:[0,0,1] neg_lo:[0,0,1] neg_hi:[0,1,0]
	v_pk_add_f32 v[96:97], v[98:99], v[126:127]
	v_pk_add_f32 v[116:117], v[100:101], v[128:129]
	v_pk_add_f32 v[118:119], v[102:103], v[134:135]
	v_pk_add_f32 v[120:121], v[104:105], v[136:137]
	v_pk_add_f32 v[98:99], v[98:99], v[126:127] op_sel:[1,1] op_sel_hi:[0,0] neg_lo:[0,1] neg_hi:[1,0]
	v_pk_add_f32 v[100:101], v[100:101], v[128:129] neg_lo:[0,1] neg_hi:[0,1]
	v_pk_add_f32 v[102:103], v[102:103], v[134:135] neg_lo:[0,1] neg_hi:[0,1]
	v_pk_add_f32 v[104:105], v[104:105], v[136:137] neg_lo:[0,1] neg_hi:[0,1]
	v_pk_mul_f32 v[128:129], v[100:101], s[4:5] op_sel:[1,0] op_sel_hi:[1,1] neg_lo:[0,1] neg_hi:[0,1]
	v_pk_mul_f32 v[134:135], v[102:103], s[16:17] op_sel:[1,0] op_sel_hi:[1,0] neg_lo:[0,1] neg_hi:[0,1]
	v_pk_mul_f32 v[136:137], v[104:105], s[4:5] op_sel:[1,1] op_sel_hi:[1,0] neg_lo:[0,1] neg_hi:[0,1]
	v_pk_fma_f32 v[128:129], v[100:101], s[4:5], v[128:129] op_sel:[0,1,0] op_sel_hi:[0,0,1] neg_lo:[0,1,1] neg_hi:[0,1,0]
	v_pk_fma_f32 v[134:135], v[102:103], s[16:17], v[134:135] op_sel:[0,0,0] op_sel_hi:[0,0,1] neg_lo:[0,1,1] neg_hi:[0,1,0]
	v_pk_fma_f32 v[136:137], v[104:105], s[4:5], v[136:137] op_sel:[0,0,0] op_sel_hi:[0,1,1] neg_lo:[0,1,1] neg_hi:[0,1,0]
	v_pk_add_f32 v[122:123], v[88:89], v[96:97]
	v_pk_add_f32 v[124:125], v[90:91], v[116:117]
	v_pk_add_f32 v[130:131], v[92:93], v[118:119]
	v_pk_add_f32 v[132:133], v[94:95], v[120:121]
	v_pk_add_f32 v[88:89], v[88:89], v[96:97] neg_lo:[0,1] neg_hi:[0,1]
	v_pk_add_f32 v[90:91], v[90:91], v[116:117] neg_lo:[0,1] neg_hi:[0,1]
	v_pk_add_f32 v[92:93], v[92:93], v[118:119] op_sel:[1,1] op_sel_hi:[0,0] neg_lo:[0,1] neg_hi:[1,0]
	v_pk_add_f32 v[94:95], v[94:95], v[120:121] neg_lo:[0,1] neg_hi:[0,1]
	v_pk_mul_f32 v[116:117], v[90:91], s[16:17] op_sel:[1,0] op_sel_hi:[1,0] neg_lo:[0,1] neg_hi:[0,0]
	v_pk_mul_f32 v[120:121], v[94:95], s[16:17] op_sel:[1,0] op_sel_hi:[1,0] neg_lo:[0,1] neg_hi:[0,1]
	v_pk_fma_f32 v[116:117], v[90:91], s[16:17], v[116:117] op_sel:[0,0,0] op_sel_hi:[0,0,1] neg_lo:[0,0,1] neg_hi:[0,1,0]
	v_pk_fma_f32 v[120:121], v[94:95], s[16:17], v[120:121] op_sel:[0,0,0] op_sel_hi:[0,0,1] neg_lo:[0,1,1] neg_hi:[0,1,0]
	v_pk_add_f32 v[140:141], v[80:81], v[98:99]
	v_pk_add_f32 v[152:153], v[108:109], v[128:129]
	v_pk_add_f32 v[154:155], v[110:111], v[134:135]
	v_pk_add_f32 v[156:157], v[112:113], v[136:137]
	v_pk_add_f32 v[80:81], v[80:81], v[98:99] neg_lo:[0,1] neg_hi:[0,1]
	v_pk_add_f32 v[108:109], v[108:109], v[128:129] neg_lo:[0,1] neg_hi:[0,1]
	v_pk_add_f32 v[110:111], v[110:111], v[134:135] op_sel:[1,1] op_sel_hi:[0,0] neg_lo:[0,1] neg_hi:[1,0]
	v_pk_add_f32 v[112:113], v[112:113], v[136:137] neg_lo:[0,1] neg_hi:[0,1]
	v_pk_mul_f32 v[128:129], v[108:109], s[16:17] op_sel:[1,0] op_sel_hi:[1,0] neg_lo:[0,1] neg_hi:[0,0]
	v_pk_mul_f32 v[136:137], v[112:113], s[16:17] op_sel:[1,0] op_sel_hi:[1,0] neg_lo:[0,1] neg_hi:[0,1]
	v_pk_fma_f32 v[128:129], v[108:109], s[16:17], v[128:129] op_sel:[0,0,0] op_sel_hi:[0,0,1] neg_lo:[0,0,1] neg_hi:[0,1,0]
	v_pk_fma_f32 v[136:137], v[112:113], s[16:17], v[136:137] op_sel:[0,0,0] op_sel_hi:[0,0,1] neg_lo:[0,1,1] neg_hi:[0,1,0]
	v_pk_add_f32 v[158:159], v[122:123], v[130:131]
	v_pk_add_f32 v[170:171], v[124:125], v[132:133]
	v_pk_add_f32 v[106:107], v[88:89], v[92:93]
	v_pk_add_f32 v[82:83], v[116:117], v[120:121]
	v_pk_add_f32 v[122:123], v[122:123], v[130:131] neg_lo:[0,1] neg_hi:[0,1]
	v_pk_add_f32 v[124:125], v[124:125], v[132:133] op_sel:[1,1] op_sel_hi:[0,0] neg_lo:[0,1] neg_hi:[1,0]
	v_pk_add_f32 v[88:89], v[88:89], v[92:93] neg_lo:[0,1] neg_hi:[0,1]
	v_pk_add_f32 v[116:117], v[116:117], v[120:121] op_sel:[1,1] op_sel_hi:[0,0] neg_lo:[0,1] neg_hi:[1,0]
	v_pk_add_f32 v[84:85], v[140:141], v[154:155]
	v_pk_add_f32 v[86:87], v[152:153], v[156:157]
	v_pk_add_f32 v[126:127], v[80:81], v[110:111]
	v_pk_add_f32 v[100:101], v[128:129], v[136:137]
	v_pk_add_f32 v[140:141], v[140:141], v[154:155] neg_lo:[0,1] neg_hi:[0,1]
	v_pk_add_f32 v[152:153], v[152:153], v[156:157] op_sel:[1,1] op_sel_hi:[0,0] neg_lo:[0,1] neg_hi:[1,0]
	v_pk_add_f32 v[80:81], v[80:81], v[110:111] neg_lo:[0,1] neg_hi:[0,1]
	v_pk_add_f32 v[128:129], v[128:129], v[136:137] op_sel:[1,1] op_sel_hi:[0,0] neg_lo:[0,1] neg_hi:[1,0]
	v_pk_add_f32 v[102:103], v[158:159], v[170:171]
	v_pk_add_f32 v[104:105], v[122:123], v[124:125]
	v_pk_add_f32 v[96:97], v[106:107], v[82:83]
	v_pk_add_f32 v[90:91], v[88:89], v[116:117]
	v_pk_add_f32 v[158:159], v[158:159], v[170:171] neg_lo:[0,1] neg_hi:[0,1]
	v_pk_add_f32 v[122:123], v[122:123], v[124:125] neg_lo:[0,1] neg_hi:[0,1]
	v_pk_add_f32 v[106:107], v[106:107], v[82:83] neg_lo:[0,1] neg_hi:[0,1]
	v_pk_add_f32 v[88:89], v[88:89], v[116:117] neg_lo:[0,1] neg_hi:[0,1]
	v_pk_add_f32 v[118:119], v[84:85], v[86:87]
	v_pk_add_f32 v[94:95], v[140:141], v[152:153]
	v_pk_add_f32 v[98:99], v[126:127], v[100:101]
	v_pk_add_f32 v[108:109], v[80:81], v[128:129]
	v_pk_add_f32 v[84:85], v[84:85], v[86:87] neg_lo:[0,1] neg_hi:[0,1]
	v_pk_add_f32 v[140:141], v[140:141], v[152:153] neg_lo:[0,1] neg_hi:[0,1]
	v_pk_add_f32 v[126:127], v[126:127], v[100:101] neg_lo:[0,1] neg_hi:[0,1]
	v_pk_add_f32 v[80:81], v[80:81], v[128:129] neg_lo:[0,1] neg_hi:[0,1]
	s_waitcnt lgkmcnt(0)
; __device__ __forceinline__ int otid() { int t = threadIdx.x; asm volatile("" : "+v"(t)); return t; }
; __device__ __forceinline__ void fft_conv(ldsf2 buf, const LAS unsigned* spec) {
;     ...
;     { const int tid = otid(); cf x[16];
; #pragma unroll
;       for (int m = 0; m < 16; ++m) { const v2f v = buf[tid * 17 + m]; x[m] = cf{v.x, v.y}; }
;       dif_reg<4>(x, cf{1.0f, 0.0f});
; #pragma unroll
;       for (int m = 0; m < 16; ++m) { const h2_t hv = __builtin_bit_cast(h2_t, spec[tid * 17 + m]); x[m] = cmul(x[m], cf{(float)hv.x, (float)hv.y}); }
;       dit_reg<4>(x, cf{1.0f, 0.0f});
	v_cvt_f32_f16_e32 v134, v160
	v_cvt_f32_f16_e32 v130, v161
	v_cvt_f32_f16_e32 v92, v162
	v_cvt_f32_f16_e32 v154, v163
	v_cvt_f32_f16_sdwa v135, v160 dst_sel:DWORD dst_unused:UNUSED_PAD src0_sel:WORD_1
	v_cvt_f32_f16_sdwa v131, v161 dst_sel:DWORD dst_unused:UNUSED_PAD src0_sel:WORD_1
	v_cvt_f32_f16_sdwa v93, v162 dst_sel:DWORD dst_unused:UNUSED_PAD src0_sel:WORD_1
	v_cvt_f32_f16_sdwa v155, v163 dst_sel:DWORD dst_unused:UNUSED_PAD src0_sel:WORD_1
	v_pk_mul_f32 v[112:113], v[102:103], v[134:135] op_sel:[1,1] op_sel_hi:[1,0]
	v_pk_mul_f32 v[132:133], v[158:159], v[130:131] op_sel:[1,1] op_sel_hi:[1,0]
	v_pk_mul_f32 v[120:121], v[104:105], v[92:93] op_sel:[1,1] op_sel_hi:[1,0]
	v_pk_mul_f32 v[156:157], v[122:123], v[154:155] op_sel:[1,1] op_sel_hi:[1,0]
	v_pk_fma_f32 v[134:135], v[102:103], v[134:135], v[112:113] op_sel:[0,0,0] op_sel_hi:[0,1,1] neg_lo:[0,0,1] neg_hi:[0,0,0]
	v_pk_fma_f32 v[130:131], v[158:159], v[130:131], v[132:133] op_sel:[0,0,0] op_sel_hi:[0,1,1] neg_lo:[0,0,1] neg_hi:[0,0,0]
	v_pk_fma_f32 v[92:93], v[104:105], v[92:93], v[120:121] op_sel:[0,0,0] op_sel_hi:[0,1,1] neg_lo:[0,0,1] neg_hi:[0,0,0]
	v_pk_fma_f32 v[154:155], v[122:123], v[154:155], v[156:157] op_sel:[0,0,0] op_sel_hi:[0,1,1] neg_lo:[0,0,1] neg_hi:[0,0,0]
	v_cvt_f32_f16_e32 v110, v164
	v_cvt_f32_f16_e32 v170, v165
	v_cvt_f32_f16_e32 v82, v166
	v_cvt_f32_f16_e32 v86, v167
	v_cvt_f32_f16_sdwa v111, v164 dst_sel:DWORD dst_unused:UNUSED_PAD src0_sel:WORD_1
	v_cvt_f32_f16_sdwa v171, v165 dst_sel:DWORD dst_unused:UNUSED_PAD src0_sel:WORD_1
	v_cvt_f32_f16_sdwa v83, v166 dst_sel:DWORD dst_unused:UNUSED_PAD src0_sel:WORD_1
	v_cvt_f32_f16_sdwa v87, v167 dst_sel:DWORD dst_unused:UNUSED_PAD src0_sel:WORD_1
	v_pk_mul_f32 v[136:137], v[96:97], v[110:111] op_sel:[1,1] op_sel_hi:[1,0]
	v_pk_mul_f32 v[124:125], v[106:107], v[170:171] op_sel:[1,1] op_sel_hi:[1,0]
	v_pk_mul_f32 v[116:117], v[90:91], v[82:83] op_sel:[1,1] op_sel_hi:[1,0]
	v_pk_mul_f32 v[152:153], v[88:89], v[86:87] op_sel:[1,1] op_sel_hi:[1,0]
	v_pk_fma_f32 v[110:111], v[96:97], v[110:111], v[136:137] op_sel:[0,0,0] op_sel_hi:[0,1,1] neg_lo:[0,0,1] neg_hi:[0,0,0]
	v_pk_fma_f32 v[170:171], v[106:107], v[170:171], v[124:125] op_sel:[0,0,0] op_sel_hi:[0,1,1] neg_lo:[0,0,1] neg_hi:[0,0,0]
	v_pk_fma_f32 v[82:83], v[90:91], v[82:83], v[116:117] op_sel:[0,0,0] op_sel_hi:[0,1,1] neg_lo:[0,0,1] neg_hi:[0,0,0]
	v_pk_fma_f32 v[86:87], v[88:89], v[86:87], v[152:153] op_sel:[0,0,0] op_sel_hi:[0,1,1] neg_lo:[0,0,1] neg_hi:[0,0,0]
	v_cvt_f32_f16_e32 v100, v168
	v_cvt_f32_f16_e32 v112, v169
	v_cvt_f32_f16_e32 v132, v142
	v_cvt_f32_f16_e32 v120, v143
	v_cvt_f32_f16_sdwa v101, v168 dst_sel:DWORD dst_unused:UNUSED_PAD src0_sel:WORD_1
	v_cvt_f32_f16_sdwa v113, v169 dst_sel:DWORD dst_unused:UNUSED_PAD src0_sel:WORD_1
	v_cvt_f32_f16_sdwa v133, v142 dst_sel:DWORD dst_unused:UNUSED_PAD src0_sel:WORD_1
	v_cvt_f32_f16_sdwa v121, v143 dst_sel:DWORD dst_unused:UNUSED_PAD src0_sel:WORD_1
	v_pk_mul_f32 v[128:129], v[118:119], v[100:101] op_sel:[1,1] op_sel_hi:[1,0]
	v_pk_mul_f32 v[102:103], v[84:85], v[112:113] op_sel:[1,1] op_sel_hi:[1,0]
	v_pk_mul_f32 v[158:159], v[94:95], v[132:133] op_sel:[1,1] op_sel_hi:[1,0]
	v_pk_mul_f32 v[104:105], v[140:141], v[120:121] op_sel:[1,1] op_sel_hi:[1,0]
	v_pk_fma_f32 v[100:101], v[118:119], v[100:101], v[128:129] op_sel:[0,0,0] op_sel_hi:[0,1,1] neg_lo:[0,0,1] neg_hi:[0,0,0]
	v_pk_fma_f32 v[112:113], v[84:85], v[112:113], v[102:103] op_sel:[0,0,0] op_sel_hi:[0,1,1] neg_lo:[0,0,1] neg_hi:[0,0,0]
	v_pk_fma_f32 v[132:133], v[94:95], v[132:133], v[158:159] op_sel:[0,0,0] op_sel_hi:[0,1,1] neg_lo:[0,0,1] neg_hi:[0,0,0]
	v_pk_fma_f32 v[120:121], v[140:141], v[120:121], v[104:105] op_sel:[0,0,0] op_sel_hi:[0,1,1] neg_lo:[0,0,1] neg_hi:[0,0,0]
	v_cvt_f32_f16_e32 v156, v138
	v_cvt_f32_f16_e32 v136, v139
	v_cvt_f32_f16_e32 v124, v172
	v_cvt_f32_f16_e32 v116, v173
	v_cvt_f32_f16_sdwa v157, v138 dst_sel:DWORD dst_unused:UNUSED_PAD src0_sel:WORD_1
	v_cvt_f32_f16_sdwa v137, v139 dst_sel:DWORD dst_unused:UNUSED_PAD src0_sel:WORD_1
	v_cvt_f32_f16_sdwa v125, v172 dst_sel:DWORD dst_unused:UNUSED_PAD src0_sel:WORD_1
	v_cvt_f32_f16_sdwa v117, v173 dst_sel:DWORD dst_unused:UNUSED_PAD src0_sel:WORD_1
	v_pk_mul_f32 v[122:123], v[98:99], v[156:157] op_sel:[1,1] op_sel_hi:[1,0]
	v_pk_mul_f32 v[96:97], v[126:127], v[136:137] op_sel:[1,1] op_sel_hi:[1,0]
	v_pk_mul_f32 v[106:107], v[108:109], v[124:125] op_sel:[1,1] op_sel_hi:[1,0]
	v_pk_mul_f32 v[90:91], v[80:81], v[116:117] op_sel:[1,1] op_sel_hi:[1,0]
	v_pk_fma_f32 v[156:157], v[98:99], v[156:157], v[122:123] op_sel:[0,0,0] op_sel_hi:[0,1,1] neg_lo:[0,0,1] neg_hi:[0,0,0]
	v_pk_fma_f32 v[136:137], v[126:127], v[136:137], v[96:97] op_sel:[0,0,0] op_sel_hi:[0,1,1] neg_lo:[0,0,1] neg_hi:[0,0,0]
	v_pk_fma_f32 v[124:125], v[108:109], v[124:125], v[106:107] op_sel:[0,0,0] op_sel_hi:[0,1,1] neg_lo:[0,0,1] neg_hi:[0,0,0]
	v_pk_fma_f32 v[116:117], v[80:81], v[116:117], v[90:91] op_sel:[0,0,0] op_sel_hi:[0,1,1] neg_lo:[0,0,1] neg_hi:[0,0,0]
	v_pk_add_f32 v[152:153], v[134:135], v[130:131]
	v_pk_add_f32 v[88:89], v[92:93], v[154:155]
	v_pk_add_f32 v[128:129], v[110:111], v[170:171]
	v_pk_add_f32 v[118:119], v[82:83], v[86:87]
	v_pk_add_f32 v[134:135], v[134:135], v[130:131] neg_lo:[0,1] neg_hi:[0,1]
	v_pk_add_f32 v[92:93], v[92:93], v[154:155] neg_lo:[0,1] neg_hi:[0,1]
	v_pk_add_f32 v[110:111], v[110:111], v[170:171] neg_lo:[0,1] neg_hi:[0,1]
	v_pk_add_f32 v[82:83], v[82:83], v[86:87] neg_lo:[0,1] neg_hi:[0,1]
	v_pk_add_f32 v[102:103], v[100:101], v[112:113]
	v_pk_add_f32 v[84:85], v[132:133], v[120:121]
	v_pk_add_f32 v[158:159], v[156:157], v[136:137]
	v_pk_add_f32 v[94:95], v[124:125], v[116:117]
; __device__ __forceinline__ cf twc(cf ws, int k16) { if (k16 == 0) return ws; if (k16 == 4) return cf{ws.y, -ws.x}; return cmul(ws, cf{c16(k16), -s16(k16)}); }
; __device__ __forceinline__ void wave_lds_fence() { asm volatile("s_waitcnt lgkmcnt(0)" ::: "memory"); }
; template <int LR> __device__ __forceinline__ void dit_reg(cf (&x)[1 << LR], cf w) {
;     constexpr int R = 1 << LR; cf wsv[LR]; wsv[0] = w;
; #pragma unroll
;     for (int s = 1; s < LR; ++s) wsv[s] = cmul(wsv[s - 1], wsv[s - 1]);
; #pragma unroll
;     for (int s = LR - 1; s >= 0; --s) { const int half = R >> (s + 1);
; #pragma unroll
;         for (int m0 = 0; m0 < R; m0 += 2 * half)
; #pragma unroll
;             for (int mm = 0; mm < half; ++mm) { const int ia = m0 + mm, ib = ia + half; const cf a = x[ia];
;                 const cf b = cmulc(x[ib], twc(wsv[s], (mm << s) * (16 / R)));
;                 x[ia] = cf{a.x + b.x, a.y + b.y}; x[ib] = cf{a.x - b.x, a.y - b.y}; } }
; }
; __device__ __forceinline__ void fft_conv(ldsf2 buf, const LAS unsigned* spec) {
;     ...
;       dit_reg<4>(x, cf{1.0f, 0.0f});
; #pragma unroll
;       for (int m = 0; m < 16; ++m) buf[tid * 17 + m] = mkv2(x[m].x, x[m].y); }
;     wave_lds_fence();
;     fft_inv_cba(buf);
	v_pk_add_f32 v[100:101], v[100:101], v[112:113] neg_lo:[0,1] neg_hi:[0,1]
	v_pk_add_f32 v[132:133], v[132:133], v[120:121] neg_lo:[0,1] neg_hi:[0,1]
	v_pk_add_f32 v[156:157], v[156:157], v[136:137] neg_lo:[0,1] neg_hi:[0,1]
	v_pk_add_f32 v[124:125], v[124:125], v[116:117] neg_lo:[0,1] neg_hi:[0,1]
	v_pk_add_f32 v[104:105], v[152:153], v[88:89]
	v_pk_add_f32 v[140:141], v[134:135], v[92:93] op_sel:[0,1] op_sel_hi:[1,0] neg_lo:[0,1] neg_hi:[0,0]
	v_pk_add_f32 v[122:123], v[128:129], v[118:119]
	v_pk_add_f32 v[98:99], v[110:111], v[82:83] op_sel:[0,1] op_sel_hi:[1,0] neg_lo:[0,1] neg_hi:[0,0]
	v_pk_add_f32 v[152:153], v[152:153], v[88:89] neg_lo:[0,1] neg_hi:[0,1]
	v_pk_add_f32 v[134:135], v[134:135], v[92:93] op_sel:[0,1] op_sel_hi:[1,0] neg_lo:[0,0] neg_hi:[0,1]
	v_pk_add_f32 v[128:129], v[128:129], v[118:119] neg_lo:[0,1] neg_hi:[0,1]
	v_pk_add_f32 v[110:111], v[110:111], v[82:83] op_sel:[0,1] op_sel_hi:[1,0] neg_lo:[0,0] neg_hi:[0,1]
	v_pk_add_f32 v[96:97], v[102:103], v[84:85]
	v_pk_add_f32 v[126:127], v[100:101], v[132:133] op_sel:[0,1] op_sel_hi:[1,0] neg_lo:[0,1] neg_hi:[0,0]
	v_pk_add_f32 v[106:107], v[158:159], v[94:95]
	v_pk_add_f32 v[108:109], v[156:157], v[124:125] op_sel:[0,1] op_sel_hi:[1,0] neg_lo:[0,1] neg_hi:[0,0]
	v_pk_add_f32 v[102:103], v[102:103], v[84:85] neg_lo:[0,1] neg_hi:[0,1]
	v_pk_add_f32 v[100:101], v[100:101], v[132:133] op_sel:[0,1] op_sel_hi:[1,0] neg_lo:[0,0] neg_hi:[0,1]
	v_pk_add_f32 v[158:159], v[158:159], v[94:95] neg_lo:[0,1] neg_hi:[0,1]
	v_pk_add_f32 v[156:157], v[156:157], v[124:125] op_sel:[0,1] op_sel_hi:[1,0] neg_lo:[0,0] neg_hi:[0,1]
	v_pk_add_f32 v[90:91], v[104:105], v[122:123]
	v_pk_mul_f32 v[80:81], v[98:99], s[16:17] op_sel:[1,0] op_sel_hi:[1,0] neg_lo:[0,1] neg_hi:[0,0]
	v_pk_add_f32 v[130:131], v[152:153], v[128:129] op_sel:[0,1] op_sel_hi:[1,0] neg_lo:[0,1] neg_hi:[0,0]
	v_pk_mul_f32 v[154:155], v[110:111], s[16:17] op_sel:[1,0] op_sel_hi:[1,0] neg_lo:[0,1] neg_hi:[0,1]
	v_pk_add_f32 v[104:105], v[104:105], v[122:123] neg_lo:[0,1] neg_hi:[0,1]
	v_pk_fma_f32 v[80:81], v[98:99], s[16:17], v[80:81] op_sel:[0,0,0] op_sel_hi:[0,0,1] neg_lo:[0,0,0] neg_hi:[0,0,0]
	v_pk_add_f32 v[152:153], v[152:153], v[128:129] op_sel:[0,1] op_sel_hi:[1,0] neg_lo:[0,0] neg_hi:[0,1]
	v_pk_fma_f32 v[154:155], v[110:111], s[16:17], v[154:155] op_sel:[0,0,0] op_sel_hi:[0,0,1] neg_lo:[0,1,0] neg_hi:[0,0,0]
	v_pk_add_f32 v[98:99], v[140:141], v[80:81] neg_lo:[0,1] neg_hi:[0,1]
	v_pk_add_f32 v[110:111], v[134:135], v[154:155] neg_lo:[0,1] neg_hi:[0,1]
	v_pk_add_f32 v[140:141], v[140:141], v[80:81]
	v_pk_add_f32 v[134:135], v[134:135], v[154:155]
	v_pk_add_f32 v[170:171], v[96:97], v[106:107]
	v_pk_mul_f32 v[86:87], v[108:109], s[16:17] op_sel:[1,0] op_sel_hi:[1,0] neg_lo:[0,1] neg_hi:[0,0]
	v_pk_add_f32 v[112:113], v[102:103], v[158:159] op_sel:[0,1] op_sel_hi:[1,0] neg_lo:[0,1] neg_hi:[0,0]
	v_pk_mul_f32 v[120:121], v[156:157], s[16:17] op_sel:[1,0] op_sel_hi:[1,0] neg_lo:[0,1] neg_hi:[0,1]
	v_pk_add_f32 v[96:97], v[96:97], v[106:107] neg_lo:[0,1] neg_hi:[0,1]
	v_pk_fma_f32 v[86:87], v[108:109], s[16:17], v[86:87] op_sel:[0,0,0] op_sel_hi:[0,0,1] neg_lo:[0,0,0] neg_hi:[0,0,0]
	v_pk_add_f32 v[102:103], v[102:103], v[158:159] op_sel:[0,1] op_sel_hi:[1,0] neg_lo:[0,0] neg_hi:[0,1]
	v_pk_fma_f32 v[120:121], v[156:157], s[16:17], v[120:121] op_sel:[0,0,0] op_sel_hi:[0,0,1] neg_lo:[0,1,0] neg_hi:[0,0,0]
	v_pk_add_f32 v[108:109], v[126:127], v[86:87] neg_lo:[0,1] neg_hi:[0,1]
	v_pk_add_f32 v[156:157], v[100:101], v[120:121] neg_lo:[0,1] neg_hi:[0,1]
	v_pk_add_f32 v[126:127], v[126:127], v[86:87]
	v_pk_add_f32 v[100:101], v[100:101], v[120:121]
	v_pk_add_f32 v[136:137], v[90:91], v[170:171]
	v_pk_mul_f32 v[116:117], v[126:127], s[4:5] op_sel:[1,1] op_sel_hi:[1,0] neg_lo:[0,1] neg_hi:[0,0]
	v_pk_mul_f32 v[88:89], v[112:113], s[16:17] op_sel:[1,0] op_sel_hi:[1,0] neg_lo:[0,1] neg_hi:[0,0]
	v_pk_mul_f32 v[92:93], v[100:101], s[4:5] op_sel:[1,0] op_sel_hi:[1,1] neg_lo:[0,1] neg_hi:[0,0]
	v_pk_add_f32 v[90:91], v[90:91], v[170:171] neg_lo:[0,1] neg_hi:[0,1]
	v_pk_fma_f32 v[116:117], v[126:127], s[4:5], v[116:117] op_sel:[0,0,0] op_sel_hi:[0,1,1] neg_lo:[0,0,0] neg_hi:[0,0,0]
	v_pk_fma_f32 v[88:89], v[112:113], s[16:17], v[88:89] op_sel:[0,0,0] op_sel_hi:[0,0,1] neg_lo:[0,0,0] neg_hi:[0,0,0]
	v_pk_fma_f32 v[92:93], v[100:101], s[4:5], v[92:93] op_sel:[0,1,0] op_sel_hi:[0,0,1] neg_lo:[0,0,0] neg_hi:[0,0,0]
	v_pk_add_f32 v[126:127], v[140:141], v[116:117] neg_lo:[0,1] neg_hi:[0,1]
	v_pk_add_f32 v[112:113], v[130:131], v[88:89] neg_lo:[0,1] neg_hi:[0,1]
	v_pk_add_f32 v[100:101], v[134:135], v[92:93] neg_lo:[0,1] neg_hi:[0,1]
	v_pk_add_f32 v[140:141], v[140:141], v[116:117]
	v_pk_add_f32 v[130:131], v[130:131], v[88:89]
	v_pk_add_f32 v[134:135], v[134:135], v[92:93]
	v_pk_add_f32 v[118:119], v[104:105], v[96:97] op_sel:[0,1] op_sel_hi:[1,0] neg_lo:[0,1] neg_hi:[0,0]
	v_pk_mul_f32 v[82:83], v[108:109], s[4:5] op_sel:[1,0] op_sel_hi:[1,1] neg_lo:[0,1] neg_hi:[0,1]
	v_pk_mul_f32 v[84:85], v[102:103], s[16:17] op_sel:[1,0] op_sel_hi:[1,0] neg_lo:[0,1] neg_hi:[0,1]
	v_pk_mul_f32 v[132:133], v[156:157], s[4:5] op_sel:[1,1] op_sel_hi:[1,0] neg_lo:[0,1] neg_hi:[0,1]
	v_pk_add_f32 v[104:105], v[104:105], v[96:97] op_sel:[0,1] op_sel_hi:[1,0] neg_lo:[0,0] neg_hi:[0,1]
	v_pk_fma_f32 v[82:83], v[108:109], s[4:5], v[82:83] op_sel:[0,1,0] op_sel_hi:[0,0,1] neg_lo:[0,1,0] neg_hi:[0,0,0]
	v_pk_fma_f32 v[84:85], v[102:103], s[16:17], v[84:85] op_sel:[0,0,0] op_sel_hi:[0,0,1] neg_lo:[0,1,0] neg_hi:[0,0,0]
	v_pk_fma_f32 v[132:133], v[156:157], s[4:5], v[132:133] op_sel:[0,0,0] op_sel_hi:[0,1,1] neg_lo:[0,1,0] neg_hi:[0,0,0]
	v_pk_add_f32 v[108:109], v[98:99], v[82:83] neg_lo:[0,1] neg_hi:[0,1]
	v_pk_add_f32 v[102:103], v[152:153], v[84:85] neg_lo:[0,1] neg_hi:[0,1]
	v_pk_add_f32 v[156:157], v[110:111], v[132:133] neg_lo:[0,1] neg_hi:[0,1]
	v_pk_add_f32 v[98:99], v[98:99], v[82:83]
	v_pk_add_f32 v[152:153], v[152:153], v[84:85]
	v_pk_add_f32 v[110:111], v[110:111], v[132:133]
	ds_write2_b64 v151, v[136:137], v[140:141] offset1:1
	ds_write2_b64 v151, v[130:131], v[134:135] offset0:2 offset1:3
	ds_write2_b64 v151, v[118:119], v[98:99] offset0:4 offset1:5
	ds_write2_b64 v151, v[152:153], v[110:111] offset0:6 offset1:7
	ds_write2_b64 v151, v[90:91], v[126:127] offset0:8 offset1:9
	ds_write2_b64 v151, v[112:113], v[100:101] offset0:10 offset1:11
	ds_write2_b64 v151, v[104:105], v[108:109] offset0:12 offset1:13
	ds_write2_b64 v151, v[102:103], v[156:157] offset0:14 offset1:15
	v_mov_b32_e32 v78, v195
	s_waitcnt lgkmcnt(0)
	s_mov_b32 s0, 0
	v_and_b32_e32 v81, 15, v78
	v_lshlrev_b32_e32 v80, 4, v78
	v_lshlrev_b32_e32 v83, 9, v81
	v_and_b32_e32 v80, 0xfffffc00, v80
	v_lshlrev_b32_e32 v82, 3, v78
	v_add_u32_e32 v83, 0, v83
	v_and_b32_e32 v79, 63, v78
	v_lshl_add_u32 v81, v81, 3, 0
	v_and_or_b32 v82, v82, s90, v80
	v_add_u32_e32 v83, 0x22000, v83
; #define LAS __attribute__((address_space(3)))
; __device__ __forceinline__ cf twc(cf ws, int k16) { if (k16 == 0) return ws; if (k16 == 4) return cf{ws.y, -ws.x}; return cmul(ws, cf{c16(k16), -s16(k16)}); }
; template <int LR> __device__ __forceinline__ void dit_reg(cf (&x)[1 << LR], cf w) {
;     constexpr int R = 1 << LR; cf wsv[LR]; wsv[0] = w;
; #pragma unroll
;     for (int s = 1; s < LR; ++s) wsv[s] = cmul(wsv[s - 1], wsv[s - 1]);
; #pragma unroll
;     for (int s = LR - 1; s >= 0; --s) { const int half = R >> (s + 1);
; #pragma unroll
;         for (int m0 = 0; m0 < R; m0 += 2 * half)
; #pragma unroll
;             for (int mm = 0; mm < half; ++mm) { const int ia = m0 + mm, ib = ia + half; const cf a = x[ia];
;                 const cf b = cmulc(x[ib], twc(wsv[s], (mm << s) * (16 / R)));
;                 x[ia] = cf{a.x + b.x, a.y + b.y}; x[ib] = cf{a.x - b.x, a.y - b.y}; } }
; }
; template <int LR, bool INV> __device__ __forceinline__ void fft_pass(ldsf2 buf, int base, int stride, int twi) {
;     constexpr int R = 1 << LR; cf x[R];
;     const v2f wv = ((ldsf2)((LAS unsigned char*)buf + 139264))[twi];
; #pragma unroll
;     for (int m = 0; m < R; ++m) { const v2f v = buf[base + m * stride]; x[m] = cf{v.x, v.y}; }
;     const cf w{wv.x, wv.y};
;     if (INV) dit_reg<LR>(x, w); else dif_reg<LR>(x, w);
; #pragma unroll
;     for (int m = 0; m < R; ++m) buf[base + m * stride] = mkv2(x[m].x, x[m].y);
; }
.LBB0_365:
	ds_read_b64 v[100:101], v83
	v_or_b32_e32 v84, s0, v82
	v_lshlrev_b32_e32 v85, 3, v84
	v_ashrrev_i32_e32 v84, 1, v84
	v_add3_u32 v130, v81, v85, v84
	ds_read2_b64 v[84:87], v130 offset1:17
	ds_read2_b64 v[88:91], v130 offset0:34 offset1:51
	ds_read2_b64 v[92:95], v130 offset0:68 offset1:85
	ds_read2_b64 v[96:99], v130 offset0:102 offset1:119
	s_movk_i32 s0, 0x200
	ds_read_b64 v[132:133], v83
	v_or_b32_e32 v134, s0, v82
	v_lshlrev_b32_e32 v136, 3, v134
	v_ashrrev_i32_e32 v134, 1, v134
	v_add3_u32 v138, v81, v136, v134
	ds_read2_b64 v[140:143], v138 offset1:17
	ds_read2_b64 v[152:155], v138 offset0:34 offset1:51
	ds_read2_b64 v[156:159], v138 offset0:68 offset1:85
	ds_read2_b64 v[160:163], v138 offset0:102 offset1:119
	s_waitcnt lgkmcnt(5)
	v_pk_add_f32 v[102:103], v[100:101], v[100:101] op_sel:[0,1] op_sel_hi:[1,0] neg_lo:[0,0] neg_hi:[0,1]
	v_pk_mul_f32 v[108:109], v[100:101], v[100:101] op_sel:[1,1] op_sel_hi:[1,0]
	v_pk_mul_f32 v[104:105], v[102:103], s[16:17] op_sel:[0,0] op_sel_hi:[1,0]
	v_pk_fma_f32 v[108:109], v[100:101], v[100:101], v[108:109] op_sel:[0,0,0] op_sel_hi:[0,1,1] neg_lo:[0,0,1] neg_hi:[0,0,0]
	v_pk_mul_f32 v[106:107], v[102:103], s[16:17] op_sel:[1,0] op_sel_hi:[0,0] neg_lo:[0,0] neg_hi:[1,0]
	s_nop 0
	v_pk_mul_f32 v[110:111], v[108:109], v[108:109] op_sel:[1,1] op_sel_hi:[1,0]
	s_nop 0
	v_pk_fma_f32 v[110:111], v[108:109], v[108:109], v[110:111] op_sel:[0,0,0] op_sel_hi:[0,1,1] neg_lo:[0,0,1] neg_hi:[0,0,0]
	v_pk_mul_f32 v[112:113], v[86:87], v[110:111] op_sel:[1,1] op_sel_hi:[1,0]
	v_pk_mul_f32 v[114:115], v[90:91], v[110:111] op_sel:[1,1] op_sel_hi:[1,0]
	v_pk_mul_f32 v[116:117], v[94:95], v[110:111] op_sel:[1,1] op_sel_hi:[1,0]
	v_pk_mul_f32 v[118:119], v[98:99], v[110:111] op_sel:[1,1] op_sel_hi:[1,0]
	v_pk_fma_f32 v[112:113], v[86:87], v[110:111], v[112:113] op_sel:[0,0,0] op_sel_hi:[0,1,1] neg_lo:[0,0,0] neg_hi:[0,1,0]
	v_pk_fma_f32 v[114:115], v[90:91], v[110:111], v[114:115] op_sel:[0,0,0] op_sel_hi:[0,1,1] neg_lo:[0,0,0] neg_hi:[0,1,0]
	v_pk_fma_f32 v[116:117], v[94:95], v[110:111], v[116:117] op_sel:[0,0,0] op_sel_hi:[0,1,1] neg_lo:[0,0,0] neg_hi:[0,1,0]
	v_pk_fma_f32 v[118:119], v[98:99], v[110:111], v[118:119] op_sel:[0,0,0] op_sel_hi:[0,1,1] neg_lo:[0,0,0] neg_hi:[0,1,0]
	v_pk_add_f32 v[86:87], v[84:85], v[112:113] neg_lo:[0,1] neg_hi:[0,1]
	v_pk_add_f32 v[90:91], v[88:89], v[114:115] neg_lo:[0,1] neg_hi:[0,1]
	v_pk_add_f32 v[94:95], v[92:93], v[116:117] neg_lo:[0,1] neg_hi:[0,1]
	v_pk_add_f32 v[98:99], v[96:97], v[118:119] neg_lo:[0,1] neg_hi:[0,1]
	v_pk_add_f32 v[84:85], v[84:85], v[112:113]
	v_pk_add_f32 v[88:89], v[88:89], v[114:115]
	v_pk_add_f32 v[92:93], v[92:93], v[116:117]
	v_pk_add_f32 v[96:97], v[96:97], v[118:119]
	v_pk_mul_f32 v[112:113], v[88:89], v[108:109] op_sel:[1,1] op_sel_hi:[1,0]
	v_pk_mul_f32 v[114:115], v[90:91], v[108:109] op_sel:[1,0] op_sel_hi:[1,1]
	v_pk_mul_f32 v[116:117], v[96:97], v[108:109] op_sel:[1,1] op_sel_hi:[1,0]
	v_pk_mul_f32 v[118:119], v[98:99], v[108:109] op_sel:[1,0] op_sel_hi:[1,1]
	v_pk_fma_f32 v[112:113], v[88:89], v[108:109], v[112:113] op_sel:[0,0,0] op_sel_hi:[0,1,1] neg_lo:[0,0,0] neg_hi:[0,1,0]
	v_pk_fma_f32 v[114:115], v[90:91], v[108:109], v[114:115] op_sel:[0,1,0] op_sel_hi:[0,0,1] neg_lo:[0,0,1] neg_hi:[0,0,0]
	v_pk_fma_f32 v[116:117], v[96:97], v[108:109], v[116:117] op_sel:[0,0,0] op_sel_hi:[0,1,1] neg_lo:[0,0,0] neg_hi:[0,1,0]
	v_pk_fma_f32 v[118:119], v[98:99], v[108:109], v[118:119] op_sel:[0,1,0] op_sel_hi:[0,0,1] neg_lo:[0,0,1] neg_hi:[0,0,0]
	v_pk_add_f32 v[88:89], v[84:85], v[112:113] neg_lo:[0,1] neg_hi:[0,1]
	v_pk_add_f32 v[90:91], v[86:87], v[114:115] neg_lo:[0,1] neg_hi:[0,1]
	v_pk_add_f32 v[96:97], v[92:93], v[116:117] neg_lo:[0,1] neg_hi:[0,1]
	v_pk_add_f32 v[98:99], v[94:95], v[118:119] neg_lo:[0,1] neg_hi:[0,1]
	v_pk_add_f32 v[84:85], v[84:85], v[112:113]
	v_pk_add_f32 v[86:87], v[86:87], v[114:115]
	v_pk_add_f32 v[92:93], v[92:93], v[116:117]
	v_pk_add_f32 v[94:95], v[94:95], v[118:119]
	v_pk_mul_f32 v[112:113], v[92:93], v[100:101] op_sel:[1,1] op_sel_hi:[1,0]
	v_pk_mul_f32 v[114:115], v[94:95], v[104:105] op_sel:[1,1] op_sel_hi:[1,0]
	v_pk_mul_f32 v[116:117], v[96:97], v[100:101] op_sel:[1,0] op_sel_hi:[1,1]
	v_pk_mul_f32 v[118:119], v[98:99], v[106:107] op_sel:[1,1] op_sel_hi:[1,0]
	v_pk_fma_f32 v[112:113], v[92:93], v[100:101], v[112:113] op_sel:[0,0,0] op_sel_hi:[0,1,1] neg_lo:[0,0,0] neg_hi:[0,1,0]
	v_pk_fma_f32 v[114:115], v[94:95], v[104:105], v[114:115] op_sel:[0,0,0] op_sel_hi:[0,1,1] neg_lo:[0,0,0] neg_hi:[0,1,0]
	v_pk_fma_f32 v[116:117], v[96:97], v[100:101], v[116:117] op_sel:[0,1,0] op_sel_hi:[0,0,1] neg_lo:[0,0,1] neg_hi:[0,0,0]
	v_pk_fma_f32 v[118:119], v[98:99], v[106:107], v[118:119] op_sel:[0,0,0] op_sel_hi:[0,1,1] neg_lo:[0,0,0] neg_hi:[0,1,0]
	v_pk_add_f32 v[92:93], v[84:85], v[112:113] neg_lo:[0,1] neg_hi:[0,1]
	v_pk_add_f32 v[94:95], v[86:87], v[114:115] neg_lo:[0,1] neg_hi:[0,1]
	v_pk_add_f32 v[96:97], v[88:89], v[116:117] neg_lo:[0,1] neg_hi:[0,1]
	v_pk_add_f32 v[98:99], v[90:91], v[118:119] neg_lo:[0,1] neg_hi:[0,1]
	v_pk_add_f32 v[84:85], v[84:85], v[112:113]
	v_pk_add_f32 v[86:87], v[86:87], v[114:115]
	v_pk_add_f32 v[88:89], v[88:89], v[116:117]
	v_pk_add_f32 v[90:91], v[90:91], v[118:119]
	ds_write2_b64 v130, v[84:85], v[86:87] offset1:17
	ds_write2_b64 v130, v[88:89], v[90:91] offset0:34 offset1:51
	ds_write2_b64 v130, v[92:93], v[94:95] offset0:68 offset1:85
	ds_write2_b64 v130, v[96:97], v[98:99] offset0:102 offset1:119
	s_waitcnt lgkmcnt(4)
; __device__ __forceinline__ int otid() { int t = threadIdx.x; asm volatile("" : "+v"(t)); return t; }
; __device__ __forceinline__ cf twc(cf ws, int k16) { if (k16 == 0) return ws; if (k16 == 4) return cf{ws.y, -ws.x}; return cmul(ws, cf{c16(k16), -s16(k16)}); }
; __device__ __forceinline__ void wave_lds_fence() { asm volatile("s_waitcnt lgkmcnt(0)" ::: "memory"); }
; template <int LR> __device__ __forceinline__ void dit_reg(cf (&x)[1 << LR], cf w) {
;     constexpr int R = 1 << LR; cf wsv[LR]; wsv[0] = w;
; #pragma unroll
;     for (int s = 1; s < LR; ++s) wsv[s] = cmul(wsv[s - 1], wsv[s - 1]);
; #pragma unroll
;     for (int s = LR - 1; s >= 0; --s) { const int half = R >> (s + 1);
; #pragma unroll
;         for (int m0 = 0; m0 < R; m0 += 2 * half)
; #pragma unroll
;             for (int mm = 0; mm < half; ++mm) { const int ia = m0 + mm, ib = ia + half; const cf a = x[ia];
;                 const cf b = cmulc(x[ib], twc(wsv[s], (mm << s) * (16 / R)));
;                 x[ia] = cf{a.x + b.x, a.y + b.y}; x[ib] = cf{a.x - b.x, a.y - b.y}; } }
; }
; __device__ __forceinline__ void fft_inv_cba(ldsf2 buf) {
;     const int tid = otid(); const int wv = tid >> 6, l = tid & 63;
; #pragma unroll 1
;     for (int u = 0; u < 2; ++u) { const int j = l + 64 * u, o = j & 15, e0 = wv * 1024 + (j >> 4) * 128 + o; fft_pass<3, true>(buf, e0 + (e0 >> 4), 17, o * 64); }
;     wave_lds_fence();
	v_pk_add_f32 v[164:165], v[132:133], v[132:133] op_sel:[0,1] op_sel_hi:[1,0] neg_lo:[0,0] neg_hi:[0,1]
	v_pk_mul_f32 v[170:171], v[132:133], v[132:133] op_sel:[1,1] op_sel_hi:[1,0]
	v_pk_mul_f32 v[166:167], v[164:165], s[16:17] op_sel:[0,0] op_sel_hi:[1,0]
	v_pk_fma_f32 v[170:171], v[132:133], v[132:133], v[170:171] op_sel:[0,0,0] op_sel_hi:[0,1,1] neg_lo:[0,0,1] neg_hi:[0,0,0]
	v_pk_mul_f32 v[168:169], v[164:165], s[16:17] op_sel:[1,0] op_sel_hi:[0,0] neg_lo:[0,0] neg_hi:[1,0]
	s_nop 0
	v_pk_mul_f32 v[172:173], v[170:171], v[170:171] op_sel:[1,1] op_sel_hi:[1,0]
	s_nop 0
	v_pk_fma_f32 v[172:173], v[170:171], v[170:171], v[172:173] op_sel:[0,0,0] op_sel_hi:[0,1,1] neg_lo:[0,0,1] neg_hi:[0,0,0]
	v_pk_mul_f32 v[174:175], v[142:143], v[172:173] op_sel:[1,1] op_sel_hi:[1,0]
	v_pk_mul_f32 v[188:189], v[154:155], v[172:173] op_sel:[1,1] op_sel_hi:[1,0]
	v_pk_mul_f32 v[190:191], v[158:159], v[172:173] op_sel:[1,1] op_sel_hi:[1,0]
	v_pk_mul_f32 v[196:197], v[162:163], v[172:173] op_sel:[1,1] op_sel_hi:[1,0]
	v_pk_fma_f32 v[174:175], v[142:143], v[172:173], v[174:175] op_sel:[0,0,0] op_sel_hi:[0,1,1] neg_lo:[0,0,0] neg_hi:[0,1,0]
	v_pk_fma_f32 v[188:189], v[154:155], v[172:173], v[188:189] op_sel:[0,0,0] op_sel_hi:[0,1,1] neg_lo:[0,0,0] neg_hi:[0,1,0]
	v_pk_fma_f32 v[190:191], v[158:159], v[172:173], v[190:191] op_sel:[0,0,0] op_sel_hi:[0,1,1] neg_lo:[0,0,0] neg_hi:[0,1,0]
	v_pk_fma_f32 v[196:197], v[162:163], v[172:173], v[196:197] op_sel:[0,0,0] op_sel_hi:[0,1,1] neg_lo:[0,0,0] neg_hi:[0,1,0]
	v_pk_add_f32 v[142:143], v[140:141], v[174:175] neg_lo:[0,1] neg_hi:[0,1]
	v_pk_add_f32 v[154:155], v[152:153], v[188:189] neg_lo:[0,1] neg_hi:[0,1]
	v_pk_add_f32 v[158:159], v[156:157], v[190:191] neg_lo:[0,1] neg_hi:[0,1]
	v_pk_add_f32 v[162:163], v[160:161], v[196:197] neg_lo:[0,1] neg_hi:[0,1]
	v_pk_add_f32 v[140:141], v[140:141], v[174:175]
	v_pk_add_f32 v[152:153], v[152:153], v[188:189]
	v_pk_add_f32 v[156:157], v[156:157], v[190:191]
	v_pk_add_f32 v[160:161], v[160:161], v[196:197]
	v_pk_mul_f32 v[174:175], v[152:153], v[170:171] op_sel:[1,1] op_sel_hi:[1,0]
	v_pk_mul_f32 v[188:189], v[154:155], v[170:171] op_sel:[1,0] op_sel_hi:[1,1]
	v_pk_mul_f32 v[190:191], v[160:161], v[170:171] op_sel:[1,1] op_sel_hi:[1,0]
	v_pk_mul_f32 v[196:197], v[162:163], v[170:171] op_sel:[1,0] op_sel_hi:[1,1]
	v_pk_fma_f32 v[174:175], v[152:153], v[170:171], v[174:175] op_sel:[0,0,0] op_sel_hi:[0,1,1] neg_lo:[0,0,0] neg_hi:[0,1,0]
	v_pk_fma_f32 v[188:189], v[154:155], v[170:171], v[188:189] op_sel:[0,1,0] op_sel_hi:[0,0,1] neg_lo:[0,0,1] neg_hi:[0,0,0]
	v_pk_fma_f32 v[190:191], v[160:161], v[170:171], v[190:191] op_sel:[0,0,0] op_sel_hi:[0,1,1] neg_lo:[0,0,0] neg_hi:[0,1,0]
	v_pk_fma_f32 v[196:197], v[162:163], v[170:171], v[196:197] op_sel:[0,1,0] op_sel_hi:[0,0,1] neg_lo:[0,0,1] neg_hi:[0,0,0]
	v_pk_add_f32 v[152:153], v[140:141], v[174:175] neg_lo:[0,1] neg_hi:[0,1]
	v_pk_add_f32 v[154:155], v[142:143], v[188:189] neg_lo:[0,1] neg_hi:[0,1]
	v_pk_add_f32 v[160:161], v[156:157], v[190:191] neg_lo:[0,1] neg_hi:[0,1]
	v_pk_add_f32 v[162:163], v[158:159], v[196:197] neg_lo:[0,1] neg_hi:[0,1]
	v_pk_add_f32 v[140:141], v[140:141], v[174:175]
	v_pk_add_f32 v[142:143], v[142:143], v[188:189]
	v_pk_add_f32 v[156:157], v[156:157], v[190:191]
	v_pk_add_f32 v[158:159], v[158:159], v[196:197]
	v_pk_mul_f32 v[174:175], v[156:157], v[132:133] op_sel:[1,1] op_sel_hi:[1,0]
	v_pk_mul_f32 v[188:189], v[158:159], v[166:167] op_sel:[1,1] op_sel_hi:[1,0]
	v_pk_mul_f32 v[190:191], v[160:161], v[132:133] op_sel:[1,0] op_sel_hi:[1,1]
	v_pk_mul_f32 v[196:197], v[162:163], v[168:169] op_sel:[1,1] op_sel_hi:[1,0]
	v_pk_fma_f32 v[174:175], v[156:157], v[132:133], v[174:175] op_sel:[0,0,0] op_sel_hi:[0,1,1] neg_lo:[0,0,0] neg_hi:[0,1,0]
	v_pk_fma_f32 v[188:189], v[158:159], v[166:167], v[188:189] op_sel:[0,0,0] op_sel_hi:[0,1,1] neg_lo:[0,0,0] neg_hi:[0,1,0]
	v_pk_fma_f32 v[190:191], v[160:161], v[132:133], v[190:191] op_sel:[0,1,0] op_sel_hi:[0,0,1] neg_lo:[0,0,1] neg_hi:[0,0,0]
	v_pk_fma_f32 v[196:197], v[162:163], v[168:169], v[196:197] op_sel:[0,0,0] op_sel_hi:[0,1,1] neg_lo:[0,0,0] neg_hi:[0,1,0]
	v_pk_add_f32 v[156:157], v[140:141], v[174:175] neg_lo:[0,1] neg_hi:[0,1]
	v_pk_add_f32 v[158:159], v[142:143], v[188:189] neg_lo:[0,1] neg_hi:[0,1]
	v_pk_add_f32 v[160:161], v[152:153], v[190:191] neg_lo:[0,1] neg_hi:[0,1]
	v_pk_add_f32 v[162:163], v[154:155], v[196:197] neg_lo:[0,1] neg_hi:[0,1]
	v_pk_add_f32 v[140:141], v[140:141], v[174:175]
	v_pk_add_f32 v[142:143], v[142:143], v[188:189]
	v_pk_add_f32 v[152:153], v[152:153], v[190:191]
	v_pk_add_f32 v[154:155], v[154:155], v[196:197]
	ds_write2_b64 v138, v[140:141], v[142:143] offset1:17
	ds_write2_b64 v138, v[152:153], v[154:155] offset0:34 offset1:51
	ds_write2_b64 v138, v[156:157], v[158:159] offset0:68 offset1:85
	ds_write2_b64 v138, v[160:161], v[162:163] offset0:102 offset1:119
	s_mov_b64 s[14:15], 0
	s_waitcnt lgkmcnt(0)
	s_mov_b32 s0, 0
	s_mov_b64 s[14:15], -1
; #define LAS __attribute__((address_space(3)))
; __device__ __forceinline__ cf twc(cf ws, int k16) { if (k16 == 0) return ws; if (k16 == 4) return cf{ws.y, -ws.x}; return cmul(ws, cf{c16(k16), -s16(k16)}); }
; template <int LR> __device__ __forceinline__ void dit_reg(cf (&x)[1 << LR], cf w) {
;     constexpr int R = 1 << LR; cf wsv[LR]; wsv[0] = w;
; #pragma unroll
;     for (int s = 1; s < LR; ++s) wsv[s] = cmul(wsv[s - 1], wsv[s - 1]);
; #pragma unroll
;     for (int s = LR - 1; s >= 0; --s) { const int half = R >> (s + 1);
; #pragma unroll
;         for (int m0 = 0; m0 < R; m0 += 2 * half)
; #pragma unroll
;             for (int mm = 0; mm < half; ++mm) { const int ia = m0 + mm, ib = ia + half; const cf a = x[ia];
;                 const cf b = cmulc(x[ib], twc(wsv[s], (mm << s) * (16 / R)));
;                 x[ia] = cf{a.x + b.x, a.y + b.y}; x[ib] = cf{a.x - b.x, a.y - b.y}; } }
; }
; __device__ __forceinline__ void lds_barrier() { asm volatile("s_waitcnt lgkmcnt(0)\n\ts_barrier" ::: "memory"); }
; template <int LR, bool INV> __device__ __forceinline__ void fft_pass(ldsf2 buf, int base, int stride, int twi) {
;     constexpr int R = 1 << LR; cf x[R];
;     const v2f wv = ((ldsf2)((LAS unsigned char*)buf + 139264))[twi];
; #pragma unroll
;     for (int m = 0; m < R; ++m) { const v2f v = buf[base + m * stride]; x[m] = cf{v.x, v.y}; }
;     const cf w{wv.x, wv.y};
;     if (INV) dit_reg<LR>(x, w); else dif_reg<LR>(x, w);
; #pragma unroll
;     for (int m = 0; m < R; ++m) buf[base + m * stride] = mkv2(x[m].x, x[m].y);
; }
.LBB0_367:
	v_or_b32_e32 v81, s0, v79
	v_or_b32_e32 v82, v81, v80
	v_lshl_add_u32 v81, v81, 6, 0
	v_add_u32_e32 v81, 0x22000, v81
	ds_read_b64 v[98:99], v81
	v_ashrrev_i32_e32 v83, 4, v82
	v_lshlrev_b32_e32 v81, 3, v82
	v_lshlrev_b32_e32 v82, 3, v83
	v_add3_u32 v81, 0, v81, v82
	v_add_u32_e32 v130, 0x1800, v81
	v_add_u32_e32 v129, 0x1000, v81
	ds_read2_b64 v[94:97], v130 offset0:48 offset1:184
	ds_read2_b64 v[90:93], v129 offset0:32 offset1:168
	v_add_u32_e32 v128, 0x800, v81
	ds_read2_b64 v[82:85], v81 offset1:136
	ds_read2_b64 v[86:89], v128 offset0:16 offset1:152
	s_mov_b32 s0, 64
	v_or_b32_e32 v132, s0, v79
	v_or_b32_e32 v134, v132, v80
	v_lshl_add_u32 v132, v132, 6, 0
	v_add_u32_e32 v132, 0x22000, v132
	ds_read_b64 v[136:137], v132
	v_ashrrev_i32_e32 v138, 4, v134
	v_lshlrev_b32_e32 v132, 3, v134
	v_lshlrev_b32_e32 v134, 3, v138
	v_add3_u32 v132, 0, v132, v134
	v_add_u32_e32 v140, 0x1800, v132
	v_add_u32_e32 v142, 0x1000, v132
	ds_read2_b64 v[152:155], v140 offset0:48 offset1:184
	ds_read2_b64 v[156:159], v142 offset0:32 offset1:168
	v_add_u32_e32 v160, 0x800, v132
	ds_read2_b64 v[162:165], v132 offset1:136
	ds_read2_b64 v[166:169], v160 offset0:16 offset1:152
	s_waitcnt lgkmcnt(5)
	v_pk_add_f32 v[100:101], v[98:99], v[98:99] op_sel:[0,1] op_sel_hi:[1,0] neg_lo:[0,0] neg_hi:[0,1]
	v_pk_mul_f32 v[106:107], v[98:99], v[98:99] op_sel:[1,1] op_sel_hi:[1,0]
	v_pk_mul_f32 v[102:103], v[100:101], s[16:17] op_sel:[0,0] op_sel_hi:[1,0]
	v_pk_fma_f32 v[106:107], v[98:99], v[98:99], v[106:107] op_sel:[0,0,0] op_sel_hi:[0,1,1] neg_lo:[0,0,1] neg_hi:[0,0,0]
	v_pk_mul_f32 v[104:105], v[100:101], s[16:17] op_sel:[1,0] op_sel_hi:[0,0] neg_lo:[0,0] neg_hi:[1,0]
	s_nop 0
	v_pk_mul_f32 v[108:109], v[106:107], v[106:107] op_sel:[1,1] op_sel_hi:[1,0]
	s_nop 0
	v_pk_fma_f32 v[108:109], v[106:107], v[106:107], v[108:109] op_sel:[0,0,0] op_sel_hi:[0,1,1] neg_lo:[0,0,1] neg_hi:[0,0,0]
	v_pk_mul_f32 v[110:111], v[84:85], v[108:109] op_sel:[1,1] op_sel_hi:[1,0]
	v_pk_mul_f32 v[112:113], v[88:89], v[108:109] op_sel:[1,1] op_sel_hi:[1,0]
	v_pk_mul_f32 v[114:115], v[92:93], v[108:109] op_sel:[1,1] op_sel_hi:[1,0]
	v_pk_mul_f32 v[116:117], v[96:97], v[108:109] op_sel:[1,1] op_sel_hi:[1,0]
	v_pk_fma_f32 v[110:111], v[84:85], v[108:109], v[110:111] op_sel:[0,0,0] op_sel_hi:[0,1,1] neg_lo:[0,0,0] neg_hi:[0,1,0]
	v_pk_fma_f32 v[112:113], v[88:89], v[108:109], v[112:113] op_sel:[0,0,0] op_sel_hi:[0,1,1] neg_lo:[0,0,0] neg_hi:[0,1,0]
	v_pk_fma_f32 v[114:115], v[92:93], v[108:109], v[114:115] op_sel:[0,0,0] op_sel_hi:[0,1,1] neg_lo:[0,0,0] neg_hi:[0,1,0]
	v_pk_fma_f32 v[116:117], v[96:97], v[108:109], v[116:117] op_sel:[0,0,0] op_sel_hi:[0,1,1] neg_lo:[0,0,0] neg_hi:[0,1,0]
	v_pk_add_f32 v[84:85], v[82:83], v[110:111] neg_lo:[0,1] neg_hi:[0,1]
	v_pk_add_f32 v[88:89], v[86:87], v[112:113] neg_lo:[0,1] neg_hi:[0,1]
	v_pk_add_f32 v[92:93], v[90:91], v[114:115] neg_lo:[0,1] neg_hi:[0,1]
	v_pk_add_f32 v[96:97], v[94:95], v[116:117] neg_lo:[0,1] neg_hi:[0,1]
	v_pk_add_f32 v[82:83], v[82:83], v[110:111]
	v_pk_add_f32 v[86:87], v[86:87], v[112:113]
	v_pk_add_f32 v[90:91], v[90:91], v[114:115]
	v_pk_add_f32 v[94:95], v[94:95], v[116:117]
	v_pk_mul_f32 v[110:111], v[86:87], v[106:107] op_sel:[1,1] op_sel_hi:[1,0]
	v_pk_mul_f32 v[112:113], v[88:89], v[106:107] op_sel:[1,0] op_sel_hi:[1,1]
	v_pk_mul_f32 v[114:115], v[94:95], v[106:107] op_sel:[1,1] op_sel_hi:[1,0]
	v_pk_mul_f32 v[116:117], v[96:97], v[106:107] op_sel:[1,0] op_sel_hi:[1,1]
	v_pk_fma_f32 v[110:111], v[86:87], v[106:107], v[110:111] op_sel:[0,0,0] op_sel_hi:[0,1,1] neg_lo:[0,0,0] neg_hi:[0,1,0]
	v_pk_fma_f32 v[112:113], v[88:89], v[106:107], v[112:113] op_sel:[0,1,0] op_sel_hi:[0,0,1] neg_lo:[0,0,1] neg_hi:[0,0,0]
	v_pk_fma_f32 v[114:115], v[94:95], v[106:107], v[114:115] op_sel:[0,0,0] op_sel_hi:[0,1,1] neg_lo:[0,0,0] neg_hi:[0,1,0]
	v_pk_fma_f32 v[116:117], v[96:97], v[106:107], v[116:117] op_sel:[0,1,0] op_sel_hi:[0,0,1] neg_lo:[0,0,1] neg_hi:[0,0,0]
	v_pk_add_f32 v[86:87], v[82:83], v[110:111] neg_lo:[0,1] neg_hi:[0,1]
	v_pk_add_f32 v[88:89], v[84:85], v[112:113] neg_lo:[0,1] neg_hi:[0,1]
	v_pk_add_f32 v[94:95], v[90:91], v[114:115] neg_lo:[0,1] neg_hi:[0,1]
	v_pk_add_f32 v[96:97], v[92:93], v[116:117] neg_lo:[0,1] neg_hi:[0,1]
	v_pk_add_f32 v[82:83], v[82:83], v[110:111]
	v_pk_add_f32 v[84:85], v[84:85], v[112:113]
	v_pk_add_f32 v[90:91], v[90:91], v[114:115]
	v_pk_add_f32 v[92:93], v[92:93], v[116:117]
	v_pk_mul_f32 v[110:111], v[90:91], v[98:99] op_sel:[1,1] op_sel_hi:[1,0]
	v_pk_mul_f32 v[112:113], v[92:93], v[102:103] op_sel:[1,1] op_sel_hi:[1,0]
	v_pk_mul_f32 v[114:115], v[94:95], v[98:99] op_sel:[1,0] op_sel_hi:[1,1]
	v_pk_mul_f32 v[116:117], v[96:97], v[104:105] op_sel:[1,1] op_sel_hi:[1,0]
	v_pk_fma_f32 v[110:111], v[90:91], v[98:99], v[110:111] op_sel:[0,0,0] op_sel_hi:[0,1,1] neg_lo:[0,0,0] neg_hi:[0,1,0]
	v_pk_fma_f32 v[112:113], v[92:93], v[102:103], v[112:113] op_sel:[0,0,0] op_sel_hi:[0,1,1] neg_lo:[0,0,0] neg_hi:[0,1,0]
	v_pk_fma_f32 v[114:115], v[94:95], v[98:99], v[114:115] op_sel:[0,1,0] op_sel_hi:[0,0,1] neg_lo:[0,0,1] neg_hi:[0,0,0]
	v_pk_fma_f32 v[116:117], v[96:97], v[104:105], v[116:117] op_sel:[0,0,0] op_sel_hi:[0,1,1] neg_lo:[0,0,0] neg_hi:[0,1,0]
	v_pk_add_f32 v[90:91], v[82:83], v[110:111] neg_lo:[0,1] neg_hi:[0,1]
	v_pk_add_f32 v[92:93], v[84:85], v[112:113] neg_lo:[0,1] neg_hi:[0,1]
	v_pk_add_f32 v[94:95], v[86:87], v[114:115] neg_lo:[0,1] neg_hi:[0,1]
	v_pk_add_f32 v[96:97], v[88:89], v[116:117] neg_lo:[0,1] neg_hi:[0,1]
	v_pk_add_f32 v[82:83], v[82:83], v[110:111]
	v_pk_add_f32 v[84:85], v[84:85], v[112:113]
	v_pk_add_f32 v[86:87], v[86:87], v[114:115]
	v_pk_add_f32 v[88:89], v[88:89], v[116:117]
	ds_write2_b64 v81, v[82:83], v[84:85] offset1:136
	ds_write2_b64 v128, v[86:87], v[88:89] offset0:16 offset1:152
	ds_write2_b64 v129, v[90:91], v[92:93] offset0:32 offset1:168
	ds_write2_b64 v130, v[94:95], v[96:97] offset0:48 offset1:184
	s_waitcnt lgkmcnt(4)
; #define LAS __attribute__((address_space(3)))
; __device__ __forceinline__ cf twc(cf ws, int k16) { if (k16 == 0) return ws; if (k16 == 4) return cf{ws.y, -ws.x}; return cmul(ws, cf{c16(k16), -s16(k16)}); }
; template <int LR> __device__ __forceinline__ void dit_reg(cf (&x)[1 << LR], cf w) {
;     constexpr int R = 1 << LR; cf wsv[LR]; wsv[0] = w;
; #pragma unroll
;     for (int s = 1; s < LR; ++s) wsv[s] = cmul(wsv[s - 1], wsv[s - 1]);
; #pragma unroll
;     for (int s = LR - 1; s >= 0; --s) { const int half = R >> (s + 1);
; #pragma unroll
;         for (int m0 = 0; m0 < R; m0 += 2 * half)
; #pragma unroll
;             for (int mm = 0; mm < half; ++mm) { const int ia = m0 + mm, ib = ia + half; const cf a = x[ia];
;                 const cf b = cmulc(x[ib], twc(wsv[s], (mm << s) * (16 / R)));
;                 x[ia] = cf{a.x + b.x, a.y + b.y}; x[ib] = cf{a.x - b.x, a.y - b.y}; } }
; }
; __device__ __forceinline__ void lds_barrier() { asm volatile("s_waitcnt lgkmcnt(0)\n\ts_barrier" ::: "memory"); }
; template <int LR, bool INV> __device__ __forceinline__ void fft_pass(ldsf2 buf, int base, int stride, int twi) {
;     constexpr int R = 1 << LR; cf x[R];
;     const v2f wv = ((ldsf2)((LAS unsigned char*)buf + 139264))[twi];
; #pragma unroll
;     for (int m = 0; m < R; ++m) { const v2f v = buf[base + m * stride]; x[m] = cf{v.x, v.y}; }
;     const cf w{wv.x, wv.y};
;     if (INV) dit_reg<LR>(x, w); else dif_reg<LR>(x, w);
; #pragma unroll
;     for (int m = 0; m < R; ++m) buf[base + m * stride] = mkv2(x[m].x, x[m].y);
; }
	v_pk_add_f32 v[170:171], v[136:137], v[136:137] op_sel:[0,1] op_sel_hi:[1,0] neg_lo:[0,0] neg_hi:[0,1]
	v_pk_mul_f32 v[188:189], v[136:137], v[136:137] op_sel:[1,1] op_sel_hi:[1,0]
	v_pk_mul_f32 v[172:173], v[170:171], s[16:17] op_sel:[0,0] op_sel_hi:[1,0]
	v_pk_fma_f32 v[188:189], v[136:137], v[136:137], v[188:189] op_sel:[0,0,0] op_sel_hi:[0,1,1] neg_lo:[0,0,1] neg_hi:[0,0,0]
	v_pk_mul_f32 v[174:175], v[170:171], s[16:17] op_sel:[1,0] op_sel_hi:[0,0] neg_lo:[0,0] neg_hi:[1,0]
	s_nop 0
	v_pk_mul_f32 v[190:191], v[188:189], v[188:189] op_sel:[1,1] op_sel_hi:[1,0]
	s_nop 0
	v_pk_fma_f32 v[190:191], v[188:189], v[188:189], v[190:191] op_sel:[0,0,0] op_sel_hi:[0,1,1] neg_lo:[0,0,1] neg_hi:[0,0,0]
	v_pk_mul_f32 v[196:197], v[164:165], v[190:191] op_sel:[1,1] op_sel_hi:[1,0]
	v_pk_mul_f32 v[198:199], v[168:169], v[190:191] op_sel:[1,1] op_sel_hi:[1,0]
	v_pk_mul_f32 v[200:201], v[158:159], v[190:191] op_sel:[1,1] op_sel_hi:[1,0]
	v_pk_mul_f32 v[202:203], v[154:155], v[190:191] op_sel:[1,1] op_sel_hi:[1,0]
	v_pk_fma_f32 v[196:197], v[164:165], v[190:191], v[196:197] op_sel:[0,0,0] op_sel_hi:[0,1,1] neg_lo:[0,0,0] neg_hi:[0,1,0]
	v_pk_fma_f32 v[198:199], v[168:169], v[190:191], v[198:199] op_sel:[0,0,0] op_sel_hi:[0,1,1] neg_lo:[0,0,0] neg_hi:[0,1,0]
	v_pk_fma_f32 v[200:201], v[158:159], v[190:191], v[200:201] op_sel:[0,0,0] op_sel_hi:[0,1,1] neg_lo:[0,0,0] neg_hi:[0,1,0]
	v_pk_fma_f32 v[202:203], v[154:155], v[190:191], v[202:203] op_sel:[0,0,0] op_sel_hi:[0,1,1] neg_lo:[0,0,0] neg_hi:[0,1,0]
	v_pk_add_f32 v[164:165], v[162:163], v[196:197] neg_lo:[0,1] neg_hi:[0,1]
	v_pk_add_f32 v[168:169], v[166:167], v[198:199] neg_lo:[0,1] neg_hi:[0,1]
	v_pk_add_f32 v[158:159], v[156:157], v[200:201] neg_lo:[0,1] neg_hi:[0,1]
	v_pk_add_f32 v[154:155], v[152:153], v[202:203] neg_lo:[0,1] neg_hi:[0,1]
	v_pk_add_f32 v[162:163], v[162:163], v[196:197]
	v_pk_add_f32 v[166:167], v[166:167], v[198:199]
	v_pk_add_f32 v[156:157], v[156:157], v[200:201]
	v_pk_add_f32 v[152:153], v[152:153], v[202:203]
	v_pk_mul_f32 v[196:197], v[166:167], v[188:189] op_sel:[1,1] op_sel_hi:[1,0]
	v_pk_mul_f32 v[198:199], v[168:169], v[188:189] op_sel:[1,0] op_sel_hi:[1,1]
	v_pk_mul_f32 v[200:201], v[152:153], v[188:189] op_sel:[1,1] op_sel_hi:[1,0]
	v_pk_mul_f32 v[202:203], v[154:155], v[188:189] op_sel:[1,0] op_sel_hi:[1,1]
	v_pk_fma_f32 v[196:197], v[166:167], v[188:189], v[196:197] op_sel:[0,0,0] op_sel_hi:[0,1,1] neg_lo:[0,0,0] neg_hi:[0,1,0]
	v_pk_fma_f32 v[198:199], v[168:169], v[188:189], v[198:199] op_sel:[0,1,0] op_sel_hi:[0,0,1] neg_lo:[0,0,1] neg_hi:[0,0,0]
	v_pk_fma_f32 v[200:201], v[152:153], v[188:189], v[200:201] op_sel:[0,0,0] op_sel_hi:[0,1,1] neg_lo:[0,0,0] neg_hi:[0,1,0]
	v_pk_fma_f32 v[202:203], v[154:155], v[188:189], v[202:203] op_sel:[0,1,0] op_sel_hi:[0,0,1] neg_lo:[0,0,1] neg_hi:[0,0,0]
	v_pk_add_f32 v[166:167], v[162:163], v[196:197] neg_lo:[0,1] neg_hi:[0,1]
	v_pk_add_f32 v[168:169], v[164:165], v[198:199] neg_lo:[0,1] neg_hi:[0,1]
	v_pk_add_f32 v[152:153], v[156:157], v[200:201] neg_lo:[0,1] neg_hi:[0,1]
	v_pk_add_f32 v[154:155], v[158:159], v[202:203] neg_lo:[0,1] neg_hi:[0,1]
	v_pk_add_f32 v[162:163], v[162:163], v[196:197]
	v_pk_add_f32 v[164:165], v[164:165], v[198:199]
	v_pk_add_f32 v[156:157], v[156:157], v[200:201]
	v_pk_add_f32 v[158:159], v[158:159], v[202:203]
	v_pk_mul_f32 v[196:197], v[156:157], v[136:137] op_sel:[1,1] op_sel_hi:[1,0]
	v_pk_mul_f32 v[198:199], v[158:159], v[172:173] op_sel:[1,1] op_sel_hi:[1,0]
	v_pk_mul_f32 v[200:201], v[152:153], v[136:137] op_sel:[1,0] op_sel_hi:[1,1]
	v_pk_mul_f32 v[202:203], v[154:155], v[174:175] op_sel:[1,1] op_sel_hi:[1,0]
	v_pk_fma_f32 v[196:197], v[156:157], v[136:137], v[196:197] op_sel:[0,0,0] op_sel_hi:[0,1,1] neg_lo:[0,0,0] neg_hi:[0,1,0]
	v_pk_fma_f32 v[198:199], v[158:159], v[172:173], v[198:199] op_sel:[0,0,0] op_sel_hi:[0,1,1] neg_lo:[0,0,0] neg_hi:[0,1,0]
	v_pk_fma_f32 v[200:201], v[152:153], v[136:137], v[200:201] op_sel:[0,1,0] op_sel_hi:[0,0,1] neg_lo:[0,0,1] neg_hi:[0,0,0]
	v_pk_fma_f32 v[202:203], v[154:155], v[174:175], v[202:203] op_sel:[0,0,0] op_sel_hi:[0,1,1] neg_lo:[0,0,0] neg_hi:[0,1,0]
	v_pk_add_f32 v[156:157], v[162:163], v[196:197] neg_lo:[0,1] neg_hi:[0,1]
	v_pk_add_f32 v[158:159], v[164:165], v[198:199] neg_lo:[0,1] neg_hi:[0,1]
	v_pk_add_f32 v[152:153], v[166:167], v[200:201] neg_lo:[0,1] neg_hi:[0,1]
	v_pk_add_f32 v[154:155], v[168:169], v[202:203] neg_lo:[0,1] neg_hi:[0,1]
	v_pk_add_f32 v[162:163], v[162:163], v[196:197]
	v_pk_add_f32 v[164:165], v[164:165], v[198:199]
	v_pk_add_f32 v[166:167], v[166:167], v[200:201]
	v_pk_add_f32 v[168:169], v[168:169], v[202:203]
	ds_write2_b64 v132, v[162:163], v[164:165] offset1:136
	ds_write2_b64 v160, v[166:167], v[168:169] offset0:16 offset1:152
	ds_write2_b64 v142, v[156:157], v[158:159] offset0:32 offset1:168
	ds_write2_b64 v140, v[152:153], v[154:155] offset0:48 offset1:184
	s_mov_b64 s[14:15], 0
	s_waitcnt lgkmcnt(0)
	s_barrier
	s_mov_b32 s0, 0
	s_mov_b64 s[30:31], -1
; #define LAS __attribute__((address_space(3)))
; __device__ __forceinline__ cf twc(cf ws, int k16) { if (k16 == 0) return ws; if (k16 == 4) return cf{ws.y, -ws.x}; return cmul(ws, cf{c16(k16), -s16(k16)}); }
; template <int LR> __device__ __forceinline__ void dit_reg(cf (&x)[1 << LR], cf w) {
;     constexpr int R = 1 << LR; cf wsv[LR]; wsv[0] = w;
; #pragma unroll
;     for (int s = 1; s < LR; ++s) wsv[s] = cmul(wsv[s - 1], wsv[s - 1]);
; #pragma unroll
;     for (int s = LR - 1; s >= 0; --s) { const int half = R >> (s + 1);
; #pragma unroll
;         for (int m0 = 0; m0 < R; m0 += 2 * half)
; #pragma unroll
;             for (int mm = 0; mm < half; ++mm) { const int ia = m0 + mm, ib = ia + half; const cf a = x[ia];
;                 const cf b = cmulc(x[ib], twc(wsv[s], (mm << s) * (16 / R)));
;                 x[ia] = cf{a.x + b.x, a.y + b.y}; x[ib] = cf{a.x - b.x, a.y - b.y}; } }
; }
; __device__ __forceinline__ void lds_barrier() { asm volatile("s_waitcnt lgkmcnt(0)\n\ts_barrier" ::: "memory"); }
; template <int LR, bool INV> __device__ __forceinline__ void fft_pass(ldsf2 buf, int base, int stride, int twi) {
;     constexpr int R = 1 << LR; cf x[R];
;     const v2f wv = ((ldsf2)((LAS unsigned char*)buf + 139264))[twi];
; #pragma unroll
;     for (int m = 0; m < R; ++m) { const v2f v = buf[base + m * stride]; x[m] = cf{v.x, v.y}; }
;     const cf w{wv.x, wv.y};
;     if (INV) dit_reg<LR>(x, w); else dif_reg<LR>(x, w);
; #pragma unroll
;     for (int m = 0; m < R; ++m) buf[base + m * stride] = mkv2(x[m].x, x[m].y);
; }
.LBB0_369:
	v_add_u32_e32 v79, s0, v78
	v_ashrrev_i32_e32 v80, 4, v79
	v_lshl_add_u32 v79, v79, 3, 0
	v_add_u32_e32 v81, 0x22000, v79
	ds_read_b64 v[96:97], v81
	v_lshl_add_u32 v79, v80, 3, v79
	ds_read2st64_b64 v[80:83], v79 offset1:17
	ds_read2st64_b64 v[84:87], v79 offset0:34 offset1:51
	ds_read2st64_b64 v[88:91], v79 offset0:68 offset1:85
	ds_read2st64_b64 v[92:95], v79 offset0:102 offset1:119
	s_movk_i32 s0, 0x200
	v_add_u32_e32 v126, s0, v78
	v_ashrrev_i32_e32 v128, 4, v126
	v_lshl_add_u32 v126, v126, 3, 0
	v_add_u32_e32 v130, 0x22000, v126
	ds_read_b64 v[132:133], v130
	v_lshl_add_u32 v126, v128, 3, v126
	ds_read2st64_b64 v[134:137], v126 offset1:17
	ds_read2st64_b64 v[138:141], v126 offset0:34 offset1:51
	ds_read2st64_b64 v[152:155], v126 offset0:68 offset1:85
	ds_read2st64_b64 v[156:159], v126 offset0:102 offset1:119
	s_waitcnt lgkmcnt(5)
	v_pk_add_f32 v[98:99], v[96:97], v[96:97] op_sel:[0,1] op_sel_hi:[1,0] neg_lo:[0,0] neg_hi:[0,1]
	v_pk_mul_f32 v[104:105], v[96:97], v[96:97] op_sel:[1,1] op_sel_hi:[1,0]
	v_pk_mul_f32 v[100:101], v[98:99], s[16:17] op_sel:[0,0] op_sel_hi:[1,0]
	v_pk_fma_f32 v[104:105], v[96:97], v[96:97], v[104:105] op_sel:[0,0,0] op_sel_hi:[0,1,1] neg_lo:[0,0,1] neg_hi:[0,0,0]
	v_pk_mul_f32 v[102:103], v[98:99], s[16:17] op_sel:[1,0] op_sel_hi:[0,0] neg_lo:[0,0] neg_hi:[1,0]
	s_nop 0
	v_pk_mul_f32 v[106:107], v[104:105], v[104:105] op_sel:[1,1] op_sel_hi:[1,0]
	s_nop 0
	v_pk_fma_f32 v[106:107], v[104:105], v[104:105], v[106:107] op_sel:[0,0,0] op_sel_hi:[0,1,1] neg_lo:[0,0,1] neg_hi:[0,0,0]
	v_pk_mul_f32 v[108:109], v[82:83], v[106:107] op_sel:[1,1] op_sel_hi:[1,0]
	v_pk_mul_f32 v[110:111], v[86:87], v[106:107] op_sel:[1,1] op_sel_hi:[1,0]
	v_pk_mul_f32 v[112:113], v[90:91], v[106:107] op_sel:[1,1] op_sel_hi:[1,0]
	v_pk_mul_f32 v[114:115], v[94:95], v[106:107] op_sel:[1,1] op_sel_hi:[1,0]
	v_pk_fma_f32 v[108:109], v[82:83], v[106:107], v[108:109] op_sel:[0,0,0] op_sel_hi:[0,1,1] neg_lo:[0,0,0] neg_hi:[0,1,0]
	v_pk_fma_f32 v[110:111], v[86:87], v[106:107], v[110:111] op_sel:[0,0,0] op_sel_hi:[0,1,1] neg_lo:[0,0,0] neg_hi:[0,1,0]
	v_pk_fma_f32 v[112:113], v[90:91], v[106:107], v[112:113] op_sel:[0,0,0] op_sel_hi:[0,1,1] neg_lo:[0,0,0] neg_hi:[0,1,0]
	v_pk_fma_f32 v[114:115], v[94:95], v[106:107], v[114:115] op_sel:[0,0,0] op_sel_hi:[0,1,1] neg_lo:[0,0,0] neg_hi:[0,1,0]
	v_pk_add_f32 v[82:83], v[80:81], v[108:109] neg_lo:[0,1] neg_hi:[0,1]
	v_pk_add_f32 v[86:87], v[84:85], v[110:111] neg_lo:[0,1] neg_hi:[0,1]
	v_pk_add_f32 v[90:91], v[88:89], v[112:113] neg_lo:[0,1] neg_hi:[0,1]
	v_pk_add_f32 v[94:95], v[92:93], v[114:115] neg_lo:[0,1] neg_hi:[0,1]
	v_pk_add_f32 v[80:81], v[80:81], v[108:109]
	v_pk_add_f32 v[84:85], v[84:85], v[110:111]
	v_pk_add_f32 v[88:89], v[88:89], v[112:113]
	v_pk_add_f32 v[92:93], v[92:93], v[114:115]
	v_pk_mul_f32 v[108:109], v[84:85], v[104:105] op_sel:[1,1] op_sel_hi:[1,0]
	v_pk_mul_f32 v[110:111], v[86:87], v[104:105] op_sel:[1,0] op_sel_hi:[1,1]
	v_pk_mul_f32 v[112:113], v[92:93], v[104:105] op_sel:[1,1] op_sel_hi:[1,0]
	v_pk_mul_f32 v[114:115], v[94:95], v[104:105] op_sel:[1,0] op_sel_hi:[1,1]
	v_pk_fma_f32 v[108:109], v[84:85], v[104:105], v[108:109] op_sel:[0,0,0] op_sel_hi:[0,1,1] neg_lo:[0,0,0] neg_hi:[0,1,0]
	v_pk_fma_f32 v[110:111], v[86:87], v[104:105], v[110:111] op_sel:[0,1,0] op_sel_hi:[0,0,1] neg_lo:[0,0,1] neg_hi:[0,0,0]
	v_pk_fma_f32 v[112:113], v[92:93], v[104:105], v[112:113] op_sel:[0,0,0] op_sel_hi:[0,1,1] neg_lo:[0,0,0] neg_hi:[0,1,0]
	v_pk_fma_f32 v[114:115], v[94:95], v[104:105], v[114:115] op_sel:[0,1,0] op_sel_hi:[0,0,1] neg_lo:[0,0,1] neg_hi:[0,0,0]
	v_pk_add_f32 v[84:85], v[80:81], v[108:109] neg_lo:[0,1] neg_hi:[0,1]
	v_pk_add_f32 v[86:87], v[82:83], v[110:111] neg_lo:[0,1] neg_hi:[0,1]
	v_pk_add_f32 v[92:93], v[88:89], v[112:113] neg_lo:[0,1] neg_hi:[0,1]
	v_pk_add_f32 v[94:95], v[90:91], v[114:115] neg_lo:[0,1] neg_hi:[0,1]
	v_pk_add_f32 v[80:81], v[80:81], v[108:109]
	v_pk_add_f32 v[82:83], v[82:83], v[110:111]
	v_pk_add_f32 v[88:89], v[88:89], v[112:113]
	v_pk_add_f32 v[90:91], v[90:91], v[114:115]
	v_pk_mul_f32 v[108:109], v[88:89], v[96:97] op_sel:[1,1] op_sel_hi:[1,0]
	v_pk_mul_f32 v[110:111], v[90:91], v[100:101] op_sel:[1,1] op_sel_hi:[1,0]
	v_pk_mul_f32 v[112:113], v[92:93], v[96:97] op_sel:[1,0] op_sel_hi:[1,1]
	v_pk_mul_f32 v[114:115], v[94:95], v[102:103] op_sel:[1,1] op_sel_hi:[1,0]
	v_pk_fma_f32 v[108:109], v[88:89], v[96:97], v[108:109] op_sel:[0,0,0] op_sel_hi:[0,1,1] neg_lo:[0,0,0] neg_hi:[0,1,0]
	v_pk_fma_f32 v[110:111], v[90:91], v[100:101], v[110:111] op_sel:[0,0,0] op_sel_hi:[0,1,1] neg_lo:[0,0,0] neg_hi:[0,1,0]
	v_pk_fma_f32 v[112:113], v[92:93], v[96:97], v[112:113] op_sel:[0,1,0] op_sel_hi:[0,0,1] neg_lo:[0,0,1] neg_hi:[0,0,0]
	v_pk_fma_f32 v[114:115], v[94:95], v[102:103], v[114:115] op_sel:[0,0,0] op_sel_hi:[0,1,1] neg_lo:[0,0,0] neg_hi:[0,1,0]
	v_pk_add_f32 v[88:89], v[80:81], v[108:109] neg_lo:[0,1] neg_hi:[0,1]
	v_pk_add_f32 v[90:91], v[82:83], v[110:111] neg_lo:[0,1] neg_hi:[0,1]
	v_pk_add_f32 v[92:93], v[84:85], v[112:113] neg_lo:[0,1] neg_hi:[0,1]
	v_pk_add_f32 v[94:95], v[86:87], v[114:115] neg_lo:[0,1] neg_hi:[0,1]
	v_pk_add_f32 v[80:81], v[80:81], v[108:109]
	v_pk_add_f32 v[82:83], v[82:83], v[110:111]
	v_pk_add_f32 v[84:85], v[84:85], v[112:113]
	v_pk_add_f32 v[86:87], v[86:87], v[114:115]
	ds_write2st64_b64 v79, v[80:81], v[82:83] offset1:17
	ds_write2st64_b64 v79, v[84:85], v[86:87] offset0:34 offset1:51
	ds_write2st64_b64 v79, v[88:89], v[90:91] offset0:68 offset1:85
	ds_write2st64_b64 v79, v[92:93], v[94:95] offset0:102 offset1:119
	s_waitcnt lgkmcnt(4)
; #define LAS __attribute__((address_space(3)))
; template <int LR> __device__ __forceinline__ void dit_reg(cf (&x)[1 << LR], cf w) {
;     constexpr int R = 1 << LR; cf wsv[LR]; wsv[0] = w;
; #pragma unroll
;     for (int s = 1; s < LR; ++s) wsv[s] = cmul(wsv[s - 1], wsv[s - 1]);
; #pragma unroll
;     for (int s = LR - 1; s >= 0; --s) { const int half = R >> (s + 1);
; #pragma unroll
;         for (int m0 = 0; m0 < R; m0 += 2 * half)
; #pragma unroll
;             for (int mm = 0; mm < half; ++mm) { const int ia = m0 + mm, ib = ia + half; const cf a = x[ia];
;                 const cf b = cmulc(x[ib], twc(wsv[s], (mm << s) * (16 / R)));
;                 x[ia] = cf{a.x + b.x, a.y + b.y}; x[ib] = cf{a.x - b.x, a.y - b.y}; } }
; }
; __device__ __forceinline__ void lds_barrier() { asm volatile("s_waitcnt lgkmcnt(0)\n\ts_barrier" ::: "memory"); }
; template <int LR, bool INV> __device__ __forceinline__ void fft_pass(ldsf2 buf, int base, int stride, int twi) {
;     constexpr int R = 1 << LR; cf x[R];
;     const v2f wv = ((ldsf2)((LAS unsigned char*)buf + 139264))[twi];
; #pragma unroll
;     for (int m = 0; m < R; ++m) { const v2f v = buf[base + m * stride]; x[m] = cf{v.x, v.y}; }
;     const cf w{wv.x, wv.y};
;     if (INV) dit_reg<LR>(x, w); else dif_reg<LR>(x, w);
; #pragma unroll
;     for (int m = 0; m < R; ++m) buf[base + m * stride] = mkv2(x[m].x, x[m].y);
; }
; __device__ void ph_hyena_fft(const Params& P, int j, const bf16_t* __restrict__ projAT, const float* __restrict__ kf, bf16_t* __restrict__ yaT, unsigned char* lds_raw) {
;     ...
;             { float xa[8], xb[8]; sconv8(xb0, n0, wb0, wb1, wb2, bb, xa); sconv8(xb1, n0, wb0, wb1, wb2, bb, xb);
;               const unsigned gw0[4] = {g0.x, g0.y, g0.z, g0.w}, gw1[4] = {g1.x, g1.y, g1.z, g1.w}; unsigned w0[4], w1[4];
; #pragma unroll
;               for (int k2 = 0; k2 < 4; ++k2) { const v2f ya = buf[ph0 + 2 * k2], yb = buf[ph0 + 2 * k2 + 1];
;                   const float ra = xa[2 * k2] * (ya.x * invN + sk1 * va[2 * k2]) * silu(__uint_as_float(gw0[k2] << 16));
;                   const float rb = xa[2 * k2 + 1] * (yb.x * invN + sk1 * va[2 * k2 + 1]) * silu(__uint_as_float(gw0[k2] & 0xffff0000u));
;                   const float rc = xb[2 * k2] * (ya.y * invN + sk1 * vb[2 * k2]) * silu(__uint_as_float(gw1[k2] << 16));
	v_pk_add_f32 v[142:143], v[132:133], v[132:133] op_sel:[0,1] op_sel_hi:[1,0] neg_lo:[0,0] neg_hi:[0,1]
	v_pk_mul_f32 v[164:165], v[132:133], v[132:133] op_sel:[1,1] op_sel_hi:[1,0]
	v_pk_mul_f32 v[160:161], v[142:143], s[16:17] op_sel:[0,0] op_sel_hi:[1,0]
	v_pk_fma_f32 v[164:165], v[132:133], v[132:133], v[164:165] op_sel:[0,0,0] op_sel_hi:[0,1,1] neg_lo:[0,0,1] neg_hi:[0,0,0]
	v_pk_mul_f32 v[162:163], v[142:143], s[16:17] op_sel:[1,0] op_sel_hi:[0,0] neg_lo:[0,0] neg_hi:[1,0]
	s_nop 0
	v_pk_mul_f32 v[166:167], v[164:165], v[164:165] op_sel:[1,1] op_sel_hi:[1,0]
	s_nop 0
	v_pk_fma_f32 v[166:167], v[164:165], v[164:165], v[166:167] op_sel:[0,0,0] op_sel_hi:[0,1,1] neg_lo:[0,0,1] neg_hi:[0,0,0]
	v_pk_mul_f32 v[168:169], v[136:137], v[166:167] op_sel:[1,1] op_sel_hi:[1,0]
	v_pk_mul_f32 v[170:171], v[140:141], v[166:167] op_sel:[1,1] op_sel_hi:[1,0]
	v_pk_mul_f32 v[172:173], v[154:155], v[166:167] op_sel:[1,1] op_sel_hi:[1,0]
	v_pk_mul_f32 v[174:175], v[158:159], v[166:167] op_sel:[1,1] op_sel_hi:[1,0]
	v_pk_fma_f32 v[168:169], v[136:137], v[166:167], v[168:169] op_sel:[0,0,0] op_sel_hi:[0,1,1] neg_lo:[0,0,0] neg_hi:[0,1,0]
	v_pk_fma_f32 v[170:171], v[140:141], v[166:167], v[170:171] op_sel:[0,0,0] op_sel_hi:[0,1,1] neg_lo:[0,0,0] neg_hi:[0,1,0]
	v_pk_fma_f32 v[172:173], v[154:155], v[166:167], v[172:173] op_sel:[0,0,0] op_sel_hi:[0,1,1] neg_lo:[0,0,0] neg_hi:[0,1,0]
	v_pk_fma_f32 v[174:175], v[158:159], v[166:167], v[174:175] op_sel:[0,0,0] op_sel_hi:[0,1,1] neg_lo:[0,0,0] neg_hi:[0,1,0]
	v_pk_add_f32 v[136:137], v[134:135], v[168:169] neg_lo:[0,1] neg_hi:[0,1]
	v_pk_add_f32 v[140:141], v[138:139], v[170:171] neg_lo:[0,1] neg_hi:[0,1]
	v_pk_add_f32 v[154:155], v[152:153], v[172:173] neg_lo:[0,1] neg_hi:[0,1]
	v_pk_add_f32 v[158:159], v[156:157], v[174:175] neg_lo:[0,1] neg_hi:[0,1]
	v_pk_add_f32 v[134:135], v[134:135], v[168:169]
	v_pk_add_f32 v[138:139], v[138:139], v[170:171]
	v_pk_add_f32 v[152:153], v[152:153], v[172:173]
	v_pk_add_f32 v[156:157], v[156:157], v[174:175]
	v_pk_mul_f32 v[168:169], v[138:139], v[164:165] op_sel:[1,1] op_sel_hi:[1,0]
	v_pk_mul_f32 v[170:171], v[140:141], v[164:165] op_sel:[1,0] op_sel_hi:[1,1]
	v_pk_mul_f32 v[172:173], v[156:157], v[164:165] op_sel:[1,1] op_sel_hi:[1,0]
	v_pk_mul_f32 v[174:175], v[158:159], v[164:165] op_sel:[1,0] op_sel_hi:[1,1]
	v_pk_fma_f32 v[168:169], v[138:139], v[164:165], v[168:169] op_sel:[0,0,0] op_sel_hi:[0,1,1] neg_lo:[0,0,0] neg_hi:[0,1,0]
	v_pk_fma_f32 v[170:171], v[140:141], v[164:165], v[170:171] op_sel:[0,1,0] op_sel_hi:[0,0,1] neg_lo:[0,0,1] neg_hi:[0,0,0]
	v_pk_fma_f32 v[172:173], v[156:157], v[164:165], v[172:173] op_sel:[0,0,0] op_sel_hi:[0,1,1] neg_lo:[0,0,0] neg_hi:[0,1,0]
	v_pk_fma_f32 v[174:175], v[158:159], v[164:165], v[174:175] op_sel:[0,1,0] op_sel_hi:[0,0,1] neg_lo:[0,0,1] neg_hi:[0,0,0]
	v_pk_add_f32 v[138:139], v[134:135], v[168:169] neg_lo:[0,1] neg_hi:[0,1]
	v_pk_add_f32 v[140:141], v[136:137], v[170:171] neg_lo:[0,1] neg_hi:[0,1]
	v_pk_add_f32 v[156:157], v[152:153], v[172:173] neg_lo:[0,1] neg_hi:[0,1]
	v_pk_add_f32 v[158:159], v[154:155], v[174:175] neg_lo:[0,1] neg_hi:[0,1]
	v_pk_add_f32 v[134:135], v[134:135], v[168:169]
	v_pk_add_f32 v[136:137], v[136:137], v[170:171]
	v_pk_add_f32 v[152:153], v[152:153], v[172:173]
	v_pk_add_f32 v[154:155], v[154:155], v[174:175]
	v_pk_mul_f32 v[168:169], v[152:153], v[132:133] op_sel:[1,1] op_sel_hi:[1,0]
	v_pk_mul_f32 v[170:171], v[154:155], v[160:161] op_sel:[1,1] op_sel_hi:[1,0]
	v_pk_mul_f32 v[172:173], v[156:157], v[132:133] op_sel:[1,0] op_sel_hi:[1,1]
	v_pk_mul_f32 v[174:175], v[158:159], v[162:163] op_sel:[1,1] op_sel_hi:[1,0]
	v_pk_fma_f32 v[168:169], v[152:153], v[132:133], v[168:169] op_sel:[0,0,0] op_sel_hi:[0,1,1] neg_lo:[0,0,0] neg_hi:[0,1,0]
	v_pk_fma_f32 v[170:171], v[154:155], v[160:161], v[170:171] op_sel:[0,0,0] op_sel_hi:[0,1,1] neg_lo:[0,0,0] neg_hi:[0,1,0]
	v_pk_fma_f32 v[172:173], v[156:157], v[132:133], v[172:173] op_sel:[0,1,0] op_sel_hi:[0,0,1] neg_lo:[0,0,1] neg_hi:[0,0,0]
	v_pk_fma_f32 v[174:175], v[158:159], v[162:163], v[174:175] op_sel:[0,0,0] op_sel_hi:[0,1,1] neg_lo:[0,0,0] neg_hi:[0,1,0]
	v_pk_add_f32 v[152:153], v[134:135], v[168:169] neg_lo:[0,1] neg_hi:[0,1]
	v_pk_add_f32 v[154:155], v[136:137], v[170:171] neg_lo:[0,1] neg_hi:[0,1]
	v_pk_add_f32 v[156:157], v[138:139], v[172:173] neg_lo:[0,1] neg_hi:[0,1]
	v_pk_add_f32 v[158:159], v[140:141], v[174:175] neg_lo:[0,1] neg_hi:[0,1]
	v_pk_add_f32 v[134:135], v[134:135], v[168:169]
	v_pk_add_f32 v[136:137], v[136:137], v[170:171]
	v_pk_add_f32 v[138:139], v[138:139], v[172:173]
	v_pk_add_f32 v[140:141], v[140:141], v[174:175]
	ds_write2st64_b64 v126, v[134:135], v[136:137] offset1:17
	ds_write2st64_b64 v126, v[138:139], v[140:141] offset0:34 offset1:51
	ds_write2st64_b64 v126, v[152:153], v[154:155] offset0:68 offset1:85
	ds_write2st64_b64 v126, v[156:157], v[158:159] offset0:102 offset1:119
	s_mov_b64 s[30:31], 0
	s_waitcnt vmcnt(6)
	v_lshlrev_b32_e32 v78, 16, v147
	v_cndmask_b32_e64 v97, 0, v78, s[42:43]
	s_waitcnt vmcnt(5)
	v_lshlrev_b32_e32 v78, 16, v148
	s_waitcnt vmcnt(1)
	v_lshlrev_b32_e32 v114, 16, v12
	v_cndmask_b32_e64 v99, 0, v78, s[44:45]
	v_and_b32_e32 v12, 0xffff0000, v12
	v_mul_f32_e32 v78, 0xbfb8aa3b, v114
	v_exp_f32_e32 v78, v78
	v_mul_f32_e32 v82, 0xbfb8aa3b, v12
	v_lshlrev_b32_e32 v104, 16, v5
	v_exp_f32_e32 v82, v82
	v_and_b32_e32 v102, 0xffff0000, v4
	v_mov_b32_e32 v96, v104
	v_lshlrev_b32_e32 v100, 16, v4
	v_and_b32_e32 v103, 0xffff0000, v5
	v_mov_b32_e32 v101, v102
	v_pk_mul_f32 v[96:97], v[38:39], v[96:97]
	v_lshlrev_b32_e32 v115, 16, v13
	v_pk_fma_f32 v[96:97], v[38:39], v[100:101], v[96:97] op_sel:[0,0,1] op_sel_hi:[1,1,0]
	v_mov_b32_e32 v101, v104
	v_pk_mul_f32 v[122:123], v[54:55], v[102:103]
	v_add_f32_e32 v78, 1.0, v78
	v_pk_fma_f32 v[100:101], v[52:53], v[100:101], v[122:123]
	v_rcp_f32_e32 v122, v78
	v_add_f32_e32 v78, 1.0, v82
	v_mul_f32_e32 v82, 0xbfb8aa3b, v115
	v_exp_f32_e32 v82, v82
	s_waitcnt lgkmcnt(0)
	s_barrier
; __device__ __forceinline__ void sconv8(const Raw8& r, int n0, float w0, float w1, float w2, float b, float (&out)[8]) {
;     float a[10]; a[0] = n0 > 0 ? bf2f(r.eL) : 0.f; a[9] = n0 + 8 < SEQ ? bf2f(r.eR) : 0.f;
;     a[1] = __uint_as_float(r.body.x << 16); a[2] = __uint_as_float(r.body.x & 0xffff0000u); a[3] = __uint_as_float(r.body.y << 16); a[4] = __uint_as_float(r.body.y & 0xffff0000u);
;     a[5] = __uint_as_float(r.body.z << 16); a[6] = __uint_as_float(r.body.z & 0xffff0000u); a[7] = __uint_as_float(r.body.w << 16); a[8] = __uint_as_float(r.body.w & 0xffff0000u);
; #pragma unroll
;     for (int k = 0; k < 8; ++k) out[k] = w0 * a[k] + w1 * a[k + 1] + w2 * a[k + 2] + b;
; }
; __device__ void ph_hyena_fft(const Params& P, int j, const bf16_t* __restrict__ projAT, const float* __restrict__ kf, bf16_t* __restrict__ yaT, unsigned char* lds_raw) {
;     const int tid = otid();
;     ldsf2 buf = (ldsf2)lds_raw; LAS unsigned* spec1 = (LAS unsigned*)(lds_raw + 69632); LAS unsigned* spec2 = spec1 + 8704;
;     const float* cw = P.in[6] + (size_t)j * 3 * 3072; const float* cb = P.in[7] + (size_t)j * 3072; const float* skip = P.in[16] + (size_t)j * 2 * 1024;
;     const float invN = 1.0f / 8192.0f;
;     const int n0 = tid * 8, ph0 = n0 + (n0 >> 4);
;     { ldsf2 twt = (ldsf2)((LAS unsigned char*)buf + 139264);
;       for (int k = tid; k < 1024; k += NT) { float sn, cs; sincospif((float)k * (2.0f / 8192.0f), &sn, &cs); twt[k] = mkv2(cs, -sn); }
;       __syncthreads(); }
; #pragma unroll 1
;     for (int c = blockIdx.x; c < 1024; c += gridDim.x) {
;         make_spec(buf, spec1, kf + (size_t)c * 8192);
;         make_spec(buf, spec2, kf + (size_t)(1024 + c) * 8192);
;         const float wv0 = cw[c], wv1 = cw[3072 + c], wv2 = cw[6144 + c], bv = cb[c];
;         const float wa0 = cw[1024 + c], wa1 = cw[3072 + 1024 + c], wa2 = cw[6144 + 1024 + c], ba = cb[1024 + c];
;         const float wb0 = cw[2048 + c], wb1 = cw[3072 + 2048 + c], wb2 = cw[6144 + 2048 + c], bb = cb[2048 + c];
;         const float sk0 = skip[c], sk1 = skip[1024 + c];
;         const bf16_t* vrow = projAT + (size_t)c * T_TOK; const bf16_t* x1row = projAT + (size_t)(1024 + c) * T_TOK;
;         const bf16_t* x2row = projAT + (size_t)(2048 + c) * T_TOK; const bf16_t* grow = projAT + (size_t)(3072 + c) * T_TOK;
; #pragma unroll 1
;         for (int bp = 0; bp < 4; ++bp) {
	ds_read2_b64 v[88:91], v145 offset1:1
	ds_read2_b64 v[92:95], v145 offset0:2 offset1:3
	v_and_b32_e32 v13, 0xffff0000, v13
	v_rcp_f32_e32 v124, v78
	v_add_f32_e32 v78, 1.0, v82
	v_rcp_f32_e32 v123, v78
	v_mul_f32_e32 v78, 0xbfb8aa3b, v13
	v_exp_f32_e32 v78, v78
	s_waitcnt lgkmcnt(1)
	v_mov_b32_e32 v126, v88
	s_waitcnt lgkmcnt(0)
	v_mov_b32_e32 v127, v92
	v_pk_fma_f32 v[96:97], v[40:41], v[102:103], v[96:97]
	v_pk_mul_f32 v[126:127], v[126:127], s[80:81] op_sel_hi:[1,0]
	v_pk_add_f32 v[96:97], v[42:43], v[96:97]
	v_pk_fma_f32 v[76:77], v[46:47], v[76:77], v[126:127]
	v_add_f32_e32 v78, 1.0, v78
	v_pk_mul_f32 v[76:77], v[96:97], v[76:77]
	v_pk_mul_f32 v[96:97], v[122:123], v[114:115]
	v_rcp_f32_e32 v125, v78
	v_lshlrev_b32_e32 v105, 16, v6
	v_pk_mul_f32 v[76:77], v[96:97], v[76:77]
	v_mov_b32_e32 v96, v90
	v_mov_b32_e32 v97, v94
	v_pk_fma_f32 v[100:101], v[40:41], v[104:105], v[100:101]
	v_pk_mul_f32 v[96:97], v[96:97], s[80:81] op_sel_hi:[1,0]
	v_pk_add_f32 v[100:101], v[42:43], v[100:101]
	v_pk_fma_f32 v[74:75], v[46:47], v[74:75], v[96:97]
	v_pk_mul_f32 v[12:13], v[124:125], v[12:13]
	v_pk_mul_f32 v[74:75], v[100:101], v[74:75]
	v_lshlrev_b32_e32 v118, 16, v14
	v_pk_mul_f32 v[12:13], v[12:13], v[74:75]
	v_and_b32_sdwa v74, v77, v229 dst_sel:DWORD dst_unused:UNUSED_PAD src0_sel:WORD_1 src1_sel:DWORD
	v_add3_u32 v74, v77, v74, s33
	v_and_b32_sdwa v77, v12, v229 dst_sel:DWORD dst_unused:UNUSED_PAD src0_sel:WORD_1 src1_sel:DWORD
	v_and_b32_sdwa v75, v76, v229 dst_sel:DWORD dst_unused:UNUSED_PAD src0_sel:WORD_1 src1_sel:DWORD
	v_add3_u32 v12, v12, v77, s33
	v_and_b32_e32 v14, 0xffff0000, v14
	v_add3_u32 v75, v76, v75, s33
	v_and_b32_e32 v12, 0xffff0000, v12
	v_or_b32_sdwa v12, v12, v75 dst_sel:DWORD dst_unused:UNUSED_PAD src0_sel:DWORD src1_sel:WORD_1
	v_mul_f32_e32 v75, 0xbfb8aa3b, v14
	v_exp_f32_e32 v75, v75
	v_lshlrev_b32_e32 v4, 16, v149
	v_lshlrev_b32_e32 v119, 16, v15
	v_and_b32_sdwa v76, v13, v229 dst_sel:DWORD dst_unused:UNUSED_PAD src0_sel:WORD_1 src1_sel:DWORD
	v_add_f32_e32 v75, 1.0, v75
	v_cndmask_b32_e64 v111, 0, v4, s[42:43]
	v_lshlrev_b32_e32 v4, 16, v150
	v_add3_u32 v13, v13, v76, s33
	v_rcp_f32_e32 v76, v75
	v_mul_f32_e32 v75, 0xbfb8aa3b, v119
	v_and_b32_e32 v106, 0xffff0000, v6
	v_lshlrev_b32_e32 v109, 16, v7
	v_and_b32_e32 v107, 0xffff0000, v7
	v_cndmask_b32_e64 v79, 0, v4, s[44:45]
	v_lshlrev_b32_e32 v112, 16, v8
	v_and_b32_e32 v86, 0xffff0000, v8
	v_lshlrev_b32_e32 v80, 16, v9
	v_and_b32_e32 v87, 0xffff0000, v9
	v_lshlrev_b32_e32 v81, 16, v10
	v_and_b32_e32 v84, 0xffff0000, v10
	v_lshlrev_b32_e32 v83, 16, v11
	v_and_b32_e32 v85, 0xffff0000, v11
	ds_read2_b64 v[4:7], v145 offset0:4 offset1:5
	ds_read2_b64 v[8:11], v145 offset0:6 offset1:7
	v_exp_f32_e32 v75, v75
	v_and_b32_e32 v15, 0xffff0000, v15
	v_and_b32_e32 v13, 0xffff0000, v13
	s_waitcnt lgkmcnt(1)
	v_mov_b32_e32 v96, v4
	v_add_f32_e32 v4, 1.0, v75
	v_rcp_f32_e32 v75, v4
	v_mul_f32_e32 v4, 0xbfb8aa3b, v15
	v_exp_f32_e32 v4, v4
	s_waitcnt lgkmcnt(0)
	v_mov_b32_e32 v97, v8
	v_or_b32_sdwa v13, v13, v74 dst_sel:DWORD dst_unused:UNUSED_PAD src0_sel:DWORD src1_sel:WORD_1
	v_mul_f32_e32 v74, 0xbfb8aa3b, v118
	v_add_f32_e32 v4, 1.0, v4
	v_pk_mul_f32 v[96:97], v[96:97], s[80:81] op_sel_hi:[1,0]
	v_rcp_f32_e32 v77, v4
	v_exp_f32_e32 v74, v74
	v_pk_fma_f32 v[72:73], v[46:47], v[72:73], v[96:97]
	v_mov_b32_e32 v96, v6
	v_mov_b32_e32 v97, v10
	v_pk_mul_f32 v[96:97], v[96:97], s[80:81] op_sel_hi:[1,0]
	v_pk_mul_f32 v[14:15], v[76:77], v[14:15]
	v_pk_fma_f32 v[70:71], v[46:47], v[70:71], v[96:97]
	v_mov_b32_e32 v96, v105
	v_mov_b32_e32 v97, v109
	v_pk_mov_b32 v[76:77], v[102:103], v[106:107] op_sel:[1,0]
	v_pk_mul_f32 v[96:97], v[54:55], v[96:97]
	v_mov_b32_e32 v104, v107
	v_mov_b32_e32 v108, v106
	v_add_f32_e32 v74, 1.0, v74
	v_pk_fma_f32 v[76:77], v[52:53], v[76:77], v[96:97]
	v_pk_mul_f32 v[96:97], v[38:39], v[104:105]
	v_mov_b32_e32 v98, v109
	v_rcp_f32_e32 v74, v74
	v_pk_fma_f32 v[96:97], v[38:39], v[108:109], v[96:97] op_sel:[0,0,1] op_sel_hi:[1,1,0]
	v_pk_fma_f32 v[76:77], v[40:41], v[106:107], v[76:77]
	v_pk_fma_f32 v[96:97], v[40:41], v[98:99], v[96:97]
	v_pk_add_f32 v[76:77], v[42:43], v[76:77]
	v_pk_add_f32 v[96:97], v[42:43], v[96:97]
	v_pk_mul_f32 v[74:75], v[74:75], v[118:119]
	v_pk_mul_f32 v[70:71], v[96:97], v[70:71]
	v_pk_mul_f32 v[72:73], v[76:77], v[72:73]
	v_pk_mul_f32 v[14:15], v[14:15], v[70:71]
	v_pk_mul_f32 v[72:73], v[74:75], v[72:73]
	v_and_b32_sdwa v8, v15, v229 dst_sel:DWORD dst_unused:UNUSED_PAD src0_sel:WORD_1 src1_sel:DWORD
	v_and_b32_sdwa v4, v73, v229 dst_sel:DWORD dst_unused:UNUSED_PAD src0_sel:WORD_1 src1_sel:DWORD
	v_and_b32_sdwa v10, v14, v229 dst_sel:DWORD dst_unused:UNUSED_PAD src0_sel:WORD_1 src1_sel:DWORD
	v_add3_u32 v8, v15, v8, s33
	s_waitcnt vmcnt(0)
; __device__ __forceinline__ bf16_t f2bf(float f) { unsigned u = __float_as_uint(f); u += 0x7FFFu + ((u >> 16) & 1u); return (bf16_t)(u >> 16); }
; __device__ __forceinline__ float silu(float x) { return x * __builtin_amdgcn_rcpf(1.0f + __expf(-x)); }
; __device__ __forceinline__ void lds_barrier() { asm volatile("s_waitcnt lgkmcnt(0)\n\ts_barrier" ::: "memory"); }
; __device__ void ph_hyena_fft(const Params& P, int j, const bf16_t* __restrict__ projAT, const float* __restrict__ kf, bf16_t* __restrict__ yaT, unsigned char* lds_raw) {
;     ...
;             { float xa[8], xb[8]; sconv8(xb0, n0, wb0, wb1, wb2, bb, xa); sconv8(xb1, n0, wb0, wb1, wb2, bb, xb);
;               const unsigned gw0[4] = {g0.x, g0.y, g0.z, g0.w}, gw1[4] = {g1.x, g1.y, g1.z, g1.w}; unsigned w0[4], w1[4];
; #pragma unroll
;               for (int k2 = 0; k2 < 4; ++k2) { const v2f ya = buf[ph0 + 2 * k2], yb = buf[ph0 + 2 * k2 + 1];
;                   const float ra = xa[2 * k2] * (ya.x * invN + sk1 * va[2 * k2]) * silu(__uint_as_float(gw0[k2] << 16));
;                   const float rb = xa[2 * k2 + 1] * (yb.x * invN + sk1 * va[2 * k2 + 1]) * silu(__uint_as_float(gw0[k2] & 0xffff0000u));
;                   const float rc = xb[2 * k2] * (ya.y * invN + sk1 * vb[2 * k2]) * silu(__uint_as_float(gw1[k2] << 16));
;                   const float rd = xb[2 * k2 + 1] * (yb.y * invN + sk1 * vb[2 * k2 + 1]) * silu(__uint_as_float(gw1[k2] & 0xffff0000u));
;                   w0[k2] = (unsigned)f2bf(ra) | ((unsigned)f2bf(rb) << 16); w1[k2] = (unsigned)f2bf(rc) | ((unsigned)f2bf(rd) << 16); }
;               *(uint4*)(yaT + (size_t)c * T_TOK + o0 + n0) = make_uint4(w0[0], w0[1], w0[2], w0[3]);
;               *(uint4*)(yaT + (size_t)c * T_TOK + o1 + n0) = make_uint4(w1[0], w1[1], w1[2], w1[3]); }
;             lds_barrier();
;         }
;     }
	v_lshlrev_b32_e32 v116, 16, v0
	v_and_b32_sdwa v6, v72, v229 dst_sel:DWORD dst_unused:UNUSED_PAD src0_sel:WORD_1 src1_sel:DWORD
	v_add3_u32 v4, v73, v4, s33
	v_add3_u32 v10, v14, v10, s33
	v_and_b32_e32 v8, 0xffff0000, v8
	v_and_b32_e32 v0, 0xffff0000, v0
	v_add3_u32 v6, v72, v6, s33
	v_and_b32_e32 v10, 0xffff0000, v10
	v_or_b32_sdwa v15, v8, v4 dst_sel:DWORD dst_unused:UNUSED_PAD src0_sel:DWORD src1_sel:WORD_1
	v_mul_f32_e32 v4, 0xbfb8aa3b, v116
	v_or_b32_sdwa v14, v10, v6 dst_sel:DWORD dst_unused:UNUSED_PAD src0_sel:DWORD src1_sel:WORD_1
	v_exp_f32_e32 v4, v4
	v_mul_f32_e32 v6, 0xbfb8aa3b, v0
	v_exp_f32_e32 v6, v6
	v_lshlrev_b32_e32 v117, 16, v1
	v_add_f32_e32 v4, 1.0, v4
	v_rcp_f32_e32 v72, v4
	v_add_f32_e32 v4, 1.0, v6
	v_rcp_f32_e32 v74, v4
	v_mul_f32_e32 v4, 0xbfb8aa3b, v117
	v_exp_f32_e32 v4, v4
	v_and_b32_e32 v1, 0xffff0000, v1
	v_lshl_add_u64 v[120:121], v[50:51], 0, s[62:63]
	v_mov_b32_e32 v110, v80
	v_add_f32_e32 v4, 1.0, v4
	v_rcp_f32_e32 v73, v4
	v_mul_f32_e32 v4, 0xbfb8aa3b, v1
	v_exp_f32_e32 v4, v4
	global_store_dwordx4 v[120:121], v[12:15], off
	v_mov_b32_e32 v113, v86
	v_mov_b32_e32 v92, v89
	v_pk_mul_f32 v[14:15], v[38:39], v[110:111]
	v_pk_mul_f32 v[76:77], v[92:93], s[80:81] op_sel_hi:[1,0]
	v_pk_fma_f32 v[14:15], v[38:39], v[112:113], v[14:15] op_sel:[0,0,1] op_sel_hi:[1,1,0]
	v_add_f32_e32 v4, 1.0, v4
	v_pk_fma_f32 v[14:15], v[40:41], v[86:87], v[14:15]
	v_mov_b32_e32 v113, v80
	v_pk_add_f32 v[14:15], v[42:43], v[14:15]
	v_pk_mul_f32 v[70:71], v[54:55], v[86:87]
	v_pk_fma_f32 v[68:69], v[46:47], v[68:69], v[76:77]
	v_rcp_f32_e32 v75, v4
	v_pk_fma_f32 v[70:71], v[52:53], v[112:113], v[70:71]
	v_pk_mul_f32 v[14:15], v[14:15], v[68:69]
	v_pk_mul_f32 v[68:69], v[72:73], v[116:117]
	v_mov_b32_e32 v94, v91
	v_pk_fma_f32 v[70:71], v[40:41], v[80:81], v[70:71]
	v_pk_mul_f32 v[14:15], v[68:69], v[14:15]
	v_pk_mul_f32 v[68:69], v[94:95], s[80:81] op_sel_hi:[1,0]
	v_pk_add_f32 v[70:71], v[42:43], v[70:71]
	v_pk_fma_f32 v[66:67], v[46:47], v[66:67], v[68:69]
	v_pk_mul_f32 v[0:1], v[74:75], v[0:1]
	v_pk_mul_f32 v[66:67], v[70:71], v[66:67]
	v_and_b32_sdwa v6, v14, v229 dst_sel:DWORD dst_unused:UNUSED_PAD src0_sel:WORD_1 src1_sel:DWORD
	v_pk_mul_f32 v[0:1], v[0:1], v[66:67]
	v_and_b32_sdwa v4, v15, v229 dst_sel:DWORD dst_unused:UNUSED_PAD src0_sel:WORD_1 src1_sel:DWORD
	v_and_b32_sdwa v10, v0, v229 dst_sel:DWORD dst_unused:UNUSED_PAD src0_sel:WORD_1 src1_sel:DWORD
	v_and_b32_sdwa v8, v1, v229 dst_sel:DWORD dst_unused:UNUSED_PAD src0_sel:WORD_1 src1_sel:DWORD
	v_add3_u32 v0, v0, v10, s33
	v_add3_u32 v6, v14, v6, s33
	v_add3_u32 v1, v1, v8, s33
	v_and_b32_e32 v0, 0xffff0000, v0
	v_lshlrev_b32_e32 v14, 16, v2
	v_and_b32_e32 v2, 0xffff0000, v2
	v_add3_u32 v4, v15, v4, s33
	v_and_b32_e32 v1, 0xffff0000, v1
	v_or_b32_sdwa v0, v0, v6 dst_sel:DWORD dst_unused:UNUSED_PAD src0_sel:DWORD src1_sel:WORD_1
	v_lshlrev_b32_e32 v15, 16, v3
	v_mul_f32_e32 v6, 0xbfb8aa3b, v2
	v_or_b32_sdwa v1, v1, v4 dst_sel:DWORD dst_unused:UNUSED_PAD src0_sel:DWORD src1_sel:WORD_1
	v_mul_f32_e32 v4, 0xbfb8aa3b, v14
	v_exp_f32_e32 v6, v6
	v_mul_f32_e32 v8, 0xbfb8aa3b, v15
	v_exp_f32_e32 v4, v4
	v_exp_f32_e32 v10, v8
	v_and_b32_e32 v3, 0xffff0000, v3
	v_add_f32_e32 v6, 1.0, v6
	v_add_f32_e32 v4, 1.0, v4
	v_rcp_f32_e32 v66, v6
	v_mov_b32_e32 v8, v5
	v_add_f32_e32 v5, 1.0, v10
	v_mul_f32_e32 v6, 0xbfb8aa3b, v3
	v_rcp_f32_e32 v4, v4
	v_rcp_f32_e32 v5, v5
	v_exp_f32_e32 v6, v6
	v_mov_b32_e32 v10, v7
	v_mov_b32_e32 v80, v85
	v_pk_mul_f32 v[4:5], v[4:5], v[14:15]
	v_add_f32_e32 v6, 1.0, v6
	v_mov_b32_e32 v14, v81
	v_mov_b32_e32 v15, v83
	v_rcp_f32_e32 v67, v6
	v_pk_mul_f32 v[6:7], v[10:11], s[80:81] op_sel_hi:[1,0]
	v_pk_mov_b32 v[10:11], v[86:87], v[84:85] op_sel:[1,0]
	v_pk_mul_f32 v[14:15], v[54:55], v[14:15]
	v_mov_b32_e32 v82, v84
	v_pk_fma_f32 v[10:11], v[52:53], v[10:11], v[14:15]
	v_pk_mul_f32 v[14:15], v[38:39], v[80:81]
	v_mov_b32_e32 v78, v83
	v_pk_mul_f32 v[8:9], v[8:9], s[80:81] op_sel_hi:[1,0]
	v_pk_fma_f32 v[10:11], v[40:41], v[84:85], v[10:11]
	v_pk_fma_f32 v[14:15], v[38:39], v[82:83], v[14:15] op_sel:[0,0,1] op_sel_hi:[1,1,0]
	v_pk_fma_f32 v[8:9], v[46:47], v[64:65], v[8:9]
	v_pk_add_f32 v[10:11], v[42:43], v[10:11]
	v_pk_fma_f32 v[14:15], v[40:41], v[78:79], v[14:15]
	v_pk_fma_f32 v[6:7], v[46:47], v[62:63], v[6:7]
	v_pk_add_f32 v[14:15], v[42:43], v[14:15]
	v_pk_mul_f32 v[8:9], v[10:11], v[8:9]
	v_pk_mul_f32 v[2:3], v[66:67], v[2:3]
	v_pk_mul_f32 v[4:5], v[4:5], v[8:9]
	v_pk_mul_f32 v[6:7], v[14:15], v[6:7]
	s_mov_b32 s7, s63
	v_pk_mul_f32 v[2:3], v[2:3], v[6:7]
	v_and_b32_sdwa v6, v5, v229 dst_sel:DWORD dst_unused:UNUSED_PAD src0_sel:WORD_1 src1_sel:DWORD
	v_and_b32_sdwa v7, v4, v229 dst_sel:DWORD dst_unused:UNUSED_PAD src0_sel:WORD_1 src1_sel:DWORD
	v_add3_u32 v4, v4, v7, s33
	v_add3_u32 v5, v5, v6, s33
	v_and_b32_sdwa v6, v3, v229 dst_sel:DWORD dst_unused:UNUSED_PAD src0_sel:WORD_1 src1_sel:DWORD
	v_and_b32_sdwa v7, v2, v229 dst_sel:DWORD dst_unused:UNUSED_PAD src0_sel:WORD_1 src1_sel:DWORD
	v_add3_u32 v3, v3, v6, s33
	v_add3_u32 v2, v2, v7, s33
	v_and_b32_e32 v3, 0xffff0000, v3
	v_and_b32_e32 v2, 0xffff0000, v2
	v_lshl_add_u64 v[12:13], v[50:51], 0, s[6:7]
	v_or_b32_sdwa v3, v3, v5 dst_sel:DWORD dst_unused:UNUSED_PAD src0_sel:DWORD src1_sel:WORD_1
	v_or_b32_sdwa v2, v2, v4 dst_sel:DWORD dst_unused:UNUSED_PAD src0_sel:DWORD src1_sel:WORD_1
	global_store_dwordx4 v[12:13], v[0:3], off
	s_waitcnt lgkmcnt(0)
	s_barrier
	s_add_i32 s53, s53, 1
	s_cmp_eq_u32 s53, 4
	s_cbranch_scc0 .LBB0_346
	s_add_i32 s46, s46, s22
	v_readlane_b32 s60, v255, 27
	s_cmpk_gt_i32 s46, 0x3ff
	v_readlane_b32 s61, v255, 28
	s_movk_i32 s59, 0xffd0
	s_cbranch_scc0 .LBB0_333
